# packed-vs-scalar fp32: 834 v_pk_mul/add/fma_f32 in the attention loops split into scalar pairs (bit-identical)
# baseline (speedup 1.0000x reference)
; #define MFMA(a, b, c) __builtin_amdgcn_mfma_f32_32x32x16_bf16((a), (b), (c), 0, 0, 0)
; DI int crow(int i, int h) { return (i & 3) + 8 * (i >> 2) + 4 * h; }
; DI void qk_tile(const bf16_t* sK, const bf16x8 (&qf)[4], f32x16 (&Sx)[2], int r, int h) {
; #pragma unroll
;   for (int mt = 0; mt < 2; ++mt) {
;     f32x16 a;
; #pragma unroll
;     for (int i = 0; i < 16; ++i) a[i] = 0.f;
; #pragma unroll
;     for (int s = 0; s < 4; ++s) {
;       const bf16x8 k = *(const bf16x8*)(sK + (mt * 32 + r) * 72 + s * 16 + h * 8);
;       a = MFMA(k, qf[s], a);
;     }
;     Sx[mt] = a;
;   }
; template <bool MASKED>
; DI void sb_weights(f32x16 (&Sx)[2], float& carry, int kt, int t, int h) {
; #pragma unroll
;     ...
;         float L[16];
; #pragma unroll
;         for (int i = 0; i < 16; ++i) {
;           const float z = Sx[mt][i];
;           const bool ok = !MASKED || (kt * 64 + mt * 32 + crow(i, h) < t);
;           const float sp = fmaxf(z, 0.f) + __logf(1.f + __expf(-fabsf(z)));
;           L[i] = ok ? -sp : 0.f;
;           Sx[mt][i] = ok ? (z - sp) : NEG;
;         }
.LBB0_277:
	s_add_i32 s44, s80, 1
	v_cmp_le_i32_e64 s[0:1], s44, v177
	s_and_saveexec_b64 s[36:37], s[0:1]
	s_cbranch_execz .LBB0_283
	ds_read_b128 v[0:3], v32
	ds_read_b128 v[4:7], v32 offset:32
	v_cmp_ge_i32_e64 s[0:1], s42, v175
	v_add_f32_e32 v188, 0, v144
	s_waitcnt lgkmcnt(1)
	v_mfma_f32_32x32x16_bf16 v[66:81], v[0:3], v[106:109], 0
	ds_read_b128 v[0:3], v32 offset:4608
	ds_read_b128 v[8:11], v32 offset:4640
	s_waitcnt lgkmcnt(1)
	v_mfma_f32_32x32x16_bf16 v[82:97], v[0:3], v[106:109], 0
	s_waitcnt lgkmcnt(0)
	v_mfma_f32_32x32x16_bf16 v[82:97], v[8:11], v[98:101], v[82:97]
	ds_read_b128 v[0:3], v32 offset:4672
	ds_read_b128 v[8:11], v32 offset:64
	ds_read_b128 v[12:15], v32 offset:96
	ds_read_b128 v[16:19], v32 offset:4704
	v_mfma_f32_32x32x16_bf16 v[66:81], v[4:7], v[98:101], v[66:81]
	s_waitcnt lgkmcnt(3)
	v_mfma_f32_32x32x16_bf16 v[82:97], v[0:3], v[102:105], v[82:97]
	v_and_b32_e32 v1, 64, v208
	v_xor_b32_e32 v0, 32, v208
	v_add_u32_e32 v1, 64, v1
	v_cmp_lt_i32_e64 s[4:5], v0, v1
	s_nop 1
	s_nop 0
	v_cndmask_b32_e64 v0, v208, v0, s[4:5]
	s_waitcnt lgkmcnt(2)
	v_mfma_f32_32x32x16_bf16 v[66:81], v[8:11], v[102:105], v[66:81]
	v_lshlrev_b32_e32 v181, 2, v0
	s_waitcnt lgkmcnt(0)
	v_mfma_f32_32x32x16_bf16 v[82:97], v[16:19], v[110:113], v[82:97]
	v_mfma_f32_32x32x16_bf16 v[66:81], v[12:15], v[110:113], v[66:81]
	s_nop 10
	v_mul_f32_e64 v1, |v82|, s76
	v_mul_f32_e64 v3, |v83|, s76
	v_mul_f32_e64 v17, |v84|, s76
	v_mul_f32_e64 v19, |v85|, s76
	v_mul_f32_e64 v21, |v86|, s76
	v_mul_f32_e64 v23, |v87|, s76
	v_mul_f32_e64 v25, |v88|, s76
	v_mul_f32_e64 v27, |v89|, s76
	v_mul_f32_e64 v29, |v90|, s76
	v_mul_f32_e64 v4, |v91|, s76
	v_mul_f32_e64 v6, |v92|, s76
	v_mul_f32_e64 v31, |v93|, s76
	v_mul_f32_e64 v147, |v94|, s76
	v_mul_f32_e64 v9, |v95|, s76
	v_mul_f32_e64 v11, |v96|, s76
	v_mul_f32_e64 v151, |v97|, s76
	v_mul_f32_e64 v13, |v66|, s76
	v_mul_f32_e64 v15, |v67|, s76
	v_mul_f32_e64 v155, |v68|, s76
	v_exp_f32_e32 v243, v1
	v_exp_f32_e32 v239, v3
	v_exp_f32_e32 v205, v17
	v_exp_f32_e32 v202, v19
	v_exp_f32_e32 v201, v21
	v_exp_f32_e32 v200, v23
	v_exp_f32_e32 v199, v25
	v_exp_f32_e32 v198, v27
	v_exp_f32_e32 v197, v29
	v_exp_f32_e32 v196, v4
	v_exp_f32_e32 v195, v6
	v_exp_f32_e32 v194, v31
	v_exp_f32_e32 v193, v147
	v_exp_f32_e32 v192, v9
	v_exp_f32_e32 v191, v11
	v_exp_f32_e32 v190, v151
	v_exp_f32_e32 v189, v13
	v_exp_f32_e32 v187, v15
	v_exp_f32_e32 v186, v155
	v_max_f32_e32 v0, v82, v82
	v_max_f32_e32 v2, v83, v83
	v_max_f32_e32 v16, v84, v84
	v_max_f32_e32 v18, v85, v85
	v_max_f32_e32 v20, v86, v86
	v_max_f32_e32 v22, v87, v87
	v_max_f32_e32 v24, v88, v88
	v_max_f32_e32 v26, v89, v89
	v_max_f32_e32 v28, v90, v90
	v_max_f32_e32 v30, v91, v91
	v_max_f32_e32 v5, v92, v92
	v_max_f32_e32 v7, v93, v93
	v_max_f32_e32 v145, v94, v94
	v_max_f32_e32 v8, v95, v95
	v_max_f32_e32 v10, v96, v96
	v_max_f32_e32 v149, v97, v97
	v_max_f32_e32 v12, v66, v66
	v_max_f32_e32 v14, v67, v67
	v_max_f32_e32 v153, v68, v68
	v_max_f32_e32 v160, 0, v0
	v_max_f32_e32 v158, 0, v2
	v_max_f32_e32 v156, 0, v16
	v_max_f32_e32 v154, 0, v18
	v_max_f32_e32 v152, 0, v20
	v_max_f32_e32 v150, 0, v22
	v_max_f32_e32 v148, 0, v24
	v_max_f32_e32 v146, 0, v26
	v_max_f32_e32 v172, 0, v28
	v_max_f32_e32 v170, 0, v30
	v_max_f32_e32 v173, 0, v5
	v_max_f32_e32 v171, 0, v7
	v_max_f32_e32 v168, 0, v145
	v_max_f32_e32 v166, 0, v8
	v_max_f32_e32 v169, 0, v10
	v_max_f32_e32 v167, 0, v149
	v_max_f32_e32 v162, 0, v12
	v_max_f32_e32 v164, 0, v14
	v_max_f32_e32 v163, 0, v153
	v_max_f32_e32 v165, v69, v69
	v_mul_f32_e64 v185, |v69|, s76
	v_max_f32_e32 v161, v70, v70
	v_mul_f32_e64 v184, |v70|, s76
	v_max_f32_e32 v159, v71, v71
	v_mul_f32_e64 v183, |v71|, s76
	v_max_f32_e32 v157, v72, v72
	v_mul_f32_e64 v182, |v72|, s76
	v_max_f32_e32 v155, v73, v73
	v_mul_f32_e64 v153, |v73|, s76
	v_max_f32_e32 v151, v74, v74
	v_mul_f32_e64 v149, |v74|, s76
	v_max_f32_e32 v147, v75, v75
	v_mul_f32_e64 v145, |v75|, s76
	s_and_saveexec_b64 s[4:5], s[0:1]
	s_xor_b64 s[38:39], exec, s[4:5]
	s_cbranch_execz .LBB0_280
	v_add_f32_e32 v0, 1.0, v243
	v_add_f32_e32 v2, 1.0, v239
	v_log_f32_e32 v0, v0
	v_log_f32_e32 v2, v2
	v_mul_f32_e32 v1, 0x3f317217, v0
	v_fma_f32 v1, v0, s77, -v1
	v_fmac_f32_e32 v1, 0x3377d1cf, v0
	v_fmac_f32_e32 v1, 0x3f317217, v0
	v_add_f32_e32 v3, 1.0, v205
	v_add_u32_e32 v22, s42, v176
	v_mov_b32_e32 v0, v1
	v_mul_f32_e32 v1, 0x3f317217, v2
	v_fma_f32 v1, v2, s77, -v1
	v_fmac_f32_e32 v1, 0x3377d1cf, v2
	v_log_f32_e32 v3, v3
	v_fmac_f32_e32 v1, 0x3f317217, v2
	v_add_f32_e32 v4, 1.0, v202
	v_subrev_u32_e32 v15, 63, v22
	v_mov_b32_e32 v2, v1
	v_mul_f32_e32 v1, 0x3f317217, v3
	v_fma_f32 v1, v3, s77, -v1
	v_log_f32_e32 v5, v4
	v_fmac_f32_e32 v1, 0x3377d1cf, v3
	v_fmac_f32_e32 v1, 0x3f317217, v3
	v_max_f32_e32 v161, 0, v161
	v_max_f32_e32 v159, 0, v159
	v_mov_b32_e32 v4, v1
	v_mul_f32_e32 v1, 0x3f317217, v5
	v_add_f32_e32 v3, 1.0, v201
	v_fma_f32 v1, v5, s77, -v1
	v_fmac_f32_e32 v1, 0x3377d1cf, v5
	v_fmac_f32_e32 v1, 0x3f317217, v5
	v_log_f32_e32 v3, v3
	v_max_f32_e32 v157, 0, v157
	v_mov_b32_e32 v6, v1
	v_add_f32_e32 v5, 1.0, v200
	v_mul_f32_e32 v8, 0x3f317217, v3
	v_fma_f32 v8, v3, s77, -v8
	v_log_f32_e32 v5, v5
	v_fmac_f32_e32 v8, 0x3377d1cf, v3
	v_fmac_f32_e32 v8, 0x3f317217, v3
	v_max_f32_e32 v155, 0, v155
	v_mul_f32_e32 v10, 0x3f317217, v5
	v_add_f32_e32 v3, 1.0, v199
	v_fma_f32 v10, v5, s77, -v10
	v_fmac_f32_e32 v10, 0x3377d1cf, v5
	v_fmac_f32_e32 v10, 0x3f317217, v5
	v_log_f32_e32 v3, v3
	v_add_f32_e32 v5, 1.0, v198
	v_mul_f32_e32 v16, 0x3f317217, v3
	v_fma_f32 v16, v3, s77, -v16
	v_log_f32_e32 v5, v5
	v_fmac_f32_e32 v16, 0x3377d1cf, v3
	v_fmac_f32_e32 v16, 0x3f317217, v3
; DI int crow(int i, int h) { return (i & 3) + 8 * (i >> 2) + 4 * h; }
; DI float shx32(float v) { return __shfl_xor(v, 32); }
; template <bool MASKED>
; DI void sb_weights(f32x16 (&Sx)[2], float& carry, int kt, int t, int h) {
;     ...
;         for (int i = 0; i < 16; ++i) {
;           const float z = Sx[mt][i];
;           const bool ok = !MASKED || (kt * 64 + mt * 32 + crow(i, h) < t);
;           const float sp = fmaxf(z, 0.f) + __logf(1.f + __expf(-fabsf(z)));
;           L[i] = ok ? -sp : 0.f;
;           Sx[mt][i] = ok ? (z - sp) : NEG;
;         }
;         float G[4], Go[4];
; #pragma unroll
;         for (int gg = 0; gg < 4; ++gg) { G[gg] = (L[4 * gg] + L[4 * gg + 1]) + (L[4 * gg + 2] + L[4 * gg + 3]); Go[gg] = shx32(G[gg]); }
;         float T[4];
;         T[3] = 0.f; T[2] = G[3] + Go[3]; T[1] = T[2] + (G[2] + Go[2]); T[0] = T[1] + (G[1] + Go[1]);
	v_mul_f32_e32 v18, 0x3f317217, v5
	v_fma_f32 v18, v5, s77, -v18
	v_fmac_f32_e32 v18, 0x3377d1cf, v5
	v_fmac_f32_e32 v18, 0x3f317217, v5
	v_add_f32_e32 v3, 1.0, v197
	v_log_f32_e32 v3, v3
	v_add_u32_e32 v1, -15, v22
	v_mul_f32_e32 v5, 0x3f317217, v3
	v_fma_f32 v5, v3, s77, -v5
	v_fmac_f32_e32 v5, 0x3377d1cf, v3
	v_fmac_f32_e32 v5, 0x3f317217, v3
	v_mov_b32_e32 v3, v5
	v_add_f32_e32 v5, 1.0, v196
	v_add_f32_e32 v3, v172, v3
	v_cmp_lt_i32_e64 s[0:1], v1, v130
	v_log_f32_e32 v5, v5
	s_nop 0
	v_cndmask_b32_e64 v1, 0, -v3, s[0:1]
	v_sub_f32_e32 v3, v90, v3
	v_cndmask_b32_e64 v24, v214, v3, s[0:1]
	v_mul_f32_e32 v7, 0x3f317217, v5
	v_fma_f32 v7, v5, s77, -v7
	v_fmac_f32_e32 v7, 0x3377d1cf, v5
	v_add_u32_e32 v3, -14, v22
	v_fmac_f32_e32 v7, 0x3f317217, v5
	v_cmp_lt_i32_e64 s[0:1], v3, v130
	v_add_f32_e32 v3, 1.0, v195
	v_mov_b32_e32 v5, v7
	v_add_f32_e32 v5, v170, v5
	v_log_f32_e32 v3, v3
	v_cndmask_b32_e64 v25, 0, -v5, s[0:1]
	v_sub_f32_e32 v5, v91, v5
	v_cndmask_b32_e64 v90, v214, v5, s[0:1]
	v_mul_f32_e32 v7, 0x3f317217, v3
	v_fma_f32 v7, v3, s77, -v7
	v_fmac_f32_e32 v7, 0x3377d1cf, v3
	v_add_u32_e32 v5, -13, v22
	v_fmac_f32_e32 v7, 0x3f317217, v3
	v_add_f32_e32 v20, v1, v25
	v_cmp_lt_i32_e64 s[0:1], v5, v130
	v_add_f32_e32 v5, 1.0, v194
	v_mov_b32_e32 v3, v7
	v_add_f32_e32 v3, v173, v3
	v_log_f32_e32 v5, v5
	v_cndmask_b32_e64 v26, 0, -v3, s[0:1]
	v_sub_f32_e32 v3, v92, v3
	v_cndmask_b32_e64 v91, v214, v3, s[0:1]
	v_mul_f32_e32 v7, 0x3f317217, v5
	v_fma_f32 v7, v5, s77, -v7
	v_fmac_f32_e32 v7, 0x3377d1cf, v5
	v_add_u32_e32 v3, -12, v22
	v_fmac_f32_e32 v7, 0x3f317217, v5
	v_cmp_lt_i32_e64 s[0:1], v3, v130
	v_add_f32_e32 v3, 1.0, v193
	v_mov_b32_e32 v5, v7
	v_add_f32_e32 v5, v171, v5
	v_log_f32_e32 v3, v3
	v_cndmask_b32_e64 v27, 0, -v5, s[0:1]
	v_sub_f32_e32 v5, v93, v5
	v_cndmask_b32_e64 v92, v214, v5, s[0:1]
	v_mul_f32_e32 v7, 0x3f317217, v3
	v_fma_f32 v7, v3, s77, -v7
	v_fmac_f32_e32 v7, 0x3377d1cf, v3
	v_fmac_f32_e32 v7, 0x3f317217, v3
	v_add_u32_e32 v5, -7, v22
	v_mov_b32_e32 v3, v7
	v_add_f32_e32 v7, 1.0, v192
	v_add_f32_e32 v3, v168, v3
	v_cmp_lt_i32_e64 s[0:1], v5, v130
	v_log_f32_e32 v7, v7
	s_nop 0
	v_cndmask_b32_e64 v5, 0, -v3, s[0:1]
	v_sub_f32_e32 v3, v94, v3
	v_cndmask_b32_e64 v3, v214, v3, s[0:1]
	v_mul_f32_e32 v11, 0x3f317217, v7
	v_fma_f32 v11, v7, s77, -v11
	v_fmac_f32_e32 v11, 0x3377d1cf, v7
	v_fmac_f32_e32 v11, 0x3f317217, v7
	v_add_u32_e32 v9, -6, v22
	v_mov_b32_e32 v7, v11
	v_add_f32_e32 v11, 1.0, v191
	v_add_f32_e32 v7, v166, v7
	v_cmp_lt_i32_e64 s[0:1], v9, v130
	v_log_f32_e32 v11, v11
	s_nop 0
	v_cndmask_b32_e64 v9, 0, -v7, s[0:1]
	v_sub_f32_e32 v7, v95, v7
	v_cndmask_b32_e64 v7, v214, v7, s[0:1]
	v_mul_f32_e32 v13, 0x3f317217, v11
	v_fma_f32 v13, v11, s77, -v13
	v_fmac_f32_e32 v13, 0x3377d1cf, v11
	v_add_u32_e32 v12, -5, v22
	v_fmac_f32_e32 v13, 0x3f317217, v11
	v_add_f32_e32 v5, v5, v9
	v_cmp_lt_i32_e64 s[0:1], v12, v130
	v_add_f32_e32 v12, 1.0, v190
	v_mov_b32_e32 v11, v13
	v_add_f32_e32 v11, v169, v11
	v_log_f32_e32 v12, v12
	v_cndmask_b32_e64 v13, 0, -v11, s[0:1]
	v_sub_f32_e32 v11, v96, v11
	v_cndmask_b32_e64 v11, v214, v11, s[0:1]
	v_mul_f32_e32 v17, 0x3f317217, v12
	v_fma_f32 v17, v12, s77, -v17
	v_fmac_f32_e32 v17, 0x3377d1cf, v12
	v_fmac_f32_e32 v17, 0x3f317217, v12
	v_add_u32_e32 v14, -4, v22
	v_mov_b32_e32 v12, v17
	v_add_f32_e32 v12, v167, v12
	v_cmp_lt_i32_e64 s[0:1], v14, v130
	s_nop 1
	s_nop 0
	v_cndmask_b32_e64 v17, 0, -v12, s[0:1]
	v_add_f32_e32 v14, v13, v17
	v_add_f32_e32 v5, v5, v14
	ds_bpermute_b32 v19, v181, v5
	v_sub_f32_e32 v12, v97, v12
	v_cndmask_b32_e64 v21, v214, v12, s[0:1]
	v_max_f32_e32 v97, v78, v78
	v_max_f32_e32 v97, 0, v97
	s_waitcnt lgkmcnt(0)
	v_cndmask_b32_e32 v1, 0, v19, vcc
	v_add_f32_e32 v1, v188, v1
	v_add_f32_e32 v14, v5, v19
	v_add_f32_e32 v5, v17, v1
	v_add_f32_e32 v1, v21, v1
	v_mul_f32_e32 v1, 0x3fb8aa3b, v1
	v_exp_f32_e32 v31, v1
	v_add_f32_e32 v1, v11, v5
	v_add_f32_e32 v13, v13, v5
	v_mul_f32_e32 v1, 0x3fb8aa3b, v1
	v_exp_f32_e32 v30, v1
	v_add_f32_e32 v1, v7, v13
	v_mul_f32_e32 v1, 0x3fb8aa3b, v1
	v_exp_f32_e32 v29, v1
	v_add_f32_e32 v1, 1.0, v189
	v_add_f32_e32 v9, v9, v13
	v_add_f32_e32 v3, v3, v9
	v_log_f32_e32 v1, v1
	v_mul_f32_e32 v3, 0x3fb8aa3b, v3
	v_exp_f32_e32 v28, v3
	v_exp_f32_e32 v9, v153
	v_mul_f32_e32 v3, 0x3f317217, v1
	v_fma_f32 v3, v1, s77, -v3
	v_fmac_f32_e32 v3, 0x3377d1cf, v1
	v_fmac_f32_e32 v3, 0x3f317217, v1
	v_exp_f32_e32 v11, v149
	v_exp_f32_e32 v13, v145
	v_mov_b32_e32 v1, v3
	v_add_f32_e32 v3, 1.0, v187
	v_add_f32_e32 v1, v162, v1
	v_cmp_lt_i32_e64 s[0:1], v15, v130
	v_log_f32_e32 v3, v3
	s_nop 0
	v_cndmask_b32_e64 v23, 0, -v1, s[0:1]
	v_sub_f32_e32 v1, v66, v1
	v_cndmask_b32_e64 v66, v214, v1, s[0:1]
	v_mul_f32_e32 v5, 0x3f317217, v3
	v_fma_f32 v5, v3, s77, -v5
	v_fmac_f32_e32 v5, 0x3377d1cf, v3
	v_subrev_u32_e32 v1, 62, v22
	v_fmac_f32_e32 v5, 0x3f317217, v3
	v_mul_f32_e64 v17, |v76|, s76
	v_exp_f32_e32 v17, v17
	v_cmp_lt_i32_e64 s[0:1], v1, v130
	v_add_f32_e32 v1, 1.0, v186
	v_mov_b32_e32 v3, v5
	v_add_f32_e32 v3, v164, v3
	v_log_f32_e32 v1, v1
	v_cndmask_b32_e64 v94, 0, -v3, s[0:1]
	v_sub_f32_e32 v3, v67, v3
	v_cndmask_b32_e64 v67, v214, v3, s[0:1]
	v_mul_f32_e32 v5, 0x3f317217, v1
	v_fma_f32 v5, v1, s77, -v5
	v_fmac_f32_e32 v5, 0x3377d1cf, v1
	v_fmac_f32_e32 v5, 0x3f317217, v1
	v_subrev_u32_e32 v3, 61, v22
	v_add_f32_e32 v17, 1.0, v17
	v_mov_b32_e32 v1, v5
	v_exp_f32_e32 v5, v185
	v_cmp_lt_i32_e64 s[0:1], v3, v130
	v_add_f32_e32 v1, v163, v1
	v_max_f32_e32 v153, 0, v151
	v_add_f32_e32 v3, 1.0, v5
	v_cndmask_b32_e64 v95, 0, -v1, s[0:1]
	v_sub_f32_e32 v1, v68, v1
	v_log_f32_e32 v3, v3
	v_cndmask_b32_e64 v68, v214, v1, s[0:1]
; DI int crow(int i, int h) { return (i & 3) + 8 * (i >> 2) + 4 * h; }
; template <bool MASKED>
; DI void sb_weights(f32x16 (&Sx)[2], float& carry, int kt, int t, int h) {
;     ...
;         for (int i = 0; i < 16; ++i) {
;           const float z = Sx[mt][i];
;           const bool ok = !MASKED || (kt * 64 + mt * 32 + crow(i, h) < t);
;           const float sp = fmaxf(z, 0.f) + __logf(1.f + __expf(-fabsf(z)));
;           L[i] = ok ? -sp : 0.f;
;           Sx[mt][i] = ok ? (z - sp) : NEG;
;         }
	v_subrev_u32_e32 v1, 60, v22
	v_max_f32_e32 v5, 0, v165
	v_mul_f32_e32 v7, 0x3f317217, v3
	v_fma_f32 v7, v3, s77, -v7
	v_fmac_f32_e32 v7, 0x3377d1cf, v3
	v_fmac_f32_e32 v7, 0x3f317217, v3
	v_max_f32_e32 v151, 0, v147
	v_add_f32_e32 v23, v23, v94
	v_mov_b32_e32 v3, v7
	v_exp_f32_e32 v7, v184
	v_cmp_lt_i32_e64 s[0:1], v1, v130
	v_add_f32_e32 v3, v5, v3
	v_add_f32_e32 v12, v26, v27
	v_add_f32_e32 v1, 1.0, v7
	v_cndmask_b32_e64 v96, 0, -v3, s[0:1]
	v_sub_f32_e32 v3, v69, v3
	v_log_f32_e32 v1, v1
	v_cndmask_b32_e64 v69, v214, v3, s[0:1]
	v_exp_f32_e32 v5, v183
	v_exp_f32_e32 v7, v182
	v_mul_f32_e32 v3, 0x3f317217, v1
	v_fma_f32 v3, v1, s77, -v3
	v_fmac_f32_e32 v3, 0x3377d1cf, v1
	v_fmac_f32_e32 v3, 0x3f317217, v1
	v_add_f32_e32 v93, v144, v14
	v_mov_b32_e32 v1, v3
	v_add_f32_e32 v3, 1.0, v5
	v_log_f32_e32 v3, v3
	v_mov_b32_e32 v1, v1
	v_add_f32_e64 v0, v160, v0
	v_add_f32_e64 v1, v161, v1
	v_mul_f32_e32 v5, 0x3f317217, v3
	v_fma_f32 v5, v3, s77, -v5
	v_fmac_f32_e32 v5, 0x3377d1cf, v3
	v_fmac_f32_e32 v5, 0x3f317217, v3
	v_mov_b32_e32 v3, v5
	v_add_f32_e32 v5, 1.0, v7
	v_log_f32_e32 v5, v5
	v_mov_b32_e32 v3, v3
	v_add_f32_e64 v2, v158, v2
	v_add_f32_e64 v3, v159, v3
	v_mul_f32_e32 v7, 0x3f317217, v5
	v_fma_f32 v7, v5, s77, -v7
	v_fmac_f32_e32 v7, 0x3377d1cf, v5
	v_fmac_f32_e32 v7, 0x3f317217, v5
	v_mov_b32_e32 v5, v7
	v_add_f32_e32 v7, 1.0, v9
	v_log_f32_e32 v7, v7
	v_mov_b32_e32 v5, v5
	v_add_f32_e64 v4, v156, v4
	v_add_f32_e64 v5, v157, v5
	v_mul_f32_e32 v9, 0x3f317217, v7
	v_fma_f32 v9, v7, s77, -v9
	v_fmac_f32_e32 v9, 0x3377d1cf, v7
	v_fmac_f32_e32 v9, 0x3f317217, v7
	v_or_b32_e32 v156, 10, v15
	v_mov_b32_e32 v7, v9
	v_add_f32_e32 v9, 1.0, v11
	v_log_f32_e32 v9, v9
	v_mov_b32_e32 v7, v7
	v_add_f32_e64 v6, v154, v6
	v_add_f32_e64 v7, v155, v7
	v_mul_f32_e32 v11, 0x3f317217, v9
	v_fma_f32 v11, v9, s77, -v11
	v_fmac_f32_e32 v11, 0x3377d1cf, v9
	v_fmac_f32_e32 v11, 0x3f317217, v9
	v_or_b32_e32 v154, 11, v15
	v_mov_b32_e32 v9, v11
	v_add_f32_e32 v11, 1.0, v13
	v_log_f32_e32 v11, v11
	v_mov_b32_e32 v9, v9
	v_add_f32_e64 v8, v152, v8
	v_add_f32_e64 v9, v153, v9
	v_mul_f32_e32 v13, 0x3f317217, v11
	v_fma_f32 v13, v11, s77, -v13
	v_fmac_f32_e32 v13, 0x3377d1cf, v11
	v_fmac_f32_e32 v13, 0x3f317217, v11
	v_or_b32_e32 v152, 16, v15
	v_mov_b32_e32 v11, v13
	v_max_f32_e32 v13, v76, v76
	v_log_f32_e32 v17, v17
	v_mul_f32_e64 v19, |v77|, s76
	v_exp_f32_e32 v19, v19
	v_max_f32_e32 v149, 0, v13
	v_mul_f32_e32 v13, 0x3f317217, v17
	v_fma_f32 v13, v17, s77, -v13
	v_fmac_f32_e32 v13, 0x3377d1cf, v17
	v_fmac_f32_e32 v13, 0x3f317217, v17
	v_add_f32_e32 v19, 1.0, v19
	v_add_f32_e64 v10, v150, v10
	v_add_f32_e64 v11, v151, v11
	v_mov_b32_e32 v17, v13
	v_max_f32_e32 v13, v77, v77
	v_log_f32_e32 v19, v19
	v_max_f32_e32 v147, 0, v13
	v_mul_f32_e64 v21, |v78|, s76
	v_exp_f32_e32 v21, v21
	v_mul_f32_e32 v13, 0x3f317217, v19
	v_fma_f32 v13, v19, s77, -v13
	v_fmac_f32_e32 v13, 0x3377d1cf, v19
	v_fmac_f32_e32 v13, 0x3f317217, v19
	v_or_b32_e32 v150, 17, v15
	v_or_b32_e32 v151, 19, v15
	v_mov_b32_e32 v19, v13
	v_add_f32_e32 v13, 1.0, v21
	v_log_f32_e32 v13, v13
	v_subrev_u32_e32 v21, 39, v22
	v_mul_f32_e32 v145, 0x3f317217, v13
	v_fma_f32 v145, v13, s77, -v145
	v_fmac_f32_e32 v145, 0x3377d1cf, v13
	v_fmac_f32_e32 v145, 0x3f317217, v13
	v_mov_b32_e32 v13, v145
	v_add_f32_e32 v13, v97, v13
	v_mul_f32_e64 v97, |v79|, s76
	v_exp_f32_e32 v97, v97
	v_cmp_lt_i32_e64 s[0:1], v21, v130
	s_nop 1
	s_nop 0
	v_cndmask_b32_e64 v21, 0, -v13, s[0:1]
	v_sub_f32_e32 v13, v78, v13
	v_cndmask_b32_e64 v162, v214, v13, s[0:1]
	v_add_f32_e32 v13, 1.0, v97
	v_max_f32_e32 v97, v79, v79
	v_max_f32_e32 v97, 0, v97
	v_log_f32_e32 v13, v13
	v_subrev_u32_e32 v78, 38, v22
	v_mul_f32_e32 v145, 0x3f317217, v13
	v_fma_f32 v145, v13, s77, -v145
	v_fmac_f32_e32 v145, 0x3377d1cf, v13
	v_fmac_f32_e32 v145, 0x3f317217, v13
	v_mov_b32_e32 v13, v145
	v_add_f32_e32 v97, v97, v13
	v_mul_f32_e64 v13, |v80|, s76
	v_exp_f32_e32 v145, v13
	v_cmp_lt_i32_e64 s[0:1], v78, v130
	v_sub_f32_e32 v78, v79, v97
	s_nop 0
	v_cndmask_b32_e64 v13, 0, -v97, s[0:1]
	v_cndmask_b32_e64 v97, v214, v78, s[0:1]
	v_add_f32_e32 v78, 1.0, v145
	v_max_f32_e32 v145, v80, v80
	v_max_f32_e32 v145, 0, v145
	v_log_f32_e32 v78, v78
	v_subrev_u32_e32 v79, 37, v22
	v_subrev_u32_e32 v22, 36, v22
	v_add_f32_e64 v20, v20, v12
	v_add_f32_e64 v21, v21, v13
	v_mul_f32_e32 v163, 0x3f317217, v78
	v_fma_f32 v163, v78, s77, -v163
	v_fmac_f32_e32 v163, 0x3377d1cf, v78
	v_fmac_f32_e32 v163, 0x3f317217, v78
	v_mov_b32_e32 v78, v163
	v_add_f32_e32 v78, v145, v78
	v_mul_f32_e64 v145, |v81|, s76
	v_exp_f32_e32 v145, v145
	v_cmp_lt_i32_e64 s[0:1], v79, v130
	s_nop 1
	s_nop 0
	v_cndmask_b32_e64 v163, 0, -v78, s[0:1]
	v_sub_f32_e32 v78, v80, v78
	v_cndmask_b32_e64 v164, v214, v78, s[0:1]
	v_add_f32_e32 v78, 1.0, v145
	v_log_f32_e32 v78, v78
	v_max_f32_e32 v79, v81, v81
	v_max_f32_e32 v79, 0, v79
	v_mul_f32_e32 v80, 0x3f317217, v78
	v_fma_f32 v80, v78, s77, -v80
	v_fmac_f32_e32 v80, 0x3377d1cf, v78
	v_fmac_f32_e32 v80, 0x3f317217, v78
	v_mov_b32_e32 v78, v80
	v_add_f32_e32 v78, v79, v78
	v_add_f32_e32 v79, v95, v96
	v_add_f32_e32 v23, v23, v79
	ds_bpermute_b32 v80, v181, v23
	v_cmp_lt_i32_e64 s[0:1], v22, v130
	v_sub_f32_e32 v22, v81, v78
	s_waitcnt lgkmcnt(0)
; DI int crow(int i, int h) { return (i & 3) + 8 * (i >> 2) + 4 * h; }
; DI float shx32(float v) { return __shfl_xor(v, 32); }
; template <bool MASKED>
; DI void sb_weights(f32x16 (&Sx)[2], float& carry, int kt, int t, int h) {
; #pragma unroll
;     ...
;         float L[16];
; #pragma unroll
;         for (int i = 0; i < 16; ++i) {
;           const float z = Sx[mt][i];
;           const bool ok = !MASKED || (kt * 64 + mt * 32 + crow(i, h) < t);
;           const float sp = fmaxf(z, 0.f) + __logf(1.f + __expf(-fabsf(z)));
;           L[i] = ok ? -sp : 0.f;
;           Sx[mt][i] = ok ? (z - sp) : NEG;
;         }
;         float G[4], Go[4];
; #pragma unroll
;         for (int gg = 0; gg < 4; ++gg) { G[gg] = (L[4 * gg] + L[4 * gg + 1]) + (L[4 * gg + 2] + L[4 * gg + 3]); Go[gg] = shx32(G[gg]); }
;         float T[4];
;         T[3] = 0.f; T[2] = G[3] + Go[3]; T[1] = T[2] + (G[2] + Go[2]); T[0] = T[1] + (G[1] + Go[1]);
;         const float tot = T[0] + (G[0] + Go[0]);
; #pragma unroll
;         for (int gg = 0; gg < 4; ++gg) {
;           const float s3 = carry + T[gg] + (h ? 0.f : Go[gg]);
;           const float s2 = s3 + L[4 * gg + 3], s1 = s2 + L[4 * gg + 2], s0 = s1 + L[4 * gg + 1];
;           Sx[mt][4 * gg + 3] = __expf(Sx[mt][4 * gg + 3] + s3);
;           Sx[mt][4 * gg + 2] = __expf(Sx[mt][4 * gg + 2] + s2);
;           Sx[mt][4 * gg + 1] = __expf(Sx[mt][4 * gg + 1] + s1);
;           Sx[mt][4 * gg + 0] = __expf(Sx[mt][4 * gg + 0] + s0);
;         }
;         carry += tot;
	v_add_f32_e32 v145, v23, v80
	v_cndmask_b32_e64 v165, 0, -v78, s[0:1]
	v_or_b32_e32 v78, 32, v15
	v_cndmask_b32_e64 v166, v214, v22, s[0:1]
	v_cndmask_b32_e32 v167, 0, v80, vcc
	v_sub_f32_e32 v22, v82, v0
	v_cmp_lt_i32_e64 s[4:5], v78, v130
	v_or_b32_e32 v80, 33, v15
	v_cmp_lt_i32_e64 s[6:7], v80, v130
	v_cndmask_b32_e64 v168, v214, v22, s[4:5]
	v_sub_f32_e32 v22, v83, v2
	v_or_b32_e32 v80, 34, v15
	v_cndmask_b32_e64 v169, v214, v22, s[6:7]
	v_sub_f32_e32 v22, v84, v4
	v_cmp_lt_i32_e64 s[8:9], v80, v130
	v_or_b32_e32 v80, 35, v15
	v_cmp_lt_i32_e64 s[10:11], v80, v130
	v_cndmask_b32_e64 v170, v214, v22, s[8:9]
	v_sub_f32_e32 v22, v85, v6
	v_or_b32_e32 v80, 40, v15
	v_cndmask_b32_e64 v171, v214, v22, s[10:11]
	v_sub_f32_e32 v22, v86, v8
	v_cmp_lt_i32_e64 s[12:13], v80, v130
	v_or_b32_e32 v80, 41, v15
	v_cmp_lt_i32_e64 s[14:15], v80, v130
	v_cndmask_b32_e64 v172, v214, v22, s[12:13]
	v_sub_f32_e32 v22, v87, v10
	v_add_f32_e64 v80, v148, v16
	v_add_f32_e64 v81, v149, v17
	v_or_b32_e32 v17, 42, v15
	v_or_b32_e32 v23, 8, v15
	v_or_b32_e32 v78, 9, v15
	v_cndmask_b32_e64 v173, v214, v22, s[14:15]
	v_sub_f32_e32 v16, v88, v80
	v_or_b32_e32 v22, 18, v15
	v_cmp_lt_i32_e64 s[16:17], v17, v130
	v_add_f32_e64 v82, v146, v18
	v_add_f32_e64 v83, v147, v19
	v_or_b32_e32 v15, 43, v15
	v_cndmask_b32_e64 v182, v214, v16, s[16:17]
	v_sub_f32_e32 v16, v89, v82
	v_cmp_lt_i32_e64 s[18:19], v15, v130
	v_cndmask_b32_e64 v88, 0, -v6, s[10:11]
	v_cmp_lt_i32_e64 s[10:11], v152, v131
	v_cndmask_b32_e64 v183, v214, v16, s[18:19]
	v_cndmask_b32_e64 v16, 0, -v0, s[4:5]
	v_cmp_lt_i32_e64 s[4:5], v78, v131
	ds_bpermute_b32 v78, v181, v20
	v_cndmask_b32_e64 v18, 0, -v8, s[12:13]
	v_cmp_lt_i32_e64 s[12:13], v150, v131
	v_cndmask_b32_e64 v146, 0, -v10, s[14:15]
	v_cmp_lt_i32_e64 s[14:15], v22, v131
	v_cndmask_b32_e64 v148, 0, -v80, s[16:17]
	v_cmp_lt_i32_e64 s[16:17], v151, v131
	v_cndmask_b32_e64 v19, 0, -v9, s[10:11]
	v_cndmask_b32_e64 v147, 0, -v11, s[12:13]
	v_cndmask_b32_e64 v149, 0, -v81, s[14:15]
	v_cndmask_b32_e64 v151, 0, -v83, s[16:17]
	v_cndmask_b32_e64 v150, 0, -v82, s[18:19]
	v_add_f32_e32 v79, v163, v165
	v_cmp_lt_i32_e64 s[0:1], v23, v131
	v_cndmask_b32_e64 v84, 0, -v2, s[6:7]
	v_cmp_lt_i32_e64 s[6:7], v156, v131
	v_cndmask_b32_e64 v86, 0, -v4, s[8:9]
	v_cmp_lt_i32_e64 s[8:9], v154, v131
	v_add_f32_e64 v18, v18, v146
	v_add_f32_e64 v19, v19, v147
	v_add_f32_e64 v22, v148, v150
	v_add_f32_e64 v23, v149, v151
	v_cndmask_b32_e64 v17, 0, -v1, s[0:1]
	v_cndmask_b32_e64 v85, 0, -v3, s[4:5]
	v_cndmask_b32_e64 v87, 0, -v5, s[6:7]
	v_cndmask_b32_e64 v89, 0, -v7, s[8:9]
	v_add_f32_e64 v18, v18, v22
	v_add_f32_e64 v19, v19, v23
	s_waitcnt lgkmcnt(0)
	v_add_f32_e64 v20, v20, v78
	v_add_f32_e64 v21, v21, v79
	v_add_f32_e64 v16, v16, v84
	v_add_f32_e64 v17, v17, v85
	ds_bpermute_b32 v152, v181, v18
	ds_bpermute_b32 v15, v181, v21
	ds_bpermute_b32 v153, v181, v19
	v_add_f32_e64 v22, v86, v88
	v_add_f32_e64 v23, v87, v89
	s_waitcnt lgkmcnt(1)
	v_add_f32_e64 v158, v20, v14
	v_add_f32_e64 v159, v21, v15
	v_add_f32_e64 v154, v16, v22
	v_add_f32_e64 v155, v17, v23
	ds_bpermute_b32 v156, v181, v154
	s_waitcnt lgkmcnt(1)
	v_add_f32_e64 v16, v18, v152
	v_add_f32_e64 v17, v19, v153
	ds_bpermute_b32 v157, v181, v155
	v_add_f32_e64 v160, v16, v158
	v_add_f32_e64 v161, v17, v159
	s_waitcnt lgkmcnt(1)
	v_cndmask_b32_e32 v2, 0, v156, vcc
	v_add_f32_e32 v0, v144, v160
	v_add_f32_e32 v0, v2, v0
	v_add_f32_e32 v2, v88, v0
	v_add_f32_e32 v0, v171, v0
	v_mul_f32_e32 v0, 0x3fb8aa3b, v0
	v_exp_f32_e32 v19, v0
	v_add_f32_e32 v0, v170, v2
	v_add_f32_e32 v4, v86, v2
	v_mul_f32_e32 v0, 0x3fb8aa3b, v0
	v_exp_f32_e32 v18, v0
	v_add_f32_e32 v0, v169, v4
	v_add_f32_e32 v6, v84, v4
	v_mul_f32_e32 v0, 0x3fb8aa3b, v0
	v_exp_f32_e32 v17, v0
	v_add_f32_e32 v0, v168, v6
	v_mul_f32_e32 v0, 0x3fb8aa3b, v0
	v_exp_f32_e32 v16, v0
	v_add_f32_e32 v0, v144, v158
	v_cndmask_b32_e32 v2, 0, v152, vcc
	v_add_f32_e32 v0, v2, v0
	v_add_f32_e32 v2, v150, v0
	v_add_f32_e32 v0, v183, v0
	v_mul_f32_e32 v0, 0x3fb8aa3b, v0
	v_exp_f32_e32 v23, v0
	v_add_f32_e32 v0, v182, v2
	v_add_f32_e32 v4, v148, v2
	v_mul_f32_e32 v0, 0x3fb8aa3b, v0
	v_exp_f32_e32 v22, v0
	v_add_f32_e32 v0, v173, v4
	v_add_f32_e32 v6, v146, v4
	v_mul_f32_e32 v0, 0x3fb8aa3b, v0
	v_exp_f32_e32 v21, v0
	v_add_f32_e32 v0, v172, v6
	v_mul_f32_e32 v0, 0x3fb8aa3b, v0
	v_exp_f32_e32 v20, v0
	v_cndmask_b32_e32 v0, 0, v78, vcc
	v_add_f32_e32 v0, v0, v93
	v_add_f32_e32 v2, v27, v0
	v_add_f32_e32 v0, v92, v0
	v_mul_f32_e32 v0, 0x3fb8aa3b, v0
	v_exp_f32_e32 v27, v0
	v_add_f32_e32 v0, v91, v2
	v_add_f32_e32 v4, v26, v2
	v_mul_f32_e32 v0, 0x3fb8aa3b, v0
	v_exp_f32_e32 v26, v0
	v_add_f32_e32 v0, v90, v4
	v_add_f32_e32 v6, v25, v4
	v_mul_f32_e32 v0, 0x3fb8aa3b, v0
	v_exp_f32_e32 v25, v0
	v_add_f32_e32 v0, v24, v6
	v_mul_f32_e32 v0, 0x3fb8aa3b, v0
	v_exp_f32_e32 v24, v0
	v_sub_f32_e32 v0, v70, v1
	v_cndmask_b32_e64 v4, v214, v0, s[0:1]
	v_sub_f32_e32 v0, v71, v3
	v_cndmask_b32_e64 v8, v214, v0, s[4:5]
	v_sub_f32_e32 v0, v72, v5
	v_cndmask_b32_e64 v5, v214, v0, s[6:7]
	v_sub_f32_e32 v0, v73, v7
	v_cndmask_b32_e64 v6, v214, v0, s[8:9]
	v_sub_f32_e32 v0, v74, v9
	v_cndmask_b32_e64 v12, v214, v0, s[10:11]
	v_sub_f32_e32 v0, v75, v11
	v_cndmask_b32_e64 v9, v214, v0, s[12:13]
	v_sub_f32_e32 v0, v76, v81
	v_cndmask_b32_e64 v10, v214, v0, s[14:15]
	v_sub_f32_e32 v0, v77, v83
	v_cndmask_b32_e64 v11, v214, v0, s[16:17]
	s_waitcnt lgkmcnt(0)
; DI int crow(int i, int h) { return (i & 3) + 8 * (i >> 2) + 4 * h; }
; DI float shx32(float v) { return __shfl_xor(v, 32); }
; template <bool MASKED>
; DI void sb_weights(f32x16 (&Sx)[2], float& carry, int kt, int t, int h) {
;     ...
;         float L[16];
; #pragma unroll
;         for (int i = 0; i < 16; ++i) {
;           const float z = Sx[mt][i];
;           const bool ok = !MASKED || (kt * 64 + mt * 32 + crow(i, h) < t);
;           const float sp = fmaxf(z, 0.f) + __logf(1.f + __expf(-fabsf(z)));
;           L[i] = ok ? -sp : 0.f;
;           Sx[mt][i] = ok ? (z - sp) : NEG;
;         }
;     ...
;         for (int gg = 0; gg < 4; ++gg) { G[gg] = (L[4 * gg] + L[4 * gg + 1]) + (L[4 * gg + 2] + L[4 * gg + 3]); Go[gg] = shx32(G[gg]); }
;         float T[4];
;         T[3] = 0.f; T[2] = G[3] + Go[3]; T[1] = T[2] + (G[2] + Go[2]); T[0] = T[1] + (G[1] + Go[1]);
;         const float tot = T[0] + (G[0] + Go[0]);
; #pragma unroll
;         for (int gg = 0; gg < 4; ++gg) {
;           const float s3 = carry + T[gg] + (h ? 0.f : Go[gg]);
;           const float s2 = s3 + L[4 * gg + 3], s1 = s2 + L[4 * gg + 2], s0 = s1 + L[4 * gg + 1];
;           Sx[mt][4 * gg + 3] = __expf(Sx[mt][4 * gg + 3] + s3);
;           Sx[mt][4 * gg + 2] = __expf(Sx[mt][4 * gg + 2] + s2);
;           Sx[mt][4 * gg + 1] = __expf(Sx[mt][4 * gg + 1] + s1);
;           Sx[mt][4 * gg + 0] = __expf(Sx[mt][4 * gg + 0] + s0);
;         }
;         carry += tot;
	v_add_f32_e64 v0, v154, v156
	v_add_f32_e64 v1, v155, v157
	s_nop 0
	v_add_f32_e64 v0, v0, v160
	v_add_f32_e64 v1, v1, v161
	s_nop 0
	v_add_f32_e64 v70, v144, v0
	v_add_f32_e64 v71, v145, v1
	s_nop 0
	v_add_f32_e32 v0, v70, v1
	v_add_f32_e32 v0, v167, v0
	v_add_f32_e32 v1, v96, v0
	v_add_f32_e32 v0, v69, v0
	v_mul_f32_e32 v0, 0x3fb8aa3b, v0
	v_exp_f32_e32 v3, v0
	v_add_f32_e32 v0, v68, v1
	v_add_f32_e32 v7, v95, v1
	v_mul_f32_e32 v0, 0x3fb8aa3b, v0
	v_exp_f32_e32 v2, v0
	v_add_f32_e32 v0, v67, v7
	v_add_f32_e32 v14, v94, v7
	v_mul_f32_e32 v0, 0x3fb8aa3b, v0
	v_exp_f32_e32 v1, v0
	v_add_f32_e32 v0, v66, v14
	v_add_f32_e32 v7, v70, v161
	v_cndmask_b32_e32 v14, 0, v157, vcc
	v_add_f32_e32 v7, v14, v7
	v_add_f32_e32 v14, v89, v7
	v_add_f32_e32 v6, v6, v7
	v_add_f32_e32 v5, v5, v14
	v_add_f32_e32 v66, v87, v14
	v_mul_f32_e32 v6, 0x3fb8aa3b, v6
	v_mul_f32_e32 v5, 0x3fb8aa3b, v5
	v_exp_f32_e32 v7, v6
	v_exp_f32_e32 v6, v5
	v_add_f32_e32 v5, v8, v66
	v_add_f32_e32 v8, v159, v70
	v_cndmask_b32_e32 v14, 0, v153, vcc
	v_add_f32_e32 v8, v14, v8
	v_add_f32_e32 v14, v151, v8
	v_add_f32_e32 v8, v11, v8
	v_mul_f32_e32 v8, 0x3fb8aa3b, v8
	v_exp_f32_e32 v11, v8
	v_add_f32_e32 v8, v10, v14
	v_add_f32_e32 v67, v85, v66
	v_add_f32_e32 v66, v149, v14
	v_mul_f32_e32 v8, 0x3fb8aa3b, v8
	v_exp_f32_e32 v10, v8
	v_add_f32_e32 v8, v9, v66
	v_add_f32_e32 v4, v4, v67
	v_add_f32_e32 v67, v147, v66
	v_mul_f32_e32 v8, 0x3fb8aa3b, v8
	v_exp_f32_e32 v9, v8
	v_add_f32_e32 v8, v12, v67
	v_add_f32_e32 v12, 0, v70
	v_cndmask_b32_e32 v14, 0, v15, vcc
	v_add_f32_e32 v12, v14, v12
	v_add_f32_e32 v14, v165, v12
	v_add_f32_e32 v12, v166, v12
	v_mul_f32_e32 v12, 0x3fb8aa3b, v12
	v_exp_f32_e32 v15, v12
	v_add_f32_e32 v12, v164, v14
	v_add_f32_e32 v66, v163, v14
	v_mul_f32_e32 v12, 0x3fb8aa3b, v12
	v_exp_f32_e32 v14, v12
	v_add_f32_e32 v12, v97, v66
	v_add_f32_e32 v67, v13, v66
	v_mul_f32_e32 v12, 0x3fb8aa3b, v12
	v_exp_f32_e32 v13, v12
	v_add_f32_e32 v12, v162, v67
	v_mul_f32_e32 v0, 0x3fb8aa3b, v0
	v_mul_f32_e32 v5, 0x3fb8aa3b, v5
	v_mul_f32_e32 v4, 0x3fb8aa3b, v4
	v_mul_f32_e32 v8, 0x3fb8aa3b, v8
	v_mul_f32_e32 v12, 0x3fb8aa3b, v12
	v_exp_f32_e32 v0, v0
	v_exp_f32_e32 v5, v5
	v_exp_f32_e32 v4, v4
	v_exp_f32_e32 v8, v8
	v_exp_f32_e32 v12, v12
	v_add_f32_e32 v144, v70, v71
.LBB0_280:
	s_andn2_saveexec_b64 s[6:7], s[38:39]
	s_cbranch_execz .LBB0_282
	v_add_f32_e32 v0, 1.0, v243
	v_mov_b32_e32 v30, v91
	v_max_f32_e32 v165, 0, v165
	v_log_f32_e32 v0, v0
	v_max_f32_e32 v161, 0, v161
	v_max_f32_e32 v159, 0, v159
	v_max_f32_e32 v157, 0, v157
	v_mul_f32_e32 v1, 0x3f317217, v0
	v_fma_f32 v1, v0, s77, -v1
	v_fmac_f32_e32 v1, 0x3377d1cf, v0
	v_fmac_f32_e32 v1, 0x3f317217, v0
	v_max_f32_e32 v155, 0, v155
	v_mov_b32_e32 v0, v1
	v_add_f32_e32 v1, 1.0, v239
	v_log_f32_e32 v1, v1
	s_nop 0
	v_mul_f32_e32 v2, 0x3f317217, v1
	v_fma_f32 v2, v1, s77, -v2
	v_fmac_f32_e32 v2, 0x3377d1cf, v1
	v_fmac_f32_e32 v2, 0x3f317217, v1
	v_add_f32_e32 v1, 1.0, v205
	v_log_f32_e32 v1, v1
	s_nop 0
	v_mul_f32_e32 v4, 0x3f317217, v1
	v_fma_f32 v4, v1, s77, -v4
	v_fmac_f32_e32 v4, 0x3377d1cf, v1
	v_fmac_f32_e32 v4, 0x3f317217, v1
	v_add_f32_e32 v1, 1.0, v202
	v_log_f32_e32 v1, v1
	s_nop 0
	v_mul_f32_e32 v6, 0x3f317217, v1
	v_fma_f32 v6, v1, s77, -v6
	v_fmac_f32_e32 v6, 0x3377d1cf, v1
	v_fmac_f32_e32 v6, 0x3f317217, v1
	v_add_f32_e32 v1, 1.0, v201
	v_log_f32_e32 v1, v1
	s_nop 0
	v_mul_f32_e32 v8, 0x3f317217, v1
	v_fma_f32 v8, v1, s77, -v8
	v_fmac_f32_e32 v8, 0x3377d1cf, v1
	v_fmac_f32_e32 v8, 0x3f317217, v1
	v_add_f32_e32 v1, 1.0, v200
	v_log_f32_e32 v1, v1
	s_nop 0
	v_mul_f32_e32 v10, 0x3f317217, v1
	v_fma_f32 v10, v1, s77, -v10
	v_fmac_f32_e32 v10, 0x3377d1cf, v1
	v_fmac_f32_e32 v10, 0x3f317217, v1
	v_add_f32_e32 v1, 1.0, v199
	v_log_f32_e32 v1, v1
	s_nop 0
	v_mul_f32_e32 v12, 0x3f317217, v1
	v_fma_f32 v12, v1, s77, -v12
	v_fmac_f32_e32 v12, 0x3377d1cf, v1
	v_fmac_f32_e32 v12, 0x3f317217, v1
	v_add_f32_e32 v1, 1.0, v198
	v_log_f32_e32 v1, v1
	s_nop 0
	v_mul_f32_e32 v14, 0x3f317217, v1
	v_fma_f32 v14, v1, s77, -v14
	v_fmac_f32_e32 v14, 0x3377d1cf, v1
	v_fmac_f32_e32 v14, 0x3f317217, v1
	v_add_f32_e32 v1, 1.0, v197
	v_log_f32_e32 v1, v1
	s_nop 0
	v_mul_f32_e32 v16, 0x3f317217, v1
	v_fma_f32 v16, v1, s77, -v16
	v_fmac_f32_e32 v16, 0x3377d1cf, v1
	v_fmac_f32_e32 v16, 0x3f317217, v1
	v_add_f32_e32 v1, 1.0, v196
	v_log_f32_e32 v1, v1
	s_nop 0
	v_mul_f32_e32 v18, 0x3f317217, v1
	v_fma_f32 v18, v1, s77, -v18
	v_fmac_f32_e32 v18, 0x3377d1cf, v1
	v_fmac_f32_e32 v18, 0x3f317217, v1
	v_add_f32_e32 v1, 1.0, v195
	v_log_f32_e32 v1, v1
	s_nop 0
	v_mul_f32_e32 v17, 0x3f317217, v1
	v_fma_f32 v17, v1, s77, -v17
	v_fmac_f32_e32 v17, 0x3377d1cf, v1
	v_fmac_f32_e32 v17, 0x3f317217, v1
	v_add_f32_e32 v1, 1.0, v194
	v_add_f32_e64 v24, v172, v16
	v_add_f32_e64 v25, v173, v17
	v_log_f32_e32 v1, v1
	s_nop 0
	v_mul_f32_e32 v19, 0x3f317217, v1
	v_fma_f32 v19, v1, s77, -v19
	v_fmac_f32_e32 v19, 0x3377d1cf, v1
	v_fmac_f32_e32 v19, 0x3f317217, v1
	v_add_f32_e32 v1, 1.0, v193
	v_add_f32_e64 v26, v170, v18
	v_add_f32_e64 v27, v171, v19
	v_log_f32_e32 v1, v1
	v_add_f32_e64 v16, -v26, -v24
	v_add_f32_e64 v17, -v27, -v25
	v_mul_f32_e32 v20, 0x3f317217, v1
	v_fma_f32 v20, v1, s77, -v20
	v_fmac_f32_e32 v20, 0x3377d1cf, v1
	v_fmac_f32_e32 v20, 0x3f317217, v1
	v_pk_add_f32 v[16:17], v[16:17], v[16:17] op_sel:[0,1] op_sel_hi:[1,0]
	ds_bpermute_b32 v18, v181, v16
	v_add_f32_e32 v1, 1.0, v192
	s_waitcnt lgkmcnt(0)
; DI int crow(int i, int h) { return (i & 3) + 8 * (i >> 2) + 4 * h; }
; DI float shx32(float v) { return __shfl_xor(v, 32); }
; template <bool MASKED>
; DI void sb_weights(f32x16 (&Sx)[2], float& carry, int kt, int t, int h) {
;     ...
;         float L[16];
; #pragma unroll
;         for (int i = 0; i < 16; ++i) {
;           const float z = Sx[mt][i];
;           const bool ok = !MASKED || (kt * 64 + mt * 32 + crow(i, h) < t);
;           const float sp = fmaxf(z, 0.f) + __logf(1.f + __expf(-fabsf(z)));
;           L[i] = ok ? -sp : 0.f;
;           Sx[mt][i] = ok ? (z - sp) : NEG;
;         }
;         float G[4], Go[4];
; #pragma unroll
;         for (int gg = 0; gg < 4; ++gg) { G[gg] = (L[4 * gg] + L[4 * gg + 1]) + (L[4 * gg + 2] + L[4 * gg + 3]); Go[gg] = shx32(G[gg]); }
;         float T[4];
;         T[3] = 0.f; T[2] = G[3] + Go[3]; T[1] = T[2] + (G[2] + Go[2]); T[0] = T[1] + (G[1] + Go[1]);
;         const float tot = T[0] + (G[0] + Go[0]);
; #pragma unroll
;         for (int gg = 0; gg < 4; ++gg) {
;           const float s3 = carry + T[gg] + (h ? 0.f : Go[gg]);
;           const float s2 = s3 + L[4 * gg + 3], s1 = s2 + L[4 * gg + 2], s0 = s1 + L[4 * gg + 1];
;           Sx[mt][4 * gg + 3] = __expf(Sx[mt][4 * gg + 3] + s3);
;           Sx[mt][4 * gg + 2] = __expf(Sx[mt][4 * gg + 2] + s2);
;           Sx[mt][4 * gg + 1] = __expf(Sx[mt][4 * gg + 1] + s1);
;           Sx[mt][4 * gg + 0] = __expf(Sx[mt][4 * gg + 0] + s0);
;         }
;         carry += tot;
	v_cndmask_b32_e32 v9, 0, v18, vcc
	v_log_f32_e32 v1, v1
	s_nop 0
	v_mul_f32_e32 v22, 0x3f317217, v1
	v_fma_f32 v22, v1, s77, -v22
	v_fmac_f32_e32 v22, 0x3377d1cf, v1
	v_fmac_f32_e32 v22, 0x3f317217, v1
	v_add_f32_e32 v1, 1.0, v191
	v_log_f32_e32 v1, v1
	s_nop 0
	v_mul_f32_e32 v21, 0x3f317217, v1
	v_fma_f32 v21, v1, s77, -v21
	v_fmac_f32_e32 v21, 0x3377d1cf, v1
	v_fmac_f32_e32 v21, 0x3f317217, v1
	v_add_f32_e32 v1, 1.0, v190
	v_add_f32_e64 v20, v168, v20
	v_add_f32_e64 v21, v169, v21
	v_log_f32_e32 v1, v1
	s_nop 0
	v_mul_f32_e32 v23, 0x3f317217, v1
	v_fma_f32 v23, v1, s77, -v23
	v_fmac_f32_e32 v23, 0x3377d1cf, v1
	v_fmac_f32_e32 v23, 0x3f317217, v1
	v_add_f32_e64 v22, v166, v22
	v_add_f32_e64 v23, v167, v23
	v_sub_f32_e32 v1, v93, v27
	v_add_f32_e64 v28, -v22, -v20
	v_add_f32_e64 v29, -v23, -v21
	v_sub_f32_e32 v3, v97, v23
	v_add_f32_e32 v5, v28, v29
	ds_bpermute_b32 v7, v181, v5
	v_mov_b32_e32 v28, v25
	v_mov_b32_e32 v29, v27
	v_mov_b32_e32 v27, v25
	v_mov_b32_e32 v25, v26
	s_waitcnt lgkmcnt(0)
	v_add_f32_e32 v166, v5, v7
	v_add_f32_e32 v5, v144, v166
	v_add_f32_e32 v93, v9, v5
	v_add_f32_e64 v28, v92, -v28
	v_add_f32_e64 v29, v93, -v29
	v_add_f32_e32 v1, v1, v93
	v_mov_b32_e32 v31, v29
	v_mul_f32_e32 v1, 0x3fb8aa3b, v1
	v_add_f32_e64 v30, v30, -v26
	v_add_f32_e64 v31, v31, -v27
	v_exp_f32_e32 v27, v1
	v_add_f32_e32 v1, v28, v29
	v_mul_f32_e32 v1, 0x3fb8aa3b, v1
	v_mov_b32_e32 v91, v31
	v_exp_f32_e32 v26, v1
	v_add_f32_e32 v1, v30, v31
	v_add_f32_e64 v90, v90, -v24
	v_add_f32_e64 v91, v91, -v25
	v_mul_f32_e32 v1, 0x3fb8aa3b, v1
	v_exp_f32_e32 v25, v1
	v_add_f32_e32 v1, v90, v91
	v_mul_f32_e32 v1, 0x3fb8aa3b, v1
	v_exp_f32_e32 v24, v1
	v_cndmask_b32_e32 v1, 0, v7, vcc
	v_add_f32_e32 v97, v188, v1
	v_mov_b32_e32 v28, v21
	v_mov_b32_e32 v29, v23
	v_add_f32_e64 v28, v96, -v28
	v_add_f32_e64 v29, v97, -v29
	v_add_f32_e32 v1, v3, v97
	v_mov_b32_e32 v30, v95
	v_mov_b32_e32 v31, v29
	v_mov_b32_e32 v23, v21
	v_mul_f32_e32 v1, 0x3fb8aa3b, v1
	v_add_f32_e64 v90, v30, -v22
	v_add_f32_e64 v91, v31, -v23
	v_exp_f32_e32 v31, v1
	v_add_f32_e32 v1, v28, v29
	v_mul_f32_e32 v1, 0x3fb8aa3b, v1
	v_mov_b32_e32 v95, v91
	v_mov_b32_e32 v21, v22
	v_exp_f32_e32 v30, v1
	v_add_f32_e32 v1, v90, v91
	v_add_f32_e64 v20, v94, -v20
	v_add_f32_e64 v21, v95, -v21
	v_mul_f32_e32 v1, 0x3fb8aa3b, v1
	v_exp_f32_e32 v29, v1
	v_add_f32_e32 v1, v20, v21
	v_mul_f32_e32 v1, 0x3fb8aa3b, v1
	v_exp_f32_e32 v28, v1
	v_add_f32_e32 v1, 1.0, v189
	v_log_f32_e32 v1, v1
	s_nop 0
	v_mul_f32_e32 v20, 0x3f317217, v1
	v_fma_f32 v20, v1, s77, -v20
	v_fmac_f32_e32 v20, 0x3377d1cf, v1
	v_fmac_f32_e32 v20, 0x3f317217, v1
	v_add_f32_e32 v1, 1.0, v187
	v_log_f32_e32 v1, v1
	s_nop 0
	v_mul_f32_e32 v22, 0x3f317217, v1
	v_fma_f32 v22, v1, s77, -v22
	v_fmac_f32_e32 v22, 0x3377d1cf, v1
	v_fmac_f32_e32 v22, 0x3f317217, v1
	v_add_f32_e32 v1, 1.0, v186
	v_log_f32_e32 v1, v1
	s_nop 0
	v_mul_f32_e32 v21, 0x3f317217, v1
	v_fma_f32 v21, v1, s77, -v21
	v_fmac_f32_e32 v21, 0x3377d1cf, v1
	v_fmac_f32_e32 v21, 0x3f317217, v1
	v_exp_f32_e32 v1, v185
	v_add_f32_e64 v96, v162, v20
	v_add_f32_e64 v97, v163, v21
	v_add_f32_e32 v1, 1.0, v1
	v_log_f32_e32 v1, v1
	s_nop 0
	v_mul_f32_e32 v23, 0x3f317217, v1
	v_fma_f32 v23, v1, s77, -v23
	v_fmac_f32_e32 v23, 0x3377d1cf, v1
	v_fmac_f32_e32 v23, 0x3f317217, v1
	v_exp_f32_e32 v1, v184
	v_add_f32_e64 v162, v164, v22
	v_add_f32_e64 v163, v165, v23
	v_add_f32_e32 v1, 1.0, v1
	v_add_f32_e64 v20, -v162, -v96
	v_add_f32_e64 v21, -v163, -v97
	v_sub_f32_e32 v170, v69, v163
	v_log_f32_e32 v1, v1
	s_nop 0
	v_mul_f32_e32 v3, 0x3f317217, v1
	v_fma_f32 v3, v1, s77, -v3
	v_fmac_f32_e32 v3, 0x3377d1cf, v1
	v_fmac_f32_e32 v3, 0x3f317217, v1
	v_mov_b32_e32 v1, v3
	v_exp_f32_e32 v3, v183
	v_add_f32_e64 v160, v160, v0
	v_add_f32_e64 v161, v161, v1
	v_add_f32_e32 v3, 1.0, v3
	v_log_f32_e32 v3, v3
	s_nop 0
	v_mul_f32_e32 v5, 0x3f317217, v3
	v_fma_f32 v5, v3, s77, -v5
	v_fmac_f32_e32 v5, 0x3377d1cf, v3
	v_fmac_f32_e32 v5, 0x3f317217, v3
	v_mov_b32_e32 v3, v5
	v_exp_f32_e32 v5, v182
	v_add_f32_e64 v158, v158, v2
	v_add_f32_e64 v159, v159, v3
	v_add_f32_e32 v5, 1.0, v5
	v_add_f32_e64 v0, -v158, -v160
	v_add_f32_e64 v1, -v159, -v161
	v_log_f32_e32 v5, v5
	s_nop 0
	v_mul_f32_e32 v7, 0x3f317217, v5
	v_fma_f32 v7, v5, s77, -v7
	v_fmac_f32_e32 v7, 0x3377d1cf, v5
	v_fmac_f32_e32 v7, 0x3f317217, v5
	v_mov_b32_e32 v5, v7
	v_exp_f32_e32 v7, v153
	v_max_f32_e32 v153, 0, v151
	v_max_f32_e32 v151, 0, v147
	v_add_f32_e64 v4, v156, v4
	v_add_f32_e64 v5, v157, v5
	v_add_f32_e32 v7, 1.0, v7
	v_log_f32_e32 v7, v7
	s_nop 0
	v_mul_f32_e32 v9, 0x3f317217, v7
	v_fma_f32 v9, v7, s77, -v9
	v_fmac_f32_e32 v9, 0x3377d1cf, v7
	v_fmac_f32_e32 v9, 0x3f317217, v7
	v_mov_b32_e32 v7, v9
	v_exp_f32_e32 v9, v149
	v_add_f32_e64 v6, v154, v6
	v_add_f32_e64 v7, v155, v7
	v_add_f32_e32 v9, 1.0, v9
	v_add_f32_e64 v2, -v6, -v4
	v_add_f32_e64 v3, -v7, -v5
	v_sub_f32_e32 v171, v85, v6
	v_log_f32_e32 v9, v9
	v_add_f32_e64 v0, v0, v2
	v_add_f32_e64 v1, v1, v3
	ds_bpermute_b32 v2, v181, v0
	ds_bpermute_b32 v3, v181, v1
	v_mul_f32_e32 v11, 0x3f317217, v9
	v_fma_f32 v11, v9, s77, -v11
	v_fmac_f32_e32 v11, 0x3377d1cf, v9
	v_fmac_f32_e32 v11, 0x3f317217, v9
	s_waitcnt lgkmcnt(1)
	v_cndmask_b32_e32 v85, 0, v2, vcc
	s_waitcnt lgkmcnt(0)
; DI int crow(int i, int h) { return (i & 3) + 8 * (i >> 2) + 4 * h; }
; DI float shx32(float v) { return __shfl_xor(v, 32); }
; template <bool MASKED>
; DI void sb_weights(f32x16 (&Sx)[2], float& carry, int kt, int t, int h) {
;     ...
;         float L[16];
; #pragma unroll
;         for (int i = 0; i < 16; ++i) {
;           const float z = Sx[mt][i];
;           const bool ok = !MASKED || (kt * 64 + mt * 32 + crow(i, h) < t);
;           const float sp = fmaxf(z, 0.f) + __logf(1.f + __expf(-fabsf(z)));
;           L[i] = ok ? -sp : 0.f;
;           Sx[mt][i] = ok ? (z - sp) : NEG;
;         }
;         float G[4], Go[4];
; #pragma unroll
;         for (int gg = 0; gg < 4; ++gg) { G[gg] = (L[4 * gg] + L[4 * gg + 1]) + (L[4 * gg + 2] + L[4 * gg + 3]); Go[gg] = shx32(G[gg]); }
;         float T[4];
;         T[3] = 0.f; T[2] = G[3] + Go[3]; T[1] = T[2] + (G[2] + Go[2]); T[0] = T[1] + (G[1] + Go[1]);
;         const float tot = T[0] + (G[0] + Go[0]);
; #pragma unroll
;         for (int gg = 0; gg < 4; ++gg) {
;           const float s3 = carry + T[gg] + (h ? 0.f : Go[gg]);
;           const float s2 = s3 + L[4 * gg + 3], s1 = s2 + L[4 * gg + 2], s0 = s1 + L[4 * gg + 1];
;           Sx[mt][4 * gg + 3] = __expf(Sx[mt][4 * gg + 3] + s3);
;           Sx[mt][4 * gg + 2] = __expf(Sx[mt][4 * gg + 2] + s2);
;           Sx[mt][4 * gg + 1] = __expf(Sx[mt][4 * gg + 1] + s1);
;           Sx[mt][4 * gg + 0] = __expf(Sx[mt][4 * gg + 0] + s0);
;         }
;         carry += tot;
	v_add_f32_e64 v0, v0, v2
	v_add_f32_e64 v1, v1, v3
	v_mov_b32_e32 v9, v11
	v_exp_f32_e32 v11, v145
	v_add_f32_e64 v8, v152, v8
	v_add_f32_e64 v9, v153, v9
	v_add_f32_e32 v11, 1.0, v11
	v_mov_b32_e32 v156, v8
	v_log_f32_e32 v11, v11
	s_nop 0
	v_mul_f32_e32 v13, 0x3f317217, v11
	v_fma_f32 v13, v11, s77, -v13
	v_fmac_f32_e32 v13, 0x3377d1cf, v11
	v_fmac_f32_e32 v13, 0x3f317217, v11
	v_mov_b32_e32 v11, v13
	v_max_f32_e32 v13, v76, v76
	v_max_f32_e32 v149, 0, v13
	v_mul_f32_e64 v13, |v76|, s76
	v_exp_f32_e32 v13, v13
	v_add_f32_e64 v10, v150, v10
	v_add_f32_e64 v11, v151, v11
	v_mov_b32_e32 v150, v160
	v_mov_b32_e32 v151, v158
	v_add_f32_e32 v13, 1.0, v13
	v_mov_b32_e32 v154, v10
	v_mov_b32_e32 v157, v10
	v_log_f32_e32 v13, v13
	s_nop 0
	v_mul_f32_e32 v15, 0x3f317217, v13
	v_fma_f32 v15, v13, s77, -v15
	v_fmac_f32_e32 v15, 0x3377d1cf, v13
	v_fmac_f32_e32 v15, 0x3f317217, v13
	v_mov_b32_e32 v13, v15
	v_max_f32_e32 v15, v77, v77
	v_max_f32_e32 v147, 0, v15
	v_mul_f32_e64 v15, |v77|, s76
	v_exp_f32_e32 v15, v15
	v_add_f32_e64 v12, v148, v12
	v_add_f32_e64 v13, v149, v13
	v_mov_b32_e32 v148, v158
	v_mov_b32_e32 v149, v4
	v_add_f32_e32 v15, 1.0, v15
	v_mov_b32_e32 v152, v12
	v_mov_b32_e32 v155, v12
	v_log_f32_e32 v15, v15
	v_mov_b32_e32 v158, v161
	v_mul_f32_e32 v17, 0x3f317217, v15
	v_fma_f32 v17, v15, s77, -v17
	v_fmac_f32_e32 v17, 0x3377d1cf, v15
	v_fmac_f32_e32 v17, 0x3f317217, v15
	v_mov_b32_e32 v15, v17
	v_max_f32_e32 v17, v78, v78
	v_max_f32_e32 v90, 0, v17
	v_mul_f32_e64 v17, |v78|, s76
	v_exp_f32_e32 v17, v17
	v_add_f32_e64 v14, v146, v14
	v_add_f32_e64 v15, v147, v15
	v_mov_b32_e32 v147, v6
	v_add_f32_e64 v22, -v14, -v12
	v_add_f32_e64 v23, -v15, -v13
	v_add_f32_e32 v17, 1.0, v17
	v_cndmask_b32_e32 v6, 0, v3, vcc
	v_mov_b32_e32 v146, v4
	v_log_f32_e32 v17, v17
	v_sub_f32_e32 v172, v89, v14
	v_mov_b32_e32 v153, v14
	v_sub_f32_e32 v160, v77, v15
	v_mul_f32_e32 v92, 0x3f317217, v17
	v_fma_f32 v92, v17, s77, -v92
	v_fmac_f32_e32 v92, 0x3377d1cf, v17
	v_fmac_f32_e32 v92, 0x3f317217, v17
	v_mov_b32_e32 v14, v13
	v_max_f32_e32 v17, v79, v79
	v_max_f32_e32 v91, 0, v17
	v_mul_f32_e64 v17, |v79|, s76
	v_exp_f32_e32 v17, v17
	s_nop 0
	v_add_f32_e32 v17, 1.0, v17
	v_log_f32_e32 v17, v17
	s_nop 0
	v_mul_f32_e32 v93, 0x3f317217, v17
	v_fma_f32 v93, v17, s77, -v93
	v_fmac_f32_e32 v93, 0x3377d1cf, v17
	v_fmac_f32_e32 v93, 0x3f317217, v17
	v_max_f32_e32 v17, v80, v80
	v_max_f32_e32 v94, 0, v17
	v_mul_f32_e64 v17, |v80|, s76
	v_exp_f32_e32 v17, v17
	v_add_f32_e64 v90, v90, v92
	v_add_f32_e64 v91, v91, v93
	v_add_f32_e32 v17, 1.0, v17
	v_log_f32_e32 v17, v17
	s_nop 0
	v_mul_f32_e32 v168, 0x3f317217, v17
	v_fma_f32 v168, v17, s77, -v168
	v_fmac_f32_e32 v168, 0x3377d1cf, v17
	v_fmac_f32_e32 v168, 0x3f317217, v17
	v_max_f32_e32 v17, v81, v81
	v_max_f32_e32 v95, 0, v17
	v_mul_f32_e64 v17, |v81|, s76
	v_exp_f32_e32 v17, v17
	s_nop 0
	v_add_f32_e32 v17, 1.0, v17
	v_log_f32_e32 v17, v17
	s_nop 0
	v_mul_f32_e32 v169, 0x3f317217, v17
	v_fma_f32 v169, v17, s77, -v169
	v_fmac_f32_e32 v169, 0x3377d1cf, v17
	v_fmac_f32_e32 v169, 0x3f317217, v17
	v_add_f32_e32 v17, v20, v21
	ds_bpermute_b32 v19, v181, v17
	v_add_f32_e64 v94, v94, v168
	v_add_f32_e64 v95, v95, v169
	v_add_f32_e64 v20, -v10, -v8
	v_add_f32_e64 v21, -v11, -v9
	v_sub_f32_e32 v8, v73, v7
	v_add_f32_e64 v20, v20, v22
	v_add_f32_e64 v21, v21, v23
	s_waitcnt lgkmcnt(0)
	v_add_f32_e32 v145, v17, v19
	v_cndmask_b32_e32 v69, 0, v19, vcc
	v_sub_f32_e64 v19, -v95, v94
	v_sub_f32_e64 v17, -v91, v90
	v_add_f32_e64 v2, v16, v18
	v_add_f32_e64 v3, v17, v19
	ds_bpermute_b32 v22, v181, v20
	ds_bpermute_b32 v23, v181, v21
	ds_bpermute_b32 v167, v181, v3
	v_mov_b32_e32 v16, v83
	v_sub_f32_e32 v168, v81, v95
	s_waitcnt lgkmcnt(2)
	v_cndmask_b32_e32 v4, 0, v22, vcc
	s_waitcnt lgkmcnt(1)
	v_add_f32_e64 v20, v20, v22
	v_add_f32_e64 v21, v21, v23
	s_waitcnt lgkmcnt(0)
; DI float shx32(float v) { return __shfl_xor(v, 32); }
; template <bool MASKED>
; DI void sb_weights(f32x16 (&Sx)[2], float& carry, int kt, int t, int h) {
;     ...
;         for (int gg = 0; gg < 4; ++gg) { G[gg] = (L[4 * gg] + L[4 * gg + 1]) + (L[4 * gg + 2] + L[4 * gg + 3]); Go[gg] = shx32(G[gg]); }
;         float T[4];
;         T[3] = 0.f; T[2] = G[3] + Go[3]; T[1] = T[2] + (G[2] + Go[2]); T[0] = T[1] + (G[1] + Go[1]);
;         const float tot = T[0] + (G[0] + Go[0]);
; #pragma unroll
;         for (int gg = 0; gg < 4; ++gg) {
;           const float s3 = carry + T[gg] + (h ? 0.f : Go[gg]);
;           const float s2 = s3 + L[4 * gg + 3], s1 = s2 + L[4 * gg + 2], s0 = s1 + L[4 * gg + 1];
;           Sx[mt][4 * gg + 3] = __expf(Sx[mt][4 * gg + 3] + s3);
;           Sx[mt][4 * gg + 2] = __expf(Sx[mt][4 * gg + 2] + s2);
;           Sx[mt][4 * gg + 1] = __expf(Sx[mt][4 * gg + 1] + s1);
;           Sx[mt][4 * gg + 0] = __expf(Sx[mt][4 * gg + 0] + s0);
;         }
;         carry += tot;
	v_add_f32_e64 v92, v2, v166
	v_add_f32_e64 v93, v3, v167
	v_cndmask_b32_e32 v10, 0, v23, vcc
	v_add_f32_e64 v164, v20, v92
	v_add_f32_e64 v165, v21, v93
	s_nop 0
	v_add_f32_e32 v2, v144, v164
	v_add_f32_e32 v85, v85, v2
	v_add_f32_e64 v2, v84, -v146
	v_add_f32_e64 v3, v85, -v147
	v_add_f32_e64 v0, v0, v164
	v_add_f32_e64 v1, v1, v165
	v_mov_b32_e32 v17, v3
	v_add_f32_e32 v2, v2, v3
	v_add_f32_e64 v16, v16, -v148
	v_add_f32_e64 v17, v17, -v149
	v_mul_f32_e32 v2, 0x3fb8aa3b, v2
	v_mov_b32_e32 v83, v17
	v_exp_f32_e32 v18, v2
	v_add_f32_e32 v2, v16, v17
	v_add_f32_e64 v20, v82, -v150
	v_add_f32_e64 v21, v83, -v151
	v_mul_f32_e32 v2, 0x3fb8aa3b, v2
	v_exp_f32_e32 v17, v2
	v_add_f32_e32 v2, v20, v21
	v_mul_f32_e32 v2, 0x3fb8aa3b, v2
	v_exp_f32_e32 v16, v2
	v_add_f32_e32 v2, v144, v92
	v_add_f32_e32 v89, v4, v2
	v_add_f32_e64 v2, v88, -v152
	v_add_f32_e64 v3, v89, -v153
	v_mov_b32_e32 v20, v87
	v_mov_b32_e32 v21, v3
	v_add_f32_e32 v2, v2, v3
	v_add_f32_e64 v20, v20, -v154
	v_add_f32_e64 v21, v21, -v155
	v_mul_f32_e32 v2, 0x3fb8aa3b, v2
	v_mov_b32_e32 v87, v21
	v_exp_f32_e32 v22, v2
	v_add_f32_e32 v2, v20, v21
	v_add_f32_e64 v82, v86, -v156
	v_add_f32_e64 v83, v87, -v157
	v_mul_f32_e32 v2, 0x3fb8aa3b, v2
	v_exp_f32_e32 v21, v2
	v_add_f32_e32 v2, v82, v83
	v_add_f32_e64 v82, v144, v0
	v_add_f32_e64 v83, v145, v1
	v_mul_f32_e32 v2, 0x3fb8aa3b, v2
	v_add_f32_e32 v0, v82, v1
	v_add_f32_e32 v69, v69, v0
	v_mov_b32_e32 v0, v97
	v_mov_b32_e32 v1, v163
	v_add_f32_e64 v0, v68, -v0
	v_add_f32_e64 v1, v69, -v1
	v_exp_f32_e32 v20, v2
	v_mov_b32_e32 v2, v67
	v_mov_b32_e32 v3, v1
	v_mov_b32_e32 v163, v97
	v_add_f32_e32 v12, v171, v85
	v_add_f32_e32 v4, v172, v89
	v_add_f32_e64 v84, v2, -v162
	v_add_f32_e64 v85, v3, -v163
	v_add_f32_e32 v2, v170, v69
	v_add_f32_e32 v0, v0, v1
	v_mul_f32_e32 v4, 0x3fb8aa3b, v4
	v_mul_f32_e32 v2, 0x3fb8aa3b, v2
	v_mul_f32_e32 v0, 0x3fb8aa3b, v0
	v_exp_f32_e32 v23, v4
	v_mov_b32_e32 v67, v85
	v_mov_b32_e32 v97, v162
	v_exp_f32_e32 v3, v2
	v_exp_f32_e32 v2, v0
	v_add_f32_e32 v0, v84, v85
	v_add_f32_e32 v4, v82, v165
	v_add_f32_e64 v66, v66, -v96
	v_add_f32_e64 v67, v67, -v97
	v_mul_f32_e32 v0, 0x3fb8aa3b, v0
	v_add_f32_e32 v73, v6, v4
	v_mov_b32_e32 v6, v5
	v_exp_f32_e32 v1, v0
	v_add_f32_e32 v0, v66, v67
	v_add_f32_e64 v66, v72, -v6
	v_add_f32_e64 v67, v73, -v7
	v_mov_b32_e32 v6, v71
	v_mov_b32_e32 v7, v67
	v_mov_b32_e32 v4, v159
	v_add_f32_e64 v4, v6, -v4
	v_add_f32_e64 v5, v7, -v5
	v_add_f32_e32 v6, v8, v73
	v_add_f32_e32 v8, v93, v82
	v_add_f32_e32 v77, v10, v8
	v_mul_f32_e32 v12, 0x3fb8aa3b, v12
	v_mul_f32_e32 v6, 0x3fb8aa3b, v6
	v_add_f32_e64 v14, v76, -v14
	v_add_f32_e64 v15, v77, -v15
	v_exp_f32_e32 v19, v12
	v_exp_f32_e32 v7, v6
	v_add_f32_e32 v6, v66, v67
	v_mov_b32_e32 v66, v75
	v_mov_b32_e32 v67, v15
	v_mov_b32_e32 v12, v11
	v_add_f32_e64 v12, v66, -v12
	v_add_f32_e64 v13, v67, -v13
	v_add_f32_e32 v8, v160, v77
	v_mov_b32_e32 v75, v13
	v_mov_b32_e32 v10, v9
	v_mul_f32_e32 v8, 0x3fb8aa3b, v8
	v_add_f32_e64 v66, v74, -v10
	v_add_f32_e64 v67, v75, -v11
	v_exp_f32_e32 v11, v8
	v_add_f32_e32 v8, v14, v15
	v_mul_f32_e32 v8, 0x3fb8aa3b, v8
	v_exp_f32_e32 v10, v8
	v_add_f32_e32 v8, v12, v13
	v_add_f32_e32 v12, 0, v82
	v_cndmask_b32_e32 v13, 0, v167, vcc
	v_add_f32_e32 v81, v13, v12
	v_mul_f32_e32 v8, 0x3fb8aa3b, v8
	v_add_f32_e64 v12, v80, -v94
	v_add_f32_e64 v13, v81, -v95
	v_exp_f32_e32 v9, v8
	v_add_f32_e32 v8, v66, v67
	v_mov_b32_e32 v14, v79
	v_mov_b32_e32 v15, v13
	v_pk_mov_b32 v[66:67], v[90:91], v[94:95] op_sel:[1,0]
	v_add_f32_e32 v12, v12, v13
	v_add_f32_e64 v66, v14, -v66
	v_add_f32_e64 v67, v15, -v67
	v_add_f32_e32 v14, v168, v81
	v_mov_b32_e32 v71, v5
	v_add_f32_e32 v4, v4, v5
	v_mul_f32_e32 v14, 0x3fb8aa3b, v14
	v_mul_f32_e32 v12, 0x3fb8aa3b, v12
	v_add_f32_e64 v68, v70, -v158
	v_add_f32_e64 v69, v71, -v159
	v_mul_f32_e32 v4, 0x3fb8aa3b, v4
	v_mov_b32_e32 v79, v67
	v_exp_f32_e32 v15, v14
	v_exp_f32_e32 v14, v12
	v_add_f32_e32 v12, v66, v67
	v_exp_f32_e32 v5, v4
	v_add_f32_e32 v4, v68, v69
	v_add_f32_e64 v68, v78, -v90
	v_add_f32_e64 v69, v79, -v91
	v_mul_f32_e32 v12, 0x3fb8aa3b, v12
	v_exp_f32_e32 v13, v12
	v_add_f32_e32 v12, v68, v69
	v_mul_f32_e32 v0, 0x3fb8aa3b, v0
	v_mul_f32_e32 v6, 0x3fb8aa3b, v6
	v_mul_f32_e32 v4, 0x3fb8aa3b, v4
	v_mul_f32_e32 v8, 0x3fb8aa3b, v8
	v_mul_f32_e32 v12, 0x3fb8aa3b, v12
	v_exp_f32_e32 v0, v0
	v_exp_f32_e32 v6, v6
	v_exp_f32_e32 v4, v4
	v_exp_f32_e32 v8, v8
	v_exp_f32_e32 v12, v12
	v_add_f32_e32 v144, v82, v83

; DI void transpose_tile(const TJob& t, int lt, unsigned char* smem, int tid) {
;     ...
;   for (int i = 0; i < 4; ++i) {
;     const int k = i * 16 + (tid >> 4), n = (tid & 15) * 4;
;     const float sc = t.ks ? t.ks[k0 + k] : 1.f;
;     tl[k * 65 + n] = v[i].x * sc; tl[k * 65 + n + 1] = v[i].y * sc; tl[k * 65 + n + 2] = v[i].z * sc; tl[k * 65 + n + 3] = v[i].w * sc;
.LBB0_324:
	s_or_b64 exec, exec, s[44:45]
	s_cmp_lg_u64 s[40:41], 0
	s_cselect_b64 s[44:45], -1, 0
	s_cmp_eq_u64 s[40:41], 0
	s_cbranch_scc1 .LBB0_463
	v_lshl_add_u64 v[20:21], v[20:21], 2, s[40:41]
	flat_load_dword v20, v[20:21]
	s_ashr_i32 s43, s42, 31
	s_waitcnt vmcnt(0) lgkmcnt(0)
	v_mul_f32_e64 v22, v12, v20
	v_mul_f32_e64 v23, v13, v20
	v_mul_f32_e64 v21, v15, v20
	v_mul_f32_e64 v20, v14, v20
	ds_write2_b32 v47, v20, v21 offset0:2 offset1:3
	v_lshl_add_u64 v[20:21], s[42:43], 0, v[18:19]
	ds_write2_b32 v47, v22, v23 offset1:1
	v_lshl_add_u64 v[20:21], v[20:21], 2, s[40:41]
	flat_load_dword v20, v[20:21] offset:64
	s_cbranch_execnz .LBB0_327

; DI void transpose_tile(const TJob& t, int lt, unsigned char* smem, int tid) {
;     ...
;   for (int i = 0; i < 4; ++i) {
;     const int k = i * 16 + (tid >> 4), n = (tid & 15) * 4;
;     const float sc = t.ks ? t.ks[k0 + k] : 1.f;
;     tl[k * 65 + n] = v[i].x * sc; tl[k * 65 + n + 1] = v[i].y * sc; tl[k * 65 + n + 2] = v[i].z * sc; tl[k * 65 + n + 3] = v[i].w * sc;
.LBB0_327:
	s_waitcnt vmcnt(0) lgkmcnt(0)
	v_mul_f32_e64 v4, v4, v20
	v_mul_f32_e64 v5, v5, v20
	v_add_u32_e32 v12, 0x1040, v47
	ds_write2_b32 v12, v4, v5 offset1:1
	v_mul_f32_e64 v4, v6, v20
	v_mul_f32_e64 v5, v7, v20
	v_add_u32_e32 v6, 0x1048, v47
	ds_write2_b32 v6, v4, v5 offset1:1
	s_andn2_b64 vcc, exec, s[44:45]
	v_add_u32_e32 v5, 0x2080, v47
	v_add_u32_e32 v6, 0x2088, v47
	s_cbranch_vccnz .LBB0_464
	s_ashr_i32 s43, s42, 31
	v_lshl_add_u64 v[12:13], s[42:43], 0, v[18:19]
	v_lshl_add_u64 v[12:13], v[12:13], 2, s[40:41]
	flat_load_dword v4, v[12:13] offset:128
	s_waitcnt vmcnt(0) lgkmcnt(0)
	v_mul_f32_e64 v14, v8, v4
	v_mul_f32_e64 v15, v9, v4
	ds_write2_b32 v5, v14, v15 offset1:1
	v_mul_f32_e64 v14, v10, v4
	v_mul_f32_e64 v15, v11, v4
	ds_write2_b32 v6, v14, v15 offset1:1
	flat_load_dword v4, v[12:13] offset:192
	s_cbranch_execnz .LBB0_330

; DI unsigned pack2(float a, float b) { bf2_t v = __builtin_convertvector((f32x2){a, b}, bf2_t); return __builtin_bit_cast(unsigned, v); }
; DI void transpose_tile(const TJob& t, int lt, unsigned char* smem, int tid) {
;     ...
;   for (int i = 0; i < 4; ++i) {
;     const int k = i * 16 + (tid >> 4), n = (tid & 15) * 4;
;     const float sc = t.ks ? t.ks[k0 + k] : 1.f;
;     tl[k * 65 + n] = v[i].x * sc; tl[k * 65 + n + 1] = v[i].y * sc; tl[k * 65 + n + 2] = v[i].z * sc; tl[k * 65 + n + 3] = v[i].w * sc;
;   }
;   __syncthreads();
; #pragma unroll
;   for (int i = 0; i < 8; ++i) {
;     const int n = i * 8 + (tid >> 5), k2 = (tid & 31) * 2;
;     if (n0 + n < t.N) *(unsigned*)(t.dst + (size_t)map_col(n0 + n, t.mode) * t.ldd + k0 + k2) = pack2(tl[k2 * 65 + n], tl[(k2 + 1) * 65 + n]);
.LBB0_330:
	s_lshl_b64 s[40:41], s[42:43], 1
	s_waitcnt vmcnt(0) lgkmcnt(0)
	v_mul_f32_e64 v0, v0, v4
	v_mul_f32_e64 v1, v1, v4
	v_add_u32_e32 v5, 0x30c0, v47
	s_add_u32 s38, s38, s40
	ds_write2_b32 v5, v0, v1 offset1:1
	v_mul_f32_e64 v0, v2, v4
	v_mul_f32_e64 v1, v3, v4
	v_add_u32_e32 v2, 0x30c8, v47
	s_addc_u32 s39, s39, s41
	v_add_u32_e32 v4, s36, v17
	ds_write2_b32 v2, v0, v1 offset1:1
	v_lshl_add_u64 v[0:1], s[38:39], 0, v[32:33]
	v_cmp_gt_i32_e32 vcc, s54, v4
	s_waitcnt lgkmcnt(0)
	s_barrier
	s_and_saveexec_b64 s[38:39], vcc
	s_cbranch_execz .LBB0_347
	ds_read2_b32 v[2:3], v24 offset1:65
	s_cmp_lt_i32 s53, 2
	s_mov_b64 s[40:41], -1
	s_cbranch_scc1 .LBB0_337
	s_cmp_gt_i32 s53, 2
	v_lshlrev_b32_e32 v6, 1, v4
	s_cbranch_scc0 .LBB0_334
	v_and_or_b32 v5, v6, s85, v40
	s_mov_b64 s[40:41], 0

; DI unsigned pack2(float a, float b) { bf2_t v = __builtin_convertvector((f32x2){a, b}, bf2_t); return __builtin_bit_cast(unsigned, v); }
; #define MFMA(a, b, c) __builtin_amdgcn_mfma_f32_32x32x16_bf16((a), (b), (c), 0, 0, 0)
; template <int NDT> DI void pv_tile(const bf16_t* sV, const f32x16 (&P)[2], f32x16 (&O)[NDT], int r, int h) {
; #pragma unroll
;   for (int mt = 0; mt < 2; ++mt)
; #pragma unroll
;     for (int sp = 0; sp < 2; ++sp) {
;       u32x4 pk;
;       pk.x = pack2(P[mt][8 * sp + 0], P[mt][8 * sp + 1]); pk.y = pack2(P[mt][8 * sp + 2], P[mt][8 * sp + 3]);
;       pk.z = pack2(P[mt][8 * sp + 4], P[mt][8 * sp + 5]); pk.w = pack2(P[mt][8 * sp + 6], P[mt][8 * sp + 7]);
;       const bf16x8 pb = __builtin_bit_cast(bf16x8, pk);
; #pragma unroll
;       for (int dt = 0; dt < NDT; ++dt) {
;         const bf16_t* vp = sV + (dt * 32 + r) * 68 + mt * 32 + sp * 16 + 4 * h;
;         const bf16x4 lo = *(const bf16x4*)vp, hi = *(const bf16x4*)(vp + 8);
;         const bf16x8 va = __builtin_shufflevector(lo, hi, 0, 1, 2, 3, 4, 5, 6, 7);
;         O[dt] = MFMA(va, pb, O[dt]);
;       }
;       if (NDT > 2) __builtin_amdgcn_sched_barrier(0);
;     }
; }
; template <int NDT> DI void scale_o(f32x16 (&O)[NDT], float a) {
; #pragma unroll
;   for (int dt = 0; dt < NDT; ++dt)
; #pragma unroll
;     for (int i = 0; i < 16; ++i) O[dt][i] *= a;
; }
.LBB0_756:
	s_or_b64 exec, exec, s[82:83]
	s_nop 5
	v_add_u32_e32 v98, v246, v247
	v_add_u32_e32 v99, 0x2000, v98
	v_add_u32_e32 v100, 0x3000, v98
	v_add_u32_e32 v101, 0x4000, v98
	v_add_u32_e32 v98, 0x5000, v98
	v_cvt_pk_bf16_f32 v0, v0, v1
	v_cvt_pk_bf16_f32 v1, v2, v3
	v_cvt_pk_bf16_f32 v2, v4, v5
	v_cvt_pk_bf16_f32 v3, v6, v7
	ds_read2_b64 v[4:7], v99 offset0:128 offset1:130
	v_cvt_pk_bf16_f32 v8, v8, v9
	v_cvt_pk_bf16_f32 v9, v10, v11
	v_cvt_pk_bf16_f32 v10, v12, v13
	v_cvt_pk_bf16_f32 v11, v14, v15
	ds_read2_b64 v[12:15], v100 offset0:160 offset1:162
	v_cvt_pk_bf16_f32 v16, v16, v17
	v_cvt_pk_bf16_f32 v17, v18, v19
	v_cvt_pk_bf16_f32 v18, v20, v21
	v_cvt_pk_bf16_f32 v19, v22, v23
	ds_read2_b64 v[20:23], v101 offset0:192 offset1:194
	v_cvt_pk_bf16_f32 v24, v24, v25
	v_cvt_pk_bf16_f32 v25, v26, v27
	v_cvt_pk_bf16_f32 v26, v28, v29
	v_cvt_pk_bf16_f32 v27, v30, v31
	ds_read2_b64 v[28:31], v98 offset0:224 offset1:226
	v_mul_f32_e64 v96, v96, v202
	v_mul_f32_e64 v97, v97, v202
	v_mul_f32_e64 v94, v94, v202
	v_mul_f32_e64 v95, v95, v202
	v_mul_f32_e64 v92, v92, v202
	v_mul_f32_e64 v93, v93, v202
	v_mul_f32_e64 v90, v90, v202
	v_mul_f32_e64 v91, v91, v202
	v_mul_f32_e64 v88, v88, v202
	v_mul_f32_e64 v89, v89, v202
	v_mul_f32_e64 v86, v86, v202
	v_mul_f32_e64 v87, v87, v202
	v_mul_f32_e64 v84, v84, v202
	v_mul_f32_e64 v85, v85, v202
	v_mul_f32_e64 v82, v82, v202
	v_mul_f32_e64 v83, v83, v202
	s_waitcnt lgkmcnt(3)
	s_nop 0
	v_mfma_f32_32x32x16_bf16 v[82:97], v[4:7], v[0:3], v[82:97]
	ds_read2_b64 v[4:7], v99 offset0:132 offset1:134
	v_mul_f32_e64 v80, v80, v202
	v_mul_f32_e64 v81, v81, v202
	v_mul_f32_e64 v78, v78, v202
	v_mul_f32_e64 v79, v79, v202
	v_mul_f32_e64 v76, v76, v202
	v_mul_f32_e64 v77, v77, v202
	v_mul_f32_e64 v74, v74, v202
	v_mul_f32_e64 v75, v75, v202
	v_mul_f32_e64 v72, v72, v202
	v_mul_f32_e64 v73, v73, v202
	v_mul_f32_e64 v70, v70, v202
	v_mul_f32_e64 v71, v71, v202
	v_mul_f32_e64 v68, v68, v202
	v_mul_f32_e64 v69, v69, v202
	v_mul_f32_e64 v66, v66, v202
	v_mul_f32_e64 v67, v67, v202
	s_waitcnt lgkmcnt(3)
	s_nop 0
	v_mfma_f32_32x32x16_bf16 v[66:81], v[12:15], v[0:3], v[66:81]
	ds_read2_b64 v[12:15], v100 offset0:164 offset1:166
	v_mul_f32_e64 v64, v64, v202
	v_mul_f32_e64 v65, v65, v202
	v_mul_f32_e64 v62, v62, v202
	v_mul_f32_e64 v63, v63, v202
	v_mul_f32_e64 v60, v60, v202
	v_mul_f32_e64 v61, v61, v202
	v_mul_f32_e64 v58, v58, v202
	v_mul_f32_e64 v59, v59, v202
	v_mul_f32_e64 v56, v56, v202
	v_mul_f32_e64 v57, v57, v202
	v_mul_f32_e64 v54, v54, v202
	v_mul_f32_e64 v55, v55, v202
	v_mul_f32_e64 v52, v52, v202
	v_mul_f32_e64 v53, v53, v202
	v_mul_f32_e64 v50, v50, v202
	v_mul_f32_e64 v51, v51, v202
	s_waitcnt lgkmcnt(3)
	s_nop 0
	v_mfma_f32_32x32x16_bf16 v[50:65], v[20:23], v[0:3], v[50:65]
	ds_read2_b64 v[20:23], v101 offset0:196 offset1:198
	v_mul_f32_e64 v48, v48, v202
	v_mul_f32_e64 v49, v49, v202
	v_mul_f32_e64 v46, v46, v202
	v_mul_f32_e64 v47, v47, v202
	v_mul_f32_e64 v44, v44, v202
	v_mul_f32_e64 v45, v45, v202
	v_mul_f32_e64 v42, v42, v202
	v_mul_f32_e64 v43, v43, v202
	v_mul_f32_e64 v40, v40, v202
	v_mul_f32_e64 v41, v41, v202
	v_mul_f32_e64 v38, v38, v202
	v_mul_f32_e64 v39, v39, v202
	v_mul_f32_e64 v36, v36, v202
	v_mul_f32_e64 v37, v37, v202
	v_mul_f32_e64 v34, v34, v202
	v_mul_f32_e64 v35, v35, v202
	s_waitcnt lgkmcnt(3)
	s_nop 0
	v_mfma_f32_32x32x16_bf16 v[34:49], v[28:31], v[0:3], v[34:49]
	ds_read2_b64 v[28:31], v98 offset0:228 offset1:230
	s_waitcnt lgkmcnt(3)
	v_mfma_f32_32x32x16_bf16 v[82:97], v[4:7], v[8:11], v[82:97]
	ds_read2_b64 v[4:7], v99 offset0:136 offset1:138
	s_waitcnt lgkmcnt(3)
	v_mfma_f32_32x32x16_bf16 v[66:81], v[12:15], v[8:11], v[66:81]
	ds_read2_b64 v[12:15], v100 offset0:168 offset1:170
	s_waitcnt lgkmcnt(3)
	v_mfma_f32_32x32x16_bf16 v[50:65], v[20:23], v[8:11], v[50:65]
	ds_read2_b64 v[20:23], v101 offset0:200 offset1:202
	s_waitcnt lgkmcnt(3)
	v_mfma_f32_32x32x16_bf16 v[34:49], v[28:31], v[8:11], v[34:49]
	ds_read2_b64 v[28:31], v98 offset0:232 offset1:234
	s_waitcnt lgkmcnt(3)
	v_mfma_f32_32x32x16_bf16 v[82:97], v[4:7], v[16:19], v[82:97]
	ds_read2_b64 v[4:7], v99 offset0:140 offset1:142
	s_waitcnt lgkmcnt(3)
	v_mfma_f32_32x32x16_bf16 v[66:81], v[12:15], v[16:19], v[66:81]
	ds_read2_b64 v[12:15], v100 offset0:172 offset1:174
	s_waitcnt lgkmcnt(3)
	v_mfma_f32_32x32x16_bf16 v[50:65], v[20:23], v[16:19], v[50:65]
	ds_read2_b64 v[20:23], v101 offset0:204 offset1:206
	s_waitcnt lgkmcnt(3)
	v_mfma_f32_32x32x16_bf16 v[34:49], v[28:31], v[16:19], v[34:49]
	ds_read2_b64 v[28:31], v98 offset0:236 offset1:238
	s_waitcnt lgkmcnt(3)
	v_mfma_f32_32x32x16_bf16 v[82:97], v[4:7], v[24:27], v[82:97]
	s_waitcnt lgkmcnt(2)
	v_mfma_f32_32x32x16_bf16 v[66:81], v[12:15], v[24:27], v[66:81]
	s_waitcnt lgkmcnt(1)
	v_mfma_f32_32x32x16_bf16 v[50:65], v[20:23], v[24:27], v[50:65]
	s_waitcnt lgkmcnt(0)
	v_mfma_f32_32x32x16_bf16 v[34:49], v[28:31], v[24:27], v[34:49]

; #define MFMA(a, b, c) __builtin_amdgcn_mfma_f32_32x32x16_bf16((a), (b), (c), 0, 0, 0)
; DI float shx32(float v) { return __shfl_xor(v, 32); }
; DI void qk_tile(const bf16_t* sK, const bf16x8 (&qf)[4], f32x16 (&Sx)[2], int r, int h) {
; #pragma unroll
;   for (int mt = 0; mt < 2; ++mt) {
;     f32x16 a;
; #pragma unroll
;     for (int i = 0; i < 16; ++i) a[i] = 0.f;
; #pragma unroll
;     for (int s = 0; s < 4; ++s) {
;       const bf16x8 k = *(const bf16x8*)(sK + (mt * 32 + r) * 72 + s * 16 + h * 8);
;       a = MFMA(k, qf[s], a);
;     }
;     Sx[mt] = a;
;   }
; template <bool MASKED>
; DI float online_softmax_t(f32x16 (&Sx)[2], unsigned vb, float& m, float& l) {
;   float mx = NEG;
; #pragma unroll
;   for (int mt = 0; mt < 2; ++mt)
; #pragma unroll
;     for (int i = 0; i < 16; ++i) {
;       float s = Sx[mt][i];
;       if (MASKED) { s = ((vb >> (mt * 16 + i)) & 1u) ? s : NEG; Sx[mt][i] = s; }
;       mx = fmaxf(mx, s);
;     }
;   mx = fmaxf(mx, shx32(mx));
;   const float mn = fmaxf(m, mx);
;   const float alpha = __builtin_amdgcn_exp2f((m - mn) * L2E);
;   const float mb = mn * L2E;
;   f32x2 sum2 = {0.f, 0.f};
;   const f32x2 l2e2 = {L2E, L2E}, mb2 = {mb, mb};
; #pragma unroll
;   for (int mt = 0; mt < 2; ++mt)
; #pragma unroll
;     for (int i = 0; i < 16; i += 2) {
;       const f32x2 t = (f32x2){Sx[mt][i], Sx[mt][i + 1]} * l2e2 - mb2;
;       f32x2 p = {__builtin_amdgcn_exp2f(t.x), __builtin_amdgcn_exp2f(t.y)};
;       if (MASKED) { p.x = ((vb >> (mt * 16 + i)) & 1u) ? p.x : 0.f; p.y = ((vb >> (mt * 16 + i + 1)) & 1u) ? p.y : 0.f; }
;       Sx[mt][i] = p.x; Sx[mt][i + 1] = p.y;
;       sum2 += p;
;     }
;   l = l * alpha + (sum2.x + sum2.y);
.LBB0_760:
	v_cmp_le_i32_e32 vcc, s91, v245
	s_and_saveexec_b64 s[78:79], vcc
	s_cbranch_execz .LBB0_757
	ds_read_b128 v[0:3], v249
	ds_read_b128 v[4:7], v249 offset:32
	ds_read_b128 v[8:11], v249 offset:64
	ds_read_b128 v[12:15], v249 offset:96
	ds_read_b128 v[16:19], v249 offset:4608
	ds_read_b128 v[20:23], v249 offset:4640
	ds_read_b128 v[24:27], v249 offset:4672
	ds_read_b128 v[28:31], v249 offset:4704
	s_add_i32 s0, s80, -1
	v_cmp_le_i32_e32 vcc, s0, v244
	s_waitcnt lgkmcnt(7)
	v_mfma_f32_32x32x16_bf16 v[114:129], v[0:3], v[130:133], 0
	s_waitcnt lgkmcnt(6)
	v_mfma_f32_32x32x16_bf16 v[114:129], v[4:7], v[134:137], v[114:129]
	s_waitcnt lgkmcnt(5)
	v_mfma_f32_32x32x16_bf16 v[114:129], v[8:11], v[138:141], v[114:129]
	s_waitcnt lgkmcnt(4)
	v_mfma_f32_32x32x16_bf16 v[114:129], v[12:15], v[142:145], v[114:129]
	s_waitcnt lgkmcnt(3)
	v_mfma_f32_32x32x16_bf16 v[98:113], v[16:19], v[130:133], 0
	s_waitcnt lgkmcnt(2)
	v_mfma_f32_32x32x16_bf16 v[98:113], v[20:23], v[134:137], v[98:113]
	s_waitcnt lgkmcnt(1)
	v_mfma_f32_32x32x16_bf16 v[98:113], v[24:27], v[138:141], v[98:113]
	s_waitcnt lgkmcnt(0)
	v_mfma_f32_32x32x16_bf16 v[98:113], v[28:31], v[142:145], v[98:113]
	s_and_saveexec_b64 s[0:1], vcc
	s_xor_b64 s[0:1], exec, s[0:1]
	s_cbranch_execz .LBB0_763
	v_max3_f32 v0, v114, s67, v115
	v_max3_f32 v0, v0, v116, v117
	v_max3_f32 v0, v0, v118, v119
	v_max3_f32 v0, v0, v120, v121
	v_max3_f32 v0, v0, v122, v123
	v_max3_f32 v0, v0, v124, v125
	v_max3_f32 v0, v0, v126, v127
	v_max3_f32 v0, v0, v128, v129
	s_nop 0
	v_max3_f32 v0, v0, v98, v99
	v_max3_f32 v0, v0, v100, v101
	v_max3_f32 v0, v0, v102, v103
	v_max3_f32 v0, v0, v104, v105
	v_and_b32_e32 v2, 64, v208
	v_max3_f32 v0, v0, v106, v107
	v_xor_b32_e32 v1, 32, v208
	v_add_u32_e32 v2, 64, v2
	v_max3_f32 v0, v0, v108, v109
	v_cmp_lt_i32_e32 vcc, v1, v2
	v_max3_f32 v0, v0, v110, v111
	v_max3_f32 v0, v0, v112, v113
	v_cndmask_b32_e32 v1, v208, v1, vcc
	v_lshlrev_b32_e32 v1, 2, v1
	ds_bpermute_b32 v1, v1, v0
	s_mov_b32 s2, 0x3fb8aa3b
	s_waitcnt lgkmcnt(0)
	v_max3_f32 v203, v205, v0, v1
	v_mul_f32_e32 v30, 0x3fb8aa3b, v203
	v_fma_f32 v0, v114, s2, -v30
	v_fma_f32 v1, v115, s2, -v30
	v_fma_f32 v2, v116, s2, -v30
	v_fma_f32 v3, v117, s2, -v30
	v_exp_f32_e32 v0, v0
	v_exp_f32_e32 v1, v1
	v_exp_f32_e32 v2, v2
	v_exp_f32_e32 v3, v3
	v_fma_f32 v6, v120, s2, -v30
	v_fma_f32 v7, v121, s2, -v30
	v_add_f32_e64 v4, v0, 0
	v_add_f32_e64 v5, v1, 0
	v_exp_f32_e32 v6, v6
	v_add_f32_e64 v12, v2, v4
	v_add_f32_e64 v13, v3, v5
	v_fma_f32 v4, v118, s2, -v30
	v_fma_f32 v5, v119, s2, -v30
	v_exp_f32_e32 v7, v7
	v_exp_f32_e32 v4, v4
	v_exp_f32_e32 v5, v5
	v_fma_f32 v8, v122, s2, -v30
	v_fma_f32 v9, v123, s2, -v30
	v_fma_f32 v10, v124, s2, -v30
	v_fma_f32 v11, v125, s2, -v30
	v_exp_f32_e32 v8, v8
	v_exp_f32_e32 v9, v9
	v_exp_f32_e32 v10, v10
	v_exp_f32_e32 v11, v11
	v_add_f32_e64 v12, v4, v12
	v_add_f32_e64 v13, v5, v13
	v_fma_f32 v14, v128, s2, -v30
	v_fma_f32 v15, v129, s2, -v30
	v_add_f32_e64 v12, v6, v12
	v_add_f32_e64 v13, v7, v13
	v_exp_f32_e32 v14, v14
	v_add_f32_e64 v12, v8, v12
	v_add_f32_e64 v13, v9, v13
	v_exp_f32_e32 v15, v15
	v_add_f32_e64 v20, v10, v12
	v_add_f32_e64 v21, v11, v13
	v_fma_f32 v12, v126, s2, -v30
	v_fma_f32 v13, v127, s2, -v30
	v_fma_f32 v16, v98, s2, -v30
	v_fma_f32 v17, v99, s2, -v30
	v_exp_f32_e32 v12, v12
	v_exp_f32_e32 v13, v13
	v_exp_f32_e32 v16, v16
	v_exp_f32_e32 v17, v17
	v_fma_f32 v18, v100, s2, -v30
	v_fma_f32 v19, v101, s2, -v30
	v_add_f32_e64 v20, v12, v20
	v_add_f32_e64 v21, v13, v21
	v_exp_f32_e32 v18, v18
	v_exp_f32_e32 v19, v19
	v_add_f32_e64 v20, v14, v20
	v_add_f32_e64 v21, v15, v21
	v_fma_f32 v22, v104, s2, -v30
	v_fma_f32 v23, v105, s2, -v30
	v_add_f32_e64 v20, v16, v20
	v_add_f32_e64 v21, v17, v21
	v_exp_f32_e32 v22, v22
	v_add_f32_e64 v28, v18, v20
	v_add_f32_e64 v29, v19, v21
	v_fma_f32 v20, v102, s2, -v30
	v_fma_f32 v21, v103, s2, -v30
	v_exp_f32_e32 v23, v23
	v_exp_f32_e32 v20, v20
	v_exp_f32_e32 v21, v21
	v_fma_f32 v24, v106, s2, -v30
	v_fma_f32 v25, v107, s2, -v30
	v_fma_f32 v26, v108, s2, -v30
	v_fma_f32 v27, v109, s2, -v30
	v_exp_f32_e32 v24, v24
	v_exp_f32_e32 v25, v25
	v_exp_f32_e32 v26, v26
	v_exp_f32_e32 v27, v27
	v_add_f32_e64 v28, v20, v28
	v_add_f32_e64 v29, v21, v29
	v_sub_f32_e32 v100, v205, v203
	v_add_f32_e64 v28, v22, v28
	v_add_f32_e64 v29, v23, v29
	v_mul_f32_e32 v100, 0x3fb8aa3b, v100
	v_add_f32_e64 v28, v24, v28
	v_add_f32_e64 v29, v25, v29
	v_exp_f32_e32 v202, v100
	v_add_f32_e64 v98, v26, v28
	v_add_f32_e64 v99, v27, v29
	v_fma_f32 v28, v110, s2, -v30
	v_fma_f32 v29, v111, s2, -v30
	v_fma_f32 v31, v113, s2, -v30
	v_fma_f32 v30, v112, s2, -v30
	v_exp_f32_e32 v28, v28
	v_exp_f32_e32 v29, v29
	v_exp_f32_e32 v30, v30
	v_exp_f32_e32 v31, v31
	v_add_f32_e64 v98, v28, v98
	v_add_f32_e64 v99, v29, v99
	s_nop 0
	v_add_f32_e64 v98, v30, v98
	v_add_f32_e64 v99, v31, v99
	s_nop 0
	v_add_f32_e32 v98, v98, v99
	v_fmac_f32_e32 v98, v179, v202
	v_mov_b32_e32 v179, v98
	v_mov_b32_e32 v205, v203
; DI int crow(int i, int h) { return (i & 3) + 8 * (i >> 2) + 4 * h; }
; DI float shx32(float v) { return __shfl_xor(v, 32); }
; template <bool MASKED>
; DI float online_softmax_t(f32x16 (&Sx)[2], unsigned vb, float& m, float& l) {
;   float mx = NEG;
; #pragma unroll
;   for (int mt = 0; mt < 2; ++mt)
; #pragma unroll
;     for (int i = 0; i < 16; ++i) {
;       float s = Sx[mt][i];
;       if (MASKED) { s = ((vb >> (mt * 16 + i)) & 1u) ? s : NEG; Sx[mt][i] = s; }
;       mx = fmaxf(mx, s);
;     }
;   mx = fmaxf(mx, shx32(mx));
; DI void diff_pass(const bf16_t* Qrow, const bf16_t* Kg, const bf16_t* VTg, int qt, int q0, int t, f32x16 (&O)[4], float& lsum,
;                   bf16_t* sK, bf16_t* sV, int tid, int r, int h) {
;     ...
;       const bool masked = (kt * 64 + 63 > q0);
;       unsigned vb = 0;
;       if (masked) {
; #pragma unroll
;         for (int mt = 0; mt < 2; ++mt)
; #pragma unroll
;           for (int i = 0; i < 16; ++i) vb |= (unsigned)(kt * 64 + mt * 32 + crow(i, h) <= t) << (mt * 16 + i);
;       }
.LBB0_763:
	s_andn2_saveexec_b64 s[82:83], s[0:1]
	s_cbranch_execz .LBB0_756
	v_add_u32_e32 v0, s80, v243
	v_subrev_u32_e32 v1, 64, v0
	v_cmp_le_i32_e64 s[16:17], v1, v184
	v_cmp_lt_i32_e64 s[12:13], v1, v184
	v_subrev_u32_e32 v8, 48, v0
	v_subrev_u32_e32 v9, 47, v0
	v_cndmask_b32_e64 v2, 0, 1, s[16:17]
	v_cndmask_b32_e64 v1, 0, 2, s[12:13]
	v_subrev_u32_e32 v4, 56, v0
	v_subrev_u32_e32 v5, 55, v0
	v_cmp_gt_i32_e64 s[2:3], v8, v184
	v_cmp_gt_i32_e32 vcc, v9, v184
	v_or_b32_e32 v1, v1, v2
	v_subrev_u32_e32 v2, 62, v0
	v_subrev_u32_e32 v3, 61, v0
	v_cmp_gt_i32_e64 s[10:11], v4, v184
	v_cmp_gt_i32_e64 s[4:5], v5, v184
	v_cndmask_b32_e64 v8, v216, 0, s[2:3]
	v_cndmask_b32_e64 v9, v217, 0, vcc
	v_cmp_gt_i32_e64 s[14:15], v2, v184
	v_cmp_gt_i32_e64 s[8:9], v3, v184
	v_cndmask_b32_e64 v4, 16, 0, s[10:11]
	v_cndmask_b32_e64 v5, 32, 0, s[4:5]
	v_subrev_u32_e32 v6, 54, v0
	v_subrev_u32_e32 v7, 53, v0
	v_or3_b32 v1, v1, v8, v9
	v_cndmask_b32_e64 v2, 4, 0, s[14:15]
	v_cndmask_b32_e64 v3, 8, 0, s[8:9]
	v_cmp_gt_i32_e64 s[6:7], v6, v184
	v_cmp_gt_i32_e64 s[0:1], v7, v184
	v_or3_b32 v1, v5, v4, v1
	v_cndmask_b32_e64 v6, 64, 0, s[6:7]
	v_cndmask_b32_e64 v7, v215, 0, s[0:1]
	v_or3_b32 v1, v3, v2, v1
	v_or3_b32 v11, v6, v7, v1
	v_subrev_u32_e32 v1, 46, v0
	v_cmp_gt_i32_e64 s[18:19], v1, v184
	v_subrev_u32_e32 v2, 45, v0
	v_cndmask_b32_e64 v3, v117, v214, s[8:9]
	v_cndmask_b32_e64 v1, v218, 0, s[18:19]
	v_cmp_gt_i32_e64 s[18:19], v2, v184
	v_cndmask_b32_e64 v5, v119, v214, s[4:5]
	v_cndmask_b32_e64 v7, v121, v214, s[0:1]
	v_cndmask_b32_e64 v2, v219, 0, s[18:19]
	v_or_b32_e32 v12, v1, v2
	v_subrev_u32_e32 v1, 40, v0
	v_cmp_gt_i32_e64 s[18:19], v1, v184
	v_subrev_u32_e32 v2, 39, v0
	v_or_b32_e32 v13, v12, v11
	v_cndmask_b32_e64 v1, v220, 0, s[18:19]
	v_cmp_gt_i32_e64 s[18:19], v2, v184
	v_cndmask_b32_e32 v9, v123, v214, vcc
	s_mov_b32 s20, 0x100000
	v_cndmask_b32_e64 v2, v221, 0, s[18:19]
	v_or_b32_e32 v14, v1, v2
	v_subrev_u32_e32 v1, 38, v0
	v_cmp_gt_i32_e64 s[18:19], v1, v184
	v_subrev_u32_e32 v2, 37, v0
	v_or_b32_e32 v15, v14, v13
	v_cndmask_b32_e64 v1, v222, 0, s[18:19]
	v_cmp_gt_i32_e64 s[18:19], v2, v184
	s_mov_b32 s21, 0x200000
	s_mov_b32 s22, 0x400000
	v_cndmask_b32_e64 v2, v223, 0, s[18:19]
	v_or_b32_e32 v16, v1, v2
	v_subrev_u32_e32 v1, 32, v0
	v_cmp_gt_i32_e64 s[18:19], v1, v184
	v_subrev_u32_e32 v2, 31, v0
	v_or_b32_e32 v17, v16, v15
	v_cndmask_b32_e64 v1, v224, 0, s[18:19]
	v_cmp_gt_i32_e64 s[18:19], v2, v184
	s_brev_b32 s23, 16
	s_brev_b32 s30, 8
	v_cndmask_b32_e64 v2, v225, 0, s[18:19]
	v_or_b32_e32 v18, v1, v2
	v_subrev_u32_e32 v1, 30, v0
	v_cmp_gt_i32_e64 s[18:19], v1, v184
	v_subrev_u32_e32 v2, 29, v0
	v_or_b32_e32 v19, v18, v17
	v_cndmask_b32_e64 v1, v226, 0, s[18:19]
	v_cmp_gt_i32_e64 s[18:19], v2, v184
	s_brev_b32 s62, 4
	s_mov_b32 s72, 0x3fb8aa3b
	v_cndmask_b32_e64 v2, v227, 0, s[18:19]
	v_or_b32_e32 v20, v1, v2
	v_subrev_u32_e32 v1, 24, v0
	v_cmp_gt_i32_e64 s[18:19], v1, v184
	v_subrev_u32_e32 v2, 23, v0
	v_or_b32_e32 v21, v20, v19
	v_cndmask_b32_e64 v1, v228, 0, s[18:19]
	v_cmp_gt_i32_e64 s[18:19], v2, v184
	s_nop 1
	v_cndmask_b32_e64 v2, v229, 0, s[18:19]
	v_or_b32_e32 v22, v1, v2
	v_subrev_u32_e32 v1, 22, v0
	v_cmp_gt_i32_e64 s[18:19], v1, v184
	v_subrev_u32_e32 v2, 21, v0
	v_or_b32_e32 v23, v22, v21
	v_cndmask_b32_e64 v1, v230, 0, s[18:19]
	v_cmp_gt_i32_e64 s[18:19], v2, v184
	s_nop 1
	v_cndmask_b32_e64 v2, v231, 0, s[18:19]
	v_or_b32_e32 v24, v1, v2
	v_add_u32_e32 v1, -16, v0
	v_cmp_gt_i32_e64 s[18:19], v1, v184
	v_add_u32_e32 v2, -15, v0
	v_or_b32_e32 v25, v24, v23
	v_cndmask_b32_e64 v1, v232, 0, s[18:19]
	v_cmp_gt_i32_e64 s[18:19], v2, v184
	s_nop 1
	v_cndmask_b32_e64 v2, v233, 0, s[18:19]
	v_or_b32_e32 v26, v1, v2
	v_add_u32_e32 v1, -14, v0
	v_cmp_gt_i32_e64 s[18:19], v1, v184
	v_add_u32_e32 v2, -13, v0
	v_or_b32_e32 v27, v26, v25
	v_cndmask_b32_e64 v1, v234, 0, s[18:19]
	v_cmp_gt_i32_e64 s[18:19], v2, v184
	s_nop 1
	v_cndmask_b32_e64 v2, v235, 0, s[18:19]
	v_or_b32_e32 v28, v1, v2
	v_add_u32_e32 v1, -8, v0
	v_cmp_gt_i32_e64 s[18:19], v1, v184
	v_add_u32_e32 v2, -7, v0
	v_or_b32_e32 v29, v28, v27
	v_cndmask_b32_e64 v1, v236, 0, s[18:19]
	v_cmp_gt_i32_e64 s[18:19], v2, v184
	s_nop 1
	v_cndmask_b32_e64 v2, v237, 0, s[18:19]
	v_or_b32_e32 v30, v1, v2
	v_add_u32_e32 v1, -6, v0
	v_cmp_gt_i32_e64 s[18:19], v1, v184
	v_add_u32_e32 v0, -5, v0
	v_cndmask_b32_e64 v2, v116, v214, s[14:15]
	v_cndmask_b32_e64 v1, 2.0, 0, s[18:19]
	v_cmp_gt_i32_e64 s[18:19], v0, v184
	v_or_b32_e32 v31, v30, v29
	s_nop 0
	v_cndmask_b32_e64 v0, v238, 0, s[18:19]
	v_or_b32_e32 v202, v1, v0
	v_cndmask_b32_e64 v0, v214, v114, s[16:17]
	v_cndmask_b32_e64 v1, v214, v115, s[12:13]
	v_max3_f32 v4, v0, s67, v1
	v_max3_f32 v6, v4, v2, v3
	v_cndmask_b32_e64 v4, v118, v214, s[10:11]
	v_max3_f32 v8, v6, v4, v5
	v_cndmask_b32_e64 v6, v120, v214, s[6:7]
	v_max3_f32 v10, v8, v6, v7
	v_cndmask_b32_e64 v8, v122, v214, s[2:3]
	v_max3_f32 v114, v10, v8, v9
	v_bitop3_b32 v10, v12, s64, v11 bitop3:0xc8
	v_bitop3_b32 v11, v12, s92, v11 bitop3:0xc8
	v_cmp_eq_u32_e64 s[60:61], 0, v10
	v_cmp_eq_u32_e64 s[50:51], 0, v11
	v_bitop3_b32 v12, v14, s65, v13 bitop3:0xc8
	v_bitop3_b32 v13, v14, s66, v13 bitop3:0xc8
	v_cndmask_b32_e64 v10, v124, v214, s[60:61]
	v_cndmask_b32_e64 v11, v125, v214, s[50:51]
	v_cmp_eq_u32_e64 s[58:59], 0, v12
	v_cmp_eq_u32_e64 s[46:47], 0, v13
	v_bitop3_b32 v14, v16, s94, v15 bitop3:0xc8
	v_bitop3_b32 v15, v16, s68, v15 bitop3:0xc8
	s_mov_b32 s18, 0x20000
	s_mov_b32 s19, 0x80000
	v_max3_f32 v114, v114, v10, v11
	v_cndmask_b32_e64 v12, v126, v214, s[58:59]
	v_cndmask_b32_e64 v13, v127, v214, s[46:47]
	v_cmp_eq_u32_e64 s[56:57], 0, v14
	v_cmp_eq_u32_e64 s[42:43], 0, v15
; DI float shx32(float v) { return __shfl_xor(v, 32); }
; template <bool MASKED>
; DI float online_softmax_t(f32x16 (&Sx)[2], unsigned vb, float& m, float& l) {
;   float mx = NEG;
; #pragma unroll
;   for (int mt = 0; mt < 2; ++mt)
; #pragma unroll
;     for (int i = 0; i < 16; ++i) {
;       float s = Sx[mt][i];
;       if (MASKED) { s = ((vb >> (mt * 16 + i)) & 1u) ? s : NEG; Sx[mt][i] = s; }
;       mx = fmaxf(mx, s);
;     }
;   mx = fmaxf(mx, shx32(mx));
;   const float mn = fmaxf(m, mx);
;   const float alpha = __builtin_amdgcn_exp2f((m - mn) * L2E);
;   const float mb = mn * L2E;
;   f32x2 sum2 = {0.f, 0.f};
;   const f32x2 l2e2 = {L2E, L2E}, mb2 = {mb, mb};
; #pragma unroll
;   for (int mt = 0; mt < 2; ++mt)
; #pragma unroll
;     for (int i = 0; i < 16; i += 2) {
;       const f32x2 t = (f32x2){Sx[mt][i], Sx[mt][i + 1]} * l2e2 - mb2;
;       f32x2 p = {__builtin_amdgcn_exp2f(t.x), __builtin_amdgcn_exp2f(t.y)};
;       if (MASKED) { p.x = ((vb >> (mt * 16 + i)) & 1u) ? p.x : 0.f; p.y = ((vb >> (mt * 16 + i + 1)) & 1u) ? p.y : 0.f; }
;       Sx[mt][i] = p.x; Sx[mt][i + 1] = p.y;
;       sum2 += p;
;     }
;   l = l * alpha + (sum2.x + sum2.y);
;   m = mn;
	v_bitop3_b32 v16, v18, s69, v17 bitop3:0xc8
	v_bitop3_b32 v17, v18, s18, v17 bitop3:0xc8
	v_max3_f32 v114, v114, v12, v13
	v_cndmask_b32_e64 v14, v128, v214, s[56:57]
	v_cndmask_b32_e64 v15, v129, v214, s[42:43]
	v_cmp_eq_u32_e64 s[54:55], 0, v16
	v_cmp_eq_u32_e64 s[38:39], 0, v17
	v_bitop3_b32 v18, v20, s52, v19 bitop3:0xc8
	v_bitop3_b32 v19, v20, s19, v19 bitop3:0xc8
	v_max3_f32 v114, v114, v14, v15
	v_cndmask_b32_e64 v16, v98, v214, s[54:55]
	v_cndmask_b32_e64 v17, v99, v214, s[38:39]
	v_cmp_eq_u32_e64 s[52:53], 0, v18
	v_cmp_eq_u32_e64 s[34:35], 0, v19
	v_bitop3_b32 v20, v22, s20, v21 bitop3:0xc8
	v_bitop3_b32 v21, v22, s21, v21 bitop3:0xc8
	v_max3_f32 v98, v114, v16, v17
	v_cndmask_b32_e64 v18, v100, v214, s[52:53]
	v_cndmask_b32_e64 v19, v101, v214, s[34:35]
	s_mov_b32 s18, 0x1000000
	s_brev_b32 s19, 64
	v_cmp_eq_u32_e64 s[48:49], 0, v20
	v_cmp_eq_u32_e64 s[28:29], 0, v21
	v_bitop3_b32 v22, v24, s22, v23 bitop3:0xc8
	v_bitop3_b32 v23, v24, s84, v23 bitop3:0xc8
	v_max3_f32 v98, v98, v18, v19
	s_brev_b32 s20, 32
	v_cndmask_b32_e64 v20, v102, v214, s[48:49]
	v_cndmask_b32_e64 v21, v103, v214, s[28:29]
	v_cmp_eq_u32_e64 s[44:45], 0, v22
	v_cmp_eq_u32_e64 s[26:27], 0, v23
	v_bitop3_b32 v24, v26, s18, v25 bitop3:0xc8
	v_bitop3_b32 v25, v26, s19, v25 bitop3:0xc8
	v_max3_f32 v98, v98, v20, v21
	v_cndmask_b32_e64 v22, v104, v214, s[44:45]
	v_cndmask_b32_e64 v23, v105, v214, s[26:27]
	v_cmp_eq_u32_e64 s[40:41], 0, v24
	v_cmp_eq_u32_e64 s[24:25], 0, v25
	v_bitop3_b32 v26, v28, s20, v27 bitop3:0xc8
	v_bitop3_b32 v27, v28, s23, v27 bitop3:0xc8
	v_and_b32_e32 v99, 64, v208
	v_or_b32_e32 v203, v202, v31
	v_max3_f32 v98, v98, v22, v23
	v_cndmask_b32_e64 v24, v106, v214, s[40:41]
	v_cndmask_b32_e64 v25, v107, v214, s[24:25]
	v_cmp_eq_u32_e64 s[36:37], 0, v26
	v_cmp_eq_u32_e64 s[22:23], 0, v27
	v_bitop3_b32 v28, v30, s30, v29 bitop3:0xc8
	v_bitop3_b32 v29, v30, s62, v29 bitop3:0xc8
	v_bitop3_b32 v30, v202, 2.0, v31 bitop3:0xc8
	v_xor_b32_e32 v31, 32, v208
	v_add_u32_e32 v99, 64, v99
	v_max3_f32 v98, v98, v24, v25
	v_cndmask_b32_e64 v26, v108, v214, s[36:37]
	v_cndmask_b32_e64 v27, v109, v214, s[22:23]
	v_cmp_eq_u32_e64 s[30:31], 0, v28
	v_cmp_eq_u32_e64 s[20:21], 0, v29
	v_cmp_lt_i32_e64 s[18:19], v31, v99
	v_max3_f32 v98, v98, v26, v27
	v_cndmask_b32_e64 v28, v110, v214, s[30:31]
	v_cndmask_b32_e64 v29, v111, v214, s[20:21]
	v_cndmask_b32_e64 v99, v208, v31, s[18:19]
	v_cmp_eq_u32_e64 s[62:63], 0, v30
	v_cmp_lt_i32_e64 s[18:19], -1, v203
	v_max3_f32 v98, v98, v28, v29
	v_cndmask_b32_e64 v30, v112, v214, s[62:63]
	v_cndmask_b32_e64 v31, v113, v214, s[18:19]
	v_max3_f32 v98, v98, v30, v31
	v_lshlrev_b32_e32 v99, 2, v99
	ds_bpermute_b32 v99, v99, v98
	s_waitcnt lgkmcnt(0)
	v_max3_f32 v102, v205, v98, v99
	v_mul_f32_e32 v98, 0x3fb8aa3b, v102
	v_fma_f32 v0, v0, s72, -v98
	v_fma_f32 v1, v1, s72, -v98
	v_fma_f32 v2, v2, s72, -v98
	v_fma_f32 v3, v3, s72, -v98
	v_exp_f32_e32 v0, v0
	v_exp_f32_e32 v1, v1
	v_exp_f32_e32 v2, v2
	v_exp_f32_e32 v3, v3
	v_fma_f32 v4, v4, s72, -v98
	v_fma_f32 v5, v5, s72, -v98
	v_fma_f32 v6, v6, s72, -v98
	v_fma_f32 v7, v7, s72, -v98
	v_exp_f32_e32 v4, v4
	v_exp_f32_e32 v5, v5
	v_exp_f32_e32 v6, v6
	v_exp_f32_e32 v7, v7
	v_fma_f32 v8, v8, s72, -v98
	v_fma_f32 v9, v9, s72, -v98
	v_cndmask_b32_e64 v0, 0, v0, s[16:17]
	v_cndmask_b32_e64 v1, 0, v1, s[12:13]
	v_exp_f32_e32 v8, v8
	v_exp_f32_e32 v9, v9
	v_fma_f32 v10, v10, s72, -v98
	v_fma_f32 v11, v11, s72, -v98
	v_add_f32_e64 v100, v0, 0
	v_add_f32_e64 v101, v1, 0
	v_cndmask_b32_e64 v2, v2, 0, s[14:15]
	v_cndmask_b32_e64 v3, v3, 0, s[8:9]
	v_exp_f32_e32 v10, v10
	v_exp_f32_e32 v11, v11
	v_fma_f32 v12, v12, s72, -v98
	v_fma_f32 v13, v13, s72, -v98
	v_add_f32_e64 v100, v2, v100
	v_add_f32_e64 v101, v3, v101
	v_cndmask_b32_e64 v4, v4, 0, s[10:11]
	v_cndmask_b32_e64 v5, v5, 0, s[4:5]
	v_exp_f32_e32 v12, v12
	v_exp_f32_e32 v13, v13
	v_fma_f32 v14, v14, s72, -v98
	v_fma_f32 v15, v15, s72, -v98
	v_add_f32_e64 v100, v4, v100
	v_add_f32_e64 v101, v5, v101
	v_cndmask_b32_e64 v6, v6, 0, s[6:7]
	v_cndmask_b32_e64 v7, v7, 0, s[0:1]
	v_exp_f32_e32 v14, v14
	v_exp_f32_e32 v15, v15
	v_fma_f32 v16, v16, s72, -v98
	v_fma_f32 v17, v17, s72, -v98
	v_add_f32_e64 v100, v6, v100
	v_add_f32_e64 v101, v7, v101
	v_cndmask_b32_e64 v8, v8, 0, s[2:3]
	v_cndmask_b32_e64 v9, v9, 0, vcc
	v_exp_f32_e32 v16, v16
	v_exp_f32_e32 v17, v17
	v_fma_f32 v18, v18, s72, -v98
	v_fma_f32 v19, v19, s72, -v98
	v_add_f32_e64 v100, v8, v100
	v_add_f32_e64 v101, v9, v101
	v_cndmask_b32_e64 v10, v10, 0, s[60:61]
	v_cndmask_b32_e64 v11, v11, 0, s[50:51]
	v_exp_f32_e32 v18, v18
	v_exp_f32_e32 v19, v19
	v_fma_f32 v20, v20, s72, -v98
	v_fma_f32 v21, v21, s72, -v98
	v_add_f32_e64 v100, v10, v100
	v_add_f32_e64 v101, v11, v101
	v_cndmask_b32_e64 v12, v12, 0, s[58:59]
	v_cndmask_b32_e64 v13, v13, 0, s[46:47]
	v_exp_f32_e32 v20, v20
	v_exp_f32_e32 v21, v21
	v_fma_f32 v22, v22, s72, -v98
	v_fma_f32 v23, v23, s72, -v98
	v_add_f32_e64 v100, v12, v100
	v_add_f32_e64 v101, v13, v101
	v_cndmask_b32_e64 v14, v14, 0, s[56:57]
	v_cndmask_b32_e64 v15, v15, 0, s[42:43]
	v_exp_f32_e32 v22, v22
	v_exp_f32_e32 v23, v23
	v_fma_f32 v24, v24, s72, -v98
	v_fma_f32 v25, v25, s72, -v98
	v_add_f32_e64 v100, v14, v100
	v_add_f32_e64 v101, v15, v101
	v_cndmask_b32_e64 v16, v16, 0, s[54:55]
	v_cndmask_b32_e64 v17, v17, 0, s[38:39]
	v_exp_f32_e32 v24, v24
	v_exp_f32_e32 v25, v25
	v_fma_f32 v26, v26, s72, -v98
	v_fma_f32 v27, v27, s72, -v98
	v_add_f32_e64 v100, v16, v100
	v_add_f32_e64 v101, v17, v101
	v_cndmask_b32_e64 v18, v18, 0, s[52:53]
	v_cndmask_b32_e64 v19, v19, 0, s[34:35]
	v_exp_f32_e32 v26, v26
	v_exp_f32_e32 v27, v27
	v_fma_f32 v28, v28, s72, -v98
; DI unsigned pack2(float a, float b) { bf2_t v = __builtin_convertvector((f32x2){a, b}, bf2_t); return __builtin_bit_cast(unsigned, v); }
; DI float shx32(float v) { return __shfl_xor(v, 32); }
; DI int otid() { int t = threadIdx.x; asm volatile("" : "+v"(t)); return t; }
; template <class T> DI T* launder(T* q) { asm volatile("" : "+s"(q)); return q; }
; template <bool MASKED>
; DI float online_softmax_t(f32x16 (&Sx)[2], unsigned vb, float& m, float& l) {
;     ...
;   for (int mt = 0; mt < 2; ++mt)
; #pragma unroll
;     for (int i = 0; i < 16; i += 2) {
;       const f32x2 t = (f32x2){Sx[mt][i], Sx[mt][i + 1]} * l2e2 - mb2;
;       f32x2 p = {__builtin_amdgcn_exp2f(t.x), __builtin_amdgcn_exp2f(t.y)};
;       if (MASKED) { p.x = ((vb >> (mt * 16 + i)) & 1u) ? p.x : 0.f; p.y = ((vb >> (mt * 16 + i + 1)) & 1u) ? p.y : 0.f; }
;       Sx[mt][i] = p.x; Sx[mt][i + 1] = p.y;
;       sum2 += p;
;     }
;   l = l * alpha + (sum2.x + sum2.y);
;   m = mn;
;   return alpha;
; DI void diff_pass(const bf16_t* Qrow, const bf16_t* Kg, const bf16_t* VTg, int qt, int q0, int t, f32x16 (&O)[4], float& lsum,
;                   bf16_t* sK, bf16_t* sV, int tid, int r, int h) {
;     ...
;   lsum = l + shx32(l);
; }
; DI void diff_item(const Params& p_, const EvenBufs& eb_, int e, int b, int hh, int qt, unsigned char* smem) {
;   Params p = p_; p.ws = launder(p.ws); p.subln = launder(p.subln);
;   const EvenBufs eb = even_bufs(p.ws + OFF_BIG);
;   const int tid = otid(), lane = tid & 63, wid = tid >> 6, r = lane & 31, h = lane >> 5;
;   bf16_t* sK = (bf16_t*)smem; bf16_t* sV = sK + 64 * 72;
;   const int q0 = qt * 128 + wid * 32, t = q0 + r;
;   const bf16_t* VTg = eb.DVT + (size_t)(b * 4 + hh) * 128 * SP;
;   f32x16 O[4]; float l1, l2;
;   diff_pass(eb.DQ + ((size_t)(b * 8 + hh * 2) * S + t) * 64, eb.DK + (size_t)(b * 8 + hh * 2) * S * 64, VTg, qt, q0, t, O, l1, sK, sV, tid, r, h);
;   unsigned* o1s = (unsigned*)(smem + 40960) + tid;
;   {
;     const float inv = 1.f / l1;
; #pragma unroll
;     for (int dt = 0; dt < 4; ++dt)
; #pragma unroll
;       for (int i = 0; i < 8; ++i) o1s[(dt * 8 + i) * 256] = pack2(O[dt][2 * i] * inv, O[dt][2 * i + 1] * inv);
;   }
	v_fma_f32 v29, v29, s72, -v98
	v_add_f32_e64 v100, v18, v100
	v_add_f32_e64 v101, v19, v101
	v_cndmask_b32_e64 v20, v20, 0, s[48:49]
	v_cndmask_b32_e64 v21, v21, 0, s[28:29]
	v_exp_f32_e32 v28, v28
	v_exp_f32_e32 v29, v29
	v_add_f32_e64 v100, v20, v100
	v_add_f32_e64 v101, v21, v101
	v_cndmask_b32_e64 v22, v22, 0, s[44:45]
	v_cndmask_b32_e64 v23, v23, 0, s[26:27]
	v_add_f32_e64 v100, v22, v100
	v_add_f32_e64 v101, v23, v101
	v_cndmask_b32_e64 v24, v24, 0, s[40:41]
	v_cndmask_b32_e64 v25, v25, 0, s[24:25]
	v_add_f32_e64 v100, v24, v100
	v_add_f32_e64 v101, v25, v101
	v_cndmask_b32_e64 v26, v26, 0, s[36:37]
	v_cndmask_b32_e64 v27, v27, 0, s[22:23]
	v_fma_f32 v30, v30, s72, -v98
	v_fma_f32 v31, v31, s72, -v98
	v_add_f32_e64 v100, v26, v100
	v_add_f32_e64 v101, v27, v101
	v_cndmask_b32_e64 v28, v28, 0, s[30:31]
	v_exp_f32_e32 v30, v30
	v_cndmask_b32_e64 v29, v29, 0, s[20:21]
	v_exp_f32_e32 v31, v31
	v_add_f32_e64 v98, v28, v100
	v_add_f32_e64 v99, v29, v101
	v_sub_f32_e32 v100, v205, v102
	v_mul_f32_e32 v100, 0x3fb8aa3b, v100
	v_exp_f32_e32 v202, v100
	v_cndmask_b32_e64 v30, v30, 0, s[62:63]
	v_cndmask_b32_e64 v31, v31, 0, s[18:19]
	v_add_f32_e64 v98, v30, v98
	v_add_f32_e64 v99, v31, v99
	s_mov_b32 s51, 0x100000
	v_add_f32_e32 v98, v98, v99
	v_fmac_f32_e32 v98, v179, v202
	s_mov_b32 s50, 0x80000
	s_mov_b32 s57, 0x400000
	s_mov_b32 s56, 0x200000
	s_mov_b32 s55, 0x20000
	s_mov_b32 s52, 0x40000
	v_mov_b32_e32 v205, v102
	v_mov_b32_e32 v179, v98
	s_branch .LBB0_756
.LBB0_765:
	v_and_b32_e32 v1, 64, v208
	v_xor_b32_e32 v0, 32, v208
	v_add_u32_e32 v1, 64, v1
	v_cmp_lt_i32_e32 vcc, v0, v1
	v_lshlrev_b32_e32 v202, 2, v171
	v_add_u32_e32 v201, 0xa000, v202
	v_cndmask_b32_e32 v0, v208, v0, vcc
	v_lshlrev_b32_e32 v200, 2, v0
	ds_bpermute_b32 v0, v200, v179
	s_or_b32 s80, s76, 0x1000
	s_mov_b32 s78, 0
	s_waitcnt lgkmcnt(0)
	v_add_f32_e32 v0, v179, v0
	v_div_scale_f32 v1, s[0:1], v0, v0, 1.0
	v_rcp_f32_e32 v2, v1
	v_div_scale_f32 v3, vcc, 1.0, v0, 1.0
	s_lshl_b32 s0, s80, 7
	v_fma_f32 v4, -v1, v2, 1.0
	v_fmac_f32_e32 v2, v4, v2
	v_mul_f32_e32 v4, v3, v2
	v_fma_f32 v5, -v1, v4, v3
	v_fmac_f32_e32 v4, v5, v2
	v_fma_f32 v1, -v1, v4, v3
	v_div_fmas_f32 v1, v1, v2, v4
	v_div_fixup_f32 v0, v1, v0, 1.0
	v_mul_f32_e64 v2, v82, v0
	v_mul_f32_e64 v3, v83, v0
	s_add_u32 s0, s89, s0
	v_cvt_pk_bf16_f32 v1, v2, v3
	v_mul_f32_e64 v2, v84, v0
	v_mul_f32_e64 v3, v85, v0
	s_addc_u32 s1, s90, 0
	v_cvt_pk_bf16_f32 v2, v2, v3
	ds_write2st64_b32 v202, v1, v2 offset0:160 offset1:164
	v_mul_f32_e64 v2, v86, v0
	v_mul_f32_e64 v3, v87, v0
	s_nop 0
	v_cvt_pk_bf16_f32 v1, v2, v3
	v_mul_f32_e64 v2, v88, v0
	v_mul_f32_e64 v3, v89, v0
	s_nop 0
	v_cvt_pk_bf16_f32 v2, v2, v3
	ds_write2st64_b32 v202, v1, v2 offset0:168 offset1:172
	v_mul_f32_e64 v2, v90, v0
	v_mul_f32_e64 v3, v91, v0
	s_nop 0
	v_cvt_pk_bf16_f32 v1, v2, v3
	v_mul_f32_e64 v2, v92, v0
	v_mul_f32_e64 v3, v93, v0
	s_nop 0
	v_cvt_pk_bf16_f32 v2, v2, v3
	ds_write2st64_b32 v202, v1, v2 offset0:176 offset1:180
	v_mul_f32_e64 v2, v94, v0
	v_mul_f32_e64 v3, v95, v0
	s_nop 0
	v_cvt_pk_bf16_f32 v1, v2, v3
	v_mul_f32_e64 v2, v96, v0
	v_mul_f32_e64 v3, v97, v0
	s_nop 0
	v_cvt_pk_bf16_f32 v2, v2, v3
	ds_write2st64_b32 v202, v1, v2 offset0:184 offset1:188
	v_mul_f32_e64 v2, v66, v0
	v_mul_f32_e64 v3, v67, v0
	s_nop 0
	v_cvt_pk_bf16_f32 v1, v2, v3
	v_mul_f32_e64 v2, v68, v0
	v_mul_f32_e64 v3, v69, v0
	s_nop 0
	v_cvt_pk_bf16_f32 v2, v2, v3
	ds_write2st64_b32 v202, v1, v2 offset0:192 offset1:196
	v_mul_f32_e64 v2, v70, v0
	v_mul_f32_e64 v3, v71, v0
	s_nop 0
	v_cvt_pk_bf16_f32 v1, v2, v3
	v_mul_f32_e64 v2, v72, v0
	v_mul_f32_e64 v3, v73, v0
	s_nop 0
	v_cvt_pk_bf16_f32 v2, v2, v3
	ds_write2st64_b32 v202, v1, v2 offset0:200 offset1:204
	v_mul_f32_e64 v2, v74, v0
	v_mul_f32_e64 v3, v75, v0
	s_nop 0
	v_cvt_pk_bf16_f32 v1, v2, v3
	v_mul_f32_e64 v2, v76, v0
	v_mul_f32_e64 v3, v77, v0
	s_nop 0
	v_cvt_pk_bf16_f32 v2, v2, v3
	ds_write2st64_b32 v202, v1, v2 offset0:208 offset1:212
	v_mul_f32_e64 v2, v78, v0
	v_mul_f32_e64 v3, v79, v0
	s_nop 0
	v_cvt_pk_bf16_f32 v1, v2, v3
	v_mul_f32_e64 v2, v80, v0
	v_mul_f32_e64 v3, v81, v0
	s_nop 0
	v_cvt_pk_bf16_f32 v2, v2, v3
	ds_write2st64_b32 v202, v1, v2 offset0:216 offset1:220
	v_mul_f32_e64 v2, v50, v0
	v_mul_f32_e64 v3, v51, v0
	s_nop 0
	v_cvt_pk_bf16_f32 v1, v2, v3
	v_mul_f32_e64 v2, v52, v0
	v_mul_f32_e64 v3, v53, v0
	s_nop 0
	v_cvt_pk_bf16_f32 v2, v2, v3
	ds_write2st64_b32 v202, v1, v2 offset0:224 offset1:228
	v_mul_f32_e64 v2, v54, v0
	v_mul_f32_e64 v3, v55, v0
	s_nop 0
	v_cvt_pk_bf16_f32 v1, v2, v3
	v_mul_f32_e64 v2, v56, v0
	v_mul_f32_e64 v3, v57, v0
	s_nop 0
	v_cvt_pk_bf16_f32 v2, v2, v3
	ds_write2st64_b32 v202, v1, v2 offset0:232 offset1:236
	v_mul_f32_e64 v2, v58, v0
	v_mul_f32_e64 v3, v59, v0
	s_nop 0
	v_cvt_pk_bf16_f32 v1, v2, v3
	v_mul_f32_e64 v2, v60, v0
	v_mul_f32_e64 v3, v61, v0
	s_nop 0
	v_cvt_pk_bf16_f32 v2, v2, v3
	ds_write2st64_b32 v202, v1, v2 offset0:240 offset1:244
	v_mul_f32_e64 v2, v62, v0
	v_mul_f32_e64 v3, v63, v0
	s_nop 0
	v_cvt_pk_bf16_f32 v1, v2, v3
	v_mul_f32_e64 v2, v64, v0
	v_mul_f32_e64 v3, v65, v0
	s_nop 0
	v_cvt_pk_bf16_f32 v2, v2, v3
	ds_write2st64_b32 v202, v1, v2 offset0:248 offset1:252
	v_mul_f32_e64 v2, v34, v0
	v_mul_f32_e64 v3, v35, v0
	s_nop 0
	v_cvt_pk_bf16_f32 v1, v2, v3
	v_mul_f32_e64 v2, v36, v0
	v_mul_f32_e64 v3, v37, v0
	s_nop 0
	v_cvt_pk_bf16_f32 v2, v2, v3
	ds_write2st64_b32 v201, v1, v2 offset0:96 offset1:100
	v_mul_f32_e64 v2, v38, v0
	v_mul_f32_e64 v3, v39, v0
	s_nop 0
	v_cvt_pk_bf16_f32 v1, v2, v3
	v_mul_f32_e64 v2, v40, v0
	v_mul_f32_e64 v3, v41, v0
	s_nop 0
	v_cvt_pk_bf16_f32 v2, v2, v3
	ds_write2st64_b32 v201, v1, v2 offset0:104 offset1:108
	v_mul_f32_e64 v2, v42, v0
	v_mul_f32_e64 v3, v43, v0
	s_nop 0
	v_cvt_pk_bf16_f32 v1, v2, v3
	v_mul_f32_e64 v2, v44, v0
	v_mul_f32_e64 v3, v45, v0
	s_nop 0
	v_cvt_pk_bf16_f32 v2, v2, v3
	ds_write2st64_b32 v201, v1, v2 offset0:112 offset1:116
	v_mul_f32_e64 v2, v46, v0
	v_mul_f32_e64 v3, v47, v0
	v_mul_f32_e64 v1, v49, v0
	v_mul_f32_e64 v0, v48, v0
	v_cvt_pk_bf16_f32 v2, v2, v3
	v_cvt_pk_bf16_f32 v0, v0, v1
	ds_write2st64_b32 v201, v2, v0 offset0:120 offset1:124
	v_lshl_add_u64 v[0:1], v[184:185], 0, s[80:81]
	v_lshlrev_b64 v[0:1], 7, v[0:1]
	v_lshl_add_u64 v[0:1], s[74:75], 0, v[0:1]
	v_lshlrev_b32_e32 v2, 1, v178
	v_mov_b32_e32 v3, v33
	v_lshl_add_u64 v[0:1], v[0:1], 0, v[2:3]
	s_waitcnt vmcnt(5)
; DI void load_q(bf16x8 (&qf)[4], const bf16_t* qrow, int h) {
; #pragma unroll
;   for (int s = 0; s < 4; ++s) qf[s] = *(const bf16x8*)(qrow + s * 16 + h * 8);
; }
; DI void diff_pass(const bf16_t* Qrow, const bf16_t* Kg, const bf16_t* VTg, int qt, int q0, int t, f32x16 (&O)[4], float& lsum,
;                   bf16_t* sK, bf16_t* sV, int tid, int r, int h) {
;   bf16x8 qf[4]; load_q(qf, Qrow, h);
;   const int kt_hi = 2 * qt + 1, my_hi = (q0 + 31) >> 6;
;   float m = NEG, l = 0.f;
;   zero_o<4>(O);
;   TR_<2> kr; TR_<4> vr;
;   tload(kr, Kg, 64, tid); tload(vr, VTg, SP, tid);
; DI void diff_item(const Params& p_, const EvenBufs& eb_, int e, int b, int hh, int qt, unsigned char* smem) {
;     ...
;   diff_pass(eb.DQ + ((size_t)(b * 8 + hh * 2 + 1) * S + t) * 64, eb.DK + (size_t)(b * 8 + hh * 2 + 1) * S * 64, VTg, qt, q0, t, O, l2, sK, sV, tid, r, h);
	flat_load_dwordx4 v[144:147], v[0:1]
	s_waitcnt vmcnt(0)
	flat_load_dwordx4 v[148:151], v[0:1] offset:32
	flat_load_dwordx4 v[152:155], v[0:1] offset:64
	flat_load_dwordx4 v[156:159], v[0:1] offset:96
	v_lshlrev_b32_e32 v0, 1, v170
	v_mov_b32_e32 v1, v33
	v_lshl_add_u64 v[0:1], s[0:1], 0, v[0:1]
	v_lshl_add_u64 v[2:3], v[174:175], 1, v[0:1]
	v_lshl_add_u64 v[0:1], v[172:173], 1, v[0:1]
	global_load_dwordx4 v[160:163], v[2:3], off
	global_load_dwordx4 v[164:167], v[0:1], off
	global_load_dwordx4 v[168:171], v[176:177], off
	global_load_dwordx4 v[172:175], v[180:181], off
	s_nop 0
	global_load_dwordx4 v[176:179], v[182:183], off
	s_nop 0
	global_load_dwordx4 v[180:183], v[198:199], off
	s_add_u32 s0, s70, s77
	s_addc_u32 s1, s71, 0
	s_add_u32 s0, s0, 0xb399000
	s_addc_u32 s1, s1, 0
	v_lshl_add_u64 v[0:1], s[0:1], 0, v[196:197]
	v_mov_b32_e32 v46, v33
	v_mov_b32_e32 v47, v33
	v_lshl_add_u64 v[196:197], v[0:1], 0, v[32:33]
	v_mov_b32_e32 v32, v33
	v_mov_b32_e32 v34, v33
	v_mov_b32_e32 v35, v33
	v_mov_b32_e32 v36, v33
	v_mov_b32_e32 v37, v33
	v_mov_b32_e32 v38, v33
	v_mov_b32_e32 v39, v33
	v_mov_b32_e32 v40, v33
	v_mov_b32_e32 v41, v33
	v_mov_b32_e32 v42, v33
	v_mov_b32_e32 v43, v33
	v_mov_b32_e32 v44, v33
	v_mov_b32_e32 v45, v33
	v_mov_b64_e32 v[62:63], v[46:47]
	v_mov_b64_e32 v[78:79], v[46:47]
	v_mov_b64_e32 v[94:95], v[46:47]
	v_mov_b64_e32 v[110:111], v[46:47]
	v_readlane_b32 s66, v255, 14
	v_mov_b32_e32 v198, 0xf149f2ca
	v_mov_b32_e32 v185, 0
	s_mov_b32 s80, 64
	v_mov_b64_e32 v[60:61], v[44:45]
	v_mov_b64_e32 v[58:59], v[42:43]
	v_mov_b64_e32 v[56:57], v[40:41]
	v_mov_b64_e32 v[54:55], v[38:39]
	v_mov_b64_e32 v[52:53], v[36:37]
	v_mov_b64_e32 v[50:51], v[34:35]
	v_mov_b64_e32 v[48:49], v[32:33]
	v_mov_b64_e32 v[76:77], v[44:45]
	v_mov_b64_e32 v[74:75], v[42:43]
	v_mov_b64_e32 v[72:73], v[40:41]
	v_mov_b64_e32 v[70:71], v[38:39]
	v_mov_b64_e32 v[68:69], v[36:37]
	v_mov_b64_e32 v[66:67], v[34:35]
	v_mov_b64_e32 v[64:65], v[32:33]
	v_mov_b64_e32 v[92:93], v[44:45]
	v_mov_b64_e32 v[90:91], v[42:43]
	v_mov_b64_e32 v[88:89], v[40:41]
	v_mov_b64_e32 v[86:87], v[38:39]
	v_mov_b64_e32 v[84:85], v[36:37]
	v_mov_b64_e32 v[82:83], v[34:35]
	v_mov_b64_e32 v[80:81], v[32:33]
	v_mov_b64_e32 v[108:109], v[44:45]
	v_mov_b64_e32 v[106:107], v[42:43]
	v_mov_b64_e32 v[104:105], v[40:41]
	v_mov_b64_e32 v[102:103], v[38:39]
	v_mov_b64_e32 v[100:101], v[36:37]
	v_mov_b64_e32 v[98:99], v[34:35]
	v_mov_b64_e32 v[96:97], v[32:33]
	s_mov_b32 s79, 0x800000
	s_movk_i32 s82, 0x800
	s_movk_i32 s83, 0x440
	s_movk_i32 s84, 0x6000
	s_movk_i32 s89, 0x400
	s_movk_i32 s90, 0x1000
	s_movk_i32 s91, 0x2000
	s_mov_b32 s92, 0xf149f2ca
	v_readlane_b32 s67, v255, 15
	s_branch .LBB0_768
; DI unsigned pack2(float a, float b) { bf2_t v = __builtin_convertvector((f32x2){a, b}, bf2_t); return __builtin_bit_cast(unsigned, v); }
; #define MFMA(a, b, c) __builtin_amdgcn_mfma_f32_32x32x16_bf16((a), (b), (c), 0, 0, 0)
; template <int NDT> DI void pv_tile(const bf16_t* sV, const f32x16 (&P)[2], f32x16 (&O)[NDT], int r, int h) {
; #pragma unroll
;   for (int mt = 0; mt < 2; ++mt)
; #pragma unroll
;     for (int sp = 0; sp < 2; ++sp) {
;       u32x4 pk;
;       pk.x = pack2(P[mt][8 * sp + 0], P[mt][8 * sp + 1]); pk.y = pack2(P[mt][8 * sp + 2], P[mt][8 * sp + 3]);
;       pk.z = pack2(P[mt][8 * sp + 4], P[mt][8 * sp + 5]); pk.w = pack2(P[mt][8 * sp + 6], P[mt][8 * sp + 7]);
;       const bf16x8 pb = __builtin_bit_cast(bf16x8, pk);
; #pragma unroll
;       for (int dt = 0; dt < NDT; ++dt) {
;         const bf16_t* vp = sV + (dt * 32 + r) * 68 + mt * 32 + sp * 16 + 4 * h;
;         const bf16x4 lo = *(const bf16x4*)vp, hi = *(const bf16x4*)(vp + 8);
;         const bf16x8 va = __builtin_shufflevector(lo, hi, 0, 1, 2, 3, 4, 5, 6, 7);
;         O[dt] = MFMA(va, pb, O[dt]);
;       }
;       if (NDT > 2) __builtin_amdgcn_sched_barrier(0);
;     }
; }
; template <int NDT> DI void scale_o(f32x16 (&O)[NDT], float a) {
; #pragma unroll
;   for (int dt = 0; dt < NDT; ++dt)
; #pragma unroll
;     for (int i = 0; i < 16; ++i) O[dt][i] *= a;
; }
.LBB0_766:
	s_or_b64 exec, exec, s[76:77]
	v_mul_f32_e64 v110, v110, v32
	v_mul_f32_e64 v111, v111, v32
	v_mul_f32_e64 v108, v108, v32
	v_mul_f32_e64 v109, v109, v32
	v_mul_f32_e64 v106, v106, v32
	v_mul_f32_e64 v107, v107, v32
	v_mul_f32_e64 v104, v104, v32
	v_mul_f32_e64 v105, v105, v32
	v_mul_f32_e64 v102, v102, v32
	v_mul_f32_e64 v103, v103, v32
	v_mul_f32_e64 v100, v100, v32
	v_mul_f32_e64 v101, v101, v32
	v_mul_f32_e64 v98, v98, v32
	v_mul_f32_e64 v99, v99, v32
	v_mul_f32_e64 v96, v96, v32
	v_mul_f32_e64 v97, v97, v32
	v_mul_f32_e64 v94, v94, v32
	v_mul_f32_e64 v95, v95, v32
	v_mul_f32_e64 v92, v92, v32
	v_mul_f32_e64 v93, v93, v32
	v_mul_f32_e64 v90, v90, v32
	v_mul_f32_e64 v91, v91, v32
	v_mul_f32_e64 v88, v88, v32
	v_mul_f32_e64 v89, v89, v32
	v_mul_f32_e64 v86, v86, v32
	v_mul_f32_e64 v87, v87, v32
	v_mul_f32_e64 v84, v84, v32
	v_mul_f32_e64 v85, v85, v32
	v_mul_f32_e64 v82, v82, v32
	v_mul_f32_e64 v83, v83, v32
	v_mul_f32_e64 v80, v80, v32
	v_mul_f32_e64 v81, v81, v32
	v_mul_f32_e64 v78, v78, v32
	v_mul_f32_e64 v79, v79, v32
	v_mul_f32_e64 v76, v76, v32
	v_mul_f32_e64 v77, v77, v32
	v_mul_f32_e64 v74, v74, v32
	v_mul_f32_e64 v75, v75, v32
	v_mul_f32_e64 v72, v72, v32
	v_mul_f32_e64 v73, v73, v32
	v_mul_f32_e64 v70, v70, v32
	v_mul_f32_e64 v71, v71, v32
	v_mul_f32_e64 v68, v68, v32
	v_mul_f32_e64 v69, v69, v32
	v_mul_f32_e64 v66, v66, v32
	v_mul_f32_e64 v67, v67, v32
	v_mul_f32_e64 v64, v64, v32
	v_mul_f32_e64 v65, v65, v32
	v_mul_f32_e64 v62, v62, v32
	v_mul_f32_e64 v63, v63, v32
	v_mul_f32_e64 v60, v60, v32
	v_mul_f32_e64 v61, v61, v32
	v_mul_f32_e64 v58, v58, v32
	v_mul_f32_e64 v59, v59, v32
	v_mul_f32_e64 v56, v56, v32
	v_mul_f32_e64 v57, v57, v32
	v_mul_f32_e64 v54, v54, v32
	v_mul_f32_e64 v55, v55, v32
	v_mul_f32_e64 v52, v52, v32
	v_mul_f32_e64 v53, v53, v32
	v_mul_f32_e64 v50, v50, v32
	v_mul_f32_e64 v51, v51, v32
	v_mul_f32_e64 v48, v48, v32
	v_mul_f32_e64 v49, v49, v32
	v_add_u32_e32 v32, v246, v247
	v_add_u32_e32 v34, 0x2000, v32
	v_add_u32_e32 v35, 0x3000, v32
	v_add_u32_e32 v36, 0x4000, v32
	v_add_u32_e32 v32, 0x5000, v32
	v_cvt_pk_bf16_f32 v0, v0, v1
	v_cvt_pk_bf16_f32 v1, v2, v3
	v_cvt_pk_bf16_f32 v2, v4, v5
	v_cvt_pk_bf16_f32 v3, v6, v7
	ds_read2_b64 v[4:7], v34 offset0:128 offset1:130
	v_cvt_pk_bf16_f32 v8, v8, v9
	v_cvt_pk_bf16_f32 v9, v10, v11
	v_cvt_pk_bf16_f32 v10, v12, v13
	v_cvt_pk_bf16_f32 v11, v14, v15
	ds_read2_b64 v[12:15], v35 offset0:160 offset1:162
	v_cvt_pk_bf16_f32 v16, v16, v17
	v_cvt_pk_bf16_f32 v17, v18, v19
	v_cvt_pk_bf16_f32 v18, v20, v21
	v_cvt_pk_bf16_f32 v19, v22, v23
	ds_read2_b64 v[20:23], v36 offset0:192 offset1:194
	v_cvt_pk_bf16_f32 v24, v24, v25
	v_cvt_pk_bf16_f32 v25, v26, v27
	v_cvt_pk_bf16_f32 v26, v28, v29
	v_cvt_pk_bf16_f32 v27, v30, v31
	ds_read2_b64 v[28:31], v32 offset0:224 offset1:226
	s_waitcnt lgkmcnt(3)
	v_mfma_f32_32x32x16_bf16 v[96:111], v[4:7], v[0:3], v[96:111]
	ds_read2_b64 v[4:7], v34 offset0:132 offset1:134
	s_waitcnt lgkmcnt(3)
	v_mfma_f32_32x32x16_bf16 v[80:95], v[12:15], v[0:3], v[80:95]
	ds_read2_b64 v[12:15], v35 offset0:164 offset1:166
	s_waitcnt lgkmcnt(3)
	v_mfma_f32_32x32x16_bf16 v[64:79], v[20:23], v[0:3], v[64:79]
	ds_read2_b64 v[20:23], v36 offset0:196 offset1:198
	s_waitcnt lgkmcnt(3)
	v_mfma_f32_32x32x16_bf16 v[48:63], v[28:31], v[0:3], v[48:63]
	ds_read2_b64 v[28:31], v32 offset0:228 offset1:230
	s_waitcnt lgkmcnt(3)
	v_mfma_f32_32x32x16_bf16 v[96:111], v[4:7], v[8:11], v[96:111]
	ds_read2_b64 v[4:7], v34 offset0:136 offset1:138
	s_waitcnt lgkmcnt(3)
	v_mfma_f32_32x32x16_bf16 v[80:95], v[12:15], v[8:11], v[80:95]
	ds_read2_b64 v[12:15], v35 offset0:168 offset1:170
	s_waitcnt lgkmcnt(3)
	v_mfma_f32_32x32x16_bf16 v[64:79], v[20:23], v[8:11], v[64:79]
	ds_read2_b64 v[20:23], v36 offset0:200 offset1:202
	s_waitcnt lgkmcnt(3)
	v_mfma_f32_32x32x16_bf16 v[48:63], v[28:31], v[8:11], v[48:63]
	ds_read2_b64 v[28:31], v32 offset0:232 offset1:234
	s_waitcnt lgkmcnt(3)
	v_mfma_f32_32x32x16_bf16 v[96:111], v[4:7], v[16:19], v[96:111]
	ds_read2_b64 v[4:7], v34 offset0:140 offset1:142
	s_waitcnt lgkmcnt(3)
	v_mfma_f32_32x32x16_bf16 v[80:95], v[12:15], v[16:19], v[80:95]
	ds_read2_b64 v[12:15], v35 offset0:172 offset1:174
	s_waitcnt lgkmcnt(3)
	v_mfma_f32_32x32x16_bf16 v[64:79], v[20:23], v[16:19], v[64:79]
	ds_read2_b64 v[20:23], v36 offset0:204 offset1:206
	s_waitcnt lgkmcnt(3)
	v_mfma_f32_32x32x16_bf16 v[48:63], v[28:31], v[16:19], v[48:63]
	ds_read2_b64 v[28:31], v32 offset0:236 offset1:238
	s_waitcnt lgkmcnt(3)
	v_mfma_f32_32x32x16_bf16 v[96:111], v[4:7], v[24:27], v[96:111]
	s_waitcnt lgkmcnt(2)
	v_mfma_f32_32x32x16_bf16 v[80:95], v[12:15], v[24:27], v[80:95]
	s_waitcnt lgkmcnt(1)
	v_mfma_f32_32x32x16_bf16 v[64:79], v[20:23], v[24:27], v[64:79]
	s_waitcnt lgkmcnt(0)
	v_mfma_f32_32x32x16_bf16 v[48:63], v[28:31], v[24:27], v[48:63]

; #define MFMA(a, b, c) __builtin_amdgcn_mfma_f32_32x32x16_bf16((a), (b), (c), 0, 0, 0)
; DI float shx32(float v) { return __shfl_xor(v, 32); }
; DI void qk_tile(const bf16_t* sK, const bf16x8 (&qf)[4], f32x16 (&Sx)[2], int r, int h) {
; #pragma unroll
;   for (int mt = 0; mt < 2; ++mt) {
;     f32x16 a;
; #pragma unroll
;     for (int i = 0; i < 16; ++i) a[i] = 0.f;
; #pragma unroll
;     for (int s = 0; s < 4; ++s) {
;       const bf16x8 k = *(const bf16x8*)(sK + (mt * 32 + r) * 72 + s * 16 + h * 8);
;       a = MFMA(k, qf[s], a);
;     }
;     Sx[mt] = a;
;   }
; template <bool MASKED>
; DI float online_softmax_t(f32x16 (&Sx)[2], unsigned vb, float& m, float& l) {
;   float mx = NEG;
; #pragma unroll
;   for (int mt = 0; mt < 2; ++mt)
; #pragma unroll
;     for (int i = 0; i < 16; ++i) {
;       float s = Sx[mt][i];
;       if (MASKED) { s = ((vb >> (mt * 16 + i)) & 1u) ? s : NEG; Sx[mt][i] = s; }
;       mx = fmaxf(mx, s);
;     }
;   mx = fmaxf(mx, shx32(mx));
;   const float mn = fmaxf(m, mx);
;   const float alpha = __builtin_amdgcn_exp2f((m - mn) * L2E);
;   const float mb = mn * L2E;
;   f32x2 sum2 = {0.f, 0.f};
;   const f32x2 l2e2 = {L2E, L2E}, mb2 = {mb, mb};
; #pragma unroll
;   for (int mt = 0; mt < 2; ++mt)
; #pragma unroll
;     for (int i = 0; i < 16; i += 2) {
;       const f32x2 t = (f32x2){Sx[mt][i], Sx[mt][i + 1]} * l2e2 - mb2;
;       f32x2 p = {__builtin_amdgcn_exp2f(t.x), __builtin_amdgcn_exp2f(t.y)};
;       if (MASKED) { p.x = ((vb >> (mt * 16 + i)) & 1u) ? p.x : 0.f; p.y = ((vb >> (mt * 16 + i + 1)) & 1u) ? p.y : 0.f; }
;       Sx[mt][i] = p.x; Sx[mt][i + 1] = p.y;
;       sum2 += p;
;     }
;   l = l * alpha + (sum2.x + sum2.y);
.LBB0_770:
	v_cmp_le_i32_e32 vcc, s78, v245
	s_and_saveexec_b64 s[74:75], vcc
	s_cbranch_execz .LBB0_767
	ds_read_b128 v[0:3], v249
	ds_read_b128 v[4:7], v249 offset:32
	ds_read_b128 v[8:11], v249 offset:64
	ds_read_b128 v[12:15], v249 offset:96
	ds_read_b128 v[16:19], v249 offset:4608
	ds_read_b128 v[20:23], v249 offset:4640
	ds_read_b128 v[24:27], v249 offset:4672
	ds_read_b128 v[28:31], v249 offset:4704
	s_add_i32 s0, s80, -1
	v_cmp_le_i32_e32 vcc, s0, v244
	s_waitcnt lgkmcnt(7)
	v_mfma_f32_32x32x16_bf16 v[128:143], v[0:3], v[144:147], 0
	s_waitcnt lgkmcnt(6)
	v_mfma_f32_32x32x16_bf16 v[128:143], v[4:7], v[148:151], v[128:143]
	s_waitcnt lgkmcnt(5)
	v_mfma_f32_32x32x16_bf16 v[128:143], v[8:11], v[152:155], v[128:143]
	s_waitcnt lgkmcnt(4)
	v_mfma_f32_32x32x16_bf16 v[128:143], v[12:15], v[156:159], v[128:143]
	s_waitcnt lgkmcnt(3)
	v_mfma_f32_32x32x16_bf16 v[112:127], v[16:19], v[144:147], 0
	s_waitcnt lgkmcnt(2)
	v_mfma_f32_32x32x16_bf16 v[112:127], v[20:23], v[148:151], v[112:127]
	s_waitcnt lgkmcnt(1)
	v_mfma_f32_32x32x16_bf16 v[112:127], v[24:27], v[152:155], v[112:127]
	s_waitcnt lgkmcnt(0)
	v_mfma_f32_32x32x16_bf16 v[112:127], v[28:31], v[156:159], v[112:127]
	s_and_saveexec_b64 s[0:1], vcc
	s_xor_b64 s[0:1], exec, s[0:1]
	s_cbranch_execz .LBB0_773
	v_max3_f32 v0, v128, s92, v129
	v_max3_f32 v0, v0, v130, v131
	v_max3_f32 v0, v0, v132, v133
	v_max3_f32 v0, v0, v134, v135
	v_max3_f32 v0, v0, v136, v137
	v_max3_f32 v0, v0, v138, v139
	v_max3_f32 v0, v0, v140, v141
	v_max3_f32 v0, v0, v142, v143
	s_nop 0
	v_max3_f32 v0, v0, v112, v113
	v_max3_f32 v0, v0, v114, v115
	v_max3_f32 v0, v0, v116, v117
	v_max3_f32 v0, v0, v118, v119
	v_max3_f32 v0, v0, v120, v121
	v_max3_f32 v0, v0, v122, v123
	v_max3_f32 v0, v0, v124, v125
	v_max3_f32 v0, v0, v126, v127
	ds_bpermute_b32 v1, v200, v0
	s_mov_b32 s2, 0x3fb8aa3b
	s_waitcnt lgkmcnt(0)
	v_max3_f32 v36, v198, v0, v1
	v_mul_f32_e32 v30, 0x3fb8aa3b, v36
	v_fma_f32 v0, v128, s2, -v30
	v_fma_f32 v1, v129, s2, -v30
	v_fma_f32 v2, v130, s2, -v30
	v_fma_f32 v3, v131, s2, -v30
	v_exp_f32_e32 v0, v0
	v_exp_f32_e32 v1, v1
	v_exp_f32_e32 v2, v2
	v_exp_f32_e32 v3, v3
	v_sub_f32_e32 v32, v198, v36
	v_add_f32_e64 v4, v0, 0
	v_add_f32_e64 v5, v1, 0
	v_mul_f32_e32 v32, 0x3fb8aa3b, v32
	v_add_f32_e64 v6, v2, v4
	v_add_f32_e64 v7, v3, v5
	v_fma_f32 v4, v132, s2, -v30
	v_fma_f32 v5, v133, s2, -v30
	v_exp_f32_e32 v32, v32
	v_exp_f32_e32 v4, v4
	v_exp_f32_e32 v5, v5
	s_nop 0
	v_add_f32_e64 v8, v4, v6
	v_add_f32_e64 v9, v5, v7
	v_fma_f32 v6, v134, s2, -v30
	v_fma_f32 v7, v135, s2, -v30
	s_nop 0
	v_exp_f32_e32 v6, v6
	v_exp_f32_e32 v7, v7
	s_nop 0
	v_add_f32_e64 v10, v6, v8
	v_add_f32_e64 v11, v7, v9
	v_fma_f32 v8, v136, s2, -v30
	v_fma_f32 v9, v137, s2, -v30
	s_nop 0
	v_exp_f32_e32 v8, v8
	v_exp_f32_e32 v9, v9
	s_nop 0
	v_add_f32_e64 v12, v8, v10
	v_add_f32_e64 v13, v9, v11
	v_fma_f32 v10, v138, s2, -v30
	v_fma_f32 v11, v139, s2, -v30
	s_nop 0
	v_exp_f32_e32 v10, v10
	v_exp_f32_e32 v11, v11
	s_nop 0
	v_add_f32_e64 v14, v10, v12
	v_add_f32_e64 v15, v11, v13
	v_fma_f32 v12, v140, s2, -v30
	v_fma_f32 v13, v141, s2, -v30
	s_nop 0
	v_exp_f32_e32 v12, v12
	v_exp_f32_e32 v13, v13
	s_nop 0
	v_add_f32_e64 v16, v12, v14
	v_add_f32_e64 v17, v13, v15
	v_fma_f32 v14, v142, s2, -v30
	v_fma_f32 v15, v143, s2, -v30
	s_nop 0
	v_exp_f32_e32 v14, v14
	v_exp_f32_e32 v15, v15
	s_nop 0
	v_add_f32_e64 v18, v14, v16
	v_add_f32_e64 v19, v15, v17
	v_fma_f32 v16, v112, s2, -v30
	v_fma_f32 v17, v113, s2, -v30
	s_nop 0
	v_exp_f32_e32 v16, v16
	v_exp_f32_e32 v17, v17
	s_nop 0
	v_add_f32_e64 v20, v16, v18
	v_add_f32_e64 v21, v17, v19
	v_fma_f32 v18, v114, s2, -v30
	v_fma_f32 v19, v115, s2, -v30
	s_nop 0
	v_exp_f32_e32 v18, v18
	v_exp_f32_e32 v19, v19
	s_nop 0
	v_add_f32_e64 v22, v18, v20
	v_add_f32_e64 v23, v19, v21
	v_fma_f32 v20, v116, s2, -v30
	v_fma_f32 v21, v117, s2, -v30
	s_nop 0
	v_exp_f32_e32 v20, v20
	v_exp_f32_e32 v21, v21
	s_nop 0
	v_add_f32_e64 v24, v20, v22
	v_add_f32_e64 v25, v21, v23
	v_fma_f32 v22, v118, s2, -v30
	v_fma_f32 v23, v119, s2, -v30
	s_nop 0
	v_exp_f32_e32 v22, v22
	v_exp_f32_e32 v23, v23
	s_nop 0
	v_add_f32_e64 v26, v22, v24
	v_add_f32_e64 v27, v23, v25
	v_fma_f32 v24, v120, s2, -v30
	v_fma_f32 v25, v121, s2, -v30
	s_nop 0
	v_exp_f32_e32 v24, v24
	v_exp_f32_e32 v25, v25
	s_nop 0
	v_add_f32_e64 v28, v24, v26
	v_add_f32_e64 v29, v25, v27
	v_fma_f32 v26, v122, s2, -v30
	v_fma_f32 v27, v123, s2, -v30
	s_nop 0
	v_exp_f32_e32 v26, v26
	v_exp_f32_e32 v27, v27
	s_nop 0
	v_add_f32_e64 v34, v26, v28
	v_add_f32_e64 v35, v27, v29
	v_fma_f32 v28, v124, s2, -v30
	v_fma_f32 v29, v125, s2, -v30
	v_fma_f32 v31, v127, s2, -v30
	v_fma_f32 v30, v126, s2, -v30
	v_exp_f32_e32 v28, v28
	v_exp_f32_e32 v29, v29
	v_exp_f32_e32 v30, v30
	v_exp_f32_e32 v31, v31
	v_add_f32_e64 v34, v28, v34
	v_add_f32_e64 v35, v29, v35
	s_nop 0
	v_add_f32_e64 v34, v30, v34
	v_add_f32_e64 v35, v31, v35
	s_nop 0
	v_add_f32_e32 v34, v34, v35
	v_fmac_f32_e32 v34, v185, v32
	v_mov_b32_e32 v185, v34
	v_mov_b32_e32 v198, v36
; DI int crow(int i, int h) { return (i & 3) + 8 * (i >> 2) + 4 * h; }
; DI float shx32(float v) { return __shfl_xor(v, 32); }
; template <bool MASKED>
; DI float online_softmax_t(f32x16 (&Sx)[2], unsigned vb, float& m, float& l) {
;   float mx = NEG;
; #pragma unroll
;   for (int mt = 0; mt < 2; ++mt)
; #pragma unroll
;     for (int i = 0; i < 16; ++i) {
;       float s = Sx[mt][i];
;       if (MASKED) { s = ((vb >> (mt * 16 + i)) & 1u) ? s : NEG; Sx[mt][i] = s; }
;       mx = fmaxf(mx, s);
;     }
;   mx = fmaxf(mx, shx32(mx));
; DI void diff_pass(const bf16_t* Qrow, const bf16_t* Kg, const bf16_t* VTg, int qt, int q0, int t, f32x16 (&O)[4], float& lsum,
;                   bf16_t* sK, bf16_t* sV, int tid, int r, int h) {
;     ...
;       const bool masked = (kt * 64 + 63 > q0);
;       unsigned vb = 0;
;       if (masked) {
; #pragma unroll
;         for (int mt = 0; mt < 2; ++mt)
; #pragma unroll
;           for (int i = 0; i < 16; ++i) vb |= (unsigned)(kt * 64 + mt * 32 + crow(i, h) <= t) << (mt * 16 + i);
;       }
.LBB0_773:
	s_andn2_saveexec_b64 s[76:77], s[0:1]
	s_cbranch_execz .LBB0_766
	v_add_u32_e32 v0, s80, v243
	v_subrev_u32_e32 v1, 64, v0
	v_cmp_le_i32_e64 s[16:17], v1, v184
	v_cmp_lt_i32_e64 s[12:13], v1, v184
	v_subrev_u32_e32 v8, 48, v0
	v_subrev_u32_e32 v9, 47, v0
	v_cndmask_b32_e64 v2, 0, 1, s[16:17]
	v_cndmask_b32_e64 v1, 0, 2, s[12:13]
	v_subrev_u32_e32 v4, 56, v0
	v_subrev_u32_e32 v5, 55, v0
	v_cmp_gt_i32_e64 s[2:3], v8, v184
	v_cmp_gt_i32_e32 vcc, v9, v184
	v_or_b32_e32 v1, v1, v2
	v_subrev_u32_e32 v2, 62, v0
	v_subrev_u32_e32 v3, 61, v0
	v_cmp_gt_i32_e64 s[10:11], v4, v184
	v_cmp_gt_i32_e64 s[4:5], v5, v184
	v_cndmask_b32_e64 v8, v216, 0, s[2:3]
	v_cndmask_b32_e64 v9, v217, 0, vcc
	v_cmp_gt_i32_e64 s[14:15], v2, v184
	v_cmp_gt_i32_e64 s[8:9], v3, v184
	v_cndmask_b32_e64 v4, 16, 0, s[10:11]
	v_cndmask_b32_e64 v5, 32, 0, s[4:5]
	v_subrev_u32_e32 v6, 54, v0
	v_subrev_u32_e32 v7, 53, v0
	v_or3_b32 v1, v1, v8, v9
	v_cndmask_b32_e64 v2, 4, 0, s[14:15]
	v_cndmask_b32_e64 v3, 8, 0, s[8:9]
	v_cmp_gt_i32_e64 s[6:7], v6, v184
	v_cmp_gt_i32_e64 s[0:1], v7, v184
	v_or3_b32 v1, v5, v4, v1
	v_cndmask_b32_e64 v6, 64, 0, s[6:7]
	v_cndmask_b32_e64 v7, v215, 0, s[0:1]
	v_or3_b32 v1, v3, v2, v1
	v_or3_b32 v11, v6, v7, v1
	v_subrev_u32_e32 v1, 46, v0
	v_cmp_gt_i32_e64 s[18:19], v1, v184
	v_subrev_u32_e32 v2, 45, v0
	v_cndmask_b32_e64 v3, v131, v214, s[8:9]
	v_cndmask_b32_e64 v1, v218, 0, s[18:19]
	v_cmp_gt_i32_e64 s[18:19], v2, v184
	v_cndmask_b32_e64 v5, v133, v214, s[4:5]
	v_cndmask_b32_e64 v7, v135, v214, s[0:1]
	v_cndmask_b32_e64 v2, v219, 0, s[18:19]
	v_or_b32_e32 v12, v1, v2
	v_subrev_u32_e32 v1, 40, v0
	v_cmp_gt_i32_e64 s[18:19], v1, v184
	v_subrev_u32_e32 v2, 39, v0
	v_cndmask_b32_e32 v9, v137, v214, vcc
	v_cndmask_b32_e64 v1, v220, 0, s[18:19]
	v_cmp_gt_i32_e64 s[18:19], v2, v184
	v_or_b32_e32 v13, v12, v11
	s_mov_b32 s20, 0x400000
	v_cndmask_b32_e64 v2, v221, 0, s[18:19]
	v_or_b32_e32 v14, v1, v2
	v_subrev_u32_e32 v1, 38, v0
	v_cmp_gt_i32_e64 s[18:19], v1, v184
	v_subrev_u32_e32 v2, 37, v0
	v_or_b32_e32 v15, v14, v13
	v_cndmask_b32_e64 v1, v222, 0, s[18:19]
	v_cmp_gt_i32_e64 s[18:19], v2, v184
	s_mov_b32 s21, 0x1000000
	s_brev_b32 s22, 64
	v_cndmask_b32_e64 v2, v223, 0, s[18:19]
	v_or_b32_e32 v16, v1, v2
	v_subrev_u32_e32 v1, 32, v0
	v_cmp_gt_i32_e64 s[18:19], v1, v184
	v_subrev_u32_e32 v2, 31, v0
	v_or_b32_e32 v17, v16, v15
	v_cndmask_b32_e64 v1, v224, 0, s[18:19]
	v_cmp_gt_i32_e64 s[18:19], v2, v184
	s_brev_b32 s23, 32
	s_brev_b32 s28, 16
	v_cndmask_b32_e64 v2, v225, 0, s[18:19]
	v_or_b32_e32 v18, v1, v2
	v_subrev_u32_e32 v1, 30, v0
	v_cmp_gt_i32_e64 s[18:19], v1, v184
	v_subrev_u32_e32 v2, 29, v0
	v_or_b32_e32 v19, v18, v17
	v_cndmask_b32_e64 v1, v226, 0, s[18:19]
	v_cmp_gt_i32_e64 s[18:19], v2, v184
	s_brev_b32 s29, 8
	s_brev_b32 s64, 4
	v_cndmask_b32_e64 v2, v227, 0, s[18:19]
	v_or_b32_e32 v20, v1, v2
	v_subrev_u32_e32 v1, 24, v0
	v_cmp_gt_i32_e64 s[18:19], v1, v184
	v_subrev_u32_e32 v2, 23, v0
	v_or_b32_e32 v21, v20, v19
	v_cndmask_b32_e64 v1, v228, 0, s[18:19]
	v_cmp_gt_i32_e64 s[18:19], v2, v184
	s_nop 1
	v_cndmask_b32_e64 v2, v229, 0, s[18:19]
	v_or_b32_e32 v22, v1, v2
	v_subrev_u32_e32 v1, 22, v0
	v_cmp_gt_i32_e64 s[18:19], v1, v184
	v_subrev_u32_e32 v2, 21, v0
	v_or_b32_e32 v23, v22, v21
	v_cndmask_b32_e64 v1, v230, 0, s[18:19]
	v_cmp_gt_i32_e64 s[18:19], v2, v184
	s_nop 1
	v_cndmask_b32_e64 v2, v231, 0, s[18:19]
	v_or_b32_e32 v24, v1, v2
	v_add_u32_e32 v1, -16, v0
	v_cmp_gt_i32_e64 s[18:19], v1, v184
	v_add_u32_e32 v2, -15, v0
	v_or_b32_e32 v25, v24, v23
	v_cndmask_b32_e64 v1, v232, 0, s[18:19]
	v_cmp_gt_i32_e64 s[18:19], v2, v184
	s_nop 1
	v_cndmask_b32_e64 v2, v233, 0, s[18:19]
	v_or_b32_e32 v26, v1, v2
	v_add_u32_e32 v1, -14, v0
	v_cmp_gt_i32_e64 s[18:19], v1, v184
	v_add_u32_e32 v2, -13, v0
	v_or_b32_e32 v27, v26, v25
	v_cndmask_b32_e64 v1, v234, 0, s[18:19]
	v_cmp_gt_i32_e64 s[18:19], v2, v184
	s_nop 1
	v_cndmask_b32_e64 v2, v235, 0, s[18:19]
	v_or_b32_e32 v28, v1, v2
	v_add_u32_e32 v1, -8, v0
	v_cmp_gt_i32_e64 s[18:19], v1, v184
	v_add_u32_e32 v2, -7, v0
	v_or_b32_e32 v29, v28, v27
	v_cndmask_b32_e64 v1, v236, 0, s[18:19]
	v_cmp_gt_i32_e64 s[18:19], v2, v184
	s_nop 1
	v_cndmask_b32_e64 v2, v237, 0, s[18:19]
	v_or_b32_e32 v30, v1, v2
	v_add_u32_e32 v1, -6, v0
	v_cmp_gt_i32_e64 s[18:19], v1, v184
	v_add_u32_e32 v0, -5, v0
	v_cndmask_b32_e64 v2, v130, v214, s[14:15]
	v_cndmask_b32_e64 v1, 2.0, 0, s[18:19]
	v_cmp_gt_i32_e64 s[18:19], v0, v184
	v_or_b32_e32 v31, v30, v29
	s_nop 0
	v_cndmask_b32_e64 v0, v238, 0, s[18:19]
	v_or_b32_e32 v32, v1, v0
	v_cndmask_b32_e64 v0, v214, v128, s[16:17]
	v_cndmask_b32_e64 v1, v214, v129, s[12:13]
	v_max3_f32 v4, v0, s92, v1
	v_max3_f32 v6, v4, v2, v3
	v_cndmask_b32_e64 v4, v132, v214, s[10:11]
	v_max3_f32 v8, v6, v4, v5
	v_cndmask_b32_e64 v6, v134, v214, s[6:7]
	v_max3_f32 v10, v8, v6, v7
	v_cndmask_b32_e64 v8, v136, v214, s[2:3]
	v_max3_f32 v35, v10, v8, v9
	v_bitop3_b32 v10, v12, s89, v11 bitop3:0xc8
	v_bitop3_b32 v11, v12, s82, v11 bitop3:0xc8
	v_cmp_eq_u32_e64 s[62:63], 0, v10
	v_cmp_eq_u32_e64 s[52:53], 0, v11
	v_bitop3_b32 v12, v14, s90, v13 bitop3:0xc8
	v_bitop3_b32 v13, v14, s91, v13 bitop3:0xc8
	v_cndmask_b32_e64 v10, v138, v214, s[62:63]
	v_cndmask_b32_e64 v11, v139, v214, s[52:53]
	v_cmp_eq_u32_e64 s[60:61], 0, v12
	v_cmp_eq_u32_e64 s[48:49], 0, v13
	v_bitop3_b32 v14, v16, s94, v15 bitop3:0xc8
	v_bitop3_b32 v15, v16, s68, v15 bitop3:0xc8
	s_mov_b32 s18, 0x40000
	v_max3_f32 v35, v35, v10, v11
	v_cndmask_b32_e64 v12, v140, v214, s[60:61]
	v_cndmask_b32_e64 v13, v141, v214, s[48:49]
	v_cmp_eq_u32_e64 s[58:59], 0, v14
	v_cmp_eq_u32_e64 s[44:45], 0, v15
	v_bitop3_b32 v16, v18, s69, v17 bitop3:0xc8
; DI float shx32(float v) { return __shfl_xor(v, 32); }
; template <bool MASKED>
; DI float online_softmax_t(f32x16 (&Sx)[2], unsigned vb, float& m, float& l) {
;   float mx = NEG;
; #pragma unroll
;   for (int mt = 0; mt < 2; ++mt)
; #pragma unroll
;     for (int i = 0; i < 16; ++i) {
;       float s = Sx[mt][i];
;       if (MASKED) { s = ((vb >> (mt * 16 + i)) & 1u) ? s : NEG; Sx[mt][i] = s; }
;       mx = fmaxf(mx, s);
;     }
;   mx = fmaxf(mx, shx32(mx));
;   const float mn = fmaxf(m, mx);
;   const float alpha = __builtin_amdgcn_exp2f((m - mn) * L2E);
;   const float mb = mn * L2E;
;   f32x2 sum2 = {0.f, 0.f};
;   const f32x2 l2e2 = {L2E, L2E}, mb2 = {mb, mb};
; #pragma unroll
;   for (int mt = 0; mt < 2; ++mt)
; #pragma unroll
;     for (int i = 0; i < 16; i += 2) {
;       const f32x2 t = (f32x2){Sx[mt][i], Sx[mt][i + 1]} * l2e2 - mb2;
;       f32x2 p = {__builtin_amdgcn_exp2f(t.x), __builtin_amdgcn_exp2f(t.y)};
;       if (MASKED) { p.x = ((vb >> (mt * 16 + i)) & 1u) ? p.x : 0.f; p.y = ((vb >> (mt * 16 + i + 1)) & 1u) ? p.y : 0.f; }
;       Sx[mt][i] = p.x; Sx[mt][i + 1] = p.y;
;       sum2 += p;
;     }
;   l = l * alpha + (sum2.x + sum2.y);
;   m = mn;
	v_bitop3_b32 v17, v18, s55, v17 bitop3:0xc8
	v_max3_f32 v35, v35, v12, v13
	v_cndmask_b32_e64 v14, v142, v214, s[58:59]
	v_cndmask_b32_e64 v15, v143, v214, s[44:45]
	s_mov_b32 s19, 0x200000
	v_cmp_eq_u32_e64 s[56:57], 0, v16
	v_cmp_eq_u32_e64 s[40:41], 0, v17
	v_bitop3_b32 v18, v20, s18, v19 bitop3:0xc8
	v_bitop3_b32 v19, v20, s50, v19 bitop3:0xc8
	v_max3_f32 v35, v35, v14, v15
	v_cndmask_b32_e64 v16, v112, v214, s[56:57]
	v_cndmask_b32_e64 v17, v113, v214, s[40:41]
	v_cmp_eq_u32_e64 s[54:55], 0, v18
	v_cmp_eq_u32_e64 s[36:37], 0, v19
	v_bitop3_b32 v20, v22, s51, v21 bitop3:0xc8
	v_bitop3_b32 v21, v22, s19, v21 bitop3:0xc8
	v_max3_f32 v35, v35, v16, v17
	v_cndmask_b32_e64 v18, v114, v214, s[54:55]
	v_cndmask_b32_e64 v19, v115, v214, s[36:37]
	v_cmp_eq_u32_e64 s[50:51], 0, v20
	v_cmp_eq_u32_e64 s[30:31], 0, v21
	v_bitop3_b32 v22, v24, s20, v23 bitop3:0xc8
	v_bitop3_b32 v23, v24, s79, v23 bitop3:0xc8
	v_max3_f32 v35, v35, v18, v19
	v_cndmask_b32_e64 v20, v116, v214, s[50:51]
	v_cndmask_b32_e64 v21, v117, v214, s[30:31]
	v_cmp_eq_u32_e64 s[46:47], 0, v22
	v_cmp_eq_u32_e64 s[26:27], 0, v23
	v_bitop3_b32 v24, v26, s21, v25 bitop3:0xc8
	v_bitop3_b32 v25, v26, s22, v25 bitop3:0xc8
	v_max3_f32 v35, v35, v20, v21
	v_cndmask_b32_e64 v22, v118, v214, s[46:47]
	v_cndmask_b32_e64 v23, v119, v214, s[26:27]
	v_cmp_eq_u32_e64 s[42:43], 0, v24
	v_cmp_eq_u32_e64 s[24:25], 0, v25
	v_bitop3_b32 v26, v28, s23, v27 bitop3:0xc8
	v_bitop3_b32 v27, v28, s28, v27 bitop3:0xc8
	v_max3_f32 v35, v35, v22, v23
	v_cndmask_b32_e64 v24, v120, v214, s[42:43]
	v_cndmask_b32_e64 v25, v121, v214, s[24:25]
	v_cmp_eq_u32_e64 s[38:39], 0, v26
	v_cmp_eq_u32_e64 s[22:23], 0, v27
	v_bitop3_b32 v28, v30, s29, v29 bitop3:0xc8
	v_bitop3_b32 v29, v30, s64, v29 bitop3:0xc8
	v_or_b32_e32 v34, v32, v31
	v_max3_f32 v35, v35, v24, v25
	v_cndmask_b32_e64 v26, v122, v214, s[38:39]
	v_cndmask_b32_e64 v27, v123, v214, s[22:23]
	v_cmp_eq_u32_e64 s[34:35], 0, v28
	v_cmp_eq_u32_e64 s[20:21], 0, v29
	v_bitop3_b32 v30, v32, 2.0, v31 bitop3:0xc8
	v_max3_f32 v35, v35, v26, v27
	v_cndmask_b32_e64 v28, v124, v214, s[34:35]
	v_cndmask_b32_e64 v29, v125, v214, s[20:21]
	v_cmp_eq_u32_e64 s[28:29], 0, v30
	v_cmp_lt_i32_e64 s[18:19], -1, v34
	v_max3_f32 v35, v35, v28, v29
	v_cndmask_b32_e64 v30, v126, v214, s[28:29]
	v_cndmask_b32_e64 v31, v127, v214, s[18:19]
	v_max3_f32 v32, v35, v30, v31
	ds_bpermute_b32 v34, v200, v32
	s_mov_b32 s64, 0x3fb8aa3b
	s_waitcnt lgkmcnt(0)
	v_max3_f32 v36, v198, v32, v34
	v_mul_f32_e32 v32, 0x3fb8aa3b, v36
	v_fma_f32 v0, v0, s64, -v32
	v_fma_f32 v1, v1, s64, -v32
	v_fma_f32 v2, v2, s64, -v32
	v_fma_f32 v3, v3, s64, -v32
	v_exp_f32_e32 v0, v0
	v_exp_f32_e32 v1, v1
	v_exp_f32_e32 v2, v2
	v_exp_f32_e32 v3, v3
	v_fma_f32 v4, v4, s64, -v32
	v_fma_f32 v5, v5, s64, -v32
	v_fma_f32 v6, v6, s64, -v32
	v_fma_f32 v7, v7, s64, -v32
	v_exp_f32_e32 v4, v4
	v_exp_f32_e32 v5, v5
	v_exp_f32_e32 v6, v6
	v_exp_f32_e32 v7, v7
	v_fma_f32 v8, v8, s64, -v32
	v_fma_f32 v9, v9, s64, -v32
	v_cndmask_b32_e64 v0, 0, v0, s[16:17]
	v_cndmask_b32_e64 v1, 0, v1, s[12:13]
	v_exp_f32_e32 v8, v8
	v_exp_f32_e32 v9, v9
	v_fma_f32 v10, v10, s64, -v32
	v_fma_f32 v11, v11, s64, -v32
	v_add_f32_e64 v34, v0, 0
	v_add_f32_e64 v35, v1, 0
	v_cndmask_b32_e64 v2, v2, 0, s[14:15]
	v_cndmask_b32_e64 v3, v3, 0, s[8:9]
	v_exp_f32_e32 v10, v10
	v_exp_f32_e32 v11, v11
	v_fma_f32 v12, v12, s64, -v32
	v_fma_f32 v13, v13, s64, -v32
	v_add_f32_e64 v34, v2, v34
	v_add_f32_e64 v35, v3, v35
	v_cndmask_b32_e64 v4, v4, 0, s[10:11]
	v_cndmask_b32_e64 v5, v5, 0, s[4:5]
	v_exp_f32_e32 v12, v12
	v_exp_f32_e32 v13, v13
	v_fma_f32 v14, v14, s64, -v32
	v_fma_f32 v15, v15, s64, -v32
	v_add_f32_e64 v34, v4, v34
	v_add_f32_e64 v35, v5, v35
	v_cndmask_b32_e64 v6, v6, 0, s[6:7]
	v_cndmask_b32_e64 v7, v7, 0, s[0:1]
	v_exp_f32_e32 v14, v14
	v_exp_f32_e32 v15, v15
	v_fma_f32 v16, v16, s64, -v32
	v_fma_f32 v17, v17, s64, -v32
	v_add_f32_e64 v34, v6, v34
	v_add_f32_e64 v35, v7, v35
	v_cndmask_b32_e64 v8, v8, 0, s[2:3]
	v_cndmask_b32_e64 v9, v9, 0, vcc
	v_exp_f32_e32 v16, v16
	v_exp_f32_e32 v17, v17
	v_fma_f32 v18, v18, s64, -v32
	v_fma_f32 v19, v19, s64, -v32
	v_add_f32_e64 v34, v8, v34
	v_add_f32_e64 v35, v9, v35
	v_cndmask_b32_e64 v10, v10, 0, s[62:63]
	v_cndmask_b32_e64 v11, v11, 0, s[52:53]
	v_exp_f32_e32 v18, v18
	v_exp_f32_e32 v19, v19
	v_fma_f32 v20, v20, s64, -v32
	v_fma_f32 v21, v21, s64, -v32
	v_add_f32_e64 v34, v10, v34
	v_add_f32_e64 v35, v11, v35
	v_cndmask_b32_e64 v12, v12, 0, s[60:61]
	v_cndmask_b32_e64 v13, v13, 0, s[48:49]
	v_exp_f32_e32 v20, v20
	v_exp_f32_e32 v21, v21
	v_fma_f32 v22, v22, s64, -v32
	v_fma_f32 v23, v23, s64, -v32
	v_add_f32_e64 v34, v12, v34
	v_add_f32_e64 v35, v13, v35
	v_cndmask_b32_e64 v14, v14, 0, s[58:59]
	v_cndmask_b32_e64 v15, v15, 0, s[44:45]
	v_exp_f32_e32 v22, v22
	v_exp_f32_e32 v23, v23
	v_fma_f32 v24, v24, s64, -v32
	v_fma_f32 v25, v25, s64, -v32
	v_add_f32_e64 v34, v14, v34
	v_add_f32_e64 v35, v15, v35
	v_cndmask_b32_e64 v16, v16, 0, s[56:57]
	v_cndmask_b32_e64 v17, v17, 0, s[40:41]
	v_exp_f32_e32 v24, v24
	v_exp_f32_e32 v25, v25
	v_fma_f32 v26, v26, s64, -v32
	v_fma_f32 v27, v27, s64, -v32
	v_add_f32_e64 v34, v16, v34
	v_add_f32_e64 v35, v17, v35
	v_cndmask_b32_e64 v18, v18, 0, s[54:55]
	v_cndmask_b32_e64 v19, v19, 0, s[36:37]
	v_exp_f32_e32 v26, v26
	v_exp_f32_e32 v27, v27
	v_fma_f32 v28, v28, s64, -v32
	v_fma_f32 v29, v29, s64, -v32
	v_add_f32_e64 v34, v18, v34
	v_add_f32_e64 v35, v19, v35
	v_cndmask_b32_e64 v20, v20, 0, s[50:51]
	v_cndmask_b32_e64 v21, v21, 0, s[30:31]
	v_exp_f32_e32 v28, v28
	v_exp_f32_e32 v29, v29
	v_fma_f32 v30, v30, s64, -v32
	v_fma_f32 v31, v31, s64, -v32
	v_add_f32_e64 v34, v20, v34
	v_add_f32_e64 v35, v21, v35
	v_cndmask_b32_e64 v22, v22, 0, s[46:47]
	v_cndmask_b32_e64 v23, v23, 0, s[26:27]
	v_exp_f32_e32 v30, v30
	v_exp_f32_e32 v31, v31
	v_add_f32_e64 v34, v22, v34
	v_add_f32_e64 v35, v23, v35
	v_cndmask_b32_e64 v24, v24, 0, s[42:43]
	v_cndmask_b32_e64 v25, v25, 0, s[24:25]
	v_sub_f32_e32 v32, v198, v36
	v_add_f32_e64 v34, v24, v34
	v_add_f32_e64 v35, v25, v35
	v_cndmask_b32_e64 v26, v26, 0, s[38:39]
	v_cndmask_b32_e64 v27, v27, 0, s[22:23]
	v_mul_f32_e32 v32, 0x3fb8aa3b, v32
	v_add_f32_e64 v34, v26, v34
	v_add_f32_e64 v35, v27, v35
	v_cndmask_b32_e64 v28, v28, 0, s[34:35]
	v_cndmask_b32_e64 v29, v29, 0, s[20:21]
	v_exp_f32_e32 v32, v32
	v_add_f32_e64 v34, v28, v34
	v_add_f32_e64 v35, v29, v35
	v_cndmask_b32_e64 v30, v30, 0, s[28:29]
	v_cndmask_b32_e64 v31, v31, 0, s[18:19]
	v_add_f32_e64 v34, v30, v34
	v_add_f32_e64 v35, v31, v35
	s_mov_b32 s52, 0x40000
	v_add_f32_e32 v34, v34, v35
	v_fmac_f32_e32 v34, v185, v32
	s_mov_b32 s57, 0x400000
	s_mov_b32 s56, 0x200000
	s_mov_b32 s55, 0x20000
	s_mov_b32 s51, 0x100000
	s_mov_b32 s50, 0x80000
	v_mov_b32_e32 v198, v36
	v_mov_b32_e32 v185, v34
	s_branch .LBB0_766
; DI void diff_item(const Params& p_, const EvenBufs& eb_, int e, int b, int hh, int qt, unsigned char* smem) {
;     ...
;   int e2 = e; asm volatile("" : "+s"(e2));
;   const float lam = ((const float*)(p.ws + OFF_CBIAS + 2048))[e2];
;   const float lam_init = 0.8f - 0.6f * __expf(-0.3f * (float)(2 * e2));
;   const float c2 = lam / l2;
;   float ss = 0.f;
; #pragma unroll
;   for (int dt = 0; dt < 4; ++dt)
; #pragma unroll
;     for (int i = 0; i < 8; ++i) {
;       const unsigned ov = o1s[(dt * 8 + i) * 256];
;       const float a0 = __uint_as_float(ov << 16), a1 = __uint_as_float(ov & 0xffff0000u);
;       const float v0 = a0 - c2 * O[dt][2 * i], v1 = a1 - c2 * O[dt][2 * i + 1];
;       O[dt][2 * i] = v0; O[dt][2 * i + 1] = v1;
;       ss += v0 * v0 + v1 * v1;
;     }
.LBB0_775:
	v_readlane_b32 s0, v254, 62
	v_readlane_b32 s1, v254, 63
	s_ashr_i32 s1, s0, 31
	s_lshl_b64 s[2:3], s[0:1], 2
	s_add_u32 s1, s70, s2
	s_addc_u32 s2, s71, s3
	v_mov_b32_e32 v0, s1
	s_mov_b32 s1, 0x101000
	v_add_co_u32_e32 v0, vcc, s1, v0
	v_mov_b32_e32 v1, s2
	s_nop 0
	v_addc_co_u32_e32 v1, vcc, 0, v1, vcc
	flat_load_dword v32, v[0:1] offset:2048
	ds_bpermute_b32 v24, v200, v185
	ds_read2st64_b32 v[0:1], v202 offset0:160 offset1:164
	ds_read2st64_b32 v[2:3], v202 offset0:168 offset1:172
	ds_read2st64_b32 v[4:5], v202 offset0:176 offset1:180
	ds_read2st64_b32 v[6:7], v202 offset0:184 offset1:188
	ds_read2st64_b32 v[8:9], v202 offset0:192 offset1:196
	ds_read2st64_b32 v[10:11], v202 offset0:200 offset1:204
	ds_read2st64_b32 v[12:13], v202 offset0:208 offset1:212
	ds_read2st64_b32 v[14:15], v202 offset0:216 offset1:220
	ds_read2st64_b32 v[16:17], v202 offset0:224 offset1:228
	ds_read2st64_b32 v[18:19], v202 offset0:232 offset1:236
	ds_read2st64_b32 v[20:21], v202 offset0:240 offset1:244
	ds_read2st64_b32 v[22:23], v202 offset0:248 offset1:252
	ds_read2st64_b32 v[134:135], v201 offset0:96 offset1:100
	ds_read2st64_b32 v[136:137], v201 offset0:104 offset1:108
	s_lshl_b32 s0, s0, 1
	v_cvt_f32_i32_e32 v139, s0
	s_waitcnt lgkmcnt(0)
	v_lshlrev_b32_e32 v132, 16, v1
	v_add_f32_e32 v138, v185, v24
	v_and_b32_e32 v133, 0xffff0000, v1
	v_lshlrev_b32_e32 v126, 16, v2
	v_and_b32_e32 v127, 0xffff0000, v2
	v_lshlrev_b32_e32 v130, 16, v0
	v_and_b32_e32 v131, 0xffff0000, v0
	v_mul_f32_e32 v0, 0xbe99999a, v139
	v_lshlrev_b32_e32 v128, 16, v3
	v_and_b32_e32 v129, 0xffff0000, v3
	v_mul_f32_e32 v0, 0x3fb8aa3b, v0
	v_lshlrev_b32_e32 v42, 16, v12
	v_and_b32_e32 v43, 0xffff0000, v12
	v_exp_f32_e32 v12, v0
	v_lshlrev_b32_e32 v122, 16, v4
	v_and_b32_e32 v123, 0xffff0000, v4
	v_lshlrev_b32_e32 v38, 16, v14
	v_and_b32_e32 v39, 0xffff0000, v14
	v_lshlrev_b32_e32 v124, 16, v5
	v_and_b32_e32 v125, 0xffff0000, v5
	v_mov_b32_e32 v5, v58
	v_mov_b32_e32 v58, v57
	v_lshlrev_b32_e32 v46, 16, v10
	v_and_b32_e32 v47, 0xffff0000, v10
	v_lshlrev_b32_e32 v112, 16, v11
	v_and_b32_e32 v113, 0xffff0000, v11
	v_lshlrev_b32_e32 v120, 16, v7
	v_and_b32_e32 v121, 0xffff0000, v7
	v_mov_b32_e32 v7, v62
	v_mov_b32_e32 v62, v61
	v_lshlrev_b32_e32 v118, 16, v6
	v_and_b32_e32 v119, 0xffff0000, v6
	v_lshlrev_b32_e32 v114, 16, v8
	v_and_b32_e32 v115, 0xffff0000, v8
	v_lshlrev_b32_e32 v116, 16, v9
	v_and_b32_e32 v117, 0xffff0000, v9
	v_mov_b32_e32 v6, v60
	v_readlane_b32 s2, v255, 16
	v_readlane_b32 s3, v255, 17
	s_movk_i32 s74, 0x880
	v_lshlrev_b32_e32 v44, 16, v13
	v_and_b32_e32 v45, 0xffff0000, v13
	v_lshlrev_b32_e32 v40, 16, v15
	v_and_b32_e32 v41, 0xffff0000, v15
	v_lshlrev_b32_e32 v34, 16, v16
	v_and_b32_e32 v35, 0xffff0000, v16
	v_lshlrev_b32_e32 v36, 16, v17
	v_and_b32_e32 v37, 0xffff0000, v17
	v_lshlrev_b32_e32 v28, 16, v18
	v_and_b32_e32 v29, 0xffff0000, v18
	v_lshlrev_b32_e32 v30, 16, v19
	v_and_b32_e32 v31, 0xffff0000, v19
	v_lshlrev_b32_e32 v24, 16, v20
	v_and_b32_e32 v25, 0xffff0000, v20
	v_lshlrev_b32_e32 v26, 16, v21
	v_and_b32_e32 v27, 0xffff0000, v21
	v_lshlrev_b32_e32 v20, 16, v22
	v_and_b32_e32 v21, 0xffff0000, v22
	v_lshlrev_b32_e32 v22, 16, v23
	v_and_b32_e32 v23, 0xffff0000, v23
	v_lshlrev_b32_e32 v16, 16, v134
	v_and_b32_e32 v17, 0xffff0000, v134
	v_lshlrev_b32_e32 v18, 16, v135
	v_and_b32_e32 v19, 0xffff0000, v135
	v_lshlrev_b32_e32 v134, 16, v136
	v_and_b32_e32 v135, 0xffff0000, v136
	v_lshlrev_b32_e32 v136, 16, v137
	v_and_b32_e32 v137, 0xffff0000, v137
	s_waitcnt vmcnt(0)
	v_div_scale_f32 v1, s[0:1], v138, v138, v32
	v_rcp_f32_e32 v2, v1
	v_div_scale_f32 v0, vcc, v32, v138, v32
	v_readlane_b32 s0, v255, 8
	v_fma_f32 v3, -v1, v2, 1.0
	v_fmac_f32_e32 v2, v3, v2
	v_mul_f32_e32 v3, v0, v2
	v_fma_f32 v4, -v1, v3, v0
	v_fmac_f32_e32 v3, v4, v2
	v_fma_f32 v0, -v1, v3, v0
	v_div_fmas_f32 v0, v0, v2, v3
	v_div_fixup_f32 v14, v0, v138, v32
	ds_read2st64_b32 v[0:1], v201 offset0:112 offset1:116
	v_mov_b32_e32 v4, v56
	v_readlane_b32 s1, v255, 9
	s_add_u32 s0, s2, s0
	s_addc_u32 s1, s3, s1
	s_waitcnt lgkmcnt(0)
	v_lshlrev_b32_e32 v3, 16, v1
	v_lshlrev_b32_e32 v2, 16, v0
	v_fma_f32 v4, -v4, v14, v2
	v_fma_f32 v5, -v5, v14, v3
	ds_read2st64_b32 v[2:3], v201 offset0:120 offset1:124
	v_and_b32_e32 v1, 0xffff0000, v1
	v_and_b32_e32 v0, 0xffff0000, v0
	v_fma_f32 v10, -v58, v14, v0
	v_fma_f32 v11, -v59, v14, v1
	s_lshl_b32 s80, s86, 1
	v_mul_f32_e64 v0, v10, v10
	v_mul_f32_e64 v1, v11, v11
	s_nop 0
	v_fma_f32 v56, v4, v4, v0
	v_fma_f32 v57, v5, v5, v1
	s_waitcnt lgkmcnt(0)
; DI float shx32(float v) { return __shfl_xor(v, 32); }
; DI void diff_item(const Params& p_, const EvenBufs& eb_, int e, int b, int hh, int qt, unsigned char* smem) {
;     ...
;   const float lam_init = 0.8f - 0.6f * __expf(-0.3f * (float)(2 * e2));
;   const float c2 = lam / l2;
;   float ss = 0.f;
; #pragma unroll
;   for (int dt = 0; dt < 4; ++dt)
; #pragma unroll
;     for (int i = 0; i < 8; ++i) {
;       const unsigned ov = o1s[(dt * 8 + i) * 256];
;       const float a0 = __uint_as_float(ov << 16), a1 = __uint_as_float(ov & 0xffff0000u);
;       const float v0 = a0 - c2 * O[dt][2 * i], v1 = a1 - c2 * O[dt][2 * i + 1];
;       O[dt][2 * i] = v0; O[dt][2 * i + 1] = v1;
;       ss += v0 * v0 + v1 * v1;
;     }
;   ss += shx32(ss);
;   const float rinv = rsqrtf(ss * (1.f / 128.f) + 1e-6f) * (1.f - lam_init);
;   const float* sub = p.subln + e * 128;
;   bf16_t* orow = (bf16_t*)(p.ws + OFF_HB) + (size_t)(b * S + t) * LDX + 512 + hh * 128;
	v_lshlrev_b32_e32 v1, 16, v3
	v_lshlrev_b32_e32 v0, 16, v2
	v_and_b32_e32 v3, 0xffff0000, v3
	v_and_b32_e32 v2, 0xffff0000, v2
	v_fma_f32 v8, -v62, v14, v2
	v_fma_f32 v9, -v63, v14, v3
	v_fma_f32 v6, -v6, v14, v0
	v_fma_f32 v7, -v7, v14, v1
	v_mul_f32_e64 v0, v8, v8
	v_mul_f32_e64 v1, v9, v9
	v_lshl_add_u32 v2, s85, 12, v184
	v_fma_f32 v60, v6, v6, v0
	v_fma_f32 v61, v7, v7, v1
	v_mov_b32_e32 v0, 0xbf4ccccd
	v_fmamk_f32 v0, v12, 0x3f19999a, v0
	v_add_f32_e32 v144, 1.0, v0
	v_mov_b64_e32 v[0:1], s[70:71]
	v_mad_i64_i32 v[0:1], s[2:3], v2, s74, v[0:1]
	v_lshl_add_u64 v[138:139], v[0:1], 0, s[80:81]
	v_lshlrev_b32_e32 v32, 2, v243
	v_lshl_add_u64 v[12:13], s[0:1], 0, v[32:33]
	flat_load_dwordx4 v[0:3], v[12:13]
	v_fma_f32 v22, -v78, v14, v22
	v_fma_f32 v23, -v79, v14, v23
	v_fma_f32 v20, -v76, v14, v20
	v_fma_f32 v21, -v77, v14, v21
	v_mov_b32_e32 v77, v23
	v_mov_b32_e32 v76, v21
	v_fma_f32 v114, -v80, v14, v114
	v_fma_f32 v115, -v81, v14, v115
	v_fma_f32 v80, -v84, v14, v46
	v_fma_f32 v81, -v85, v14, v47
	v_fma_f32 v46, -v88, v14, v42
	v_fma_f32 v47, -v89, v14, v43
	v_fma_f32 v42, -v92, v14, v38
	v_fma_f32 v43, -v93, v14, v39
	v_fma_f32 v38, -v64, v14, v34
	v_fma_f32 v39, -v65, v14, v35
	v_fma_f32 v34, -v68, v14, v28
	v_fma_f32 v35, -v69, v14, v29
	v_fma_f32 v28, -v72, v14, v24
	v_fma_f32 v29, -v73, v14, v25
	v_mov_b32_e32 v24, v20
	v_mov_b32_e32 v25, v22
	v_mul_f32_e64 v76, v76, v76
	v_mul_f32_e64 v77, v77, v77
	v_fma_f32 v18, -v50, v14, v18
	v_fma_f32 v19, -v51, v14, v19
	v_fma_f32 v76, v24, v24, v76
	v_fma_f32 v77, v25, v25, v77
	v_fma_f32 v24, -v48, v14, v16
	v_fma_f32 v25, -v49, v14, v17
	v_mov_b32_e32 v49, v19
	v_mov_b32_e32 v48, v25
	v_mov_b32_e32 v16, v24
	v_mov_b32_e32 v17, v18
	v_mul_f32_e64 v48, v48, v48
	v_mul_f32_e64 v49, v49, v49
	v_fma_f32 v132, -v98, v14, v132
	v_fma_f32 v133, -v99, v14, v133
	v_fma_f32 v130, -v96, v14, v130
	v_fma_f32 v131, -v97, v14, v131
	v_fma_f32 v102, -v102, v14, v128
	v_fma_f32 v103, -v103, v14, v129
	v_fma_f32 v100, -v100, v14, v126
	v_fma_f32 v101, -v101, v14, v127
	v_fma_f32 v98, -v106, v14, v124
	v_fma_f32 v99, -v107, v14, v125
	v_fma_f32 v104, -v104, v14, v122
	v_fma_f32 v105, -v105, v14, v123
	v_fma_f32 v96, -v110, v14, v120
	v_fma_f32 v97, -v111, v14, v121
	v_fma_f32 v108, -v108, v14, v118
	v_fma_f32 v109, -v109, v14, v119
	v_fma_f32 v62, -v82, v14, v116
	v_fma_f32 v63, -v83, v14, v117
	v_fma_f32 v58, -v86, v14, v112
	v_fma_f32 v59, -v87, v14, v113
	v_fma_f32 v44, -v90, v14, v44
	v_fma_f32 v45, -v91, v14, v45
	v_fma_f32 v40, -v94, v14, v40
	v_fma_f32 v41, -v95, v14, v41
	v_fma_f32 v36, -v66, v14, v36
	v_fma_f32 v37, -v67, v14, v37
	v_fma_f32 v30, -v70, v14, v30
	v_fma_f32 v31, -v71, v14, v31
	v_fma_f32 v26, -v74, v14, v26
	v_fma_f32 v27, -v75, v14, v27
	v_fma_f32 v48, v16, v16, v48
	v_fma_f32 v49, v17, v17, v49
	v_fma_f32 v16, -v54, v14, v136
	v_fma_f32 v17, -v55, v14, v137
	v_fma_f32 v15, -v53, v14, v135
	v_fma_f32 v14, -v52, v14, v134
	v_mov_b32_e32 v53, v17
	v_mov_b32_e32 v52, v15
	v_mul_f32_e64 v140, v132, v132
	v_mul_f32_e64 v141, v133, v133
	v_mul_f32_e64 v142, v130, v130
	v_mul_f32_e64 v143, v131, v131
	v_mov_b32_e32 v50, v14
	v_mov_b32_e32 v51, v16
	v_mul_f32_e64 v52, v52, v52
	v_mul_f32_e64 v53, v53, v53
	v_mul_f32_e64 v126, v100, v100
	v_mul_f32_e64 v127, v101, v101
	v_fma_f32 v50, v50, v50, v52
	v_fma_f32 v51, v51, v51, v53
	v_add_f32_e32 v32, v140, v141
	v_add_f32_e32 v52, v142, v143
	v_mul_f32_e64 v128, v102, v102
	v_mul_f32_e64 v129, v103, v103
	v_add_f32_e32 v32, v52, v32
	v_add_f32_e32 v52, v126, v127
	v_mul_f32_e64 v122, v104, v104
	v_mul_f32_e64 v123, v105, v105
	v_add_f32_e32 v32, v32, v52
	v_add_f32_e32 v52, v128, v129
	v_mul_f32_e64 v106, v98, v98
	v_mul_f32_e64 v107, v99, v99
	v_add_f32_e32 v32, v32, v52
	v_add_f32_e32 v52, v122, v123
	v_mul_f32_e64 v118, v108, v108
	v_mul_f32_e64 v119, v109, v109
	v_add_f32_e32 v32, v32, v52
	v_add_f32_e32 v52, v106, v107
	v_mul_f32_e64 v110, v96, v96
	v_mul_f32_e64 v111, v97, v97
	v_add_f32_e32 v32, v32, v52
	v_add_f32_e32 v52, v118, v119
	v_mul_f32_e64 v116, v114, v114
	v_mul_f32_e64 v117, v115, v115
	v_add_f32_e32 v32, v32, v52
	v_add_f32_e32 v52, v110, v111
	v_mul_f32_e64 v82, v62, v62
	v_mul_f32_e64 v83, v63, v63
	v_add_f32_e32 v32, v32, v52
	v_add_f32_e32 v52, v116, v117
	v_mul_f32_e64 v84, v80, v80
	v_mul_f32_e64 v85, v81, v81
	v_add_f32_e32 v32, v32, v52
	v_add_f32_e32 v52, v82, v83
	v_mul_f32_e64 v86, v58, v58
	v_mul_f32_e64 v87, v59, v59
	v_add_f32_e32 v32, v32, v52
	v_add_f32_e32 v52, v84, v85
	v_mul_f32_e64 v88, v46, v46
	v_mul_f32_e64 v89, v47, v47
	v_add_f32_e32 v32, v32, v52
	v_add_f32_e32 v52, v86, v87
	v_mul_f32_e64 v90, v44, v44
	v_mul_f32_e64 v91, v45, v45
	v_add_f32_e32 v32, v32, v52
	v_add_f32_e32 v52, v88, v89
	v_mul_f32_e64 v92, v42, v42
	v_mul_f32_e64 v93, v43, v43
	v_add_f32_e32 v32, v32, v52
	v_add_f32_e32 v52, v90, v91
	v_mul_f32_e64 v94, v40, v40
	v_mul_f32_e64 v95, v41, v41
	v_add_f32_e32 v32, v32, v52
	v_add_f32_e32 v52, v92, v93
	v_mul_f32_e64 v64, v38, v38
	v_mul_f32_e64 v65, v39, v39
	v_add_f32_e32 v32, v32, v52
	v_add_f32_e32 v52, v94, v95
	v_mul_f32_e64 v66, v36, v36
	v_mul_f32_e64 v67, v37, v37
	v_add_f32_e32 v32, v32, v52
	v_add_f32_e32 v52, v64, v65
	v_mul_f32_e64 v68, v34, v34
	v_mul_f32_e64 v69, v35, v35
	v_add_f32_e32 v32, v32, v52
	v_add_f32_e32 v52, v66, v67
	v_mul_f32_e64 v70, v30, v30
	v_mul_f32_e64 v71, v31, v31
	v_add_f32_e32 v32, v32, v52
	v_add_f32_e32 v52, v68, v69
	v_mul_f32_e64 v72, v28, v28
	v_mul_f32_e64 v73, v29, v29
	v_add_f32_e32 v32, v32, v52
	v_add_f32_e32 v52, v70, v71
	v_mul_f32_e64 v74, v26, v26
	v_mul_f32_e64 v75, v27, v27
	v_add_f32_e32 v32, v32, v52
	v_add_f32_e32 v52, v72, v73
	v_add_f32_e32 v32, v32, v52
	v_add_f32_e32 v52, v74, v75
	v_add_f32_e32 v32, v32, v52
	v_add_f32_e32 v32, v32, v76
	v_add_f32_e32 v32, v32, v77
	v_add_f32_e32 v32, v32, v48
	v_add_f32_e32 v32, v32, v49
	v_add_f32_e32 v32, v32, v50
	v_add_f32_e32 v32, v32, v51
	v_add_f32_e32 v32, v32, v56
	v_add_f32_e32 v32, v32, v57
	v_add_f32_e32 v32, v32, v60
	v_add_f32_e32 v32, v32, v61
	ds_bpermute_b32 v48, v200, v32
	s_mov_b64 s[0:1], 0x36d6400
	s_waitcnt lgkmcnt(0)
; DI unsigned pack2(float a, float b) { bf2_t v = __builtin_convertvector((f32x2){a, b}, bf2_t); return __builtin_bit_cast(unsigned, v); }
; DI float shx32(float v) { return __shfl_xor(v, 32); }
; DI void diff_item(const Params& p_, const EvenBufs& eb_, int e, int b, int hh, int qt, unsigned char* smem) {
;     ...
;   ss += shx32(ss);
;   const float rinv = rsqrtf(ss * (1.f / 128.f) + 1e-6f) * (1.f - lam_init);
;   const float* sub = p.subln + e * 128;
;   bf16_t* orow = (bf16_t*)(p.ws + OFF_HB) + (size_t)(b * S + t) * LDX + 512 + hh * 128;
; #pragma unroll
;   for (int dt = 0; dt < 4; ++dt)
; #pragma unroll
;     for (int g = 0; g < 4; ++g) {
;       __builtin_amdgcn_sched_barrier(0);
;       const int d = dt * 32 + 8 * g + 4 * h;
;       const f32x4 sg = *(const f32x4*)(sub + d);
;       u32x2 w;
;       w.x = pack2(O[dt][4 * g] * rinv * sg.x, O[dt][4 * g + 1] * rinv * sg.y);
;       w.y = pack2(O[dt][4 * g + 2] * rinv * sg.z, O[dt][4 * g + 3] * rinv * sg.w);
;       *(u32x2*)(orow + d) = w;
;     }
	v_add_f32_e32 v32, v32, v48
	v_fmamk_f32 v32, v32, 0x3c000000, v240
	v_mul_f32_e32 v48, 0x4b800000, v32
	v_cmp_gt_f32_e32 vcc, s79, v32
	s_nop 1
	v_cndmask_b32_e32 v32, v32, v48, vcc
	v_rsq_f32_e32 v52, v32
	v_lshlrev_b32_e32 v32, 1, v243
	v_lshl_add_u64 v[50:51], v[138:139], 0, v[32:33]
	v_lshl_add_u64 v[48:49], v[50:51], 0, s[0:1]
	v_mul_f32_e32 v32, 0x45800000, v52
	v_cndmask_b32_e32 v32, v52, v32, vcc
	v_mul_f32_e32 v32, v144, v32
	v_mul_f32_e64 v52, v130, v32
	v_mul_f32_e64 v53, v131, v32
	s_mov_b32 s0, 0x36d6000
	s_waitcnt vmcnt(0)
	v_mul_f32_e64 v0, v0, v52
	v_mul_f32_e64 v1, v1, v53
	v_mul_f32_e64 v52, v132, v32
	v_mul_f32_e64 v53, v133, v32
	v_cvt_pk_bf16_f32 v0, v0, v1
	v_mul_f32_e64 v2, v2, v52
	v_mul_f32_e64 v3, v3, v53
	s_nop 0
	v_cvt_pk_bf16_f32 v1, v2, v3
	v_add_co_u32_e32 v2, vcc, s0, v50
	s_nop 1
	v_addc_co_u32_e32 v3, vcc, 0, v51, vcc
	flat_store_dwordx2 v[2:3], v[0:1] offset:1024
	flat_load_dwordx4 v[0:3], v[12:13] offset:32
	v_mul_f32_e64 v50, v100, v32
	v_mul_f32_e64 v51, v101, v32
	v_mul_f32_e64 v52, v102, v32
	v_mul_f32_e64 v53, v103, v32
	s_waitcnt vmcnt(0) lgkmcnt(0)
	v_mul_f32_e64 v0, v0, v50
	v_mul_f32_e64 v1, v1, v51
	v_mul_f32_e64 v2, v2, v52
	v_mul_f32_e64 v3, v3, v53
	v_cvt_pk_bf16_f32 v0, v0, v1
	v_cvt_pk_bf16_f32 v1, v2, v3
	flat_store_dwordx2 v[48:49], v[0:1] offset:16
	flat_load_dwordx4 v[0:3], v[12:13] offset:64
	v_mul_f32_e64 v50, v104, v32
	v_mul_f32_e64 v51, v105, v32
	v_mul_f32_e64 v52, v98, v32
	v_mul_f32_e64 v53, v99, v32
	s_waitcnt vmcnt(0) lgkmcnt(0)
	v_mul_f32_e64 v0, v0, v50
	v_mul_f32_e64 v1, v1, v51
	v_mul_f32_e64 v2, v2, v52
	v_mul_f32_e64 v3, v3, v53
	v_cvt_pk_bf16_f32 v0, v0, v1
	v_cvt_pk_bf16_f32 v1, v2, v3
	flat_store_dwordx2 v[48:49], v[0:1] offset:32
	flat_load_dwordx4 v[0:3], v[12:13] offset:96
	v_mul_f32_e64 v50, v108, v32
	v_mul_f32_e64 v51, v109, v32
	v_mul_f32_e64 v52, v96, v32
	v_mul_f32_e64 v53, v97, v32
	s_waitcnt vmcnt(0) lgkmcnt(0)
	v_mul_f32_e64 v0, v0, v50
	v_mul_f32_e64 v1, v1, v51
	v_mul_f32_e64 v2, v2, v52
	v_mul_f32_e64 v3, v3, v53
	v_cvt_pk_bf16_f32 v0, v0, v1
	v_cvt_pk_bf16_f32 v1, v2, v3
	flat_store_dwordx2 v[48:49], v[0:1] offset:48
	flat_load_dwordx4 v[0:3], v[12:13] offset:128
	v_mul_f32_e64 v50, v114, v32
	v_mul_f32_e64 v51, v115, v32
	v_mul_f32_e64 v52, v62, v32
	v_mul_f32_e64 v53, v63, v32
	s_waitcnt vmcnt(0) lgkmcnt(0)
	v_mul_f32_e64 v0, v0, v50
	v_mul_f32_e64 v1, v1, v51
	v_mul_f32_e64 v2, v2, v52
	v_mul_f32_e64 v3, v3, v53
	v_cvt_pk_bf16_f32 v0, v0, v1
	v_cvt_pk_bf16_f32 v1, v2, v3
	flat_store_dwordx2 v[48:49], v[0:1] offset:64
	flat_load_dwordx4 v[0:3], v[12:13] offset:160
	v_mul_f32_e64 v50, v80, v32
	v_mul_f32_e64 v51, v81, v32
	v_mul_f32_e64 v52, v58, v32
	v_mul_f32_e64 v53, v59, v32
	s_waitcnt vmcnt(0) lgkmcnt(0)
	v_mul_f32_e64 v0, v50, v0
	v_mul_f32_e64 v1, v51, v1
	v_mul_f32_e64 v2, v52, v2
	v_mul_f32_e64 v3, v53, v3
	v_cvt_pk_bf16_f32 v0, v0, v1
	v_cvt_pk_bf16_f32 v1, v2, v3
	flat_store_dwordx2 v[48:49], v[0:1] offset:80
	flat_load_dwordx4 v[0:3], v[12:13] offset:192
	v_mul_f32_e64 v46, v46, v32
	v_mul_f32_e64 v47, v47, v32
	v_mul_f32_e64 v44, v44, v32
	v_mul_f32_e64 v45, v45, v32
	s_waitcnt vmcnt(0) lgkmcnt(0)
	v_mul_f32_e64 v0, v46, v0
	v_mul_f32_e64 v1, v47, v1
	v_mul_f32_e64 v2, v44, v2
	v_mul_f32_e64 v3, v45, v3
	v_cvt_pk_bf16_f32 v0, v0, v1
	v_cvt_pk_bf16_f32 v1, v2, v3
	flat_store_dwordx2 v[48:49], v[0:1] offset:96
	flat_load_dwordx4 v[0:3], v[12:13] offset:224
	v_mul_f32_e64 v42, v42, v32
	v_mul_f32_e64 v43, v43, v32
	v_mul_f32_e64 v40, v40, v32
	v_mul_f32_e64 v41, v41, v32
	s_waitcnt vmcnt(0) lgkmcnt(0)
	v_mul_f32_e64 v0, v42, v0
	v_mul_f32_e64 v1, v43, v1
	v_mul_f32_e64 v2, v40, v2
	v_mul_f32_e64 v3, v41, v3
	v_cvt_pk_bf16_f32 v0, v0, v1
	v_cvt_pk_bf16_f32 v1, v2, v3
	flat_store_dwordx2 v[48:49], v[0:1] offset:112
	flat_load_dwordx4 v[0:3], v[12:13] offset:256
	v_mul_f32_e64 v38, v38, v32
	v_mul_f32_e64 v39, v39, v32
	v_mul_f32_e64 v36, v36, v32
	v_mul_f32_e64 v37, v37, v32
	s_waitcnt vmcnt(0) lgkmcnt(0)
; DI unsigned pack2(float a, float b) { bf2_t v = __builtin_convertvector((f32x2){a, b}, bf2_t); return __builtin_bit_cast(unsigned, v); }
; DI void diff_item(const Params& p_, const EvenBufs& eb_, int e, int b, int hh, int qt, unsigned char* smem) {
;     ...
; #pragma unroll
;   for (int dt = 0; dt < 4; ++dt)
; #pragma unroll
;     for (int g = 0; g < 4; ++g) {
;       __builtin_amdgcn_sched_barrier(0);
;       const int d = dt * 32 + 8 * g + 4 * h;
;       const f32x4 sg = *(const f32x4*)(sub + d);
;       u32x2 w;
;       w.x = pack2(O[dt][4 * g] * rinv * sg.x, O[dt][4 * g + 1] * rinv * sg.y);
;       w.y = pack2(O[dt][4 * g + 2] * rinv * sg.z, O[dt][4 * g + 3] * rinv * sg.w);
;       *(u32x2*)(orow + d) = w;
;     }
	v_mul_f32_e64 v0, v38, v0
	v_mul_f32_e64 v1, v39, v1
	v_mul_f32_e64 v2, v36, v2
	v_mul_f32_e64 v3, v37, v3
	v_cvt_pk_bf16_f32 v0, v0, v1
	v_cvt_pk_bf16_f32 v1, v2, v3
	flat_store_dwordx2 v[48:49], v[0:1] offset:128
	flat_load_dwordx4 v[0:3], v[12:13] offset:288
	v_mul_f32_e64 v34, v34, v32
	v_mul_f32_e64 v35, v35, v32
	v_mul_f32_e64 v30, v30, v32
	v_mul_f32_e64 v31, v31, v32
	s_waitcnt vmcnt(0) lgkmcnt(0)
	v_mul_f32_e64 v0, v34, v0
	v_mul_f32_e64 v1, v35, v1
	v_mul_f32_e64 v2, v30, v2
	v_mul_f32_e64 v3, v31, v3
	v_cvt_pk_bf16_f32 v0, v0, v1
	v_cvt_pk_bf16_f32 v1, v2, v3
	flat_store_dwordx2 v[48:49], v[0:1] offset:144
	flat_load_dwordx4 v[0:3], v[12:13] offset:320
	v_mul_f32_e64 v28, v28, v32
	v_mul_f32_e64 v29, v29, v32
	v_mul_f32_e64 v26, v26, v32
	v_mul_f32_e64 v27, v27, v32
	s_waitcnt vmcnt(0) lgkmcnt(0)
	v_mul_f32_e64 v0, v28, v0
	v_mul_f32_e64 v1, v29, v1
	v_mul_f32_e64 v2, v26, v2
	v_mul_f32_e64 v3, v27, v3
	v_cvt_pk_bf16_f32 v0, v0, v1
	v_cvt_pk_bf16_f32 v1, v2, v3
	flat_store_dwordx2 v[48:49], v[0:1] offset:160
	flat_load_dwordx4 v[0:3], v[12:13] offset:352
	v_mul_f32_e64 v20, v20, v32
	v_mul_f32_e64 v21, v21, v32
	v_mul_f32_e64 v22, v22, v32
	v_mul_f32_e64 v23, v23, v32
	s_waitcnt vmcnt(0) lgkmcnt(0)
	v_mul_f32_e64 v0, v20, v0
	v_mul_f32_e64 v1, v21, v1
	v_mul_f32_e64 v2, v22, v2
	v_mul_f32_e64 v3, v23, v3
	v_cvt_pk_bf16_f32 v0, v0, v1
	v_cvt_pk_bf16_f32 v1, v2, v3
	flat_store_dwordx2 v[48:49], v[0:1] offset:176
	flat_load_dwordx4 v[0:3], v[12:13] offset:384
	v_mul_f32_e64 v20, v24, v32
	v_mul_f32_e64 v21, v25, v32
	v_mul_f32_e64 v18, v18, v32
	v_mul_f32_e64 v19, v19, v32
	s_waitcnt vmcnt(0) lgkmcnt(0)
	v_mul_f32_e64 v0, v20, v0
	v_mul_f32_e64 v1, v21, v1
	v_mul_f32_e64 v2, v18, v2
	v_mul_f32_e64 v3, v19, v3
	v_cvt_pk_bf16_f32 v0, v0, v1
	v_cvt_pk_bf16_f32 v1, v2, v3
	flat_store_dwordx2 v[48:49], v[0:1] offset:192
	flat_load_dwordx4 v[0:3], v[12:13] offset:416
	v_mul_f32_e64 v14, v14, v32
	v_mul_f32_e64 v15, v15, v32
	v_mul_f32_e64 v16, v16, v32
	v_mul_f32_e64 v17, v17, v32
	s_waitcnt vmcnt(0) lgkmcnt(0)
	v_mul_f32_e64 v0, v14, v0
	v_mul_f32_e64 v1, v15, v1
	v_mul_f32_e64 v2, v16, v2
	v_mul_f32_e64 v3, v17, v3
	v_cvt_pk_bf16_f32 v0, v0, v1
	v_cvt_pk_bf16_f32 v1, v2, v3
	flat_store_dwordx2 v[48:49], v[0:1] offset:208
	flat_load_dwordx4 v[0:3], v[12:13] offset:448
	v_mov_b32_e32 v14, v4
	v_mov_b32_e32 v15, v10
	v_mov_b32_e32 v10, v5
	v_mul_f32_e64 v4, v14, v32
	v_mul_f32_e64 v5, v15, v32
	v_mul_f32_e64 v10, v10, v32
	v_mul_f32_e64 v11, v11, v32
	s_waitcnt vmcnt(0) lgkmcnt(0)
	v_mul_f32_e64 v0, v4, v0
	v_mul_f32_e64 v1, v5, v1
	v_mul_f32_e64 v2, v10, v2
	v_mul_f32_e64 v3, v11, v3
	v_cvt_pk_bf16_f32 v0, v0, v1
	v_cvt_pk_bf16_f32 v1, v2, v3
	flat_store_dwordx2 v[48:49], v[0:1] offset:224
	flat_load_dwordx4 v[0:3], v[12:13] offset:480
	v_mov_b32_e32 v4, v6
	v_mov_b32_e32 v5, v8
	v_mov_b32_e32 v8, v7
	v_mul_f32_e64 v4, v4, v32
	v_mul_f32_e64 v5, v5, v32
	v_mul_f32_e64 v6, v8, v32
	v_mul_f32_e64 v7, v9, v32
	v_readlane_b32 s2, v255, 12
	v_readlane_b32 s3, v255, 13
	s_mov_b64 s[0:1], 0
	s_movk_i32 s75, 0x1800
	s_mov_b32 s76, 0xbfb8aa3b
	s_mov_b32 s77, 0x3f317217
	s_mov_b32 s78, 0x7f800000
	s_movk_i32 s85, 0xffc0
	s_movk_i32 s86, 0x4ff
	s_movk_i32 s87, 0x517
	s_movk_i32 s88, 0x500
	s_mov_b32 s70, 0x8000
	s_mov_b32 s71, 0x10000
	s_mov_b64 s[68:69], 0x2000
	s_mov_b32 s96, 0x3fb8aa3b
	s_mov_b32 s97, s73
	s_mov_b64 s[72:73], s[2:3]
	v_mov_b32_e32 v252, v204
	v_mov_b32_e32 v253, v206
	s_waitcnt vmcnt(0) lgkmcnt(0)
	v_mul_f32_e64 v0, v4, v0
	v_mul_f32_e64 v1, v5, v1
	v_mul_f32_e64 v2, v6, v2
	v_mul_f32_e64 v3, v7, v3
	v_cvt_pk_bf16_f32 v0, v0, v1
	v_cvt_pk_bf16_f32 v1, v2, v3
	flat_store_dwordx2 v[48:49], v[0:1] offset:240

; DI void transpose_tile(const TJob& t, int lt, unsigned char* smem, int tid) {
;     ...
;   for (int i = 0; i < 4; ++i) {
;     const int k = i * 16 + (tid >> 4), n = (tid & 15) * 4;
;     const float sc = t.ks ? t.ks[k0 + k] : 1.f;
;     tl[k * 65 + n] = v[i].x * sc; tl[k * 65 + n + 1] = v[i].y * sc; tl[k * 65 + n + 2] = v[i].z * sc; tl[k * 65 + n + 3] = v[i].w * sc;
;   }
.LBB0_812:
	s_or_b64 exec, exec, s[34:35]
	s_cmp_lg_u64 s[28:29], 0
	s_cselect_b64 s[34:35], -1, 0
	s_cmp_eq_u64 s[28:29], 0
	s_cbranch_scc1 .LBB0_951
	v_lshl_add_u64 v[20:21], v[20:21], 2, s[28:29]
	flat_load_dword v20, v[20:21]
	s_ashr_i32 s31, s30, 31
	s_waitcnt vmcnt(0) lgkmcnt(0)
	v_mul_f32_e64 v22, v12, v20
	v_mul_f32_e64 v23, v13, v20
	v_mul_f32_e64 v21, v15, v20
	v_mul_f32_e64 v20, v14, v20
	ds_write2_b32 v47, v20, v21 offset0:2 offset1:3
	v_lshl_add_u64 v[20:21], s[30:31], 0, v[18:19]
	ds_write2_b32 v47, v22, v23 offset1:1
	v_lshl_add_u64 v[20:21], v[20:21], 2, s[28:29]
	flat_load_dword v20, v[20:21] offset:64
	s_cbranch_execnz .LBB0_815

; DI void transpose_tile(const TJob& t, int lt, unsigned char* smem, int tid) {
;     ...
;   for (int i = 0; i < 4; ++i) {
;     const int k = i * 16 + (tid >> 4), n = (tid & 15) * 4;
;     const float sc = t.ks ? t.ks[k0 + k] : 1.f;
;     tl[k * 65 + n] = v[i].x * sc; tl[k * 65 + n + 1] = v[i].y * sc; tl[k * 65 + n + 2] = v[i].z * sc; tl[k * 65 + n + 3] = v[i].w * sc;
;   }
.LBB0_815:
	s_waitcnt vmcnt(0) lgkmcnt(0)
	v_mul_f32_e64 v4, v4, v20
	v_mul_f32_e64 v5, v5, v20
	v_add_u32_e32 v12, 0x1040, v47
	ds_write2_b32 v12, v4, v5 offset1:1
	v_mul_f32_e64 v4, v6, v20
	v_mul_f32_e64 v5, v7, v20
	v_add_u32_e32 v6, 0x1048, v47
	ds_write2_b32 v6, v4, v5 offset1:1
	s_andn2_b64 vcc, exec, s[34:35]
	v_add_u32_e32 v5, 0x2080, v47
	v_add_u32_e32 v6, 0x2088, v47
	s_cbranch_vccnz .LBB0_952
	s_ashr_i32 s31, s30, 31
	v_lshl_add_u64 v[12:13], s[30:31], 0, v[18:19]
	v_lshl_add_u64 v[12:13], v[12:13], 2, s[28:29]
	flat_load_dword v4, v[12:13] offset:128
	s_waitcnt vmcnt(0) lgkmcnt(0)
	v_mul_f32_e64 v14, v8, v4
	v_mul_f32_e64 v15, v9, v4
	ds_write2_b32 v5, v14, v15 offset1:1
	v_mul_f32_e64 v14, v10, v4
	v_mul_f32_e64 v15, v11, v4
	ds_write2_b32 v6, v14, v15 offset1:1
	flat_load_dword v4, v[12:13] offset:192
	s_cbranch_execnz .LBB0_818

; DI unsigned pack2(float a, float b) { bf2_t v = __builtin_convertvector((f32x2){a, b}, bf2_t); return __builtin_bit_cast(unsigned, v); }
; DI void transpose_tile(const TJob& t, int lt, unsigned char* smem, int tid) {
;     ...
;   for (int i = 0; i < 4; ++i) {
;     const int k = i * 16 + (tid >> 4), n = (tid & 15) * 4;
;     const float sc = t.ks ? t.ks[k0 + k] : 1.f;
;     tl[k * 65 + n] = v[i].x * sc; tl[k * 65 + n + 1] = v[i].y * sc; tl[k * 65 + n + 2] = v[i].z * sc; tl[k * 65 + n + 3] = v[i].w * sc;
;   }
;   __syncthreads();
; #pragma unroll
;   for (int i = 0; i < 8; ++i) {
;     const int n = i * 8 + (tid >> 5), k2 = (tid & 31) * 2;
;     if (n0 + n < t.N) *(unsigned*)(t.dst + (size_t)map_col(n0 + n, t.mode) * t.ldd + k0 + k2) = pack2(tl[k2 * 65 + n], tl[(k2 + 1) * 65 + n]);
.LBB0_818:
	s_lshl_b64 s[28:29], s[30:31], 1
	s_waitcnt vmcnt(0) lgkmcnt(0)
	v_mul_f32_e64 v0, v0, v4
	v_mul_f32_e64 v1, v1, v4
	v_add_u32_e32 v5, 0x30c0, v47
	s_add_u32 s26, s26, s28
	ds_write2_b32 v5, v0, v1 offset1:1
	v_mul_f32_e64 v0, v2, v4
	v_mul_f32_e64 v1, v3, v4
	v_add_u32_e32 v2, 0x30c8, v47
	s_addc_u32 s27, s27, s29
	v_add_u32_e32 v4, s24, v17
	ds_write2_b32 v2, v0, v1 offset1:1
	v_lshl_add_u64 v[0:1], s[26:27], 0, v[32:33]
	v_cmp_gt_i32_e32 vcc, s44, v4
	s_waitcnt lgkmcnt(0)
	s_barrier
	s_and_saveexec_b64 s[26:27], vcc
	s_cbranch_execz .LBB0_835
	ds_read2_b32 v[2:3], v24 offset1:65
	s_cmp_lt_i32 s43, 2
	s_mov_b64 s[28:29], -1
	s_cbranch_scc1 .LBB0_825
	s_cmp_gt_i32 s43, 2
	v_lshlrev_b32_e32 v6, 1, v4
	s_cbranch_scc0 .LBB0_822
	v_and_or_b32 v5, v6, s85, v40
	s_mov_b64 s[28:29], 0

; DI u32x2 pack4(float a, float b, float c, float d) { u32x2 w; w.x = pack2(a, b); w.y = pack2(c, d); return w; }
;   DI void operator()(const f32x16 (&acc)[4][2], bool vt, int row0, int col0, int r, int h, const float*, float*) const {
;     ...
;     for (int mi = 0; mi < 4; ++mi) {
;       if (tr) {
; #pragma unroll
;         for (int g = 0; g < 4; ++g) {
;           const int R = row0 + mi * 32 + 8 * g + 4 * h, bg = R >> 8, n = R & 255;
; #pragma unroll
;           for (int ni = 0; ni < 2; ++ni) {
;             const float bv = sBias[ni * 32 + r];
;             float v[4];
; #pragma unroll
;             for (int q = 0; q < 4; ++q) v[q] = (n + q == 255) ? 0.f : acc[mi][ni][4 * g + q] + bv;
;             *(u32x2*)(dst + ((size_t)bg * 64 + ni * 32 + r) * 256 + n) = pack4(v[0], v[1], v[2], v[3]);
;           }
;         }
;       } else {
;         const int R = row0 + mi * 32 + r, bg = R >> 8, n = R & 255;
; #pragma unroll
;         for (int ni = 0; ni < 2; ++ni)
; #pragma unroll
;           for (int g = 0; g < 4; ++g) {
;             const int d0 = ni * 32 + 8 * g + 4 * h;
;             float v[4];
; #pragma unroll
;             for (int q = 0; q < 4; ++q) v[q] = (n == 255) ? 0.f : acc[mi][ni][4 * g + q] + sBias[d0 + q];
;             *(u32x2*)(dst + ((size_t)bg * 256 + n) * 64 + d0) = pack4(v[0], v[1], v[2], v[3]);
;           }
.LBB0_968:
	s_and_b64 s[4:5], s[4:5], exec
	v_and_b32_e32 v32, 0xffffff80, v154
	s_mov_b32 s4, 0xd516000
	v_lshl_add_u32 v132, s8, 8, v32
	v_lshlrev_b32_e32 v140, 2, v155
	s_cselect_b32 s4, s4, 0xd556000
	v_or_b32_e32 v143, v140, v132
	s_add_u32 s4, s0, s4
	v_ashrrev_i32_e32 v134, 8, v132
	v_cndmask_b32_e64 v32, 0, 1, s[2:3]
	v_lshlrev_b32_e32 v133, 2, v131
	v_lshlrev_b32_e32 v136, 1, v143
	s_addc_u32 s5, s1, 0
	s_mov_b64 s[8:9], -1
	v_cmp_ne_u32_e64 s[0:1], 1, v32
	s_andn2_b64 vcc, exec, s[2:3]
	v_ashrrev_i32_e32 v135, 31, v134
	v_or_b32_e32 v142, 0x12000, v133
	v_lshlrev_b32_e32 v32, 9, v131
	v_and_b32_e32 v136, 0x108, v136
	v_or_b32_e32 v141, 0x12080, v133
	s_cbranch_vccnz .LBB0_970
	s_waitcnt vmcnt(0)
	ds_read_b32 v138, v142
	v_mov_b32_e32 v137, v33
	s_mov_b64 s[2:3], 0x4000
	s_mov_b64 s[8:9], 0
	s_waitcnt lgkmcnt(0)
	v_add_f32_e64 v144, v114, v138
	v_add_f32_e64 v145, v115, v138
	v_add_f32_e64 v139, v117, v138
	v_add_f32_e64 v138, v116, v138
	v_cvt_pk_bf16_f32 v144, v144, v145
	v_cvt_pk_bf16_f32 v145, v138, v139
	v_lshlrev_b64 v[138:139], 15, v[134:135]
	v_lshl_add_u64 v[138:139], s[4:5], 0, v[138:139]
	v_lshl_add_u64 v[138:139], v[138:139], 0, v[32:33]
	v_lshl_add_u64 v[146:147], v[138:139], 0, v[136:137]
	flat_store_dwordx2 v[146:147], v[144:145]
	ds_read_b32 v144, v141
	v_lshl_add_u64 v[138:139], v[138:139], 0, s[2:3]
	s_waitcnt lgkmcnt(0)
	v_add_f32_e64 v148, v98, v144
	v_add_f32_e64 v149, v99, v144
	v_add_f32_e64 v145, v101, v144
	v_add_f32_e64 v144, v100, v144
	v_cvt_pk_bf16_f32 v148, v148, v149
	v_cvt_pk_bf16_f32 v149, v144, v145
	v_lshl_add_u64 v[144:145], v[138:139], 0, v[136:137]
	flat_store_dwordx2 v[144:145], v[148:149]
	ds_read_b32 v144, v142
	s_waitcnt lgkmcnt(0)
	v_add_f32_e64 v148, v118, v144
	v_add_f32_e64 v149, v119, v144
	v_add_f32_e64 v145, v121, v144
	v_add_f32_e64 v144, v120, v144
	v_cvt_pk_bf16_f32 v148, v148, v149
	v_cvt_pk_bf16_f32 v149, v144, v145
	flat_store_dwordx2 v[146:147], v[148:149] offset:16
	ds_read_b32 v144, v141
	s_waitcnt lgkmcnt(0)
	v_add_f32_e64 v148, v102, v144
	v_add_f32_e64 v149, v103, v144
	v_add_f32_e64 v145, v105, v144
	v_add_f32_e64 v144, v104, v144
	v_cvt_pk_bf16_f32 v148, v148, v149
	v_cvt_pk_bf16_f32 v149, v144, v145
	v_or_b32_e32 v144, 16, v136
	v_mov_b32_e32 v145, v33
	v_lshl_add_u64 v[144:145], v[138:139], 0, v[144:145]
	flat_store_dwordx2 v[144:145], v[148:149]
	ds_read_b32 v144, v142
	s_waitcnt lgkmcnt(0)
	v_add_f32_e64 v148, v122, v144
	v_add_f32_e64 v149, v123, v144
	v_add_f32_e64 v145, v125, v144
	v_add_f32_e64 v144, v124, v144
	v_cvt_pk_bf16_f32 v148, v148, v149
	v_cvt_pk_bf16_f32 v149, v144, v145
	flat_store_dwordx2 v[146:147], v[148:149] offset:32
	ds_read_b32 v144, v141
	s_waitcnt lgkmcnt(0)
	v_add_f32_e64 v148, v106, v144
	v_add_f32_e64 v149, v107, v144
	v_add_f32_e64 v145, v109, v144
	v_add_f32_e64 v144, v108, v144
	v_cvt_pk_bf16_f32 v148, v148, v149
	v_cvt_pk_bf16_f32 v149, v144, v145
	v_or_b32_e32 v144, 32, v136
	v_mov_b32_e32 v145, v33
	v_lshl_add_u64 v[144:145], v[138:139], 0, v[144:145]
	flat_store_dwordx2 v[144:145], v[148:149]
	ds_read_b32 v144, v142
	s_waitcnt lgkmcnt(0)
	v_add_f32_e64 v148, v126, v144
	v_add_f32_e64 v149, v127, v144
	v_add_f32_e64 v145, v129, v144
	v_add_f32_e64 v144, v128, v144
	v_cvt_pk_bf16_f32 v148, v148, v149
	v_cvt_pk_bf16_f32 v149, v144, v145
	flat_store_dwordx2 v[146:147], v[148:149] offset:48
	ds_read_b32 v144, v141
	s_waitcnt lgkmcnt(0)
	v_add_f32_e64 v146, v110, v144
	v_add_f32_e64 v147, v111, v144
	v_add_f32_e64 v145, v113, v144
	v_add_f32_e64 v144, v112, v144
	v_cvt_pk_bf16_f32 v146, v146, v147
	v_cvt_pk_bf16_f32 v147, v144, v145
	v_or_b32_e32 v144, 48, v136
	v_mov_b32_e32 v145, v33
	v_lshl_add_u64 v[138:139], v[138:139], 0, v[144:145]
	flat_store_dwordx2 v[138:139], v[146:147]
.LBB0_970:
	v_or_b32_e32 v131, v132, v131
	v_lshlrev_b32_e32 v133, 7, v131
	s_andn2_b64 vcc, exec, s[8:9]
	v_lshlrev_b32_e32 v132, 1, v140
	v_and_b32_e32 v138, 0x4f80, v133
	s_cbranch_vccnz .LBB0_972
	v_lshlrev_b32_e32 v137, 2, v140
	v_or_b32_e32 v133, 0x12000, v137
	s_waitcnt vmcnt(0)
	ds_read_b128 v[144:147], v133
	v_lshlrev_b64 v[148:149], 15, v[134:135]
	v_lshl_add_u64 v[148:149], s[4:5], 0, v[148:149]
	v_mov_b32_e32 v139, v33
	v_mov_b32_e32 v133, v33
	s_waitcnt lgkmcnt(0)
	v_add_f32_e64 v114, v114, v144
	v_add_f32_e64 v115, v115, v145
	v_add_f32_e64 v116, v116, v146
	v_add_f32_e64 v117, v117, v147
	v_cvt_pk_bf16_f32 v114, v114, v115
	v_cvt_pk_bf16_f32 v115, v116, v117
	v_lshl_add_u64 v[116:117], v[148:149], 0, v[138:139]
	v_lshl_add_u64 v[144:145], v[116:117], 0, v[132:133]
	flat_store_dwordx2 v[144:145], v[114:115]
	v_or_b32_e32 v114, 0x12020, v137
	ds_read_b128 v[114:117], v114
	s_waitcnt lgkmcnt(0)
	v_add_f32_e64 v114, v118, v114
	v_add_f32_e64 v115, v119, v115
	v_add_f32_e64 v116, v120, v116
	v_add_f32_e64 v117, v121, v117
	v_cvt_pk_bf16_f32 v114, v114, v115
	v_cvt_pk_bf16_f32 v115, v116, v117
	flat_store_dwordx2 v[144:145], v[114:115] offset:16
	v_or_b32_e32 v114, 0x12040, v137
	ds_read_b128 v[114:117], v114
	s_waitcnt lgkmcnt(0)
	v_add_f32_e64 v114, v122, v114
	v_add_f32_e64 v115, v123, v115
	v_add_f32_e64 v116, v124, v116
	v_add_f32_e64 v117, v125, v117
	v_cvt_pk_bf16_f32 v114, v114, v115
	v_cvt_pk_bf16_f32 v115, v116, v117
	flat_store_dwordx2 v[144:145], v[114:115] offset:32
	v_or_b32_e32 v114, 0x12060, v137
	ds_read_b128 v[114:117], v114
	s_waitcnt lgkmcnt(0)
	v_add_f32_e64 v114, v126, v114
	v_add_f32_e64 v115, v127, v115
	v_add_f32_e64 v116, v128, v116
	v_add_f32_e64 v117, v129, v117
	v_cvt_pk_bf16_f32 v114, v114, v115
	v_cvt_pk_bf16_f32 v115, v116, v117
	flat_store_dwordx2 v[144:145], v[114:115] offset:48
	v_or_b32_e32 v114, 0x12080, v137
	ds_read_b128 v[114:117], v114
	s_waitcnt lgkmcnt(0)
	v_add_f32_e64 v98, v98, v114
	v_add_f32_e64 v99, v99, v115
	v_add_f32_e64 v100, v100, v116
	v_add_f32_e64 v101, v101, v117
	v_cvt_pk_bf16_f32 v98, v98, v99
	v_cvt_pk_bf16_f32 v99, v100, v101
	flat_store_dwordx2 v[144:145], v[98:99] offset:64
	v_or_b32_e32 v98, 0x120a0, v137
	ds_read_b128 v[98:101], v98
	v_or_b32_e32 v114, 0x120c0, v137
	s_waitcnt lgkmcnt(0)
	v_add_f32_e64 v98, v102, v98
	v_add_f32_e64 v99, v103, v99
	v_add_f32_e64 v100, v104, v100
	v_add_f32_e64 v101, v105, v101
	v_cvt_pk_bf16_f32 v98, v98, v99
	v_cvt_pk_bf16_f32 v99, v100, v101
	flat_store_dwordx2 v[144:145], v[98:99] offset:80
	ds_read_b128 v[98:101], v114
	v_or_b32_e32 v102, 0x120e0, v137
	s_waitcnt lgkmcnt(0)
	v_add_f32_e64 v98, v106, v98
	v_add_f32_e64 v99, v107, v99
	v_add_f32_e64 v100, v108, v100
	v_add_f32_e64 v101, v109, v101
	v_cvt_pk_bf16_f32 v98, v98, v99
	v_cvt_pk_bf16_f32 v99, v100, v101
	flat_store_dwordx2 v[144:145], v[98:99] offset:96
	ds_read_b128 v[98:101], v102
	s_waitcnt lgkmcnt(0)
	v_add_f32_e64 v98, v110, v98
	v_add_f32_e64 v99, v111, v99
	v_add_f32_e64 v100, v112, v100
	v_add_f32_e64 v101, v113, v101
	v_cvt_pk_bf16_f32 v98, v98, v99
	v_cvt_pk_bf16_f32 v99, v100, v101
	flat_store_dwordx2 v[144:145], v[98:99] offset:112
; DI u32x2 pack4(float a, float b, float c, float d) { u32x2 w; w.x = pack2(a, b); w.y = pack2(c, d); return w; }
;   DI void operator()(const f32x16 (&acc)[4][2], bool vt, int row0, int col0, int r, int h, const float*, float*) const {
;     ...
;       if (tr) {
; #pragma unroll
;         for (int g = 0; g < 4; ++g) {
;           const int R = row0 + mi * 32 + 8 * g + 4 * h, bg = R >> 8, n = R & 255;
; #pragma unroll
;           for (int ni = 0; ni < 2; ++ni) {
;             const float bv = sBias[ni * 32 + r];
;             float v[4];
; #pragma unroll
;             for (int q = 0; q < 4; ++q) v[q] = (n + q == 255) ? 0.f : acc[mi][ni][4 * g + q] + bv;
;             *(u32x2*)(dst + ((size_t)bg * 64 + ni * 32 + r) * 256 + n) = pack4(v[0], v[1], v[2], v[3]);
;           }
;         }
.LBB0_972:
	s_and_b64 vcc, exec, s[0:1]
	s_mov_b64 s[2:3], -1
	s_cbranch_vccnz .LBB0_974
	s_waitcnt vmcnt(0)
	ds_read_b32 v98, v142
	v_lshlrev_b64 v[100:101], 15, v[134:135]
	v_lshl_add_u64 v[100:101], s[4:5], 0, v[100:101]
	v_mov_b32_e32 v137, v33
	s_mov_b64 s[2:3], 0x4000
	s_waitcnt lgkmcnt(0)
	v_add_f32_e64 v102, v82, v98
	v_add_f32_e64 v103, v83, v98
	v_add_f32_e64 v99, v85, v98
	v_add_f32_e64 v98, v84, v98
	v_cvt_pk_bf16_f32 v102, v102, v103
	v_cvt_pk_bf16_f32 v103, v98, v99
	v_lshl_add_u64 v[98:99], v[100:101], 0, v[32:33]
	v_lshl_add_u64 v[100:101], v[98:99], 0, v[136:137]
	flat_store_dwordx2 v[100:101], v[102:103] offset:64
	ds_read_b32 v102, v141
	v_lshl_add_u64 v[98:99], v[98:99], 0, s[2:3]
	s_mov_b64 s[2:3], 0
	s_waitcnt lgkmcnt(0)
	v_add_f32_e64 v104, v66, v102
	v_add_f32_e64 v105, v67, v102
	v_add_f32_e64 v103, v69, v102
	v_add_f32_e64 v102, v68, v102
	v_cvt_pk_bf16_f32 v104, v104, v105
	v_cvt_pk_bf16_f32 v105, v102, v103
	v_or_b32_e32 v102, 64, v136
	v_mov_b32_e32 v103, v33
	v_lshl_add_u64 v[102:103], v[98:99], 0, v[102:103]
	flat_store_dwordx2 v[102:103], v[104:105]
	ds_read_b32 v102, v142
	s_waitcnt lgkmcnt(0)
	v_add_f32_e64 v104, v86, v102
	v_add_f32_e64 v105, v87, v102
	v_add_f32_e64 v103, v89, v102
	v_add_f32_e64 v102, v88, v102
	v_cvt_pk_bf16_f32 v104, v104, v105
	v_cvt_pk_bf16_f32 v105, v102, v103
	flat_store_dwordx2 v[100:101], v[104:105] offset:80
	ds_read_b32 v102, v141
	s_waitcnt lgkmcnt(0)
	v_add_f32_e64 v104, v70, v102
	v_add_f32_e64 v105, v71, v102
	v_add_f32_e64 v103, v73, v102
	v_add_f32_e64 v102, v72, v102
	v_cvt_pk_bf16_f32 v104, v104, v105
	v_cvt_pk_bf16_f32 v105, v102, v103
	v_or_b32_e32 v102, 0x50, v136
	v_mov_b32_e32 v103, v33
	v_lshl_add_u64 v[102:103], v[98:99], 0, v[102:103]
	flat_store_dwordx2 v[102:103], v[104:105]
	ds_read_b32 v102, v142
	s_waitcnt lgkmcnt(0)
	v_add_f32_e64 v104, v90, v102
	v_add_f32_e64 v105, v91, v102
	v_add_f32_e64 v103, v93, v102
	v_add_f32_e64 v102, v92, v102
	v_cvt_pk_bf16_f32 v104, v104, v105
	v_cvt_pk_bf16_f32 v105, v102, v103
	flat_store_dwordx2 v[100:101], v[104:105] offset:96
	ds_read_b32 v102, v141
	s_waitcnt lgkmcnt(0)
	v_add_f32_e64 v104, v74, v102
	v_add_f32_e64 v105, v75, v102
	v_add_f32_e64 v103, v77, v102
	v_add_f32_e64 v102, v76, v102
	v_cvt_pk_bf16_f32 v104, v104, v105
	v_cvt_pk_bf16_f32 v105, v102, v103
	v_or_b32_e32 v102, 0x60, v136
	v_mov_b32_e32 v103, v33
	v_lshl_add_u64 v[102:103], v[98:99], 0, v[102:103]
	flat_store_dwordx2 v[102:103], v[104:105]
	ds_read_b32 v102, v142
	s_waitcnt lgkmcnt(0)
	v_add_f32_e64 v104, v94, v102
	v_add_f32_e64 v105, v95, v102
	v_add_f32_e64 v103, v97, v102
	v_add_f32_e64 v102, v96, v102
	v_cvt_pk_bf16_f32 v104, v104, v105
	v_cvt_pk_bf16_f32 v105, v102, v103
	flat_store_dwordx2 v[100:101], v[104:105] offset:112
	ds_read_b32 v100, v141
	v_or_b32_e32 v102, 0x70, v136
	v_mov_b32_e32 v103, v33
	v_lshl_add_u64 v[98:99], v[98:99], 0, v[102:103]
	s_waitcnt lgkmcnt(0)
	v_add_f32_e64 v104, v78, v100
	v_add_f32_e64 v105, v79, v100
	v_add_f32_e64 v101, v81, v100
	v_add_f32_e64 v100, v80, v100
	v_cvt_pk_bf16_f32 v104, v104, v105
	v_cvt_pk_bf16_f32 v105, v100, v101
	flat_store_dwordx2 v[98:99], v[104:105]
; DI u32x2 pack4(float a, float b, float c, float d) { u32x2 w; w.x = pack2(a, b); w.y = pack2(c, d); return w; }
;   DI void operator()(const f32x16 (&acc)[4][2], bool vt, int row0, int col0, int r, int h, const float*, float*) const {
;     ...
;       } else {
;         const int R = row0 + mi * 32 + r, bg = R >> 8, n = R & 255;
; #pragma unroll
;         for (int ni = 0; ni < 2; ++ni)
; #pragma unroll
;           for (int g = 0; g < 4; ++g) {
;             const int d0 = ni * 32 + 8 * g + 4 * h;
;             float v[4];
; #pragma unroll
;             for (int q = 0; q < 4; ++q) v[q] = (n == 255) ? 0.f : acc[mi][ni][4 * g + q] + sBias[d0 + q];
;             *(u32x2*)(dst + ((size_t)bg * 256 + n) * 64 + d0) = pack4(v[0], v[1], v[2], v[3]);
;           }
.LBB0_974:
	s_waitcnt vmcnt(0)
	v_or_b32_e32 v118, 8, v140
	v_or_b32_e32 v117, 16, v140
	v_or_b32_e32 v116, 24, v140
	v_or_b32_e32 v115, 32, v140
	v_or_b32_e32 v114, 40, v140
	v_or_b32_e32 v113, 48, v140
	v_or_b32_e32 v112, 56, v140
	s_andn2_b64 vcc, exec, s[2:3]
	v_lshlrev_b32_e32 v110, 1, v118
	v_lshlrev_b32_e32 v108, 1, v117
	v_lshlrev_b32_e32 v106, 1, v116
	v_lshlrev_b32_e32 v104, 1, v115
	v_lshlrev_b32_e32 v102, 1, v114
	v_lshlrev_b32_e32 v100, 1, v113
	v_lshlrev_b32_e32 v98, 1, v112
	s_cbranch_vccnz .LBB0_1048
	v_lshl_or_b32 v99, v140, 2, v210
	ds_read_b128 v[120:123], v99
	v_lshlrev_b64 v[124:125], 15, v[134:135]
	v_lshl_add_u64 v[124:125], s[4:5], 0, v[124:125]
	v_mov_b32_e32 v139, v33
	s_mov_b64 s[2:3], 0x1000
	s_waitcnt lgkmcnt(0)
	v_add_f32_e64 v82, v82, v120
	v_add_f32_e64 v83, v83, v121
	v_add_f32_e64 v84, v84, v122
	v_add_f32_e64 v85, v85, v123
	v_cvt_pk_bf16_f32 v82, v82, v83
	v_cvt_pk_bf16_f32 v83, v84, v85
	v_lshl_add_u64 v[84:85], v[124:125], 0, v[138:139]
	v_lshl_add_u64 v[120:121], v[84:85], 0, s[2:3]
	v_mov_b32_e32 v133, v33
	v_lshl_add_u64 v[84:85], v[120:121], 0, v[132:133]
	flat_store_dwordx2 v[84:85], v[82:83]
	v_lshl_or_b32 v82, v118, 2, v210
	ds_read_b128 v[82:85], v82
	v_mov_b32_e32 v111, v33
	v_mov_b32_e32 v109, v33
	v_mov_b32_e32 v107, v33
	v_mov_b32_e32 v105, v33
	s_waitcnt lgkmcnt(0)
	v_add_f32_e64 v82, v86, v82
	v_add_f32_e64 v83, v87, v83
	v_add_f32_e64 v84, v88, v84
	v_add_f32_e64 v85, v89, v85
	v_cvt_pk_bf16_f32 v82, v82, v83
	v_cvt_pk_bf16_f32 v83, v84, v85
	v_lshl_add_u64 v[84:85], v[120:121], 0, v[110:111]
	flat_store_dwordx2 v[84:85], v[82:83]
	v_lshl_or_b32 v82, v117, 2, v210
	ds_read_b128 v[82:85], v82
	v_mov_b32_e32 v103, v33
	v_mov_b32_e32 v101, v33
	v_mov_b32_e32 v99, v33
	s_waitcnt lgkmcnt(0)
	v_add_f32_e64 v82, v90, v82
	v_add_f32_e64 v83, v91, v83
	v_add_f32_e64 v84, v92, v84
	v_add_f32_e64 v85, v93, v85
	v_cvt_pk_bf16_f32 v82, v82, v83
	v_cvt_pk_bf16_f32 v83, v84, v85
	v_lshl_add_u64 v[84:85], v[120:121], 0, v[108:109]
	flat_store_dwordx2 v[84:85], v[82:83]
	v_lshl_or_b32 v82, v116, 2, v210
	ds_read_b128 v[82:85], v82
	s_waitcnt lgkmcnt(0)
	v_add_f32_e64 v82, v94, v82
	v_add_f32_e64 v83, v95, v83
	v_add_f32_e64 v84, v96, v84
	v_add_f32_e64 v85, v97, v85
	v_cvt_pk_bf16_f32 v82, v82, v83
	v_cvt_pk_bf16_f32 v83, v84, v85
	v_lshl_add_u64 v[84:85], v[120:121], 0, v[106:107]
	flat_store_dwordx2 v[84:85], v[82:83]
	v_lshl_or_b32 v82, v115, 2, v210
	ds_read_b128 v[82:85], v82
	s_waitcnt lgkmcnt(0)
	v_add_f32_e64 v66, v66, v82
	v_add_f32_e64 v67, v67, v83
	v_add_f32_e64 v68, v68, v84
	v_add_f32_e64 v69, v69, v85
	v_cvt_pk_bf16_f32 v66, v66, v67
	v_cvt_pk_bf16_f32 v67, v68, v69
	v_lshl_add_u64 v[68:69], v[120:121], 0, v[104:105]
	flat_store_dwordx2 v[68:69], v[66:67]
	v_lshl_or_b32 v66, v114, 2, v210
	ds_read_b128 v[66:69], v66
	s_waitcnt lgkmcnt(0)
	v_add_f32_e64 v66, v70, v66
	v_add_f32_e64 v67, v71, v67
	v_add_f32_e64 v68, v72, v68
	v_add_f32_e64 v69, v73, v69
	v_cvt_pk_bf16_f32 v66, v66, v67
	v_cvt_pk_bf16_f32 v67, v68, v69
	v_lshl_add_u64 v[68:69], v[120:121], 0, v[102:103]
	flat_store_dwordx2 v[68:69], v[66:67]
	v_lshl_or_b32 v66, v113, 2, v210
	ds_read_b128 v[66:69], v66
	s_waitcnt lgkmcnt(0)
	v_add_f32_e64 v66, v74, v66
	v_add_f32_e64 v67, v75, v67
	v_add_f32_e64 v68, v76, v68
	v_add_f32_e64 v69, v77, v69
	v_cvt_pk_bf16_f32 v66, v66, v67
	v_cvt_pk_bf16_f32 v67, v68, v69
	v_lshl_add_u64 v[68:69], v[120:121], 0, v[100:101]
	flat_store_dwordx2 v[68:69], v[66:67]
	v_lshl_or_b32 v66, v112, 2, v210
	ds_read_b128 v[66:69], v66
	s_waitcnt lgkmcnt(0)
	v_add_f32_e64 v66, v78, v66
	v_add_f32_e64 v67, v79, v67
	v_add_f32_e64 v68, v80, v68
	v_add_f32_e64 v69, v81, v69
	v_cvt_pk_bf16_f32 v66, v66, v67
	v_cvt_pk_bf16_f32 v67, v68, v69
	v_lshl_add_u64 v[68:69], v[120:121], 0, v[98:99]
	flat_store_dwordx2 v[68:69], v[66:67]
	s_and_b64 vcc, exec, s[0:1]
	s_mov_b64 s[2:3], -1
	s_cbranch_vccz .LBB0_1049

; DI u32x2 pack4(float a, float b, float c, float d) { u32x2 w; w.x = pack2(a, b); w.y = pack2(c, d); return w; }
;   DI void operator()(const f32x16 (&acc)[4][2], bool vt, int row0, int col0, int r, int h, const float*, float*) const {
;     ...
;     for (int mi = 0; mi < 4; ++mi) {
;       if (tr) {
; #pragma unroll
;         for (int g = 0; g < 4; ++g) {
;           const int R = row0 + mi * 32 + 8 * g + 4 * h, bg = R >> 8, n = R & 255;
; #pragma unroll
;           for (int ni = 0; ni < 2; ++ni) {
;             const float bv = sBias[ni * 32 + r];
;             float v[4];
; #pragma unroll
;             for (int q = 0; q < 4; ++q) v[q] = (n + q == 255) ? 0.f : acc[mi][ni][4 * g + q] + bv;
;             *(u32x2*)(dst + ((size_t)bg * 64 + ni * 32 + r) * 256 + n) = pack4(v[0], v[1], v[2], v[3]);
;           }
;         }
;       } else {
;         const int R = row0 + mi * 32 + r, bg = R >> 8, n = R & 255;
; #pragma unroll
;         for (int ni = 0; ni < 2; ++ni)
; #pragma unroll
;           for (int g = 0; g < 4; ++g) {
;             const int d0 = ni * 32 + 8 * g + 4 * h;
;             float v[4];
; #pragma unroll
;             for (int q = 0; q < 4; ++q) v[q] = (n == 255) ? 0.f : acc[mi][ni][4 * g + q] + sBias[d0 + q];
;             *(u32x2*)(dst + ((size_t)bg * 256 + n) * 64 + d0) = pack4(v[0], v[1], v[2], v[3]);
;           }
.LBB0_977:
	v_lshl_or_b32 v66, v140, 2, v210
	ds_read_b128 v[66:69], v66
	v_lshlrev_b64 v[70:71], 15, v[134:135]
	v_lshl_add_u64 v[70:71], s[4:5], 0, v[70:71]
	v_mov_b32_e32 v139, v33
	v_mov_b32_e32 v133, v33
	s_waitcnt lgkmcnt(0)
	v_add_f32_e64 v50, v50, v66
	v_add_f32_e64 v51, v51, v67
	v_add_f32_e64 v52, v52, v68
	v_add_f32_e64 v53, v53, v69
	v_cvt_pk_bf16_f32 v50, v50, v51
	v_cvt_pk_bf16_f32 v51, v52, v53
	v_lshl_add_u64 v[52:53], v[70:71], 0, v[138:139]
	v_lshl_add_u64 v[66:67], v[52:53], 0, s[68:69]
	v_lshl_add_u64 v[52:53], v[66:67], 0, v[132:133]
	flat_store_dwordx2 v[52:53], v[50:51]
	v_lshl_or_b32 v50, v118, 2, v210
	ds_read_b128 v[50:53], v50
	v_mov_b32_e32 v111, v33
	v_mov_b32_e32 v109, v33
	v_mov_b32_e32 v107, v33
	v_mov_b32_e32 v105, v33
	s_waitcnt lgkmcnt(0)
	v_add_f32_e64 v50, v54, v50
	v_add_f32_e64 v51, v55, v51
	v_add_f32_e64 v52, v56, v52
	v_add_f32_e64 v53, v57, v53
	v_cvt_pk_bf16_f32 v50, v50, v51
	v_cvt_pk_bf16_f32 v51, v52, v53
	v_lshl_add_u64 v[52:53], v[66:67], 0, v[110:111]
	flat_store_dwordx2 v[52:53], v[50:51]
	v_lshl_or_b32 v50, v117, 2, v210
	ds_read_b128 v[50:53], v50
	v_mov_b32_e32 v103, v33
	v_mov_b32_e32 v101, v33
	v_mov_b32_e32 v99, v33
	s_waitcnt lgkmcnt(0)
	v_add_f32_e64 v50, v58, v50
	v_add_f32_e64 v51, v59, v51
	v_add_f32_e64 v52, v60, v52
	v_add_f32_e64 v53, v61, v53
	v_cvt_pk_bf16_f32 v50, v50, v51
	v_cvt_pk_bf16_f32 v51, v52, v53
	v_lshl_add_u64 v[52:53], v[66:67], 0, v[108:109]
	flat_store_dwordx2 v[52:53], v[50:51]
	v_lshl_or_b32 v50, v116, 2, v210
	ds_read_b128 v[50:53], v50
	s_waitcnt lgkmcnt(0)
	v_add_f32_e64 v50, v62, v50
	v_add_f32_e64 v51, v63, v51
	v_add_f32_e64 v52, v64, v52
	v_add_f32_e64 v53, v65, v53
	v_cvt_pk_bf16_f32 v50, v50, v51
	v_cvt_pk_bf16_f32 v51, v52, v53
	v_lshl_add_u64 v[52:53], v[66:67], 0, v[106:107]
	flat_store_dwordx2 v[52:53], v[50:51]
	v_lshl_or_b32 v50, v115, 2, v210
	ds_read_b128 v[50:53], v50
	s_waitcnt lgkmcnt(0)
	v_add_f32_e64 v34, v34, v50
	v_add_f32_e64 v35, v35, v51
	v_add_f32_e64 v36, v36, v52
	v_add_f32_e64 v37, v37, v53
	v_cvt_pk_bf16_f32 v34, v34, v35
	v_cvt_pk_bf16_f32 v35, v36, v37
	v_lshl_add_u64 v[36:37], v[66:67], 0, v[104:105]
	flat_store_dwordx2 v[36:37], v[34:35]
	v_lshl_or_b32 v34, v114, 2, v210
	ds_read_b128 v[34:37], v34
	s_waitcnt lgkmcnt(0)
	v_add_f32_e64 v34, v38, v34
	v_add_f32_e64 v35, v39, v35
	v_add_f32_e64 v36, v40, v36
	v_add_f32_e64 v37, v41, v37
	v_cvt_pk_bf16_f32 v34, v34, v35
	v_cvt_pk_bf16_f32 v35, v36, v37
	v_lshl_add_u64 v[36:37], v[66:67], 0, v[102:103]
	flat_store_dwordx2 v[36:37], v[34:35]
	v_lshl_or_b32 v34, v113, 2, v210
	ds_read_b128 v[34:37], v34
	s_waitcnt lgkmcnt(0)
	v_add_f32_e64 v34, v42, v34
	v_add_f32_e64 v35, v43, v35
	v_add_f32_e64 v36, v44, v36
	v_add_f32_e64 v37, v45, v37
	v_cvt_pk_bf16_f32 v34, v34, v35
	v_cvt_pk_bf16_f32 v35, v36, v37
	v_lshl_add_u64 v[36:37], v[66:67], 0, v[100:101]
	flat_store_dwordx2 v[36:37], v[34:35]
	v_lshl_or_b32 v34, v112, 2, v210
	ds_read_b128 v[34:37], v34
	s_waitcnt lgkmcnt(0)
	v_add_f32_e64 v34, v46, v34
	v_add_f32_e64 v35, v47, v35
	v_add_f32_e64 v36, v48, v36
	v_add_f32_e64 v37, v49, v37
	v_cvt_pk_bf16_f32 v34, v34, v35
	v_cvt_pk_bf16_f32 v35, v36, v37
	v_lshl_add_u64 v[36:37], v[66:67], 0, v[98:99]
	flat_store_dwordx2 v[36:37], v[34:35]
.LBB0_978:
	v_lshlrev_b64 v[34:35], 15, v[134:135]
	s_mov_b64 s[2:3], -1
	s_and_b64 vcc, exec, s[0:1]
	v_lshl_add_u64 v[34:35], s[4:5], 0, v[34:35]
	s_cbranch_vccnz .LBB0_980
	ds_read_b32 v36, v142
	v_and_b32_e32 v44, 0x84, v143
	s_mov_b64 s[0:1], 0x4000
	s_mov_b64 s[2:3], 0
	s_waitcnt lgkmcnt(0)
	v_add_f32_e64 v38, v16, v36
	v_add_f32_e64 v39, v17, v36
	v_add_f32_e64 v37, v19, v36
	v_add_f32_e64 v36, v18, v36
	v_cvt_pk_bf16_f32 v38, v38, v39
	v_cvt_pk_bf16_f32 v39, v36, v37
	v_lshl_add_u64 v[36:37], v[34:35], 0, v[32:33]
	v_lshlrev_b32_e32 v32, 1, v44
	v_lshl_add_u64 v[40:41], v[36:37], 0, v[32:33]
	flat_store_dwordx2 v[40:41], v[38:39] offset:192
	ds_read_b32 v38, v141
	v_lshl_add_u64 v[36:37], v[36:37], 0, s[0:1]
	s_movk_i32 s0, 0x84
	v_cmp_eq_u32_e32 vcc, s0, v44
	s_waitcnt lgkmcnt(0)
	v_add_f32_e64 v42, v0, v38
	v_add_f32_e64 v43, v1, v38
	v_add_f32_e64 v39, v3, v38
	v_add_f32_e64 v38, v2, v38
	v_cvt_pk_bf16_f32 v42, v42, v43
	v_cvt_pk_bf16_f32 v43, v38, v39
	v_or_b32_e32 v38, 0xc0, v32
	v_mov_b32_e32 v39, v33
	v_lshl_add_u64 v[38:39], v[36:37], 0, v[38:39]
	flat_store_dwordx2 v[38:39], v[42:43]
	ds_read_b32 v38, v142
	s_waitcnt lgkmcnt(0)
	v_add_f32_e64 v42, v20, v38
	v_add_f32_e64 v43, v21, v38
	v_add_f32_e64 v39, v23, v38
	v_add_f32_e64 v38, v22, v38
	v_cvt_pk_bf16_f32 v42, v42, v43
	v_cvt_pk_bf16_f32 v43, v38, v39
	flat_store_dwordx2 v[40:41], v[42:43] offset:208
	ds_read_b32 v38, v141
	s_waitcnt lgkmcnt(0)
	v_add_f32_e64 v42, v4, v38
	v_add_f32_e64 v43, v5, v38
	v_add_f32_e64 v39, v7, v38
	v_add_f32_e64 v38, v6, v38
	v_cvt_pk_bf16_f32 v42, v42, v43
	v_cvt_pk_bf16_f32 v43, v38, v39
	v_or_b32_e32 v38, 0xd0, v32
	v_mov_b32_e32 v39, v33
	v_lshl_add_u64 v[38:39], v[36:37], 0, v[38:39]
	flat_store_dwordx2 v[38:39], v[42:43]
	ds_read_b32 v38, v142
	s_waitcnt lgkmcnt(0)
	v_add_f32_e64 v42, v24, v38
	v_add_f32_e64 v43, v25, v38
	v_add_f32_e64 v39, v27, v38
	v_add_f32_e64 v38, v26, v38
	v_cvt_pk_bf16_f32 v42, v42, v43
	v_cvt_pk_bf16_f32 v43, v38, v39
	flat_store_dwordx2 v[40:41], v[42:43] offset:224
	ds_read_b32 v38, v141
	s_waitcnt lgkmcnt(0)
	v_add_f32_e64 v42, v8, v38
	v_add_f32_e64 v43, v9, v38
	v_add_f32_e64 v39, v11, v38
	v_add_f32_e64 v38, v10, v38
	v_cvt_pk_bf16_f32 v42, v42, v43
	v_cvt_pk_bf16_f32 v43, v38, v39
	v_or_b32_e32 v38, 0xe0, v32
	v_mov_b32_e32 v39, v33
	v_lshl_add_u64 v[38:39], v[36:37], 0, v[38:39]
	flat_store_dwordx2 v[38:39], v[42:43]
	ds_read_b32 v38, v142
	v_or_b32_e32 v32, 0xf0, v32
	v_lshl_add_u64 v[36:37], v[36:37], 0, v[32:33]
	s_waitcnt lgkmcnt(0)
	v_add_f32_e64 v42, v28, v38
	v_add_f32_e64 v43, v29, v38
	v_add_f32_e32 v39, v30, v38
	v_add_f32_e32 v38, v31, v38
	v_cndmask_b32_e64 v44, v38, 0, vcc
	v_cvt_pk_bf16_f32 v38, v42, v43
	v_cvt_pk_bf16_f32 v39, v39, v44
	flat_store_dwordx2 v[40:41], v[38:39] offset:240
	ds_read_b32 v38, v141
	s_waitcnt lgkmcnt(0)
	v_add_f32_e64 v40, v12, v38
	v_add_f32_e64 v41, v13, v38
	v_add_f32_e32 v39, v14, v38
	v_add_f32_e32 v38, v15, v38
	v_cndmask_b32_e64 v42, v38, 0, vcc
	v_cvt_pk_bf16_f32 v38, v40, v41
	v_cvt_pk_bf16_f32 v39, v39, v42
	flat_store_dwordx2 v[36:37], v[38:39]

; DI u32x2 pack4(float a, float b, float c, float d) { u32x2 w; w.x = pack2(a, b); w.y = pack2(c, d); return w; }
;   DI void operator()(const f32x16 (&acc)[4][2], bool vt, int row0, int col0, int r, int h, const float*, float*) const {
;     ...
;       if (tr) {
; #pragma unroll
;         for (int g = 0; g < 4; ++g) {
;           const int R = row0 + mi * 32 + 8 * g + 4 * h, bg = R >> 8, n = R & 255;
; #pragma unroll
;           for (int ni = 0; ni < 2; ++ni) {
;             const float bv = sBias[ni * 32 + r];
;             float v[4];
; #pragma unroll
;             for (int q = 0; q < 4; ++q) v[q] = (n + q == 255) ? 0.f : acc[mi][ni][4 * g + q] + bv;
;             *(u32x2*)(dst + ((size_t)bg * 64 + ni * 32 + r) * 256 + n) = pack4(v[0], v[1], v[2], v[3]);
;           }
;         }
.LBB0_1049:
	ds_read_b32 v66, v142
	v_lshlrev_b64 v[68:69], 15, v[134:135]
	v_lshl_add_u64 v[68:69], s[4:5], 0, v[68:69]
	v_mov_b32_e32 v137, v33
	s_mov_b64 s[2:3], 0x4000
	s_waitcnt lgkmcnt(0)
	v_add_f32_e64 v70, v50, v66
	v_add_f32_e64 v71, v51, v66
	v_add_f32_e64 v67, v53, v66
	v_add_f32_e64 v66, v52, v66
	v_cvt_pk_bf16_f32 v70, v70, v71
	v_cvt_pk_bf16_f32 v71, v66, v67
	v_lshl_add_u64 v[66:67], v[68:69], 0, v[32:33]
	v_lshl_add_u64 v[68:69], v[66:67], 0, v[136:137]
	flat_store_dwordx2 v[68:69], v[70:71] offset:128
	ds_read_b32 v70, v141
	v_lshl_add_u64 v[66:67], v[66:67], 0, s[2:3]
	s_waitcnt lgkmcnt(0)
	v_add_f32_e64 v72, v34, v70
	v_add_f32_e64 v73, v35, v70
	v_add_f32_e64 v71, v37, v70
	v_add_f32_e64 v70, v36, v70
	v_cvt_pk_bf16_f32 v72, v72, v73
	v_cvt_pk_bf16_f32 v73, v70, v71
	v_or_b32_e32 v70, 0x80, v136
	v_mov_b32_e32 v71, v33
	v_lshl_add_u64 v[70:71], v[66:67], 0, v[70:71]
	flat_store_dwordx2 v[70:71], v[72:73]
	ds_read_b32 v70, v142
	s_waitcnt lgkmcnt(0)
	v_add_f32_e64 v72, v54, v70
	v_add_f32_e64 v73, v55, v70
	v_add_f32_e64 v71, v57, v70
	v_add_f32_e64 v70, v56, v70
	v_cvt_pk_bf16_f32 v72, v72, v73
	v_cvt_pk_bf16_f32 v73, v70, v71
	flat_store_dwordx2 v[68:69], v[72:73] offset:144
	ds_read_b32 v70, v141
	s_waitcnt lgkmcnt(0)
	v_add_f32_e64 v72, v38, v70
	v_add_f32_e64 v73, v39, v70
	v_add_f32_e64 v71, v41, v70
	v_add_f32_e64 v70, v40, v70
	v_cvt_pk_bf16_f32 v72, v72, v73
	v_cvt_pk_bf16_f32 v73, v70, v71
	v_or_b32_e32 v70, 0x90, v136
	v_mov_b32_e32 v71, v33
	v_lshl_add_u64 v[70:71], v[66:67], 0, v[70:71]
	flat_store_dwordx2 v[70:71], v[72:73]
	ds_read_b32 v70, v142
	s_waitcnt lgkmcnt(0)
	v_add_f32_e64 v72, v58, v70
	v_add_f32_e64 v73, v59, v70
	v_add_f32_e64 v71, v61, v70
	v_add_f32_e64 v70, v60, v70
	v_cvt_pk_bf16_f32 v72, v72, v73
	v_cvt_pk_bf16_f32 v73, v70, v71
	flat_store_dwordx2 v[68:69], v[72:73] offset:160
	ds_read_b32 v70, v141
	s_waitcnt lgkmcnt(0)
	v_add_f32_e64 v72, v42, v70
	v_add_f32_e64 v73, v43, v70
	v_add_f32_e64 v71, v45, v70
	v_add_f32_e64 v70, v44, v70
	v_cvt_pk_bf16_f32 v72, v72, v73
	v_cvt_pk_bf16_f32 v73, v70, v71
	v_or_b32_e32 v70, 0xa0, v136
	v_mov_b32_e32 v71, v33
	v_lshl_add_u64 v[70:71], v[66:67], 0, v[70:71]
	flat_store_dwordx2 v[70:71], v[72:73]
	ds_read_b32 v70, v142
	s_waitcnt lgkmcnt(0)
	v_add_f32_e64 v72, v62, v70
	v_add_f32_e64 v73, v63, v70
	v_add_f32_e64 v71, v65, v70
	v_add_f32_e64 v70, v64, v70
	v_cvt_pk_bf16_f32 v72, v72, v73
	v_cvt_pk_bf16_f32 v73, v70, v71
	flat_store_dwordx2 v[68:69], v[72:73] offset:176
	ds_read_b32 v68, v141
	v_or_b32_e32 v70, 0xb0, v136
	v_mov_b32_e32 v71, v33
	v_lshl_add_u64 v[66:67], v[66:67], 0, v[70:71]
	s_waitcnt lgkmcnt(0)
	v_add_f32_e64 v72, v46, v68
	v_add_f32_e64 v73, v47, v68
	v_add_f32_e64 v69, v49, v68
	v_add_f32_e64 v68, v48, v68
	v_cvt_pk_bf16_f32 v72, v72, v73
	v_cvt_pk_bf16_f32 v73, v68, v69
	flat_store_dwordx2 v[66:67], v[72:73]
	s_cbranch_execz .LBB0_977
	s_branch .LBB0_978

; DI unsigned pack2(float a, float b) { bf2_t v = __builtin_convertvector((f32x2){a, b}, bf2_t); return __builtin_bit_cast(unsigned, v); }
; DI int crow(int i, int h) { return (i & 3) + 8 * (i >> 2) + 4 * h; }
; DI void nsa_item(const Params& p_, const EvenBufs& eb_, int b, int g, int tt, unsigned char* smem) {
;     ...
;     l += shx32(l);
;     const float c = g1 / l;
; #pragma unroll
;     for (int dt = 0; dt < 2; ++dt)
; #pragma unroll
;       for (int i = 0; i < 16; ++i) acc[dt][i] += c * O[dt][i];
;   }
;   {
;     const bf16_t* Kg = eb.KW + (size_t)bg * S * 64;
;     const bf16_t* VTg = eb.VWT + (size_t)bg * 64 * SP;
;     m = NEG; l = 0.f; zero_o<2>(O);
;     const int lo0 = t0 - 511;
;     const int kt_lo = (lo0 > 0 ? lo0 : 0) >> 6, kt_hi = t0 >> 6;
;     TR_<2> kr, vr; tload(kr, Kg + (size_t)kt_lo * 64 * 64, 64, tid); tload(vr, VTg + kt_lo * 64, SP, tid);
;     for (int kt = kt_lo; kt <= kt_hi; ++kt) {
;       __syncthreads();
;       tstore72(kr, sK, tid); tstore68(vr, sV, tid);
;       __syncthreads();
;       if (kt < kt_hi) { tload(kr, Kg + (size_t)(kt + 1) * 64 * 64, 64, tid); tload(vr, VTg + (kt + 1) * 64, SP, tid); }
;       f32x16 Sx[2]; qk_tile(sK, qf, Sx, r, h);
;       const bool masked = !((kt * 64 + 63 <= t0) && (kt * 64 > t0 + 31 - 512));
;       unsigned vb = 0;
;       if (masked) {
; #pragma unroll
;         for (int mt = 0; mt < 2; ++mt)
; #pragma unroll
;           for (int i = 0; i < 16; ++i) {
;             const int key = kt * 64 + mt * 32 + crow(i, h);
;             vb |= (unsigned)((key <= t) && (key > t - 512)) << (mt * 16 + i);
;           }
;       }
;       if (!masked) vb = 0xffffffffu;
;       const float alpha = online_softmax_t<true>(Sx, vb, m, l);
;       scale_o<2>(O, alpha);
;       pv_tile<2>(sV, Sx, O, r, h);
;     }
;     l += shx32(l);
;     const float c = g2 / l;
; #pragma unroll
;     for (int dt = 0; dt < 2; ++dt)
; #pragma unroll
;       for (int i = 0; i < 16; ++i) acc[dt][i] += c * O[dt][i];
;   }
;   bf16_t* orow = (bf16_t*)(p.ws + OFF_HB) + (size_t)(b * S + t) * LDX + head * 64;
; #pragma unroll
;   for (int dt = 0; dt < 2; ++dt)
; #pragma unroll
;     for (int gg = 0; gg < 4; ++gg) {
;       u32x2 w; w.x = pack2(acc[dt][4 * gg], acc[dt][4 * gg + 1]); w.y = pack2(acc[dt][4 * gg + 2], acc[dt][4 * gg + 3]);
;       *(u32x2*)(orow + dt * 32 + 8 * gg + 4 * h) = w;
.LBB0_1057:
	s_waitcnt lgkmcnt(0)
	v_add_f32_e32 v32, v184, v185
	s_waitcnt vmcnt(7)
	v_div_scale_f32 v98, s[0:1], v32, v32, v163
	v_rcp_f32_e32 v99, v98
	v_readlane_b32 s66, v255, 14
	v_readlane_b32 s67, v255, 15
	s_mov_b32 s70, 0x8000
	v_fma_f32 v100, -v98, v99, 1.0
	v_fmac_f32_e32 v99, v100, v99
	v_div_scale_f32 v100, vcc, v163, v32, v163
	v_mul_f32_e32 v101, v100, v99
	s_waitcnt vmcnt(6)
	v_fma_f32 v102, -v98, v101, v100
	v_fmac_f32_e32 v101, v102, v99
	v_fma_f32 v98, -v98, v101, v100
	v_div_fmas_f32 v98, v98, v99, v101
	v_div_fixup_f32 v32, v98, v32, v163
	ds_bpermute_b32 v98, v169, v190
	v_mul_f32_e64 v34, v34, v32
	v_mul_f32_e64 v35, v35, v32
	v_mul_f32_e64 v50, v50, v32
	v_mul_f32_e64 v51, v51, v32
	v_fma_f32 v0, v162, v0, v34
	v_fma_f32 v1, v162, v1, v35
	v_mul_f32_e64 v34, v36, v32
	v_mul_f32_e64 v35, v37, v32
	s_waitcnt lgkmcnt(0)
	v_add_f32_e32 v98, v190, v98
	v_div_scale_f32 v99, s[0:1], v98, v98, v164
	v_rcp_f32_e32 v100, v99
	v_fma_f32 v2, v162, v2, v34
	v_fma_f32 v3, v162, v3, v35
	v_mul_f32_e64 v34, v38, v32
	v_mul_f32_e64 v35, v39, v32
	v_fma_f32 v16, v162, v16, v50
	v_fma_f32 v17, v162, v17, v51
	v_fma_f32 v4, v162, v4, v34
	v_fma_f32 v5, v162, v5, v35
	v_mul_f32_e64 v34, v40, v32
	v_mul_f32_e64 v35, v41, v32
	v_fma_f32 v101, -v99, v100, 1.0
	v_mul_f32_e64 v50, v52, v32
	v_mul_f32_e64 v51, v53, v32
	v_fma_f32 v6, v162, v6, v34
	v_fma_f32 v7, v162, v7, v35
	v_mul_f32_e64 v34, v42, v32
	v_mul_f32_e64 v35, v43, v32
	v_fmac_f32_e32 v100, v101, v100
	v_div_scale_f32 v101, vcc, v164, v98, v164
	v_fma_f32 v18, v162, v18, v50
	v_fma_f32 v19, v162, v19, v51
	v_mul_f32_e64 v50, v54, v32
	v_mul_f32_e64 v51, v55, v32
	v_fma_f32 v8, v162, v8, v34
	v_fma_f32 v9, v162, v9, v35
	v_mul_f32_e64 v34, v44, v32
	v_mul_f32_e64 v35, v45, v32
	v_mul_f32_e32 v102, v101, v100
	v_fma_f32 v20, v162, v20, v50
	v_fma_f32 v21, v162, v21, v51
	v_mul_f32_e64 v50, v56, v32
	v_mul_f32_e64 v51, v57, v32
	v_fma_f32 v10, v162, v10, v34
	v_fma_f32 v11, v162, v11, v35
	v_mul_f32_e64 v34, v46, v32
	v_mul_f32_e64 v35, v47, v32
	v_readlane_b32 s0, v255, 20
	v_fma_f32 v103, -v99, v102, v101
	v_fma_f32 v22, v162, v22, v50
	v_fma_f32 v23, v162, v23, v51
	v_mul_f32_e64 v50, v58, v32
	v_mul_f32_e64 v51, v59, v32
	v_fma_f32 v12, v162, v12, v34
	v_fma_f32 v13, v162, v13, v35
	v_mul_f32_e64 v34, v48, v32
	v_mul_f32_e64 v35, v49, v32
	v_readlane_b32 s1, v255, 21
	v_fmac_f32_e32 v102, v103, v100
	v_fma_f32 v24, v162, v24, v50
	v_fma_f32 v25, v162, v25, v51
	v_mul_f32_e64 v50, v60, v32
	v_mul_f32_e64 v51, v61, v32
	v_fma_f32 v14, v162, v14, v34
	v_fma_f32 v15, v162, v15, v35
	v_mov_b64_e32 v[34:35], s[0:1]
	v_lshlrev_b32_e32 v36, 6, v165
	v_fma_f32 v99, -v99, v102, v101
	v_fma_f32 v26, v162, v26, v50
	v_fma_f32 v27, v162, v27, v51
	v_mul_f32_e64 v50, v62, v32
	v_mul_f32_e64 v51, v63, v32
	v_mad_u64_u32 v[34:35], s[0:1], v166, s74, v[34:35]
	v_ashrrev_i32_e32 v37, 31, v36
	v_div_fmas_f32 v99, v99, v100, v102
	v_fma_f32 v28, v162, v28, v50
	v_fma_f32 v29, v162, v29, v51
	v_mul_f32_e64 v50, v64, v32
	v_mul_f32_e64 v51, v65, v32
	v_lshl_add_u64 v[34:35], v[36:37], 1, v[34:35]
	v_lshlrev_b32_e32 v32, 1, v167
	v_div_fixup_f32 v98, v99, v98, v164
	v_lshl_add_u64 v[34:35], v[34:35], 0, v[32:33]
	s_mov_b64 s[0:1], 0x36d6000
	v_fma_f32 v16, v82, v98, v16
	v_fma_f32 v17, v83, v98, v17
	v_fma_f32 v18, v84, v98, v18
	v_fma_f32 v19, v85, v98, v19
	v_lshl_add_u64 v[36:37], v[34:35], 0, s[0:1]
	s_mov_b32 s0, 0x36d6000
	v_fma_f32 v0, v66, v98, v0
	v_fma_f32 v1, v67, v98, v1
	v_fma_f32 v2, v68, v98, v2
	v_fma_f32 v3, v69, v98, v3
	v_cvt_pk_bf16_f32 v16, v16, v17
	v_cvt_pk_bf16_f32 v17, v18, v19
	v_add_co_u32_e32 v18, vcc, s0, v34
	v_fma_f32 v20, v86, v98, v20
	v_fma_f32 v21, v87, v98, v21
	v_fma_f32 v22, v88, v98, v22
	v_fma_f32 v23, v89, v98, v23
	v_fma_f32 v4, v70, v98, v4
	v_fma_f32 v5, v71, v98, v5
	v_fma_f32 v6, v72, v98, v6
	v_fma_f32 v7, v73, v98, v7
	v_addc_co_u32_e32 v19, vcc, 0, v35, vcc
	v_cvt_pk_bf16_f32 v0, v0, v1
	v_cvt_pk_bf16_f32 v1, v2, v3
	v_fma_f32 v24, v90, v98, v24
	v_fma_f32 v25, v91, v98, v25
	v_fma_f32 v26, v92, v98, v26
	v_fma_f32 v27, v93, v98, v27
	v_fma_f32 v30, v162, v30, v50
	v_fma_f32 v31, v162, v31, v51
	v_fma_f32 v8, v74, v98, v8
	v_fma_f32 v9, v75, v98, v9
	v_fma_f32 v10, v76, v98, v10
	v_fma_f32 v11, v77, v98, v11
	flat_store_dwordx2 v[18:19], v[16:17]
	v_cvt_pk_bf16_f32 v16, v20, v21
	v_cvt_pk_bf16_f32 v17, v22, v23
	flat_store_dwordx2 v[36:37], v[0:1] offset:64
	v_cvt_pk_bf16_f32 v0, v4, v5
	v_cvt_pk_bf16_f32 v1, v6, v7
	v_fma_f32 v28, v94, v98, v28
	v_fma_f32 v29, v95, v98, v29
	v_fma_f32 v30, v96, v98, v30
	v_fma_f32 v31, v97, v98, v31
	v_fma_f32 v12, v78, v98, v12
	v_fma_f32 v13, v79, v98, v13
	v_fma_f32 v14, v80, v98, v14
	v_fma_f32 v15, v81, v98, v15
	flat_store_dwordx2 v[36:37], v[16:17] offset:16
	v_cvt_pk_bf16_f32 v16, v24, v25
	v_cvt_pk_bf16_f32 v17, v26, v27
	flat_store_dwordx2 v[36:37], v[0:1] offset:80
	v_cvt_pk_bf16_f32 v0, v8, v9
	v_cvt_pk_bf16_f32 v1, v10, v11
	flat_store_dwordx2 v[36:37], v[16:17] offset:32
	v_cvt_pk_bf16_f32 v16, v28, v29
	v_cvt_pk_bf16_f32 v17, v30, v31
	flat_store_dwordx2 v[36:37], v[0:1] offset:96
	v_cvt_pk_bf16_f32 v0, v12, v13
	v_cvt_pk_bf16_f32 v1, v14, v15
	s_mov_b64 s[0:1], 0
	s_mov_b32 s71, 0x10000
	flat_store_dwordx2 v[36:37], v[16:17] offset:48
	flat_store_dwordx2 v[36:37], v[0:1] offset:112

; #define MFMA(a, b, c) __builtin_amdgcn_mfma_f32_32x32x16_bf16((a), (b), (c), 0, 0, 0)
; DI int crow(int i, int h) { return (i & 3) + 8 * (i >> 2) + 4 * h; }
; DI void qk_tile(const bf16_t* sK, const bf16x8 (&qf)[4], f32x16 (&Sx)[2], int r, int h) {
; #pragma unroll
;   for (int mt = 0; mt < 2; ++mt) {
;     f32x16 a;
; #pragma unroll
;     for (int i = 0; i < 16; ++i) a[i] = 0.f;
; #pragma unroll
;     for (int s = 0; s < 4; ++s) {
;       const bf16x8 k = *(const bf16x8*)(sK + (mt * 32 + r) * 72 + s * 16 + h * 8);
;       a = MFMA(k, qf[s], a);
;     }
;     Sx[mt] = a;
;   }
; }
; DI void nsa_item(const Params& p_, const EvenBufs& eb_, int b, int g, int tt, unsigned char* smem) {
;     ...
;   for (int kt = 0; kt < nct; ++kt) {
;     TR_<2> kr; tload(kr, Kc + kt * 64 * 64, 64, tid);
;     __syncthreads();
;     tstore72(kr, sK, tid);
;     __syncthreads();
;     f32x16 Sx[2]; qk_tile(sK, qf, Sx, r, h);
;     unsigned vb = 0;
; #pragma unroll
;     for (int mt = 0; mt < 2; ++mt)
; #pragma unroll
;       for (int i = 0; i < 16; ++i) vb |= (unsigned)(kt * 64 + mt * 32 + crow(i, h) <= nlim) << (mt * 16 + i);
;     online_softmax_t<true>(Sx, vb, m, l);
.LBB0_1063:
	global_load_dwordx4 v[0:3], v[36:37], off offset:-4096
	global_load_dwordx4 v[4:7], v[36:37], off
	v_add_u32_e32 v16, s66, v167
	v_cmp_le_i32_e32 vcc, v16, v70
	v_cmp_lt_i32_e64 s[6:7], v16, v70
	v_add_u32_e32 v22, 10, v16
	v_cndmask_b32_e64 v17, 0, 1, vcc
	v_cndmask_b32_e64 v18, 0, 2, s[6:7]
	v_add_u32_e32 v23, 11, v16
	v_or_b32_e32 v17, v18, v17
	v_add_u32_e32 v18, 2, v16
	v_add_u32_e32 v19, 3, v16
	v_cmp_gt_i32_e64 s[4:5], v22, v70
	v_cmp_gt_i32_e64 s[12:13], v23, v70
	v_cmp_gt_i32_e64 s[0:1], v18, v70
	v_cmp_gt_i32_e64 s[8:9], v19, v70
	v_add_u32_e32 v20, 8, v16
	v_add_u32_e32 v21, 9, v16
	v_cndmask_b32_e64 v22, 64, 0, s[4:5]
	v_cndmask_b32_e64 v23, v215, 0, s[12:13]
	v_cndmask_b32_e64 v18, 4, 0, s[0:1]
	v_cndmask_b32_e64 v19, 8, 0, s[8:9]
	v_cmp_gt_i32_e64 s[2:3], v20, v70
	v_cmp_gt_i32_e64 s[10:11], v21, v70
	v_or3_b32 v17, v17, v22, v23
	v_cndmask_b32_e64 v20, 16, 0, s[2:3]
	v_cndmask_b32_e64 v21, 32, 0, s[10:11]
	v_or3_b32 v17, v18, v19, v17
	v_or3_b32 v56, v20, v21, v17
	v_add_u32_e32 v17, 16, v16
	v_cmp_gt_i32_e64 s[14:15], v17, v70
	v_add_u32_e32 v18, 17, v16
	s_waitcnt lgkmcnt(0)
	v_cndmask_b32_e64 v17, v216, 0, s[14:15]
	v_cmp_gt_i32_e64 s[14:15], v18, v70
	s_barrier
	s_nop 0
	v_cndmask_b32_e64 v18, v217, 0, s[14:15]
	v_or_b32_e32 v57, v17, v18
	v_add_u32_e32 v17, 18, v16
	v_cmp_gt_i32_e64 s[14:15], v17, v70
	v_add_u32_e32 v18, 19, v16
	s_waitcnt vmcnt(1)
	ds_write_b128 v178, v[0:3]
	s_waitcnt vmcnt(0)
	ds_write_b128 v178, v[4:7] offset:4608
	v_cndmask_b32_e64 v17, v218, 0, s[14:15]
	v_cmp_gt_i32_e64 s[14:15], v18, v70
	s_waitcnt lgkmcnt(0)
	s_barrier
	v_cndmask_b32_e64 v18, v219, 0, s[14:15]
	v_or_b32_e32 v59, v17, v18
	v_add_u32_e32 v17, 24, v16
	v_cmp_gt_i32_e64 s[14:15], v17, v70
	v_add_u32_e32 v18, 25, v16
	s_nop 0
	v_cndmask_b32_e64 v17, v220, 0, s[14:15]
	v_cmp_gt_i32_e64 s[14:15], v18, v70
	ds_read_b128 v[0:3], v179
	ds_read_b128 v[4:7], v179 offset:32
	ds_read_b128 v[8:11], v179 offset:64
	ds_read_b128 v[12:15], v179 offset:96
	ds_read_b128 v[40:43], v179 offset:4608
	ds_read_b128 v[44:47], v179 offset:4640
	ds_read_b128 v[48:51], v179 offset:4672
	ds_read_b128 v[52:55], v179 offset:4704
	v_cndmask_b32_e64 v18, v221, 0, s[14:15]
	v_or_b32_e32 v61, v17, v18
	v_add_u32_e32 v17, 26, v16
	v_cmp_gt_i32_e64 s[14:15], v17, v70
	v_add_u32_e32 v18, 27, v16
	s_movk_i32 s16, 0x200
	v_cndmask_b32_e64 v17, v222, 0, s[14:15]
	v_cmp_gt_i32_e64 s[14:15], v18, v70
	v_or_b32_e32 v58, v57, v56
	v_or_b32_e32 v60, v59, v58
	v_cndmask_b32_e64 v18, v223, 0, s[14:15]
	v_or_b32_e32 v63, v17, v18
	v_add_u32_e32 v17, 32, v16
	v_cmp_gt_i32_e64 s[14:15], v17, v70
	v_add_u32_e32 v18, 33, v16
	v_or_b32_e32 v62, v61, v60
	v_cndmask_b32_e64 v17, v224, 0, s[14:15]
	v_cmp_gt_i32_e64 s[14:15], v18, v70
	v_or_b32_e32 v64, v63, v62
	s_add_i32 s66, s66, 64
	v_cndmask_b32_e64 v18, v225, 0, s[14:15]
	v_or_b32_e32 v65, v17, v18
	v_add_u32_e32 v17, 34, v16
	v_cmp_gt_i32_e64 s[14:15], v17, v70
	v_add_u32_e32 v18, 35, v16
	v_or_b32_e32 v69, v65, v64
	v_cndmask_b32_e64 v17, v226, 0, s[14:15]
	v_cmp_gt_i32_e64 s[14:15], v18, v70
	v_lshl_add_u64 v[36:37], v[36:37], 0, s[76:77]
	s_cmp_eq_u32 s65, s66
	v_cndmask_b32_e64 v18, v227, 0, s[14:15]
	v_or_b32_e32 v72, v17, v18
	v_add_u32_e32 v17, 40, v16
	v_cmp_gt_i32_e64 s[14:15], v17, v70
	v_add_u32_e32 v18, 41, v16
	v_or_b32_e32 v74, v72, v69
	v_cndmask_b32_e64 v17, v228, 0, s[14:15]
	v_cmp_gt_i32_e64 s[14:15], v18, v70
	s_nop 1
	v_cndmask_b32_e64 v18, v229, 0, s[14:15]
	v_or_b32_e32 v75, v17, v18
	v_add_u32_e32 v17, 42, v16
	v_cmp_gt_i32_e64 s[14:15], v17, v70
	v_add_u32_e32 v18, 43, v16
	v_or_b32_e32 v76, v75, v74
	v_cndmask_b32_e64 v17, v230, 0, s[14:15]
	v_cmp_gt_i32_e64 s[14:15], v18, v70
	s_nop 1
	v_cndmask_b32_e64 v18, v231, 0, s[14:15]
	v_or_b32_e32 v77, v17, v18
	v_add_u32_e32 v17, 48, v16
	v_cmp_gt_i32_e64 s[14:15], v17, v70
	v_add_u32_e32 v18, 49, v16
	v_or_b32_e32 v78, v77, v76
	v_cndmask_b32_e64 v17, v232, 0, s[14:15]
	v_cmp_gt_i32_e64 s[14:15], v18, v70
	s_nop 1
	v_cndmask_b32_e64 v18, v233, 0, s[14:15]
	v_or_b32_e32 v79, v17, v18
	v_add_u32_e32 v17, 50, v16
	v_cmp_gt_i32_e64 s[14:15], v17, v70
	v_add_u32_e32 v18, 51, v16
	v_or_b32_e32 v80, v79, v78
	v_cndmask_b32_e64 v17, v234, 0, s[14:15]
	v_cmp_gt_i32_e64 s[14:15], v18, v70
	s_nop 1
	v_cndmask_b32_e64 v18, v235, 0, s[14:15]
	v_or_b32_e32 v81, v17, v18
	v_add_u32_e32 v17, 56, v16
	v_cmp_gt_i32_e64 s[14:15], v17, v70
	v_add_u32_e32 v18, 57, v16
	v_or_b32_e32 v82, v81, v80
	v_cndmask_b32_e64 v17, v236, 0, s[14:15]
	v_cmp_gt_i32_e64 s[14:15], v18, v70
	s_nop 1
	v_cndmask_b32_e64 v18, v237, 0, s[14:15]
	v_or_b32_e32 v83, v17, v18
	v_add_u32_e32 v17, 58, v16
	v_cmp_gt_i32_e64 s[14:15], v17, v70
	v_add_u32_e32 v16, 59, v16
	v_or_b32_e32 v86, v83, v82
	v_cndmask_b32_e64 v17, 2.0, 0, s[14:15]
	v_cmp_gt_i32_e64 s[14:15], v16, v70
	s_nop 1
	v_cndmask_b32_e64 v16, v238, 0, s[14:15]
	v_or_b32_e32 v87, v17, v16
	s_waitcnt lgkmcnt(7)
	v_mfma_f32_32x32x16_bf16 v[16:31], v[0:3], v[138:141], 0
	s_movk_i32 s14, 0x100
	v_or_b32_e32 v88, v87, v86
	v_cmp_lt_i32_e64 s[62:63], -1, v88
	s_waitcnt lgkmcnt(6)
	v_mfma_f32_32x32x16_bf16 v[16:31], v[4:7], v[130:133], v[16:31]
	s_waitcnt lgkmcnt(5)
	v_mfma_f32_32x32x16_bf16 v[16:31], v[8:11], v[134:137], v[16:31]
	s_waitcnt lgkmcnt(4)
	v_mfma_f32_32x32x16_bf16 v[16:31], v[12:15], v[142:145], v[16:31]
	s_waitcnt lgkmcnt(3)
	v_mfma_f32_32x32x16_bf16 v[0:15], v[40:43], v[138:141], 0
	s_nop 9
	v_cndmask_b32_e32 v40, v214, v16, vcc
	v_cndmask_b32_e64 v41, v214, v17, s[6:7]
	v_max3_f32 v16, v40, s92, v41
	v_cndmask_b32_e64 v42, v18, v214, s[0:1]
	v_cndmask_b32_e64 v43, v19, v214, s[8:9]
	v_max3_f32 v16, v16, v42, v43
	v_cndmask_b32_e64 v18, v20, v214, s[2:3]
	s_waitcnt lgkmcnt(2)
; DI float shx32(float v) { return __shfl_xor(v, 32); }
; template <bool MASKED>
; DI float online_softmax_t(f32x16 (&Sx)[2], unsigned vb, float& m, float& l) {
;   float mx = NEG;
; #pragma unroll
;   for (int mt = 0; mt < 2; ++mt)
; #pragma unroll
;     for (int i = 0; i < 16; ++i) {
;       float s = Sx[mt][i];
;       if (MASKED) { s = ((vb >> (mt * 16 + i)) & 1u) ? s : NEG; Sx[mt][i] = s; }
;       mx = fmaxf(mx, s);
;     }
;   mx = fmaxf(mx, shx32(mx));
;   const float mn = fmaxf(m, mx);
;   const float alpha = __builtin_amdgcn_exp2f((m - mn) * L2E);
;   const float mb = mn * L2E;
;   f32x2 sum2 = {0.f, 0.f};
;   const f32x2 l2e2 = {L2E, L2E}, mb2 = {mb, mb};
; #pragma unroll
;   for (int mt = 0; mt < 2; ++mt)
; #pragma unroll
;     for (int i = 0; i < 16; i += 2) {
;       const f32x2 t = (f32x2){Sx[mt][i], Sx[mt][i + 1]} * l2e2 - mb2;
;       f32x2 p = {__builtin_amdgcn_exp2f(t.x), __builtin_amdgcn_exp2f(t.y)};
;       if (MASKED) { p.x = ((vb >> (mt * 16 + i)) & 1u) ? p.x : 0.f; p.y = ((vb >> (mt * 16 + i + 1)) & 1u) ? p.y : 0.f; }
;       Sx[mt][i] = p.x; Sx[mt][i + 1] = p.y;
;       sum2 += p;
;     }
;   l = l * alpha + (sum2.x + sum2.y);
;   m = mn;
;   return alpha;
; }
	v_mfma_f32_32x32x16_bf16 v[0:15], v[44:47], v[130:133], v[0:15]
	v_cndmask_b32_e64 v19, v21, v214, s[10:11]
	v_max3_f32 v20, v16, v18, v19
	v_cndmask_b32_e64 v16, v22, v214, s[4:5]
	v_cndmask_b32_e64 v17, v23, v214, s[12:13]
	v_max3_f32 v22, v20, v16, v17
	v_bitop3_b32 v20, v57, s14, v56 bitop3:0xc8
	v_bitop3_b32 v21, v57, s16, v56 bitop3:0xc8
	s_waitcnt lgkmcnt(1)
	v_mfma_f32_32x32x16_bf16 v[0:15], v[48:51], v[134:137], v[0:15]
	v_cmp_eq_u32_e64 s[14:15], 0, v20
	v_cmp_eq_u32_e64 s[18:19], 0, v21
	v_bitop3_b32 v23, v59, s82, v58 bitop3:0xc8
	v_cndmask_b32_e64 v20, v24, v214, s[14:15]
	v_cndmask_b32_e64 v21, v25, v214, s[18:19]
	v_max3_f32 v24, v22, v20, v21
	v_bitop3_b32 v22, v59, s89, v58 bitop3:0xc8
	v_cmp_eq_u32_e64 s[16:17], 0, v22
	v_cmp_eq_u32_e64 s[22:23], 0, v23
	s_waitcnt lgkmcnt(0)
	v_mfma_f32_32x32x16_bf16 v[0:15], v[52:55], v[142:145], v[0:15]
	v_cndmask_b32_e64 v22, v26, v214, s[16:17]
	v_cndmask_b32_e64 v23, v27, v214, s[22:23]
	v_max3_f32 v26, v24, v22, v23
	v_bitop3_b32 v24, v61, s90, v60 bitop3:0xc8
	v_bitop3_b32 v25, v61, s91, v60 bitop3:0xc8
	v_cmp_eq_u32_e64 s[20:21], 0, v24
	v_cmp_eq_u32_e64 s[26:27], 0, v25
	v_bitop3_b32 v27, v63, s70, v62 bitop3:0xc8
	v_cndmask_b32_e64 v24, v28, v214, s[20:21]
	v_cndmask_b32_e64 v25, v29, v214, s[26:27]
	v_max3_f32 v28, v26, v24, v25
	v_bitop3_b32 v26, v63, s94, v62 bitop3:0xc8
	v_cmp_eq_u32_e64 s[24:25], 0, v26
	v_cmp_eq_u32_e64 s[30:31], 0, v27
	v_cndmask_b32_e64 v15, v15, v214, s[62:63]
	v_cndmask_b32_e64 v26, v30, v214, s[24:25]
	v_cndmask_b32_e64 v27, v31, v214, s[30:31]
	v_max3_f32 v30, v28, v26, v27
	v_bitop3_b32 v28, v65, s71, v64 bitop3:0xc8
	v_cmp_eq_u32_e64 s[28:29], 0, v28
	s_nop 1
	v_cndmask_b32_e64 v28, v0, v214, s[28:29]
	v_bitop3_b32 v0, v65, s55, v64 bitop3:0xc8
	v_cmp_eq_u32_e64 s[36:37], 0, v0
	s_nop 1
	v_cndmask_b32_e64 v29, v1, v214, s[36:37]
	v_bitop3_b32 v1, v72, s52, v69 bitop3:0xc8
	v_cmp_eq_u32_e64 s[34:35], 0, v1
	v_bitop3_b32 v1, v72, s50, v69 bitop3:0xc8
	v_cmp_eq_u32_e64 s[40:41], 0, v1
	v_bitop3_b32 v1, v75, s51, v74 bitop3:0xc8
	v_cmp_eq_u32_e64 s[38:39], 0, v1
	v_bitop3_b32 v1, v75, s56, v74 bitop3:0xc8
	v_cmp_eq_u32_e64 s[44:45], 0, v1
	v_bitop3_b32 v1, v77, s57, v76 bitop3:0xc8
	v_cmp_eq_u32_e64 s[42:43], 0, v1
	v_bitop3_b32 v1, v77, s79, v76 bitop3:0xc8
	v_cmp_eq_u32_e64 s[48:49], 0, v1
	v_bitop3_b32 v1, v79, s33, v78 bitop3:0xc8
	v_cmp_eq_u32_e64 s[46:47], 0, v1
	v_bitop3_b32 v1, v79, s68, v78 bitop3:0xc8
	v_max3_f32 v0, v30, v28, v29
	v_cndmask_b32_e64 v2, v2, v214, s[34:35]
	v_cndmask_b32_e64 v3, v3, v214, s[40:41]
	v_cmp_eq_u32_e64 s[52:53], 0, v1
	v_bitop3_b32 v1, v81, s69, v80 bitop3:0xc8
	v_max3_f32 v0, v0, v2, v3
	v_cndmask_b32_e64 v4, v4, v214, s[38:39]
	v_cndmask_b32_e64 v5, v5, v214, s[44:45]
	v_cmp_eq_u32_e64 s[50:51], 0, v1
	v_bitop3_b32 v1, v81, s72, v80 bitop3:0xc8
	v_max3_f32 v0, v0, v4, v5
	v_cndmask_b32_e64 v6, v6, v214, s[42:43]
	v_cndmask_b32_e64 v7, v7, v214, s[48:49]
	v_cmp_eq_u32_e64 s[56:57], 0, v1
	v_bitop3_b32 v1, v83, s73, v82 bitop3:0xc8
	v_max3_f32 v0, v0, v6, v7
	v_cndmask_b32_e64 v8, v8, v214, s[46:47]
	v_cndmask_b32_e64 v9, v9, v214, s[52:53]
	v_cmp_eq_u32_e64 s[54:55], 0, v1
	v_bitop3_b32 v1, v83, s74, v82 bitop3:0xc8
	v_max3_f32 v0, v0, v8, v9
	v_cndmask_b32_e64 v10, v10, v214, s[50:51]
	v_cndmask_b32_e64 v11, v11, v214, s[56:57]
	v_cmp_eq_u32_e64 s[60:61], 0, v1
	v_bitop3_b32 v1, v87, 2.0, v86 bitop3:0xc8
	v_max3_f32 v0, v0, v10, v11
	v_cndmask_b32_e64 v12, v12, v214, s[54:55]
	v_cndmask_b32_e64 v13, v13, v214, s[60:61]
	v_cmp_eq_u32_e64 s[58:59], 0, v1
	v_max3_f32 v0, v0, v12, v13
	s_nop 0
	v_cndmask_b32_e64 v14, v14, v214, s[58:59]
	v_max3_f32 v0, v0, v14, v15
	ds_bpermute_b32 v1, v169, v0
	s_waitcnt lgkmcnt(0)
	v_max3_f32 v0, v35, v0, v1
	v_mul_f32_e32 v72, 0x3fb8aa3b, v0
	v_fma_f32 v30, v40, s96, -v72
	v_fma_f32 v31, v41, s96, -v72
	v_fma_f32 v40, v42, s96, -v72
	v_fma_f32 v41, v43, s96, -v72
	v_exp_f32_e32 v1, v30
	v_fma_f32 v18, v18, s96, -v72
	v_fma_f32 v19, v19, s96, -v72
	v_exp_f32_e32 v31, v31
	v_exp_f32_e32 v41, v41
	v_cndmask_b32_e32 v30, 0, v1, vcc
	v_exp_f32_e32 v1, v40
	v_exp_f32_e32 v19, v19
	v_fma_f32 v16, v16, s96, -v72
	v_fma_f32 v17, v17, s96, -v72
	v_cndmask_b32_e64 v31, 0, v31, s[6:7]
	v_cndmask_b32_e64 v40, v1, 0, s[0:1]
	v_exp_f32_e32 v1, v18
	v_exp_f32_e32 v17, v17
	v_add_f32_e64 v30, v30, 0
	v_add_f32_e64 v31, v31, 0
	v_cndmask_b32_e64 v41, v41, 0, s[8:9]
	v_cndmask_b32_e64 v18, v1, 0, s[2:3]
	v_exp_f32_e32 v1, v16
	v_add_f32_e64 v30, v40, v30
	v_add_f32_e64 v31, v41, v31
	v_cndmask_b32_e64 v19, v19, 0, s[10:11]
	v_add_f32_e64 v18, v18, v30
	v_add_f32_e64 v19, v19, v31
	v_cndmask_b32_e64 v16, v1, 0, s[4:5]
	v_cndmask_b32_e64 v17, v17, 0, s[12:13]
	v_add_f32_e64 v16, v16, v18
	v_add_f32_e64 v17, v17, v19
	v_fma_f32 v18, v20, s96, -v72
	v_fma_f32 v19, v21, s96, -v72
	v_fma_f32 v2, v2, s96, -v72
	v_fma_f32 v3, v3, s96, -v72
	v_exp_f32_e32 v1, v18
	v_exp_f32_e32 v19, v19
	v_exp_f32_e32 v3, v3
	v_fma_f32 v4, v4, s96, -v72
	v_fma_f32 v5, v5, s96, -v72
	v_cndmask_b32_e64 v18, v1, 0, s[14:15]
	v_cndmask_b32_e64 v19, v19, 0, s[18:19]
	v_add_f32_e64 v16, v18, v16
	v_add_f32_e64 v17, v19, v17
	v_fma_f32 v18, v22, s96, -v72
	v_fma_f32 v19, v23, s96, -v72
	v_exp_f32_e32 v5, v5
	v_exp_f32_e32 v1, v18
	v_exp_f32_e32 v19, v19
	v_cndmask_b32_e64 v3, v3, 0, s[40:41]
	v_cndmask_b32_e64 v5, v5, 0, s[44:45]
	v_cndmask_b32_e64 v18, v1, 0, s[16:17]
	v_cndmask_b32_e64 v19, v19, 0, s[22:23]
	v_add_f32_e64 v16, v18, v16
	v_add_f32_e64 v17, v19, v17
	v_fma_f32 v18, v24, s96, -v72
	v_fma_f32 v19, v25, s96, -v72
	s_nop 0
	v_exp_f32_e32 v1, v18
	v_exp_f32_e32 v19, v19
	v_cndmask_b32_e64 v18, v1, 0, s[20:21]
; DI float shx32(float v) { return __shfl_xor(v, 32); }
; template <bool MASKED>
; DI float online_softmax_t(f32x16 (&Sx)[2], unsigned vb, float& m, float& l) {
;     ...
;   const float alpha = __builtin_amdgcn_exp2f((m - mn) * L2E);
;   const float mb = mn * L2E;
;   f32x2 sum2 = {0.f, 0.f};
;   const f32x2 l2e2 = {L2E, L2E}, mb2 = {mb, mb};
; #pragma unroll
;   for (int mt = 0; mt < 2; ++mt)
; #pragma unroll
;     for (int i = 0; i < 16; i += 2) {
;       const f32x2 t = (f32x2){Sx[mt][i], Sx[mt][i + 1]} * l2e2 - mb2;
;       f32x2 p = {__builtin_amdgcn_exp2f(t.x), __builtin_amdgcn_exp2f(t.y)};
;       if (MASKED) { p.x = ((vb >> (mt * 16 + i)) & 1u) ? p.x : 0.f; p.y = ((vb >> (mt * 16 + i + 1)) & 1u) ? p.y : 0.f; }
;       Sx[mt][i] = p.x; Sx[mt][i + 1] = p.y;
;       sum2 += p;
;     }
;   l = l * alpha + (sum2.x + sum2.y);
;   m = mn;
;   return alpha;
; }
; DI void nsa_item(const Params& p_, const EvenBufs& eb_, int b, int g, int tt, unsigned char* smem) {
;     ...
;   l += shx32(l);
;   const float invl = l > 0.f ? 1.f / l : 0.f;
;   const float mb = m * L2E;
;   zero_o<2>(O);
	v_cndmask_b32_e64 v19, v19, 0, s[26:27]
	v_add_f32_e64 v16, v18, v16
	v_add_f32_e64 v17, v19, v17
	v_fma_f32 v18, v26, s96, -v72
	v_fma_f32 v19, v27, s96, -v72
	s_nop 0
	v_exp_f32_e32 v1, v18
	v_exp_f32_e32 v19, v19
	v_cndmask_b32_e64 v18, v1, 0, s[24:25]
	v_cndmask_b32_e64 v19, v19, 0, s[30:31]
	v_add_f32_e64 v16, v18, v16
	v_add_f32_e64 v17, v19, v17
	v_fma_f32 v18, v28, s96, -v72
	v_fma_f32 v19, v29, s96, -v72
	s_nop 0
	v_exp_f32_e32 v1, v18
	v_exp_f32_e32 v19, v19
	v_cndmask_b32_e64 v18, v1, 0, s[28:29]
	v_exp_f32_e32 v1, v2
	v_cndmask_b32_e64 v19, v19, 0, s[36:37]
	v_add_f32_e64 v16, v18, v16
	v_add_f32_e64 v17, v19, v17
	v_cndmask_b32_e64 v2, v1, 0, s[34:35]
	v_exp_f32_e32 v1, v4
	v_add_f32_e64 v2, v2, v16
	v_add_f32_e64 v3, v3, v17
	v_cndmask_b32_e64 v4, v1, 0, s[38:39]
	v_add_f32_e64 v2, v4, v2
	v_add_f32_e64 v3, v5, v3
	v_fma_f32 v4, v6, s96, -v72
	v_fma_f32 v5, v7, s96, -v72
	s_nop 0
	v_exp_f32_e32 v1, v4
	v_exp_f32_e32 v5, v5
	v_cndmask_b32_e64 v4, v1, 0, s[42:43]
	v_cndmask_b32_e64 v5, v5, 0, s[48:49]
	v_add_f32_e64 v2, v4, v2
	v_add_f32_e64 v3, v5, v3
	v_fma_f32 v4, v8, s96, -v72
	v_fma_f32 v5, v9, s96, -v72
	s_nop 0
	v_exp_f32_e32 v1, v4
	v_exp_f32_e32 v5, v5
	v_cndmask_b32_e64 v4, v1, 0, s[46:47]
	v_cndmask_b32_e64 v5, v5, 0, s[52:53]
	v_add_f32_e64 v2, v4, v2
	v_add_f32_e64 v3, v5, v3
	v_fma_f32 v4, v10, s96, -v72
	v_fma_f32 v5, v11, s96, -v72
	s_mov_b32 s52, 0x40000
	v_exp_f32_e32 v1, v4
	v_exp_f32_e32 v5, v5
	v_cndmask_b32_e64 v4, v1, 0, s[50:51]
	v_cndmask_b32_e64 v5, v5, 0, s[56:57]
	v_add_f32_e64 v2, v4, v2
	v_add_f32_e64 v3, v5, v3
	v_fma_f32 v4, v12, s96, -v72
	v_fma_f32 v5, v13, s96, -v72
	s_mov_b32 s51, 0x100000
	v_exp_f32_e32 v1, v4
	v_exp_f32_e32 v5, v5
	s_mov_b32 s50, 0x80000
	s_mov_b32 s57, 0x400000
	v_cndmask_b32_e64 v4, v1, 0, s[54:55]
	v_cndmask_b32_e64 v5, v5, 0, s[60:61]
	v_add_f32_e64 v2, v4, v2
	v_add_f32_e64 v3, v5, v3
	v_fma_f32 v4, v14, s96, -v72
	v_fma_f32 v5, v15, s96, -v72
	s_mov_b32 s56, 0x200000
	v_exp_f32_e32 v1, v4
	v_exp_f32_e32 v5, v5
	s_mov_b32 s55, 0x20000
	v_cndmask_b32_e64 v4, v1, 0, s[58:59]
	v_sub_f32_e32 v1, v35, v0
	v_mul_f32_e32 v1, 0x3fb8aa3b, v1
	v_cndmask_b32_e64 v5, v5, 0, s[62:63]
	v_exp_f32_e32 v1, v1
	v_add_f32_e64 v2, v4, v2
	v_add_f32_e64 v3, v5, v3
	v_mov_b32_e32 v35, v0
	v_add_f32_e32 v2, v2, v3
	v_mov_b32_e32 v3, v39
	v_mov_b32_e32 v39, v2
	v_fmac_f32_e32 v39, v3, v1
	s_cbranch_scc0 .LBB0_1063
	ds_bpermute_b32 v2, v169, v39
	v_readlane_b32 s0, v255, 20
	v_readlane_b32 s1, v255, 21
	s_add_u32 s0, s0, s67
	s_addc_u32 s1, s1, 0
	v_mov_b32_e32 v35, v33
	v_lshl_add_u64 v[0:1], s[0:1], 0, v[34:35]
	s_mov_b64 s[2:3], 0xd516000
	v_lshl_add_u64 v[78:79], v[0:1], 0, s[2:3]
	s_waitcnt lgkmcnt(0)
	v_add_f32_e32 v0, v39, v2
	v_div_scale_f32 v1, s[2:3], v0, v0, 1.0
	v_rcp_f32_e32 v2, v1
	s_add_u32 s0, s0, 0xd55a000
	v_add_u32_e32 v74, 32, v66
	s_movk_i32 s2, 0x88
	v_fma_f32 v3, -v1, v2, 1.0
	v_fmac_f32_e32 v2, v3, v2
	v_div_scale_f32 v3, vcc, 1.0, v0, 1.0
	v_mul_f32_e32 v4, v3, v2
	v_fma_f32 v5, -v1, v4, v3
	v_fmac_f32_e32 v4, v5, v2
	v_fma_f32 v1, -v1, v4, v3
	v_div_fmas_f32 v1, v1, v2, v4
	v_div_fixup_f32 v1, v1, v0, 1.0
	v_cmp_lt_f32_e32 vcc, 0, v0
	v_lshlrev_b32_e32 v3, 13, v85
	v_lshlrev_b32_e32 v4, 8, v71
	v_cndmask_b32_e32 v80, 0, v1, vcc
	v_lshlrev_b64 v[0:1], 9, v[66:67]
	s_addc_u32 s1, s1, 0
	v_ashrrev_i32_e32 v75, 31, v74
	v_mov_b32_e32 v88, 0
	v_mul_lo_u32 v2, v66, s2
	v_sub_u32_e32 v5, v32, v38
	v_mul_u32_u24_e32 v6, 0x88, v71
	v_or3_b32 v3, v3, v4, v167
	v_lshl_add_u64 v[0:1], s[0:1], 0, v[0:1]
	s_mov_b32 s80, 0
	v_lshlrev_b64 v[76:77], 7, v[74:75]
	v_cmp_gt_u32_e32 vcc, 32, v84
	v_mov_b32_e32 v69, v70
	v_mov_b32_e32 v81, v80
	v_add_u32_e32 v32, 0x4800, v3
	v_lshl_add_u64 v[82:83], v[0:1], 0, v[116:117]
	v_add_u32_e32 v86, v34, v2
	v_add_u32_e32 v87, v5, v6
	s_mov_b32 s2, s80
	v_mov_b32_e32 v16, 0
	v_mov_b32_e32 v17, v88
	v_mov_b32_e32 v18, v88
	v_mov_b32_e32 v19, v88
	v_mov_b32_e32 v20, v88
	v_mov_b32_e32 v21, v88
	v_mov_b32_e32 v22, v88
	v_mov_b32_e32 v23, v88
	v_mov_b32_e32 v24, v88
	v_mov_b32_e32 v25, v88
	v_mov_b32_e32 v26, v88
	v_mov_b32_e32 v27, v88
	v_mov_b32_e32 v28, v88
	v_mov_b32_e32 v29, v88
	v_mov_b32_e32 v30, v88
	v_mov_b32_e32 v31, v88
	v_mov_b32_e32 v0, 0
	v_mov_b32_e32 v1, v88
	v_mov_b32_e32 v2, v88
	v_mov_b32_e32 v3, v88
	v_mov_b32_e32 v4, v88
	v_mov_b32_e32 v5, v88
	v_mov_b32_e32 v6, v88
	v_mov_b32_e32 v7, v88
	v_mov_b32_e32 v8, v88
	v_mov_b32_e32 v9, v88
	v_mov_b32_e32 v10, v88
	v_mov_b32_e32 v11, v88
	v_mov_b32_e32 v12, v88
	v_mov_b32_e32 v13, v88
	v_mov_b32_e32 v14, v88
	v_mov_b32_e32 v15, v88
; DI int crow(int i, int h) { return (i & 3) + 8 * (i >> 2) + 4 * h; }
; DI float shx32(float v) { return __shfl_xor(v, 32); }
; DI void nsa_item(const Params& p_, const EvenBufs& eb_, int b, int g, int tt, unsigned char* smem) {
;     ...
;   for (int kt = 0; kt < nct; ++kt) {
;     TR_<2> kr, vr; tload(kr, Kc + kt * 64 * 64, 64, tid); tload(vr, VcT + kt * 64, 256, tid);
;     __syncthreads();
;     tstore72(kr, sK, tid); tstore68(vr, sV, tid);
;     __syncthreads();
;     f32x16 Sx[2]; qk_tile(sK, qf, Sx, r, h);
; #pragma unroll
;     for (int mt = 0; mt < 2; ++mt) {
; #pragma unroll
;       for (int i = 0; i < 16; ++i) {
;         const bool ok = (kt * 64 + mt * 32 + crow(i, h)) <= nlim;
;         const float pr = __builtin_amdgcn_exp2f(Sx[mt][i] * L2E - mb) * invl;
;         Sx[mt][i] = ok ? pr : 0.f;
;       }
;       float x[4];
; #pragma unroll
;       for (int gg = 0; gg < 4; ++gg) x[gg] = shx32(Sx[mt][4 * gg + 3]);
; #pragma unroll
;       for (int gg = 0; gg < 4; ++gg) {
;         const float prev = h ? x[gg] : (gg ? x[gg > 0 ? gg - 1 : 0] : carry_prev);
;         const float val = Sx[mt][4 * gg] + Sx[mt][4 * gg + 1] + Sx[mt][4 * gg + 2] + Sx[mt][4 * gg + 3] + prev;
;         impW[(wid * 32 + r) * 64 + kt * 16 + mt * 8 + 2 * gg + h] = val;
;       }
;       carry_prev = x[3];
;     }
;     pv_tile<2>(sV, Sx, O, r, h);
.LBB0_1065:
	v_add_u32_e32 v89, s2, v167
	v_add_u32_e32 v89, 59, v89
	v_cmp_gt_i32_e64 s[98:99], v89, v70
	s_cmp_eq_u64 s[98:99], 0
	s_cbranch_scc1 .Lcmpb_fast
	v_lshl_add_u64 v[38:39], s[80:81], 1, v[78:79]
	v_lshl_add_u64 v[34:35], v[38:39], 0, v[114:115]
	v_lshl_add_u64 v[38:39], v[38:39], 0, v[76:77]
	global_load_dwordx4 v[34:37], v[34:35], off
	s_nop 0
	global_load_dwordx4 v[38:41], v[38:39], off
	s_movk_i32 s0, 0xc000
	v_add_co_u32_e64 v42, s[0:1], s0, v82
	s_nop 1
	v_addc_co_u32_e64 v43, s[0:1], -1, v83, s[0:1]
	global_load_dwordx4 v[42:45], v[42:43], off
	s_nop 0
	global_load_dwordx4 v[46:49], v[82:83], off
	v_add_u32_e32 v180, 0x2400, v86
	v_add_u32_e32 v181, 0x3500, v86
	s_barrier
	s_waitcnt vmcnt(3)
	ds_write_b128 v178, v[34:37]
	s_waitcnt vmcnt(2)
	ds_write_b128 v178, v[38:41] offset:4608
	s_waitcnt vmcnt(1)
	ds_write2_b64 v180, v[42:43], v[44:45] offset1:1
	s_waitcnt vmcnt(0)
	ds_write2_b64 v181, v[46:47], v[48:49] offset1:1
	s_waitcnt lgkmcnt(0)
	s_barrier
	ds_read_b128 v[34:37], v179
	ds_read_b128 v[38:41], v179 offset:32
	s_waitcnt lgkmcnt(1)
	v_mfma_f32_32x32x16_bf16 v[50:65], v[34:37], v[138:141], 0
	ds_read_b128 v[34:37], v179 offset:64
	ds_read_b128 v[90:93], v179 offset:4640
	v_add_u32_e32 v89, s2, v167
	v_cmp_le_i32_e64 s[0:1], v89, v70
	v_add_u32_e32 v182, 0x2000, v87
	v_add_u32_e32 v183, 0x3000, v87
	s_addk_i32 s80, 0x1000
	s_waitcnt lgkmcnt(2)
	v_mfma_f32_32x32x16_bf16 v[50:65], v[38:41], v[130:133], v[50:65]
	s_waitcnt lgkmcnt(1)
	v_mfma_f32_32x32x16_bf16 v[50:65], v[34:37], v[134:137], v[50:65]
	ds_read_b128 v[34:37], v179 offset:96
	s_waitcnt lgkmcnt(0)
	v_mfma_f32_32x32x16_bf16 v[50:65], v[34:37], v[142:145], v[50:65]
	ds_read_b128 v[34:37], v179 offset:4608
	s_waitcnt lgkmcnt(0)
	v_mfma_f32_32x32x16_bf16 v[34:49], v[34:37], v[138:141], 0
	s_nop 8
	v_fma_f32 v50, v50, s96, -v72
	v_exp_f32_e32 v50, v50
	s_nop 0
	v_mul_f32_e32 v50, v80, v50
	v_mfma_f32_32x32x16_bf16 v[34:49], v[90:93], v[130:133], v[34:49]
	ds_read_b128 v[90:93], v179 offset:4672
	s_waitcnt lgkmcnt(0)
	v_mfma_f32_32x32x16_bf16 v[34:49], v[90:93], v[134:137], v[34:49]
	ds_read_b128 v[90:93], v179 offset:4704
	s_waitcnt lgkmcnt(0)
	v_mfma_f32_32x32x16_bf16 v[34:49], v[90:93], v[142:145], v[34:49]
	v_cndmask_b32_e64 v91, 0, v50, s[0:1]
	v_fma_f32 v50, v51, s96, -v72
	v_exp_f32_e32 v50, v50
	v_cmp_lt_i32_e64 s[0:1], v89, v70
	v_fma_f32 v51, v53, s96, -v72
	v_exp_f32_e32 v51, v51
	v_mul_f32_e32 v50, v80, v50
	v_cndmask_b32_e64 v92, 0, v50, s[0:1]
	v_fma_f32 v50, v52, s96, -v72
	v_exp_f32_e32 v50, v50
	v_or_b32_e32 v52, 3, v89
	v_or_b32_e32 v53, 2, v89
	v_cmp_le_i32_e64 s[0:1], v52, v69
	v_mul_f32_e64 v50, v80, v50
	v_mul_f32_e64 v51, v81, v51
	v_or_b32_e32 v52, 9, v89
	v_cndmask_b32_e64 v93, 0, v51, s[0:1]
	v_cmp_le_i32_e64 s[0:1], v53, v70
	v_fma_f32 v51, v55, s96, -v72
	v_exp_f32_e32 v51, v51
	v_cndmask_b32_e64 v94, 0, v50, s[0:1]
	v_fma_f32 v50, v54, s96, -v72
	v_exp_f32_e32 v50, v50
	v_or_b32_e32 v53, 8, v89
	v_cmp_le_i32_e64 s[0:1], v52, v69
	v_or_b32_e32 v52, 11, v89
	v_mul_f32_e64 v50, v80, v50
	v_mul_f32_e64 v51, v81, v51
	v_or_b32_e32 v54, 17, v89
	v_cndmask_b32_e64 v95, 0, v51, s[0:1]
	v_cmp_le_i32_e64 s[0:1], v53, v70
	v_fma_f32 v51, v57, s96, -v72
	v_exp_f32_e32 v51, v51
	v_cndmask_b32_e64 v96, 0, v50, s[0:1]
	v_fma_f32 v50, v56, s96, -v72
	v_exp_f32_e32 v50, v50
	v_or_b32_e32 v53, 10, v89
	v_cmp_le_i32_e64 s[0:1], v52, v69
	v_or_b32_e32 v55, 16, v89
	v_mul_f32_e64 v50, v80, v50
	v_mul_f32_e64 v51, v81, v51
	v_or_b32_e32 v56, 19, v89
	v_cndmask_b32_e64 v97, 0, v51, s[0:1]
	v_cmp_le_i32_e64 s[0:1], v53, v70
	v_fma_f32 v51, v59, s96, -v72
	v_exp_f32_e32 v51, v51
	v_cndmask_b32_e64 v98, 0, v50, s[0:1]
	v_fma_f32 v50, v58, s96, -v72
	v_exp_f32_e32 v50, v50
	v_cmp_le_i32_e64 s[0:1], v54, v69
	v_or_b32_e32 v57, 18, v89
	v_or_b32_e32 v58, 25, v89
	v_mul_f32_e64 v52, v80, v50
	v_mul_f32_e64 v53, v81, v51
	v_or_b32_e32 v59, 24, v89
	v_cndmask_b32_e64 v50, 0, v53, s[0:1]
	v_cmp_le_i32_e64 s[0:1], v55, v70
	v_fma_f32 v53, v61, s96, -v72
	v_exp_f32_e32 v53, v53
	v_cndmask_b32_e64 v51, 0, v52, s[0:1]
	v_fma_f32 v52, v60, s96, -v72
	v_exp_f32_e32 v52, v52
	v_cmp_le_i32_e64 s[0:1], v56, v69
	v_or_b32_e32 v60, 27, v89
	v_or_b32_e32 v61, 26, v89
	v_mul_f32_e64 v54, v80, v52
	v_mul_f32_e64 v55, v81, v53
	v_add_u32_e32 v90, s2, v32
	v_cndmask_b32_e64 v52, 0, v55, s[0:1]
	v_cmp_le_i32_e64 s[0:1], v57, v70
	v_fma_f32 v55, v63, s96, -v72
	v_exp_f32_e32 v55, v55
	v_cndmask_b32_e64 v53, 0, v54, s[0:1]
	v_fma_f32 v54, v62, s96, -v72
	v_exp_f32_e32 v54, v54
	v_cmp_le_i32_e64 s[0:1], v58, v69
	v_add_f32_e32 v62, v91, v92
	v_add_f32_e32 v62, v94, v62
	v_mul_f32_e64 v56, v80, v54
	v_mul_f32_e64 v57, v81, v55
	v_add_f32_e32 v62, v93, v62
	v_cndmask_b32_e64 v54, 0, v57, s[0:1]
	v_cmp_le_i32_e64 s[0:1], v59, v70
	v_fma_f32 v57, v65, s96, -v72
	v_exp_f32_e32 v57, v57
	v_cndmask_b32_e64 v55, 0, v56, s[0:1]
	v_fma_f32 v56, v64, s96, -v72
	v_exp_f32_e32 v56, v56
	v_cmp_le_i32_e64 s[0:1], v60, v69
	ds_bpermute_b32 v60, v169, v52
	v_fma_f32 v34, v34, s96, -v72
	v_mul_f32_e64 v58, v80, v56
	v_mul_f32_e64 v59, v81, v57
	v_fma_f32 v35, v35, s96, -v72
	v_cndmask_b32_e64 v56, 0, v59, s[0:1]
	v_cmp_le_i32_e64 s[0:1], v61, v70
	ds_bpermute_b32 v59, v169, v97
	ds_bpermute_b32 v99, v169, v56
	v_cndmask_b32_e64 v57, 0, v58, s[0:1]
	ds_bpermute_b32 v58, v169, v93
	v_exp_f32_e32 v34, v34
	v_exp_f32_e32 v35, v35
	s_add_i32 s2, s2, 64
	s_cmp_eq_u32 s65, s2
	s_waitcnt lgkmcnt(0)
; DI int crow(int i, int h) { return (i & 3) + 8 * (i >> 2) + 4 * h; }
; DI float shx32(float v) { return __shfl_xor(v, 32); }
; DI void nsa_item(const Params& p_, const EvenBufs& eb_, int b, int g, int tt, unsigned char* smem) {
;     ...
;     f32x16 Sx[2]; qk_tile(sK, qf, Sx, r, h);
; #pragma unroll
;     for (int mt = 0; mt < 2; ++mt) {
; #pragma unroll
;       for (int i = 0; i < 16; ++i) {
;         const bool ok = (kt * 64 + mt * 32 + crow(i, h)) <= nlim;
;         const float pr = __builtin_amdgcn_exp2f(Sx[mt][i] * L2E - mb) * invl;
;         Sx[mt][i] = ok ? pr : 0.f;
;       }
;       float x[4];
; #pragma unroll
;       for (int gg = 0; gg < 4; ++gg) x[gg] = shx32(Sx[mt][4 * gg + 3]);
; #pragma unroll
;       for (int gg = 0; gg < 4; ++gg) {
;         const float prev = h ? x[gg] : (gg ? x[gg > 0 ? gg - 1 : 0] : carry_prev);
;         const float val = Sx[mt][4 * gg] + Sx[mt][4 * gg + 1] + Sx[mt][4 * gg + 2] + Sx[mt][4 * gg + 3] + prev;
;         impW[(wid * 32 + r) * 64 + kt * 16 + mt * 8 + 2 * gg + h] = val;
;       }
;       carry_prev = x[3];
;     }
;     pv_tile<2>(sV, Sx, O, r, h);
;   }
	v_cndmask_b32_e32 v61, v58, v88, vcc
	v_add_f32_e32 v61, v62, v61
	v_add_f32_e32 v62, v96, v95
	v_add_f32_e32 v62, v98, v62
	v_cndmask_b32_e32 v58, v59, v58, vcc
	v_add_f32_e32 v62, v97, v62
	v_add_f32_e32 v58, v62, v58
	ds_write2_b32 v90, v61, v58 offset1:2
	v_cndmask_b32_e32 v58, v60, v59, vcc
	v_add_f32_e32 v59, v51, v50
	v_add_f32_e32 v59, v53, v59
	v_add_f32_e32 v59, v52, v59
	v_add_f32_e32 v58, v59, v58
	v_cndmask_b32_e32 v59, v99, v60, vcc
	v_add_f32_e32 v60, v55, v54
	v_add_f32_e32 v60, v57, v60
	v_add_f32_e32 v60, v56, v60
	v_add_f32_e32 v59, v60, v59
	ds_write2_b32 v90, v58, v59 offset0:4 offset1:6
	v_or_b32_e32 v58, 33, v89
	v_or_b32_e32 v59, 32, v89
	v_mul_f32_e64 v34, v80, v34
	v_mul_f32_e64 v35, v81, v35
	v_cmp_le_i32_e64 s[0:1], v58, v69
	s_nop 1
	v_cndmask_b32_e64 v58, 0, v35, s[0:1]
	v_cmp_le_i32_e64 s[0:1], v59, v70
	v_fma_f32 v35, v37, s96, -v72
	v_exp_f32_e32 v35, v35
	v_cndmask_b32_e64 v59, 0, v34, s[0:1]
	v_fma_f32 v34, v36, s96, -v72
	v_exp_f32_e32 v34, v34
	v_or_b32_e32 v36, 35, v89
	v_or_b32_e32 v37, 34, v89
	v_cmp_le_i32_e64 s[0:1], v36, v69
	v_mul_f32_e64 v34, v80, v34
	v_mul_f32_e64 v35, v81, v35
	v_or_b32_e32 v36, 41, v89
	v_cndmask_b32_e64 v60, 0, v35, s[0:1]
	v_cmp_le_i32_e64 s[0:1], v37, v70
	v_fma_f32 v35, v39, s96, -v72
	v_exp_f32_e32 v35, v35
	v_cndmask_b32_e64 v61, 0, v34, s[0:1]
	v_fma_f32 v34, v38, s96, -v72
	v_exp_f32_e32 v34, v34
	v_or_b32_e32 v37, 40, v89
	v_cmp_le_i32_e64 s[0:1], v36, v69
	v_or_b32_e32 v36, 43, v89
	v_mul_f32_e64 v34, v80, v34
	v_mul_f32_e64 v35, v81, v35
	v_add_f32_e32 v38, v59, v58
	v_cndmask_b32_e64 v62, 0, v35, s[0:1]
	v_cmp_le_i32_e64 s[0:1], v37, v70
	v_fma_f32 v35, v41, s96, -v72
	v_exp_f32_e32 v35, v35
	v_cndmask_b32_e64 v63, 0, v34, s[0:1]
	v_fma_f32 v34, v40, s96, -v72
	v_exp_f32_e32 v34, v34
	v_or_b32_e32 v37, 42, v89
	v_cmp_le_i32_e64 s[0:1], v36, v69
	v_or_b32_e32 v36, 49, v89
	v_mul_f32_e64 v34, v80, v34
	v_mul_f32_e64 v35, v81, v35
	v_add_f32_e32 v38, v61, v38
	v_cndmask_b32_e64 v64, 0, v35, s[0:1]
	v_cmp_le_i32_e64 s[0:1], v37, v70
	v_fma_f32 v35, v43, s96, -v72
	v_exp_f32_e32 v35, v35
	v_cndmask_b32_e64 v65, 0, v34, s[0:1]
	v_fma_f32 v34, v42, s96, -v72
	v_exp_f32_e32 v34, v34
	v_or_b32_e32 v37, 48, v89
	v_cmp_le_i32_e64 s[0:1], v36, v69
	v_or_b32_e32 v36, 51, v89
	v_mul_f32_e64 v34, v80, v34
	v_mul_f32_e64 v35, v81, v35
	v_add_f32_e32 v38, v60, v38
	v_cndmask_b32_e64 v42, 0, v35, s[0:1]
	v_cmp_le_i32_e64 s[0:1], v37, v70
	v_fma_f32 v35, v45, s96, -v72
	v_exp_f32_e32 v35, v35
	v_cndmask_b32_e64 v43, 0, v34, s[0:1]
	v_fma_f32 v34, v44, s96, -v72
	v_exp_f32_e32 v34, v34
	v_or_b32_e32 v37, 50, v89
	v_cmp_le_i32_e64 s[0:1], v36, v69
	v_or_b32_e32 v36, 57, v89
	v_mul_f32_e64 v34, v80, v34
	v_mul_f32_e64 v35, v81, v35
	s_nop 0
	v_cndmask_b32_e64 v44, 0, v35, s[0:1]
	v_cmp_le_i32_e64 s[0:1], v37, v70
	v_fma_f32 v35, v47, s96, -v72
	v_exp_f32_e32 v35, v35
	v_cndmask_b32_e64 v45, 0, v34, s[0:1]
	v_fma_f32 v34, v46, s96, -v72
	v_exp_f32_e32 v34, v34
	v_or_b32_e32 v37, 56, v89
	v_cmp_le_i32_e64 s[0:1], v36, v69
	v_or_b32_e32 v36, 59, v89
	v_mul_f32_e64 v34, v80, v34
	v_mul_f32_e64 v35, v81, v35
	s_nop 0
	v_cndmask_b32_e64 v46, 0, v35, s[0:1]
	v_cmp_le_i32_e64 s[0:1], v37, v70
	v_fma_f32 v35, v49, s96, -v72
	v_exp_f32_e32 v35, v35
	v_cndmask_b32_e64 v47, 0, v34, s[0:1]
	v_fma_f32 v34, v48, s96, -v72
	v_exp_f32_e32 v34, v34
	v_or_b32_e32 v37, 58, v89
	v_cmp_le_i32_e64 s[0:1], v36, v69
	ds_bpermute_b32 v36, v169, v44
	v_mul_f32_e64 v34, v80, v34
	v_mul_f32_e64 v35, v81, v35
	s_nop 0
	v_cndmask_b32_e64 v48, 0, v35, s[0:1]
	v_cmp_le_i32_e64 s[0:1], v37, v70
	ds_bpermute_b32 v35, v169, v64
	ds_bpermute_b32 v88, v169, v48
	v_cndmask_b32_e64 v49, 0, v34, s[0:1]
	ds_bpermute_b32 v34, v169, v60
	s_mov_b64 s[0:1], 0x80
	v_lshl_add_u64 v[82:83], v[82:83], 0, s[0:1]
	s_waitcnt lgkmcnt(0)
	v_cndmask_b32_e32 v37, v34, v99, vcc
	v_add_f32_e32 v37, v38, v37
	v_add_f32_e32 v38, v63, v62
	v_add_f32_e32 v38, v65, v38
	v_cndmask_b32_e32 v34, v35, v34, vcc
	v_add_f32_e32 v38, v64, v38
	v_add_f32_e32 v34, v38, v34
	ds_write2_b32 v90, v37, v34 offset0:8 offset1:10
	v_cndmask_b32_e32 v34, v36, v35, vcc
	v_add_f32_e32 v35, v43, v42
	v_add_f32_e32 v35, v45, v35
	v_add_f32_e32 v35, v44, v35
	v_add_f32_e32 v34, v35, v34
	v_cndmask_b32_e32 v35, v88, v36, vcc
	v_add_f32_e32 v36, v47, v46
	v_add_f32_e32 v36, v49, v36
	v_add_f32_e32 v36, v48, v36
	v_add_f32_e32 v35, v36, v35
	ds_write2_b32 v90, v34, v35 offset0:12 offset1:14
	v_cvt_pk_bf16_f32 v34, v91, v92
	v_cvt_pk_bf16_f32 v35, v94, v93
	ds_read2_b64 v[90:93], v182 offset0:128 offset1:130
	ds_read2_b64 v[38:41], v182 offset0:132 offset1:134
	v_cvt_pk_bf16_f32 v36, v96, v95
	v_cvt_pk_bf16_f32 v37, v98, v97
	s_waitcnt lgkmcnt(1)
	s_nop 0
	v_mfma_f32_32x32x16_bf16 v[16:31], v[90:93], v[34:37], v[16:31]
	ds_read2_b64 v[90:93], v183 offset0:160 offset1:162
	s_waitcnt lgkmcnt(0)
	v_mfma_f32_32x32x16_bf16 v[0:15], v[90:93], v[34:37], v[0:15]
	v_cvt_pk_bf16_f32 v34, v51, v50
	v_cvt_pk_bf16_f32 v35, v53, v52
	v_cvt_pk_bf16_f32 v36, v55, v54
	v_cvt_pk_bf16_f32 v37, v57, v56
	s_nop 1
	v_mfma_f32_32x32x16_bf16 v[16:31], v[38:41], v[34:37], v[16:31]
	ds_read2_b64 v[38:41], v183 offset0:164 offset1:166
	s_waitcnt lgkmcnt(0)
	v_mfma_f32_32x32x16_bf16 v[0:15], v[38:41], v[34:37], v[0:15]
	ds_read2_b64 v[38:41], v182 offset0:136 offset1:138
	v_cvt_pk_bf16_f32 v34, v59, v58
	v_cvt_pk_bf16_f32 v35, v61, v60
	v_cvt_pk_bf16_f32 v36, v63, v62
	v_cvt_pk_bf16_f32 v37, v65, v64
	s_waitcnt lgkmcnt(0)
	s_nop 0
	v_mfma_f32_32x32x16_bf16 v[16:31], v[38:41], v[34:37], v[16:31]
	ds_read2_b64 v[38:41], v183 offset0:168 offset1:170
	s_waitcnt lgkmcnt(0)
	v_mfma_f32_32x32x16_bf16 v[0:15], v[38:41], v[34:37], v[0:15]
	ds_read2_b64 v[38:41], v182 offset0:140 offset1:142
	v_cvt_pk_bf16_f32 v34, v43, v42
	v_cvt_pk_bf16_f32 v35, v45, v44
	v_cvt_pk_bf16_f32 v36, v47, v46
	v_cvt_pk_bf16_f32 v37, v49, v48
	s_waitcnt lgkmcnt(0)
	s_nop 0
	v_mfma_f32_32x32x16_bf16 v[16:31], v[38:41], v[34:37], v[16:31]
	ds_read2_b64 v[38:41], v183 offset0:172 offset1:174
	s_waitcnt lgkmcnt(0)
	v_mfma_f32_32x32x16_bf16 v[0:15], v[38:41], v[34:37], v[0:15]
	s_cbranch_scc0 .LBB0_1065

; DI int crow(int i, int h) { return (i & 3) + 8 * (i >> 2) + 4 * h; }
; DI float shx32(float v) { return __shfl_xor(v, 32); }
; template <bool MASKED>
; DI float online_softmax_t(f32x16 (&Sx)[2], unsigned vb, float& m, float& l) {
;   float mx = NEG;
; #pragma unroll
;   for (int mt = 0; mt < 2; ++mt)
; #pragma unroll
;     for (int i = 0; i < 16; ++i) {
;       float s = Sx[mt][i];
;       if (MASKED) { s = ((vb >> (mt * 16 + i)) & 1u) ? s : NEG; Sx[mt][i] = s; }
;       mx = fmaxf(mx, s);
;     }
;   mx = fmaxf(mx, shx32(mx));
;   const float mn = fmaxf(m, mx);
;   const float alpha = __builtin_amdgcn_exp2f((m - mn) * L2E);
; DI void nsa_item(const Params& p_, const EvenBufs& eb_, int b, int g, int tt, unsigned char* smem) {
;     ...
;       f32x16 Sx[2]; qk_tile(sK, qf, Sx, r, h);
;       const bool sb = (mysel >> j) & 1ull;
;       unsigned vb = sb ? 0xffffffffu : 0u;
;       bool masked = (__ballot(sb) != ~0ull);
;       if (j == (t0 >> 6)) {
;         masked = true; vb = 0;
; #pragma unroll
;         for (int mt = 0; mt < 2; ++mt)
; #pragma unroll
;           for (int i = 0; i < 16; ++i) vb |= (unsigned)(sb && (j * 64 + mt * 32 + crow(i, h) <= t)) << (mt * 16 + i);
;       }
;       if (!masked) vb = 0xffffffffu;
;       const float alpha = online_softmax_t<true>(Sx, vb, m, l);
.LBB0_1079:
	v_cndmask_b32_e64 v128, -1, v128, s[4:5]
	v_and_b32_e32 v129, 1, v128
	v_cmp_eq_u32_e64 s[64:65], 0, v129
	v_cmp_lt_i32_e64 s[20:21], -1, v128
	s_cmp_gt_i32 s33, -1
	v_cndmask_b32_e64 v150, v82, v214, s[64:65]
	v_and_b32_e32 v82, 2, v128
	v_cmp_eq_u32_e64 s[66:67], 0, v82
	s_nop 1
	v_cndmask_b32_e64 v151, v83, v214, s[66:67]
	v_and_b32_e32 v83, 4, v128
	v_cmp_eq_u32_e64 s[60:61], 0, v83
	v_and_b32_e32 v83, 8, v128
	v_cmp_eq_u32_e64 s[62:63], 0, v83
	v_and_b32_e32 v83, 16, v128
	v_cmp_eq_u32_e64 s[56:57], 0, v83
	v_and_b32_e32 v83, 32, v128
	v_cmp_eq_u32_e64 s[58:59], 0, v83
	v_and_b32_e32 v83, 64, v128
	v_cmp_eq_u32_e64 s[52:53], 0, v83
	v_and_b32_e32 v83, 0x80, v128
	v_cmp_eq_u32_e64 s[54:55], 0, v83
	v_and_b32_e32 v83, 0x100, v128
	v_cmp_eq_u32_e64 s[48:49], 0, v83
	v_and_b32_e32 v83, 0x200, v128
	v_cmp_eq_u32_e64 s[50:51], 0, v83
	v_and_b32_e32 v83, 0x400, v128
	v_max3_f32 v82, v150, s92, v151
	v_cndmask_b32_e64 v152, v84, v214, s[60:61]
	v_cndmask_b32_e64 v153, v85, v214, s[62:63]
	v_cmp_eq_u32_e64 s[44:45], 0, v83
	v_and_b32_e32 v83, 0x800, v128
	v_max3_f32 v82, v82, v152, v153
	v_cndmask_b32_e64 v154, v86, v214, s[56:57]
	v_cndmask_b32_e64 v155, v87, v214, s[58:59]
	v_cmp_eq_u32_e64 s[46:47], 0, v83
	v_and_b32_e32 v83, 0x1000, v128
	v_max3_f32 v82, v82, v154, v155
	v_cndmask_b32_e64 v156, v88, v214, s[52:53]
	v_cndmask_b32_e64 v157, v89, v214, s[54:55]
	v_cmp_eq_u32_e64 s[40:41], 0, v83
	v_and_b32_e32 v83, 0x2000, v128
	v_max3_f32 v82, v82, v156, v157
	v_cndmask_b32_e64 v158, v90, v214, s[48:49]
	v_cndmask_b32_e64 v159, v91, v214, s[50:51]
	v_cmp_eq_u32_e64 s[42:43], 0, v83
	v_and_b32_e32 v83, 0x4000, v128
	v_max3_f32 v82, v82, v158, v159
	v_cndmask_b32_e64 v160, v92, v214, s[44:45]
	v_cndmask_b32_e64 v161, v93, v214, s[46:47]
	v_cmp_eq_u32_e64 s[36:37], 0, v83
	v_and_b32_e32 v83, 0x8000, v128
	v_max3_f32 v82, v82, v160, v161
	v_cndmask_b32_e64 v174, v94, v214, s[40:41]
	v_cndmask_b32_e64 v175, v95, v214, s[42:43]
	v_cmp_eq_u32_e64 s[38:39], 0, v83
	v_max3_f32 v82, v82, v174, v175
	v_cndmask_b32_e64 v176, v96, v214, s[36:37]
	v_cndmask_b32_e64 v177, v97, v214, s[38:39]
	v_max3_f32 v84, v82, v176, v177
	v_and_b32_e32 v82, 0x10000, v128
	v_cmp_eq_u32_e64 s[30:31], 0, v82
	s_nop 1
	v_cndmask_b32_e64 v82, v66, v214, s[30:31]
	v_and_b32_e32 v66, 0x20000, v128
	v_cmp_eq_u32_e64 s[34:35], 0, v66
	s_nop 1
	v_cndmask_b32_e64 v83, v67, v214, s[34:35]
	v_and_b32_e32 v67, 0x40000, v128
	v_cmp_eq_u32_e64 s[26:27], 0, v67
	v_and_b32_e32 v67, 0x80000, v128
	v_cmp_eq_u32_e64 s[28:29], 0, v67
	v_and_b32_e32 v67, 0x100000, v128
	v_cmp_eq_u32_e64 s[22:23], 0, v67
	v_and_b32_e32 v67, 0x200000, v128
	v_cmp_eq_u32_e64 s[24:25], 0, v67
	v_and_b32_e32 v67, 0x400000, v128
	v_cmp_eq_u32_e64 s[2:3], 0, v67
	v_and_b32_e32 v67, 0x800000, v128
	v_cmp_eq_u32_e64 s[4:5], 0, v67
	v_and_b32_e32 v67, 0x1000000, v128
	v_cmp_eq_u32_e64 s[6:7], 0, v67
	v_and_b32_e32 v67, 0x2000000, v128
	v_max3_f32 v66, v84, v82, v83
	v_cndmask_b32_e64 v84, v68, v214, s[26:27]
	v_cndmask_b32_e64 v85, v69, v214, s[28:29]
	v_cmp_eq_u32_e64 s[8:9], 0, v67
	v_and_b32_e32 v67, 0x4000000, v128
	v_max3_f32 v66, v66, v84, v85
	v_cndmask_b32_e64 v88, v70, v214, s[22:23]
	v_cndmask_b32_e64 v89, v71, v214, s[24:25]
	v_cmp_eq_u32_e64 s[10:11], 0, v67
	v_and_b32_e32 v67, 0x8000000, v128
	v_max3_f32 v66, v66, v88, v89
	v_cndmask_b32_e64 v92, v72, v214, s[2:3]
	v_cndmask_b32_e64 v93, v73, v214, s[4:5]
	v_cmp_eq_u32_e64 s[12:13], 0, v67
	v_and_b32_e32 v67, 0x10000000, v128
	v_max3_f32 v66, v66, v92, v93
	v_cndmask_b32_e64 v72, v74, v214, s[6:7]
	v_cndmask_b32_e64 v73, v75, v214, s[8:9]
	v_cmp_eq_u32_e64 s[14:15], 0, v67
	v_and_b32_e32 v67, 0x20000000, v128
	v_max3_f32 v66, v66, v72, v73
	v_cndmask_b32_e64 v74, v76, v214, s[10:11]
	v_cndmask_b32_e64 v75, v77, v214, s[12:13]
	v_cmp_eq_u32_e64 s[16:17], 0, v67
	v_and_b32_e32 v67, 2.0, v128
	v_max3_f32 v66, v66, v74, v75
	v_cndmask_b32_e64 v76, v78, v214, s[14:15]
	v_cndmask_b32_e64 v77, v79, v214, s[16:17]
	v_cmp_eq_u32_e64 s[18:19], 0, v67
	v_max3_f32 v66, v66, v76, v77
	v_cndmask_b32_e64 v79, v81, v214, s[20:21]
	v_cndmask_b32_e64 v78, v80, v214, s[18:19]
	v_max3_f32 v66, v66, v78, v79
	ds_bpermute_b32 v67, v169, v66
	s_waitcnt lgkmcnt(0)
	v_max3_f32 v129, v148, v66, v67
	v_mul_f32_e32 v128, 0x3fb8aa3b, v129
	v_fma_f32 v68, v152, s96, -v128
	v_fma_f32 v69, v153, s96, -v128
	v_fma_f32 v66, v150, s96, -v128
	v_fma_f32 v67, v151, s96, -v128
	v_exp_f32_e32 v68, v68
	v_exp_f32_e32 v69, v69
	v_exp_f32_e32 v66, v66
	v_exp_f32_e32 v67, v67
	v_cndmask_b32_e64 v90, v68, 0, s[60:61]
	v_cndmask_b32_e64 v91, v69, 0, s[62:63]
	v_fma_f32 v68, v154, s96, -v128
	v_fma_f32 v69, v155, s96, -v128
	v_cndmask_b32_e64 v86, v66, 0, s[64:65]
	v_exp_f32_e32 v68, v68
	v_exp_f32_e32 v69, v69
	v_cndmask_b32_e64 v87, v67, 0, s[66:67]
	v_add_f32_e64 v66, v86, 0
	v_add_f32_e64 v67, v87, 0
	v_cndmask_b32_e64 v94, v68, 0, s[56:57]
	v_cndmask_b32_e64 v95, v69, 0, s[58:59]
	v_fma_f32 v68, v156, s96, -v128
	v_fma_f32 v69, v157, s96, -v128
	v_add_f32_e64 v66, v90, v66
	v_add_f32_e64 v67, v91, v67
	v_exp_f32_e32 v68, v68
	v_exp_f32_e32 v69, v69
	v_add_f32_e64 v66, v94, v66
	v_add_f32_e64 v67, v95, v67
	v_fma_f32 v82, v82, s96, -v128
	v_fma_f32 v83, v83, s96, -v128
	v_cndmask_b32_e64 v96, v68, 0, s[52:53]
	v_cndmask_b32_e64 v97, v69, 0, s[54:55]
	v_add_f32_e64 v68, v96, v66
	v_add_f32_e64 v69, v97, v67
	v_fma_f32 v66, v158, s96, -v128
	v_fma_f32 v67, v159, s96, -v128
	v_exp_f32_e32 v82, v82
	v_exp_f32_e32 v66, v66
	v_exp_f32_e32 v67, v67
	v_exp_f32_e32 v83, v83
	v_fma_f32 v84, v84, s96, -v128
	v_fma_f32 v85, v85, s96, -v128
	v_cndmask_b32_e64 v66, v66, 0, s[48:49]
; template <bool MASKED>
; DI float online_softmax_t(f32x16 (&Sx)[2], unsigned vb, float& m, float& l) {
;     ...
;   const float alpha = __builtin_amdgcn_exp2f((m - mn) * L2E);
;   const float mb = mn * L2E;
;   f32x2 sum2 = {0.f, 0.f};
;   const f32x2 l2e2 = {L2E, L2E}, mb2 = {mb, mb};
; #pragma unroll
;   for (int mt = 0; mt < 2; ++mt)
; #pragma unroll
;     for (int i = 0; i < 16; i += 2) {
;       const f32x2 t = (f32x2){Sx[mt][i], Sx[mt][i + 1]} * l2e2 - mb2;
;       f32x2 p = {__builtin_amdgcn_exp2f(t.x), __builtin_amdgcn_exp2f(t.y)};
;       if (MASKED) { p.x = ((vb >> (mt * 16 + i)) & 1u) ? p.x : 0.f; p.y = ((vb >> (mt * 16 + i + 1)) & 1u) ? p.y : 0.f; }
;       Sx[mt][i] = p.x; Sx[mt][i + 1] = p.y;
;       sum2 += p;
;     }
;   l = l * alpha + (sum2.x + sum2.y);
;   m = mn;
;   return alpha;
; DI void nsa_item(const Params& p_, const EvenBufs& eb_, int b, int g, int tt, unsigned char* smem) {
;     ...
;       const float alpha = online_softmax_t<true>(Sx, vb, m, l);
;       scale_o<2>(O, alpha);
;       pv_tile<2>(sV, Sx, O, r, h);
	v_cndmask_b32_e64 v67, v67, 0, s[50:51]
	v_add_f32_e64 v70, v66, v68
	v_add_f32_e64 v71, v67, v69
	v_fma_f32 v68, v160, s96, -v128
	v_fma_f32 v69, v161, s96, -v128
	v_exp_f32_e32 v84, v84
	v_exp_f32_e32 v68, v68
	v_exp_f32_e32 v69, v69
	v_exp_f32_e32 v85, v85
	v_fma_f32 v88, v88, s96, -v128
	v_fma_f32 v89, v89, s96, -v128
	v_cndmask_b32_e64 v68, v68, 0, s[44:45]
	v_cndmask_b32_e64 v69, v69, 0, s[46:47]
	v_add_f32_e64 v80, v68, v70
	v_add_f32_e64 v81, v69, v71
	v_fma_f32 v70, v174, s96, -v128
	v_fma_f32 v71, v175, s96, -v128
	v_exp_f32_e32 v88, v88
	v_exp_f32_e32 v70, v70
	v_exp_f32_e32 v71, v71
	v_exp_f32_e32 v89, v89
	v_fma_f32 v92, v92, s96, -v128
	v_fma_f32 v93, v93, s96, -v128
	v_cndmask_b32_e64 v70, v70, 0, s[40:41]
	v_cndmask_b32_e64 v71, v71, 0, s[42:43]
	v_add_f32_e64 v150, v70, v80
	v_add_f32_e64 v151, v71, v81
	v_fma_f32 v80, v176, s96, -v128
	v_fma_f32 v81, v177, s96, -v128
	v_exp_f32_e32 v92, v92
	v_exp_f32_e32 v80, v80
	v_exp_f32_e32 v81, v81
	v_exp_f32_e32 v93, v93
	v_fma_f32 v72, v72, s96, -v128
	v_fma_f32 v73, v73, s96, -v128
	v_cndmask_b32_e64 v80, v80, 0, s[36:37]
	v_cndmask_b32_e64 v81, v81, 0, s[38:39]
	v_add_f32_e64 v150, v80, v150
	v_add_f32_e64 v151, v81, v151
	v_cndmask_b32_e64 v82, v82, 0, s[30:31]
	v_cndmask_b32_e64 v83, v83, 0, s[34:35]
	v_exp_f32_e32 v72, v72
	v_exp_f32_e32 v73, v73
	v_fma_f32 v74, v74, s96, -v128
	v_fma_f32 v75, v75, s96, -v128
	v_add_f32_e64 v150, v82, v150
	v_add_f32_e64 v151, v83, v151
	v_cndmask_b32_e64 v84, v84, 0, s[26:27]
	v_cndmask_b32_e64 v85, v85, 0, s[28:29]
	v_exp_f32_e32 v74, v74
	v_exp_f32_e32 v75, v75
	v_fma_f32 v76, v76, s96, -v128
	v_fma_f32 v77, v77, s96, -v128
	v_add_f32_e64 v150, v84, v150
	v_add_f32_e64 v151, v85, v151
	v_cndmask_b32_e64 v88, v88, 0, s[22:23]
	v_cndmask_b32_e64 v89, v89, 0, s[24:25]
	v_exp_f32_e32 v76, v76
	v_exp_f32_e32 v77, v77
	v_fma_f32 v78, v78, s96, -v128
	v_fma_f32 v79, v79, s96, -v128
	v_add_f32_e64 v150, v88, v150
	v_add_f32_e64 v151, v89, v151
	v_cndmask_b32_e64 v92, v92, 0, s[2:3]
	v_cndmask_b32_e64 v93, v93, 0, s[4:5]
	v_exp_f32_e32 v78, v78
	v_exp_f32_e32 v79, v79
	v_add_f32_e64 v150, v92, v150
	v_add_f32_e64 v151, v93, v151
	v_cndmask_b32_e64 v72, v72, 0, s[6:7]
	v_cndmask_b32_e64 v73, v73, 0, s[8:9]
	v_add_f32_e64 v150, v72, v150
	v_add_f32_e64 v151, v73, v151
	v_cndmask_b32_e64 v74, v74, 0, s[10:11]
	v_cndmask_b32_e64 v75, v75, 0, s[12:13]
	v_add_f32_e64 v150, v74, v150
	v_add_f32_e64 v151, v75, v151
	v_cndmask_b32_e64 v76, v76, 0, s[14:15]
	v_cndmask_b32_e64 v77, v77, 0, s[16:17]
	v_sub_f32_e32 v128, v148, v129
	v_add_f32_e64 v150, v76, v150
	v_add_f32_e64 v151, v77, v151
	v_cndmask_b32_e64 v78, v78, 0, s[18:19]
	v_cndmask_b32_e64 v79, v79, 0, s[20:21]
	v_mul_f32_e32 v128, 0x3fb8aa3b, v128
	v_add_f32_e64 v150, v78, v150
	v_add_f32_e64 v151, v79, v151
	v_exp_f32_e32 v128, v128
	v_add_f32_e32 v184, v150, v151
	v_cvt_pk_bf16_f32 v150, v94, v95
	v_cvt_pk_bf16_f32 v151, v96, v97
	ds_read2_b64 v[94:97], v182 offset0:128 offset1:130
	ds_read2_b64 v[152:155], v182 offset0:132 offset1:134
	v_mul_f32_e64 v50, v50, v128
	v_mul_f32_e64 v51, v51, v128
	v_mul_f32_e64 v52, v52, v128
	v_mul_f32_e64 v53, v53, v128
	v_mul_f32_e64 v54, v54, v128
	v_mul_f32_e64 v55, v55, v128
	v_mul_f32_e64 v56, v56, v128
	v_mul_f32_e64 v57, v57, v128
	v_mul_f32_e64 v58, v58, v128
	v_mul_f32_e64 v59, v59, v128
	v_mul_f32_e64 v60, v60, v128
	v_mul_f32_e64 v61, v61, v128
	v_mul_f32_e64 v62, v62, v128
	v_mul_f32_e64 v63, v63, v128
	v_mul_f32_e64 v64, v64, v128
	v_mul_f32_e64 v65, v65, v128
	v_cvt_pk_bf16_f32 v148, v86, v87
	v_cvt_pk_bf16_f32 v149, v90, v91
	v_mul_f32_e64 v34, v34, v128
	v_mul_f32_e64 v35, v35, v128
	v_mul_f32_e64 v36, v36, v128
	v_mul_f32_e64 v37, v37, v128
	s_waitcnt lgkmcnt(1)
	v_mfma_f32_32x32x16_bf16 v[50:65], v[94:97], v[148:151], v[50:65]
	ds_read2_b64 v[94:97], v183 offset0:160 offset1:162
	v_mul_f32_e64 v38, v38, v128
	v_mul_f32_e64 v39, v39, v128
	v_mul_f32_e64 v40, v40, v128
	v_mul_f32_e64 v41, v41, v128
	v_mul_f32_e64 v42, v42, v128
	v_mul_f32_e64 v43, v43, v128
	v_mul_f32_e64 v44, v44, v128
	v_mul_f32_e64 v45, v45, v128
	v_mul_f32_e64 v46, v46, v128
	v_mul_f32_e64 v47, v47, v128
	v_mul_f32_e64 v48, v48, v128
	v_mul_f32_e64 v49, v49, v128
	v_cvt_pk_bf16_f32 v66, v66, v67
	v_cvt_pk_bf16_f32 v67, v68, v69
	s_waitcnt lgkmcnt(0)
	v_mfma_f32_32x32x16_bf16 v[34:49], v[94:97], v[148:151], v[34:49]
	ds_read2_b64 v[94:97], v183 offset0:164 offset1:166
	v_cvt_pk_bf16_f32 v68, v70, v71
	v_cvt_pk_bf16_f32 v69, v80, v81
	v_fmac_f32_e32 v184, v147, v128
	s_nop 0
	v_mfma_f32_32x32x16_bf16 v[50:65], v[152:155], v[66:69], v[50:65]
	s_waitcnt lgkmcnt(0)
	v_mfma_f32_32x32x16_bf16 v[34:49], v[94:97], v[66:69], v[34:49]
	v_cvt_pk_bf16_f32 v66, v82, v83
	ds_read2_b64 v[80:83], v182 offset0:136 offset1:138
	v_cvt_pk_bf16_f32 v67, v84, v85
	v_cvt_pk_bf16_f32 v68, v88, v89
	v_cvt_pk_bf16_f32 v69, v92, v93
	s_waitcnt lgkmcnt(0)
	s_nop 0
	v_mfma_f32_32x32x16_bf16 v[50:65], v[80:83], v[66:69], v[50:65]
	ds_read2_b64 v[80:83], v183 offset0:168 offset1:170
	s_waitcnt lgkmcnt(0)
	v_mfma_f32_32x32x16_bf16 v[34:49], v[80:83], v[66:69], v[34:49]
	v_cvt_pk_bf16_f32 v66, v72, v73
	ds_read2_b64 v[70:73], v182 offset0:140 offset1:142
	v_cvt_pk_bf16_f32 v67, v74, v75
	v_cvt_pk_bf16_f32 v68, v76, v77
	v_cvt_pk_bf16_f32 v69, v78, v79
	s_waitcnt lgkmcnt(0)
	s_nop 0
	v_mfma_f32_32x32x16_bf16 v[50:65], v[70:73], v[66:69], v[50:65]
	ds_read2_b64 v[70:73], v183 offset0:172 offset1:174
	s_waitcnt lgkmcnt(0)
	v_mfma_f32_32x32x16_bf16 v[34:49], v[70:73], v[66:69], v[34:49]
	s_cbranch_scc0 .LBB0_1081
	v_mov_b32_e32 v147, v184
	v_mov_b32_e32 v148, v129
	s_mov_b64 s[4:5], s[68:69]
	s_mov_b32 s6, s33
	s_branch .LBB0_1073
; DI float shx32(float v) { return __shfl_xor(v, 32); }
; template <bool MASKED>
; DI float online_softmax_t(f32x16 (&Sx)[2], unsigned vb, float& m, float& l) {
;   float mx = NEG;
; #pragma unroll
;   for (int mt = 0; mt < 2; ++mt)
; #pragma unroll
;     for (int i = 0; i < 16; ++i) {
;       float s = Sx[mt][i];
;       if (MASKED) { s = ((vb >> (mt * 16 + i)) & 1u) ? s : NEG; Sx[mt][i] = s; }
;       mx = fmaxf(mx, s);
;     }
;   mx = fmaxf(mx, shx32(mx));
;   const float mn = fmaxf(m, mx);
;   const float alpha = __builtin_amdgcn_exp2f((m - mn) * L2E);
;   const float mb = mn * L2E;
;   f32x2 sum2 = {0.f, 0.f};
;   const f32x2 l2e2 = {L2E, L2E}, mb2 = {mb, mb};
; #pragma unroll
;   for (int mt = 0; mt < 2; ++mt)
; #pragma unroll
;     for (int i = 0; i < 16; i += 2) {
;       const f32x2 t = (f32x2){Sx[mt][i], Sx[mt][i + 1]} * l2e2 - mb2;
;       f32x2 p = {__builtin_amdgcn_exp2f(t.x), __builtin_amdgcn_exp2f(t.y)};
;       if (MASKED) { p.x = ((vb >> (mt * 16 + i)) & 1u) ? p.x : 0.f; p.y = ((vb >> (mt * 16 + i + 1)) & 1u) ? p.y : 0.f; }
;       Sx[mt][i] = p.x; Sx[mt][i + 1] = p.y;
;       sum2 += p;
;     }
;   l = l * alpha + (sum2.x + sum2.y);
;   m = mn;
;   return alpha;
; }
.Lsel_fast:
	s_nop 3
	v_cndmask_b32_e64 v128, -1, v128, s[4:5]
	v_and_b32_e32 v129, 1, v128
	v_cmp_eq_u32_e64 s[64:65], 0, v129
	s_cmp_gt_i32 s33, -1
	s_nop 0
	v_cndmask_b32_e64 v150, v82, v214, s[64:65]
	s_nop 1
	v_cndmask_b32_e64 v151, v83, v214, s[64:65]
	v_max3_f32 v82, v150, s92, v151
	v_cndmask_b32_e64 v152, v84, v214, s[64:65]
	v_cndmask_b32_e64 v153, v85, v214, s[64:65]
	v_max3_f32 v82, v82, v152, v153
	v_cndmask_b32_e64 v154, v86, v214, s[64:65]
	v_cndmask_b32_e64 v155, v87, v214, s[64:65]
	v_max3_f32 v82, v82, v154, v155
	v_cndmask_b32_e64 v156, v88, v214, s[64:65]
	v_cndmask_b32_e64 v157, v89, v214, s[64:65]
	v_max3_f32 v82, v82, v156, v157
	v_cndmask_b32_e64 v158, v90, v214, s[64:65]
	v_cndmask_b32_e64 v159, v91, v214, s[64:65]
	v_max3_f32 v82, v82, v158, v159
	v_cndmask_b32_e64 v160, v92, v214, s[64:65]
	v_cndmask_b32_e64 v161, v93, v214, s[64:65]
	v_max3_f32 v82, v82, v160, v161
	v_cndmask_b32_e64 v174, v94, v214, s[64:65]
	v_cndmask_b32_e64 v175, v95, v214, s[64:65]
	v_max3_f32 v82, v82, v174, v175
	v_cndmask_b32_e64 v176, v96, v214, s[64:65]
	v_cndmask_b32_e64 v177, v97, v214, s[64:65]
	v_max3_f32 v84, v82, v176, v177
	s_nop 1
	v_cndmask_b32_e64 v82, v66, v214, s[64:65]
	s_nop 1
	v_cndmask_b32_e64 v83, v67, v214, s[64:65]
	v_max3_f32 v66, v84, v82, v83
	v_cndmask_b32_e64 v84, v68, v214, s[64:65]
	v_cndmask_b32_e64 v85, v69, v214, s[64:65]
	v_max3_f32 v66, v66, v84, v85
	v_cndmask_b32_e64 v88, v70, v214, s[64:65]
	v_cndmask_b32_e64 v89, v71, v214, s[64:65]
	v_max3_f32 v66, v66, v88, v89
	v_cndmask_b32_e64 v92, v72, v214, s[64:65]
	v_cndmask_b32_e64 v93, v73, v214, s[64:65]
	v_max3_f32 v66, v66, v92, v93
	v_cndmask_b32_e64 v72, v74, v214, s[64:65]
	v_cndmask_b32_e64 v73, v75, v214, s[64:65]
	v_max3_f32 v66, v66, v72, v73
	v_cndmask_b32_e64 v74, v76, v214, s[64:65]
	v_cndmask_b32_e64 v75, v77, v214, s[64:65]
	v_max3_f32 v66, v66, v74, v75
	v_cndmask_b32_e64 v76, v78, v214, s[64:65]
	v_cndmask_b32_e64 v77, v79, v214, s[64:65]
	v_max3_f32 v66, v66, v76, v77
	v_cndmask_b32_e64 v79, v81, v214, s[64:65]
	v_cndmask_b32_e64 v78, v80, v214, s[64:65]
	v_max3_f32 v66, v66, v78, v79
	ds_bpermute_b32 v67, v169, v66
	s_waitcnt lgkmcnt(0)
	v_max3_f32 v129, v148, v66, v67
	v_mul_f32_e32 v128, 0x3fb8aa3b, v129
	v_fma_f32 v68, v152, s96, -v128
	v_fma_f32 v69, v153, s96, -v128
	v_fma_f32 v66, v150, s96, -v128
	v_fma_f32 v67, v151, s96, -v128
	v_exp_f32_e32 v68, v68
	v_exp_f32_e32 v69, v69
	v_exp_f32_e32 v66, v66
	v_exp_f32_e32 v67, v67
	v_cndmask_b32_e64 v90, v68, 0, s[64:65]
	v_cndmask_b32_e64 v91, v69, 0, s[64:65]
	v_fma_f32 v68, v154, s96, -v128
	v_fma_f32 v69, v155, s96, -v128
	v_cndmask_b32_e64 v86, v66, 0, s[64:65]
	v_exp_f32_e32 v68, v68
	v_exp_f32_e32 v69, v69
	v_cndmask_b32_e64 v87, v67, 0, s[64:65]
	v_add_f32_e64 v66, v86, 0
	v_add_f32_e64 v67, v87, 0
	v_cndmask_b32_e64 v94, v68, 0, s[64:65]
	v_cndmask_b32_e64 v95, v69, 0, s[64:65]
	v_fma_f32 v68, v156, s96, -v128
	v_fma_f32 v69, v157, s96, -v128
	v_add_f32_e64 v66, v90, v66
	v_add_f32_e64 v67, v91, v67
	v_exp_f32_e32 v68, v68
	v_exp_f32_e32 v69, v69
	v_add_f32_e64 v66, v94, v66
	v_add_f32_e64 v67, v95, v67
	v_fma_f32 v82, v82, s96, -v128
	v_fma_f32 v83, v83, s96, -v128
	v_cndmask_b32_e64 v96, v68, 0, s[64:65]
	v_cndmask_b32_e64 v97, v69, 0, s[64:65]
	v_add_f32_e64 v68, v96, v66
	v_add_f32_e64 v69, v97, v67
	v_fma_f32 v66, v158, s96, -v128
	v_fma_f32 v67, v159, s96, -v128
	v_exp_f32_e32 v82, v82
	v_exp_f32_e32 v66, v66
	v_exp_f32_e32 v67, v67
	v_exp_f32_e32 v83, v83
	v_fma_f32 v84, v84, s96, -v128
	v_fma_f32 v85, v85, s96, -v128
	v_cndmask_b32_e64 v66, v66, 0, s[64:65]
	v_cndmask_b32_e64 v67, v67, 0, s[64:65]
	v_add_f32_e64 v70, v66, v68
	v_add_f32_e64 v71, v67, v69
	v_fma_f32 v68, v160, s96, -v128
	v_fma_f32 v69, v161, s96, -v128
	v_exp_f32_e32 v84, v84
	v_exp_f32_e32 v68, v68
	v_exp_f32_e32 v69, v69
	v_exp_f32_e32 v85, v85
	v_fma_f32 v88, v88, s96, -v128
	v_fma_f32 v89, v89, s96, -v128
	v_cndmask_b32_e64 v68, v68, 0, s[64:65]
	v_cndmask_b32_e64 v69, v69, 0, s[64:65]
	v_add_f32_e64 v80, v68, v70
	v_add_f32_e64 v81, v69, v71
	v_fma_f32 v70, v174, s96, -v128
	v_fma_f32 v71, v175, s96, -v128
	v_exp_f32_e32 v88, v88
	v_exp_f32_e32 v70, v70
	v_exp_f32_e32 v71, v71
	v_exp_f32_e32 v89, v89
	v_fma_f32 v92, v92, s96, -v128
	v_fma_f32 v93, v93, s96, -v128
	v_cndmask_b32_e64 v70, v70, 0, s[64:65]
	v_cndmask_b32_e64 v71, v71, 0, s[64:65]
	v_add_f32_e64 v150, v70, v80
	v_add_f32_e64 v151, v71, v81
	v_fma_f32 v80, v176, s96, -v128
	v_fma_f32 v81, v177, s96, -v128
	v_exp_f32_e32 v92, v92
	v_exp_f32_e32 v80, v80
	v_exp_f32_e32 v81, v81
	v_exp_f32_e32 v93, v93
	v_fma_f32 v72, v72, s96, -v128
	v_fma_f32 v73, v73, s96, -v128
	v_cndmask_b32_e64 v80, v80, 0, s[64:65]
	v_cndmask_b32_e64 v81, v81, 0, s[64:65]
	v_add_f32_e64 v150, v80, v150
	v_add_f32_e64 v151, v81, v151
	v_cndmask_b32_e64 v82, v82, 0, s[64:65]
	v_cndmask_b32_e64 v83, v83, 0, s[64:65]
	v_exp_f32_e32 v72, v72
	v_exp_f32_e32 v73, v73
	v_fma_f32 v74, v74, s96, -v128
	v_fma_f32 v75, v75, s96, -v128
	v_add_f32_e64 v150, v82, v150
	v_add_f32_e64 v151, v83, v151
	v_cndmask_b32_e64 v84, v84, 0, s[64:65]
	v_cndmask_b32_e64 v85, v85, 0, s[64:65]
	v_exp_f32_e32 v74, v74
	v_exp_f32_e32 v75, v75
	v_fma_f32 v76, v76, s96, -v128
	v_fma_f32 v77, v77, s96, -v128
	v_add_f32_e64 v150, v84, v150
	v_add_f32_e64 v151, v85, v151
	v_cndmask_b32_e64 v88, v88, 0, s[64:65]
	v_cndmask_b32_e64 v89, v89, 0, s[64:65]
	v_exp_f32_e32 v76, v76
	v_exp_f32_e32 v77, v77
	v_fma_f32 v78, v78, s96, -v128
	v_fma_f32 v79, v79, s96, -v128
	v_add_f32_e64 v150, v88, v150
	v_add_f32_e64 v151, v89, v151
	v_cndmask_b32_e64 v92, v92, 0, s[64:65]
	v_cndmask_b32_e64 v93, v93, 0, s[64:65]
; template <bool MASKED>
; DI float online_softmax_t(f32x16 (&Sx)[2], unsigned vb, float& m, float& l) {
;     ...
;   const float alpha = __builtin_amdgcn_exp2f((m - mn) * L2E);
;   const float mb = mn * L2E;
;   f32x2 sum2 = {0.f, 0.f};
;   const f32x2 l2e2 = {L2E, L2E}, mb2 = {mb, mb};
; #pragma unroll
;   for (int mt = 0; mt < 2; ++mt)
; #pragma unroll
;     for (int i = 0; i < 16; i += 2) {
;       const f32x2 t = (f32x2){Sx[mt][i], Sx[mt][i + 1]} * l2e2 - mb2;
;       f32x2 p = {__builtin_amdgcn_exp2f(t.x), __builtin_amdgcn_exp2f(t.y)};
;       if (MASKED) { p.x = ((vb >> (mt * 16 + i)) & 1u) ? p.x : 0.f; p.y = ((vb >> (mt * 16 + i + 1)) & 1u) ? p.y : 0.f; }
;       Sx[mt][i] = p.x; Sx[mt][i + 1] = p.y;
;       sum2 += p;
;     }
;   l = l * alpha + (sum2.x + sum2.y);
;   m = mn;
;   return alpha;
; }
; DI void nsa_item(const Params& p_, const EvenBufs& eb_, int b, int g, int tt, unsigned char* smem) {
;     ...
;   for (int kt = 0; kt < nct; ++kt) {
;     TR_<2> kr, vr; tload(kr, Kc + kt * 64 * 64, 64, tid); tload(vr, VcT + kt * 64, 256, tid);
;     __syncthreads();
;     tstore72(kr, sK, tid); tstore68(vr, sV, tid);
;     __syncthreads();
;     f32x16 Sx[2]; qk_tile(sK, qf, Sx, r, h);
	v_exp_f32_e32 v78, v78
	v_exp_f32_e32 v79, v79
	v_add_f32_e64 v150, v92, v150
	v_add_f32_e64 v151, v93, v151
	v_cndmask_b32_e64 v72, v72, 0, s[64:65]
	v_cndmask_b32_e64 v73, v73, 0, s[64:65]
	v_add_f32_e64 v150, v72, v150
	v_add_f32_e64 v151, v73, v151
	v_cndmask_b32_e64 v74, v74, 0, s[64:65]
	v_cndmask_b32_e64 v75, v75, 0, s[64:65]
	v_add_f32_e64 v150, v74, v150
	v_add_f32_e64 v151, v75, v151
	v_cndmask_b32_e64 v76, v76, 0, s[64:65]
	v_cndmask_b32_e64 v77, v77, 0, s[64:65]
	v_sub_f32_e32 v128, v148, v129
	v_add_f32_e64 v150, v76, v150
	v_add_f32_e64 v151, v77, v151
	v_cndmask_b32_e64 v78, v78, 0, s[64:65]
	v_cndmask_b32_e64 v79, v79, 0, s[64:65]
	v_mul_f32_e32 v128, 0x3fb8aa3b, v128
	v_add_f32_e64 v150, v78, v150
	v_add_f32_e64 v151, v79, v151
	v_exp_f32_e32 v128, v128
	v_add_f32_e32 v184, v150, v151
	v_cvt_pk_bf16_f32 v150, v94, v95
	v_cvt_pk_bf16_f32 v151, v96, v97
	ds_read2_b64 v[94:97], v182 offset0:128 offset1:130
	ds_read2_b64 v[152:155], v182 offset0:132 offset1:134
	v_mul_f32_e64 v50, v50, v128
	v_mul_f32_e64 v51, v51, v128
	v_mul_f32_e64 v52, v52, v128
	v_mul_f32_e64 v53, v53, v128
	v_mul_f32_e64 v54, v54, v128
	v_mul_f32_e64 v55, v55, v128
	v_mul_f32_e64 v56, v56, v128
	v_mul_f32_e64 v57, v57, v128
	v_mul_f32_e64 v58, v58, v128
	v_mul_f32_e64 v59, v59, v128
	v_mul_f32_e64 v60, v60, v128
	v_mul_f32_e64 v61, v61, v128
	v_mul_f32_e64 v62, v62, v128
	v_mul_f32_e64 v63, v63, v128
	v_mul_f32_e64 v64, v64, v128
	v_mul_f32_e64 v65, v65, v128
	v_cvt_pk_bf16_f32 v148, v86, v87
	v_cvt_pk_bf16_f32 v149, v90, v91
	v_mul_f32_e64 v34, v34, v128
	v_mul_f32_e64 v35, v35, v128
	v_mul_f32_e64 v36, v36, v128
	v_mul_f32_e64 v37, v37, v128
	s_waitcnt lgkmcnt(1)
	v_mfma_f32_32x32x16_bf16 v[50:65], v[94:97], v[148:151], v[50:65]
	ds_read2_b64 v[94:97], v183 offset0:160 offset1:162
	v_mul_f32_e64 v38, v38, v128
	v_mul_f32_e64 v39, v39, v128
	v_mul_f32_e64 v40, v40, v128
	v_mul_f32_e64 v41, v41, v128
	v_mul_f32_e64 v42, v42, v128
	v_mul_f32_e64 v43, v43, v128
	v_mul_f32_e64 v44, v44, v128
	v_mul_f32_e64 v45, v45, v128
	v_mul_f32_e64 v46, v46, v128
	v_mul_f32_e64 v47, v47, v128
	v_mul_f32_e64 v48, v48, v128
	v_mul_f32_e64 v49, v49, v128
	v_cvt_pk_bf16_f32 v66, v66, v67
	v_cvt_pk_bf16_f32 v67, v68, v69
	s_waitcnt lgkmcnt(0)
	v_mfma_f32_32x32x16_bf16 v[34:49], v[94:97], v[148:151], v[34:49]
	ds_read2_b64 v[94:97], v183 offset0:164 offset1:166
	v_cvt_pk_bf16_f32 v68, v70, v71
	v_cvt_pk_bf16_f32 v69, v80, v81
	v_fmac_f32_e32 v184, v147, v128
	s_nop 0
	v_mfma_f32_32x32x16_bf16 v[50:65], v[152:155], v[66:69], v[50:65]
	s_waitcnt lgkmcnt(0)
	v_mfma_f32_32x32x16_bf16 v[34:49], v[94:97], v[66:69], v[34:49]
	v_cvt_pk_bf16_f32 v66, v82, v83
	ds_read2_b64 v[80:83], v182 offset0:136 offset1:138
	v_cvt_pk_bf16_f32 v67, v84, v85
	v_cvt_pk_bf16_f32 v68, v88, v89
	v_cvt_pk_bf16_f32 v69, v92, v93
	s_waitcnt lgkmcnt(0)
	s_nop 0
	v_mfma_f32_32x32x16_bf16 v[50:65], v[80:83], v[66:69], v[50:65]
	ds_read2_b64 v[80:83], v183 offset0:168 offset1:170
	s_waitcnt lgkmcnt(0)
	v_mfma_f32_32x32x16_bf16 v[34:49], v[80:83], v[66:69], v[34:49]
	v_cvt_pk_bf16_f32 v66, v72, v73
	ds_read2_b64 v[70:73], v182 offset0:140 offset1:142
	v_cvt_pk_bf16_f32 v67, v74, v75
	v_cvt_pk_bf16_f32 v68, v76, v77
	v_cvt_pk_bf16_f32 v69, v78, v79
	s_waitcnt lgkmcnt(0)
	s_nop 0
	v_mfma_f32_32x32x16_bf16 v[50:65], v[70:73], v[66:69], v[50:65]
	ds_read2_b64 v[70:73], v183 offset0:172 offset1:174
	s_waitcnt lgkmcnt(0)
	v_mfma_f32_32x32x16_bf16 v[34:49], v[70:73], v[66:69], v[34:49]
	s_cbranch_scc0 .LBB0_1081
	v_mov_b32_e32 v147, v184
	v_mov_b32_e32 v148, v129
	s_mov_b64 s[4:5], s[68:69]
	s_mov_b32 s6, s33
	s_branch .LBB0_1073
.Lcmpb_fast:
	v_lshl_add_u64 v[38:39], s[80:81], 1, v[78:79]
	v_lshl_add_u64 v[34:35], v[38:39], 0, v[114:115]
	v_lshl_add_u64 v[38:39], v[38:39], 0, v[76:77]
	global_load_dwordx4 v[34:37], v[34:35], off
	s_nop 0
	global_load_dwordx4 v[38:41], v[38:39], off
	s_movk_i32 s0, 0xc000
	v_add_co_u32_e64 v42, s[0:1], s0, v82
	s_nop 1
	v_addc_co_u32_e64 v43, s[0:1], -1, v83, s[0:1]
	global_load_dwordx4 v[42:45], v[42:43], off
	s_nop 0
	global_load_dwordx4 v[46:49], v[82:83], off
	v_add_u32_e32 v180, 0x2400, v86
	v_add_u32_e32 v181, 0x3500, v86
	s_barrier
	s_waitcnt vmcnt(3)
	ds_write_b128 v178, v[34:37]
	s_waitcnt vmcnt(2)
	ds_write_b128 v178, v[38:41] offset:4608
	s_waitcnt vmcnt(1)
	ds_write2_b64 v180, v[42:43], v[44:45] offset1:1
	s_waitcnt vmcnt(0)
	ds_write2_b64 v181, v[46:47], v[48:49] offset1:1
	s_waitcnt lgkmcnt(0)
	s_barrier
; DI int crow(int i, int h) { return (i & 3) + 8 * (i >> 2) + 4 * h; }
; DI float shx32(float v) { return __shfl_xor(v, 32); }
; DI void nsa_item(const Params& p_, const EvenBufs& eb_, int b, int g, int tt, unsigned char* smem) {
;     ...
;     f32x16 Sx[2]; qk_tile(sK, qf, Sx, r, h);
; #pragma unroll
;     for (int mt = 0; mt < 2; ++mt) {
; #pragma unroll
;       for (int i = 0; i < 16; ++i) {
;         const bool ok = (kt * 64 + mt * 32 + crow(i, h)) <= nlim;
;         const float pr = __builtin_amdgcn_exp2f(Sx[mt][i] * L2E - mb) * invl;
;         Sx[mt][i] = ok ? pr : 0.f;
;       }
;       float x[4];
; #pragma unroll
;       for (int gg = 0; gg < 4; ++gg) x[gg] = shx32(Sx[mt][4 * gg + 3]);
; #pragma unroll
;       for (int gg = 0; gg < 4; ++gg) {
;         const float prev = h ? x[gg] : (gg ? x[gg > 0 ? gg - 1 : 0] : carry_prev);
;         const float val = Sx[mt][4 * gg] + Sx[mt][4 * gg + 1] + Sx[mt][4 * gg + 2] + Sx[mt][4 * gg + 3] + prev;
	ds_read_b128 v[34:37], v179
	ds_read_b128 v[38:41], v179 offset:32
	s_waitcnt lgkmcnt(1)
	v_mfma_f32_32x32x16_bf16 v[50:65], v[34:37], v[138:141], 0
	ds_read_b128 v[34:37], v179 offset:64
	ds_read_b128 v[90:93], v179 offset:4640
	v_add_u32_e32 v89, s2, v167
	v_add_u32_e32 v182, 0x2000, v87
	v_add_u32_e32 v183, 0x3000, v87
	s_addk_i32 s80, 0x1000
	s_waitcnt lgkmcnt(2)
	v_mfma_f32_32x32x16_bf16 v[50:65], v[38:41], v[130:133], v[50:65]
	s_waitcnt lgkmcnt(1)
	v_mfma_f32_32x32x16_bf16 v[50:65], v[34:37], v[134:137], v[50:65]
	ds_read_b128 v[34:37], v179 offset:96
	s_waitcnt lgkmcnt(0)
	v_mfma_f32_32x32x16_bf16 v[50:65], v[34:37], v[142:145], v[50:65]
	ds_read_b128 v[34:37], v179 offset:4608
	s_waitcnt lgkmcnt(0)
	v_mfma_f32_32x32x16_bf16 v[34:49], v[34:37], v[138:141], 0
	s_nop 8
	v_fma_f32 v50, v50, s96, -v72
	v_exp_f32_e32 v50, v50
	s_nop 0
	v_mul_f32_e32 v50, v80, v50
	v_mfma_f32_32x32x16_bf16 v[34:49], v[90:93], v[130:133], v[34:49]
	ds_read_b128 v[90:93], v179 offset:4672
	s_waitcnt lgkmcnt(0)
	v_mfma_f32_32x32x16_bf16 v[34:49], v[90:93], v[134:137], v[34:49]
	ds_read_b128 v[90:93], v179 offset:4704
	s_waitcnt lgkmcnt(0)
	v_mfma_f32_32x32x16_bf16 v[34:49], v[90:93], v[142:145], v[34:49]
	v_mov_b32_e32 v91, v50
	v_fma_f32 v50, v51, s96, -v72
	v_exp_f32_e32 v50, v50
	v_fma_f32 v51, v53, s96, -v72
	v_exp_f32_e32 v51, v51
	v_mul_f32_e32 v50, v80, v50
	v_mov_b32_e32 v92, v50
	v_fma_f32 v50, v52, s96, -v72
	v_exp_f32_e32 v50, v50
	s_nop 0
	v_mul_f32_e64 v50, v80, v50
	v_mul_f32_e64 v51, v81, v51
	v_mov_b32_e32 v93, v51
	v_fma_f32 v51, v55, s96, -v72
	v_exp_f32_e32 v51, v51
	v_mov_b32_e32 v94, v50
	v_fma_f32 v50, v54, s96, -v72
	v_exp_f32_e32 v50, v50
	s_nop 0
	v_mul_f32_e64 v50, v80, v50
	v_mul_f32_e64 v51, v81, v51
	v_mov_b32_e32 v95, v51
	v_fma_f32 v51, v57, s96, -v72
	v_exp_f32_e32 v51, v51
	v_mov_b32_e32 v96, v50
	v_fma_f32 v50, v56, s96, -v72
	v_exp_f32_e32 v50, v50
	s_nop 0
	v_mul_f32_e64 v50, v80, v50
	v_mul_f32_e64 v51, v81, v51
	v_mov_b32_e32 v97, v51
	v_fma_f32 v51, v59, s96, -v72
	v_exp_f32_e32 v51, v51
	v_mov_b32_e32 v98, v50
	v_fma_f32 v50, v58, s96, -v72
	v_exp_f32_e32 v50, v50
	s_nop 0
	v_mul_f32_e64 v52, v80, v50
	v_mul_f32_e64 v53, v81, v51
	v_mov_b32_e32 v50, v53
	v_fma_f32 v53, v61, s96, -v72
	v_exp_f32_e32 v53, v53
	v_mov_b32_e32 v51, v52
	v_fma_f32 v52, v60, s96, -v72
	v_exp_f32_e32 v52, v52
	s_nop 0
	v_mul_f32_e64 v54, v80, v52
	v_mul_f32_e64 v55, v81, v53
	v_add_u32_e32 v90, s2, v32
	v_mov_b32_e32 v52, v55
	v_fma_f32 v55, v63, s96, -v72
	v_exp_f32_e32 v55, v55
	v_mov_b32_e32 v53, v54
	v_fma_f32 v54, v62, s96, -v72
	v_exp_f32_e32 v54, v54
	v_add_f32_e32 v62, v91, v92
	v_add_f32_e32 v62, v94, v62
	v_mul_f32_e64 v56, v80, v54
	v_mul_f32_e64 v57, v81, v55
	v_add_f32_e32 v62, v93, v62
	v_mov_b32_e32 v54, v57
	v_fma_f32 v57, v65, s96, -v72
	v_exp_f32_e32 v57, v57
	v_mov_b32_e32 v55, v56
	v_fma_f32 v56, v64, s96, -v72
	v_exp_f32_e32 v56, v56
	ds_bpermute_b32 v60, v169, v52
	v_fma_f32 v34, v34, s96, -v72
	v_mul_f32_e64 v58, v80, v56
	v_mul_f32_e64 v59, v81, v57
	v_fma_f32 v35, v35, s96, -v72
	v_mov_b32_e32 v56, v59
	ds_bpermute_b32 v59, v169, v97
	ds_bpermute_b32 v99, v169, v56
	v_mov_b32_e32 v57, v58
	ds_bpermute_b32 v58, v169, v93
	v_exp_f32_e32 v34, v34
	v_exp_f32_e32 v35, v35
	s_add_i32 s2, s2, 64
	s_cmp_eq_u32 s65, s2
	s_waitcnt lgkmcnt(0)
; DI int crow(int i, int h) { return (i & 3) + 8 * (i >> 2) + 4 * h; }
; DI float shx32(float v) { return __shfl_xor(v, 32); }
; DI void nsa_item(const Params& p_, const EvenBufs& eb_, int b, int g, int tt, unsigned char* smem) {
;     ...
;     f32x16 Sx[2]; qk_tile(sK, qf, Sx, r, h);
; #pragma unroll
;     for (int mt = 0; mt < 2; ++mt) {
; #pragma unroll
;       for (int i = 0; i < 16; ++i) {
;         const bool ok = (kt * 64 + mt * 32 + crow(i, h)) <= nlim;
;         const float pr = __builtin_amdgcn_exp2f(Sx[mt][i] * L2E - mb) * invl;
;         Sx[mt][i] = ok ? pr : 0.f;
;       }
;       float x[4];
; #pragma unroll
;       for (int gg = 0; gg < 4; ++gg) x[gg] = shx32(Sx[mt][4 * gg + 3]);
; #pragma unroll
;       for (int gg = 0; gg < 4; ++gg) {
;         const float prev = h ? x[gg] : (gg ? x[gg > 0 ? gg - 1 : 0] : carry_prev);
;         const float val = Sx[mt][4 * gg] + Sx[mt][4 * gg + 1] + Sx[mt][4 * gg + 2] + Sx[mt][4 * gg + 3] + prev;
;         impW[(wid * 32 + r) * 64 + kt * 16 + mt * 8 + 2 * gg + h] = val;
;       }
;       carry_prev = x[3];
;     }
;     pv_tile<2>(sV, Sx, O, r, h);
;   }
	v_cndmask_b32_e32 v61, v58, v88, vcc
	v_add_f32_e32 v61, v62, v61
	v_add_f32_e32 v62, v96, v95
	v_add_f32_e32 v62, v98, v62
	v_cndmask_b32_e32 v58, v59, v58, vcc
	v_add_f32_e32 v62, v97, v62
	v_add_f32_e32 v58, v62, v58
	ds_write2_b32 v90, v61, v58 offset1:2
	v_cndmask_b32_e32 v58, v60, v59, vcc
	v_add_f32_e32 v59, v51, v50
	v_add_f32_e32 v59, v53, v59
	v_add_f32_e32 v59, v52, v59
	v_add_f32_e32 v58, v59, v58
	v_cndmask_b32_e32 v59, v99, v60, vcc
	v_add_f32_e32 v60, v55, v54
	v_add_f32_e32 v60, v57, v60
	v_add_f32_e32 v60, v56, v60
	v_add_f32_e32 v59, v60, v59
	ds_write2_b32 v90, v58, v59 offset0:4 offset1:6
	v_mul_f32_e64 v34, v80, v34
	v_mul_f32_e64 v35, v81, v35
	s_nop 1
	v_mov_b32_e32 v58, v35
	v_fma_f32 v35, v37, s96, -v72
	v_exp_f32_e32 v35, v35
	v_mov_b32_e32 v59, v34
	v_fma_f32 v34, v36, s96, -v72
	v_exp_f32_e32 v34, v34
	s_nop 0
	v_mul_f32_e64 v34, v80, v34
	v_mul_f32_e64 v35, v81, v35
	v_mov_b32_e32 v60, v35
	v_fma_f32 v35, v39, s96, -v72
	v_exp_f32_e32 v35, v35
	v_mov_b32_e32 v61, v34
	v_fma_f32 v34, v38, s96, -v72
	v_exp_f32_e32 v34, v34
	s_nop 0
	v_mul_f32_e64 v34, v80, v34
	v_mul_f32_e64 v35, v81, v35
	v_add_f32_e32 v38, v59, v58
	v_mov_b32_e32 v62, v35
	v_fma_f32 v35, v41, s96, -v72
	v_exp_f32_e32 v35, v35
	v_mov_b32_e32 v63, v34
	v_fma_f32 v34, v40, s96, -v72
	v_exp_f32_e32 v34, v34
	s_nop 0
	v_mul_f32_e64 v34, v80, v34
	v_mul_f32_e64 v35, v81, v35
	v_add_f32_e32 v38, v61, v38
	v_mov_b32_e32 v64, v35
	v_fma_f32 v35, v43, s96, -v72
	v_exp_f32_e32 v35, v35
	v_mov_b32_e32 v65, v34
	v_fma_f32 v34, v42, s96, -v72
	v_exp_f32_e32 v34, v34
	s_nop 0
	v_mul_f32_e64 v34, v80, v34
	v_mul_f32_e64 v35, v81, v35
	v_add_f32_e32 v38, v60, v38
	v_mov_b32_e32 v42, v35
	v_fma_f32 v35, v45, s96, -v72
	v_exp_f32_e32 v35, v35
	v_mov_b32_e32 v43, v34
	v_fma_f32 v34, v44, s96, -v72
	v_exp_f32_e32 v34, v34
	s_nop 0
	v_mul_f32_e64 v34, v80, v34
	v_mul_f32_e64 v35, v81, v35
	s_nop 0
	v_mov_b32_e32 v44, v35
	v_fma_f32 v35, v47, s96, -v72
	v_exp_f32_e32 v35, v35
	v_mov_b32_e32 v45, v34
	v_fma_f32 v34, v46, s96, -v72
	v_exp_f32_e32 v34, v34
	s_nop 0
	v_mul_f32_e64 v34, v80, v34
	v_mul_f32_e64 v35, v81, v35
	s_nop 0
	v_mov_b32_e32 v46, v35
	v_fma_f32 v35, v49, s96, -v72
	v_exp_f32_e32 v35, v35
	v_mov_b32_e32 v47, v34
	v_fma_f32 v34, v48, s96, -v72
	v_exp_f32_e32 v34, v34
	ds_bpermute_b32 v36, v169, v44
	v_mul_f32_e64 v34, v80, v34
	v_mul_f32_e64 v35, v81, v35
	s_nop 0
	v_mov_b32_e32 v48, v35
	ds_bpermute_b32 v35, v169, v64
	ds_bpermute_b32 v88, v169, v48
	v_mov_b32_e32 v49, v34
	ds_bpermute_b32 v34, v169, v60
	s_mov_b64 s[0:1], 0x80
	v_lshl_add_u64 v[82:83], v[82:83], 0, s[0:1]
	s_waitcnt lgkmcnt(0)
	v_cndmask_b32_e32 v37, v34, v99, vcc
	v_add_f32_e32 v37, v38, v37
	v_add_f32_e32 v38, v63, v62
	v_add_f32_e32 v38, v65, v38
	v_cndmask_b32_e32 v34, v35, v34, vcc
	v_add_f32_e32 v38, v64, v38
	v_add_f32_e32 v34, v38, v34
	ds_write2_b32 v90, v37, v34 offset0:8 offset1:10
	v_cndmask_b32_e32 v34, v36, v35, vcc
	v_add_f32_e32 v35, v43, v42
	v_add_f32_e32 v35, v45, v35
	v_add_f32_e32 v35, v44, v35
	v_add_f32_e32 v34, v35, v34
	v_cndmask_b32_e32 v35, v88, v36, vcc
	v_add_f32_e32 v36, v47, v46
	v_add_f32_e32 v36, v49, v36
	v_add_f32_e32 v36, v48, v36
	v_add_f32_e32 v35, v36, v35
	ds_write2_b32 v90, v34, v35 offset0:12 offset1:14
	v_cvt_pk_bf16_f32 v34, v91, v92
	v_cvt_pk_bf16_f32 v35, v94, v93
	ds_read2_b64 v[90:93], v182 offset0:128 offset1:130
	ds_read2_b64 v[38:41], v182 offset0:132 offset1:134
	v_cvt_pk_bf16_f32 v36, v96, v95
	v_cvt_pk_bf16_f32 v37, v98, v97
	s_waitcnt lgkmcnt(1)
	s_nop 0
	v_mfma_f32_32x32x16_bf16 v[16:31], v[90:93], v[34:37], v[16:31]
	ds_read2_b64 v[90:93], v183 offset0:160 offset1:162
	s_waitcnt lgkmcnt(0)
	v_mfma_f32_32x32x16_bf16 v[0:15], v[90:93], v[34:37], v[0:15]
	v_cvt_pk_bf16_f32 v34, v51, v50
	v_cvt_pk_bf16_f32 v35, v53, v52
	v_cvt_pk_bf16_f32 v36, v55, v54
	v_cvt_pk_bf16_f32 v37, v57, v56
	s_nop 1
	s_nop 0
	v_mfma_f32_32x32x16_bf16 v[16:31], v[38:41], v[34:37], v[16:31]
	ds_read2_b64 v[38:41], v183 offset0:164 offset1:166
	s_waitcnt lgkmcnt(0)
	v_mfma_f32_32x32x16_bf16 v[0:15], v[38:41], v[34:37], v[0:15]
	ds_read2_b64 v[38:41], v182 offset0:136 offset1:138
	v_cvt_pk_bf16_f32 v34, v59, v58
	v_cvt_pk_bf16_f32 v35, v61, v60
	v_cvt_pk_bf16_f32 v36, v63, v62
	v_cvt_pk_bf16_f32 v37, v65, v64
	s_waitcnt lgkmcnt(0)
	s_nop 0
	v_mfma_f32_32x32x16_bf16 v[16:31], v[38:41], v[34:37], v[16:31]
	ds_read2_b64 v[38:41], v183 offset0:168 offset1:170
	s_waitcnt lgkmcnt(0)
	v_mfma_f32_32x32x16_bf16 v[0:15], v[38:41], v[34:37], v[0:15]
	ds_read2_b64 v[38:41], v182 offset0:140 offset1:142
	v_cvt_pk_bf16_f32 v34, v43, v42
	v_cvt_pk_bf16_f32 v35, v45, v44
	v_cvt_pk_bf16_f32 v36, v47, v46
	v_cvt_pk_bf16_f32 v37, v49, v48
	s_waitcnt lgkmcnt(0)
	s_nop 0
	v_mfma_f32_32x32x16_bf16 v[16:31], v[38:41], v[34:37], v[16:31]
	ds_read2_b64 v[38:41], v183 offset0:172 offset1:174
	s_waitcnt lgkmcnt(0)
	v_mfma_f32_32x32x16_bf16 v[0:15], v[38:41], v[34:37], v[0:15]
	s_cbranch_scc0 .LBB0_1065
	s_branch .Lcmpb_exit

; DI int crow(int i, int h) { return (i & 3) + 8 * (i >> 2) + 4 * h; }
; DI float shx32(float v) { return __shfl_xor(v, 32); }
; template <bool MASKED>
; DI float online_softmax_t(f32x16 (&Sx)[2], unsigned vb, float& m, float& l) {
;   float mx = NEG;
; #pragma unroll
;   for (int mt = 0; mt < 2; ++mt)
; #pragma unroll
;     for (int i = 0; i < 16; ++i) {
;       float s = Sx[mt][i];
;       if (MASKED) { s = ((vb >> (mt * 16 + i)) & 1u) ? s : NEG; Sx[mt][i] = s; }
;       mx = fmaxf(mx, s);
;     }
;   mx = fmaxf(mx, shx32(mx));
; DI void nsa_item(const Params& p_, const EvenBufs& eb_, int b, int g, int tt, unsigned char* smem) {
;     ...
;     for (int kt = kt_lo; kt <= kt_hi; ++kt) {
;       __syncthreads();
;       tstore72(kr, sK, tid); tstore68(vr, sV, tid);
;       __syncthreads();
;       if (kt < kt_hi) { tload(kr, Kg + (size_t)(kt + 1) * 64 * 64, 64, tid); tload(vr, VTg + (kt + 1) * 64, SP, tid); }
;       f32x16 Sx[2]; qk_tile(sK, qf, Sx, r, h);
;       const bool masked = !((kt * 64 + 63 <= t0) && (kt * 64 > t0 + 31 - 512));
;       unsigned vb = 0;
;       if (masked) {
; #pragma unroll
;         for (int mt = 0; mt < 2; ++mt)
; #pragma unroll
;           for (int i = 0; i < 16; ++i) {
;             const int key = kt * 64 + mt * 32 + crow(i, h);
;             vb |= (unsigned)((key <= t) && (key > t - 512)) << (mt * 16 + i);
;           }
;       }
;       if (!masked) vb = 0xffffffffu;
;       const float alpha = online_softmax_t<true>(Sx, vb, m, l);
.LBB0_1087:
	v_and_b32_e32 v187, 1, v32
	v_cmp_eq_u32_e64 s[60:61], 0, v187
	v_cmp_lt_i32_e64 s[16:17], -1, v32
	s_add_i32 s64, s64, 1
	v_cndmask_b32_e64 v190, v114, v214, s[60:61]
	v_and_b32_e32 v114, 2, v32
	v_cmp_eq_u32_e64 s[62:63], 0, v114
	s_add_i32 s80, s80, 64
	s_nop 0
	v_cndmask_b32_e64 v191, v115, v214, s[62:63]
	v_and_b32_e32 v115, 4, v32
	v_cmp_eq_u32_e64 s[56:57], 0, v115
	v_and_b32_e32 v115, 8, v32
	v_cmp_eq_u32_e64 s[58:59], 0, v115
	v_and_b32_e32 v115, 16, v32
	v_cmp_eq_u32_e64 s[52:53], 0, v115
	v_and_b32_e32 v115, 32, v32
	v_cmp_eq_u32_e64 s[54:55], 0, v115
	v_and_b32_e32 v115, 64, v32
	v_cmp_eq_u32_e64 s[48:49], 0, v115
	v_and_b32_e32 v115, 0x80, v32
	v_cmp_eq_u32_e64 s[50:51], 0, v115
	v_and_b32_e32 v115, 0x100, v32
	v_cmp_eq_u32_e64 s[44:45], 0, v115
	v_and_b32_e32 v115, 0x200, v32
	v_cmp_eq_u32_e64 s[46:47], 0, v115
	v_and_b32_e32 v115, 0x400, v32
	v_max3_f32 v114, v190, s92, v191
	v_cndmask_b32_e64 v192, v116, v214, s[56:57]
	v_cndmask_b32_e64 v193, v117, v214, s[58:59]
	v_cmp_eq_u32_e64 s[40:41], 0, v115
	v_and_b32_e32 v115, 0x800, v32
	v_max3_f32 v114, v114, v192, v193
	v_cndmask_b32_e64 v194, v118, v214, s[52:53]
	v_cndmask_b32_e64 v195, v119, v214, s[54:55]
	v_cmp_eq_u32_e64 s[42:43], 0, v115
	v_and_b32_e32 v115, 0x1000, v32
	v_max3_f32 v114, v114, v194, v195
	v_cndmask_b32_e64 v196, v120, v214, s[48:49]
	v_cndmask_b32_e64 v197, v121, v214, s[50:51]
	v_cmp_eq_u32_e64 s[36:37], 0, v115
	v_and_b32_e32 v115, 0x2000, v32
	v_max3_f32 v114, v114, v196, v197
	v_cndmask_b32_e64 v198, v122, v214, s[44:45]
	v_cndmask_b32_e64 v199, v123, v214, s[46:47]
	v_cmp_eq_u32_e64 s[38:39], 0, v115
	v_and_b32_e32 v115, 0x4000, v32
	v_max3_f32 v114, v114, v198, v199
	v_cndmask_b32_e64 v200, v124, v214, s[40:41]
	v_cndmask_b32_e64 v201, v125, v214, s[42:43]
	v_cmp_eq_u32_e64 s[30:31], 0, v115
	v_and_b32_e32 v115, 0x8000, v32
	v_max3_f32 v114, v114, v200, v201
	v_cndmask_b32_e64 v202, v126, v214, s[36:37]
	v_cndmask_b32_e64 v203, v127, v214, s[38:39]
	v_cmp_eq_u32_e64 s[34:35], 0, v115
	v_max3_f32 v114, v114, v202, v203
	v_cndmask_b32_e64 v204, v128, v214, s[30:31]
	v_cndmask_b32_e64 v205, v129, v214, s[34:35]
	v_max3_f32 v116, v114, v204, v205
	v_and_b32_e32 v114, 0x10000, v32
	v_cmp_eq_u32_e64 s[26:27], 0, v114
	s_nop 1
	v_cndmask_b32_e64 v114, v98, v214, s[26:27]
	v_and_b32_e32 v98, 0x20000, v32
	v_cmp_eq_u32_e64 s[28:29], 0, v98
	s_nop 1
	v_cndmask_b32_e64 v115, v99, v214, s[28:29]
	v_and_b32_e32 v99, 0x40000, v32
	v_cmp_eq_u32_e64 s[22:23], 0, v99
	v_and_b32_e32 v99, 0x80000, v32
	v_cmp_eq_u32_e64 s[24:25], 0, v99
	v_and_b32_e32 v99, 0x100000, v32
	v_cmp_eq_u32_e64 s[18:19], 0, v99
	v_and_b32_e32 v99, 0x200000, v32
	v_cmp_eq_u32_e64 s[20:21], 0, v99
	v_and_b32_e32 v99, 0x400000, v32
	v_cmp_eq_u32_e32 vcc, 0, v99
	v_and_b32_e32 v99, 0x800000, v32
	v_cmp_eq_u32_e64 s[0:1], 0, v99
	v_and_b32_e32 v99, 0x1000000, v32
	v_cmp_eq_u32_e64 s[2:3], 0, v99
	v_and_b32_e32 v99, 0x2000000, v32
	v_max3_f32 v98, v116, v114, v115
	v_cndmask_b32_e64 v116, v100, v214, s[22:23]
	v_cndmask_b32_e64 v117, v101, v214, s[24:25]
	v_cmp_eq_u32_e64 s[4:5], 0, v99
	v_and_b32_e32 v99, 0x4000000, v32
	v_max3_f32 v98, v98, v116, v117
	v_cndmask_b32_e64 v120, v102, v214, s[18:19]
	v_cndmask_b32_e64 v121, v103, v214, s[20:21]
	v_cmp_eq_u32_e64 s[6:7], 0, v99
	v_and_b32_e32 v99, 0x8000000, v32
	v_max3_f32 v98, v98, v120, v121
	v_cndmask_b32_e32 v124, v104, v214, vcc
	v_cndmask_b32_e64 v125, v105, v214, s[0:1]
	v_cmp_eq_u32_e64 s[8:9], 0, v99
	v_and_b32_e32 v99, 0x10000000, v32
	v_max3_f32 v98, v98, v124, v125
	v_cndmask_b32_e64 v104, v106, v214, s[2:3]
	v_cndmask_b32_e64 v105, v107, v214, s[4:5]
	v_cmp_eq_u32_e64 s[10:11], 0, v99
	v_and_b32_e32 v99, 0x20000000, v32
	v_max3_f32 v98, v98, v104, v105
	v_cndmask_b32_e64 v106, v108, v214, s[6:7]
	v_cndmask_b32_e64 v107, v109, v214, s[8:9]
	v_cmp_eq_u32_e64 s[12:13], 0, v99
	v_and_b32_e32 v99, 2.0, v32
	v_max3_f32 v98, v98, v106, v107
	v_cndmask_b32_e64 v108, v110, v214, s[10:11]
	v_cndmask_b32_e64 v109, v111, v214, s[12:13]
	v_cmp_eq_u32_e64 s[14:15], 0, v99
	v_max3_f32 v98, v98, v108, v109
	v_cndmask_b32_e64 v111, v113, v214, s[16:17]
	v_cndmask_b32_e64 v110, v112, v214, s[14:15]
	v_max3_f32 v32, v98, v110, v111
	ds_bpermute_b32 v98, v169, v32
	s_waitcnt lgkmcnt(0)
; #define MFMA(a, b, c) __builtin_amdgcn_mfma_f32_32x32x16_bf16((a), (b), (c), 0, 0, 0)
; template <int NDT> DI void pv_tile(const bf16_t* sV, const f32x16 (&P)[2], f32x16 (&O)[NDT], int r, int h) {
; #pragma unroll
;   for (int mt = 0; mt < 2; ++mt)
; #pragma unroll
;     for (int sp = 0; sp < 2; ++sp) {
;       u32x4 pk;
;       pk.x = pack2(P[mt][8 * sp + 0], P[mt][8 * sp + 1]); pk.y = pack2(P[mt][8 * sp + 2], P[mt][8 * sp + 3]);
;       pk.z = pack2(P[mt][8 * sp + 4], P[mt][8 * sp + 5]); pk.w = pack2(P[mt][8 * sp + 6], P[mt][8 * sp + 7]);
;       const bf16x8 pb = __builtin_bit_cast(bf16x8, pk);
; #pragma unroll
;       for (int dt = 0; dt < NDT; ++dt) {
;         const bf16_t* vp = sV + (dt * 32 + r) * 68 + mt * 32 + sp * 16 + 4 * h;
;         const bf16x4 lo = *(const bf16x4*)vp, hi = *(const bf16x4*)(vp + 8);
;         const bf16x8 va = __builtin_shufflevector(lo, hi, 0, 1, 2, 3, 4, 5, 6, 7);
;         O[dt] = MFMA(va, pb, O[dt]);
;       }
;       if (NDT > 2) __builtin_amdgcn_sched_barrier(0);
;     }
; }
; template <bool MASKED>
; DI float online_softmax_t(f32x16 (&Sx)[2], unsigned vb, float& m, float& l) {
;     ...
;   const float alpha = __builtin_amdgcn_exp2f((m - mn) * L2E);
;   const float mb = mn * L2E;
;   f32x2 sum2 = {0.f, 0.f};
;   const f32x2 l2e2 = {L2E, L2E}, mb2 = {mb, mb};
; #pragma unroll
;   for (int mt = 0; mt < 2; ++mt)
; #pragma unroll
;     for (int i = 0; i < 16; i += 2) {
;       const f32x2 t = (f32x2){Sx[mt][i], Sx[mt][i + 1]} * l2e2 - mb2;
;       f32x2 p = {__builtin_amdgcn_exp2f(t.x), __builtin_amdgcn_exp2f(t.y)};
;       if (MASKED) { p.x = ((vb >> (mt * 16 + i)) & 1u) ? p.x : 0.f; p.y = ((vb >> (mt * 16 + i + 1)) & 1u) ? p.y : 0.f; }
;       Sx[mt][i] = p.x; Sx[mt][i + 1] = p.y;
;       sum2 += p;
;     }
;   l = l * alpha + (sum2.x + sum2.y);
;   m = mn;
;   return alpha;
; }
; DI float online_softmax(f32x16 (&Sx)[2], unsigned vb, bool masked, float& m, float& l) {
;   float alpha;
;   if (masked) alpha = online_softmax_t<true>(Sx, vb, m, l);
;   else { __builtin_amdgcn_sched_barrier(0); alpha = online_softmax_t<false>(Sx, vb, m, l); __builtin_amdgcn_sched_barrier(0); }
;   return alpha;
; }
; template <int NDT> DI void scale_o(f32x16 (&O)[NDT], float a) {
; #pragma unroll
;   for (int dt = 0; dt < NDT; ++dt)
; #pragma unroll
;     for (int i = 0; i < 16; ++i) O[dt][i] *= a;
; }
	v_max3_f32 v187, v189, v32, v98
	v_mul_f32_e32 v32, 0x3fb8aa3b, v187
	v_fma_f32 v100, v192, s96, -v32
	v_fma_f32 v101, v193, s96, -v32
	v_fma_f32 v98, v190, s96, -v32
	v_fma_f32 v99, v191, s96, -v32
	v_exp_f32_e32 v100, v100
	v_exp_f32_e32 v101, v101
	v_exp_f32_e32 v98, v98
	v_exp_f32_e32 v99, v99
	v_cndmask_b32_e64 v122, v100, 0, s[56:57]
	v_cndmask_b32_e64 v123, v101, 0, s[58:59]
	v_fma_f32 v100, v194, s96, -v32
	v_fma_f32 v101, v195, s96, -v32
	v_cndmask_b32_e64 v118, v98, 0, s[60:61]
	v_exp_f32_e32 v100, v100
	v_exp_f32_e32 v101, v101
	v_cndmask_b32_e64 v119, v99, 0, s[62:63]
	v_add_f32_e64 v98, v118, 0
	v_add_f32_e64 v99, v119, 0
	v_cndmask_b32_e64 v126, v100, 0, s[52:53]
	v_cndmask_b32_e64 v127, v101, 0, s[54:55]
	v_fma_f32 v100, v196, s96, -v32
	v_fma_f32 v101, v197, s96, -v32
	v_add_f32_e64 v98, v122, v98
	v_add_f32_e64 v99, v123, v99
	v_exp_f32_e32 v100, v100
	v_exp_f32_e32 v101, v101
	v_add_f32_e64 v98, v126, v98
	v_add_f32_e64 v99, v127, v99
	v_fma_f32 v110, v110, s96, -v32
	v_fma_f32 v111, v111, s96, -v32
	v_cndmask_b32_e64 v128, v100, 0, s[48:49]
	v_cndmask_b32_e64 v129, v101, 0, s[50:51]
	v_add_f32_e64 v100, v128, v98
	v_add_f32_e64 v101, v129, v99
	v_fma_f32 v98, v198, s96, -v32
	v_fma_f32 v99, v199, s96, -v32
	v_fma_f32 v114, v114, s96, -v32
	v_fma_f32 v115, v115, s96, -v32
	v_exp_f32_e32 v98, v98
	v_exp_f32_e32 v99, v99
	v_fma_f32 v116, v116, s96, -v32
	v_fma_f32 v117, v117, s96, -v32
	v_fma_f32 v120, v120, s96, -v32
	v_fma_f32 v121, v121, s96, -v32
	v_cndmask_b32_e64 v98, v98, 0, s[44:45]
	v_cndmask_b32_e64 v99, v99, 0, s[46:47]
	v_add_f32_e64 v102, v98, v100
	v_add_f32_e64 v103, v99, v101
	v_fma_f32 v100, v200, s96, -v32
	v_fma_f32 v101, v201, s96, -v32
	v_fma_f32 v124, v124, s96, -v32
	v_fma_f32 v125, v125, s96, -v32
	v_exp_f32_e32 v100, v100
	v_exp_f32_e32 v101, v101
	v_fma_f32 v104, v104, s96, -v32
	v_fma_f32 v105, v105, s96, -v32
	v_fma_f32 v106, v106, s96, -v32
	v_fma_f32 v107, v107, s96, -v32
	v_cndmask_b32_e64 v100, v100, 0, s[40:41]
	v_cndmask_b32_e64 v101, v101, 0, s[42:43]
	v_add_f32_e64 v112, v100, v102
	v_add_f32_e64 v113, v101, v103
	v_fma_f32 v102, v202, s96, -v32
	v_fma_f32 v103, v203, s96, -v32
	v_fma_f32 v108, v108, s96, -v32
	v_fma_f32 v109, v109, s96, -v32
	v_exp_f32_e32 v102, v102
	v_exp_f32_e32 v103, v103
	v_cvt_pk_bf16_f32 v194, v126, v127
	v_cvt_pk_bf16_f32 v195, v128, v129
	v_cndmask_b32_e64 v102, v102, 0, s[36:37]
	v_cndmask_b32_e64 v103, v103, 0, s[38:39]
	v_add_f32_e64 v190, v102, v112
	v_add_f32_e64 v191, v103, v113
	v_fma_f32 v112, v204, s96, -v32
	v_fma_f32 v113, v205, s96, -v32
	v_exp_f32_e32 v32, v110
	ds_read2_b64 v[126:129], v182 offset0:128 offset1:130
	ds_read2_b64 v[196:199], v182 offset0:132 offset1:134
	v_cvt_pk_bf16_f32 v192, v118, v119
	v_cvt_pk_bf16_f32 v193, v122, v123
	v_cndmask_b32_e64 v110, v32, 0, s[14:15]
	v_sub_f32_e32 v32, v189, v187
	v_mul_f32_e32 v32, 0x3fb8aa3b, v32
	v_exp_f32_e32 v32, v32
	v_exp_f32_e32 v112, v112
	v_exp_f32_e32 v113, v113
	v_exp_f32_e32 v114, v114
	v_mul_f32_e64 v82, v82, v32
	v_mul_f32_e64 v83, v83, v32
	v_mul_f32_e64 v84, v84, v32
	v_mul_f32_e64 v85, v85, v32
	v_mul_f32_e64 v86, v86, v32
	v_mul_f32_e64 v87, v87, v32
	v_mul_f32_e64 v88, v88, v32
	v_mul_f32_e64 v89, v89, v32
	v_mul_f32_e64 v90, v90, v32
	v_mul_f32_e64 v91, v91, v32
	v_mul_f32_e64 v92, v92, v32
	v_mul_f32_e64 v93, v93, v32
	v_mul_f32_e64 v94, v94, v32
	v_mul_f32_e64 v95, v95, v32
	v_mul_f32_e64 v96, v96, v32
	v_mul_f32_e64 v97, v97, v32
	v_mul_f32_e64 v66, v66, v32
	v_mul_f32_e64 v67, v67, v32
	v_mul_f32_e64 v68, v68, v32
	v_mul_f32_e64 v69, v69, v32
	s_waitcnt lgkmcnt(1)
	v_mfma_f32_32x32x16_bf16 v[82:97], v[126:129], v[192:195], v[82:97]
	ds_read2_b64 v[126:129], v183 offset0:160 offset1:162
	v_mul_f32_e64 v70, v70, v32
	v_mul_f32_e64 v71, v71, v32
	v_mul_f32_e64 v72, v72, v32
	v_mul_f32_e64 v73, v73, v32
	v_mul_f32_e64 v74, v74, v32
	v_mul_f32_e64 v75, v75, v32
	v_mul_f32_e64 v76, v76, v32
	v_mul_f32_e64 v77, v77, v32
	v_mul_f32_e64 v78, v78, v32
	v_mul_f32_e64 v79, v79, v32
	v_mul_f32_e64 v80, v80, v32
	v_mul_f32_e64 v81, v81, v32
	v_exp_f32_e32 v115, v115
	v_cndmask_b32_e64 v112, v112, 0, s[30:31]
	s_waitcnt lgkmcnt(0)
	v_mfma_f32_32x32x16_bf16 v[66:81], v[126:129], v[192:195], v[66:81]
	ds_read2_b64 v[126:129], v183 offset0:164 offset1:166
	v_cndmask_b32_e64 v113, v113, 0, s[34:35]
	v_add_f32_e64 v190, v112, v190
	v_add_f32_e64 v191, v113, v191
	v_cndmask_b32_e64 v114, v114, 0, s[26:27]
	v_cndmask_b32_e64 v115, v115, 0, s[28:29]
	v_cvt_pk_bf16_f32 v98, v98, v99
	v_cvt_pk_bf16_f32 v99, v100, v101
	v_cvt_pk_bf16_f32 v100, v102, v103
	v_cvt_pk_bf16_f32 v101, v112, v113
	v_add_f32_e64 v190, v114, v190
	v_add_f32_e64 v191, v115, v191
	v_exp_f32_e32 v116, v116
	v_mfma_f32_32x32x16_bf16 v[82:97], v[196:199], v[98:101], v[82:97]
	v_exp_f32_e32 v117, v117
	v_exp_f32_e32 v120, v120
	v_exp_f32_e32 v121, v121
	v_exp_f32_e32 v124, v124
	v_exp_f32_e32 v125, v125
	v_cndmask_b32_e64 v116, v116, 0, s[22:23]
	v_cndmask_b32_e64 v117, v117, 0, s[24:25]
	s_waitcnt lgkmcnt(0)
	v_mfma_f32_32x32x16_bf16 v[66:81], v[126:129], v[98:101], v[66:81]
	v_cvt_pk_bf16_f32 v98, v114, v115
	ds_read2_b64 v[112:115], v182 offset0:136 offset1:138
	v_cndmask_b32_e64 v120, v120, 0, s[18:19]
	v_cndmask_b32_e64 v121, v121, 0, s[20:21]
	v_cndmask_b32_e64 v124, v124, 0, vcc
	v_cndmask_b32_e64 v125, v125, 0, s[0:1]
	v_cvt_pk_bf16_f32 v99, v116, v117
	v_cvt_pk_bf16_f32 v100, v120, v121
	v_cvt_pk_bf16_f32 v101, v124, v125
	v_exp_f32_e32 v104, v104
	v_exp_f32_e32 v105, v105
	s_waitcnt lgkmcnt(0)
; DI unsigned pack2(float a, float b) { bf2_t v = __builtin_convertvector((f32x2){a, b}, bf2_t); return __builtin_bit_cast(unsigned, v); }
; #define MFMA(a, b, c) __builtin_amdgcn_mfma_f32_32x32x16_bf16((a), (b), (c), 0, 0, 0)
; template <int NDT> DI void pv_tile(const bf16_t* sV, const f32x16 (&P)[2], f32x16 (&O)[NDT], int r, int h) {
; #pragma unroll
;   for (int mt = 0; mt < 2; ++mt)
; #pragma unroll
;     for (int sp = 0; sp < 2; ++sp) {
;       u32x4 pk;
;       pk.x = pack2(P[mt][8 * sp + 0], P[mt][8 * sp + 1]); pk.y = pack2(P[mt][8 * sp + 2], P[mt][8 * sp + 3]);
;       pk.z = pack2(P[mt][8 * sp + 4], P[mt][8 * sp + 5]); pk.w = pack2(P[mt][8 * sp + 6], P[mt][8 * sp + 7]);
;       const bf16x8 pb = __builtin_bit_cast(bf16x8, pk);
; #pragma unroll
;       for (int dt = 0; dt < NDT; ++dt) {
;         const bf16_t* vp = sV + (dt * 32 + r) * 68 + mt * 32 + sp * 16 + 4 * h;
;         const bf16x4 lo = *(const bf16x4*)vp, hi = *(const bf16x4*)(vp + 8);
;         const bf16x8 va = __builtin_shufflevector(lo, hi, 0, 1, 2, 3, 4, 5, 6, 7);
;         O[dt] = MFMA(va, pb, O[dt]);
;       }
;       if (NDT > 2) __builtin_amdgcn_sched_barrier(0);
;     }
; }
; template <bool MASKED>
; DI float online_softmax_t(f32x16 (&Sx)[2], unsigned vb, float& m, float& l) {
;     ...
;       if (MASKED) { p.x = ((vb >> (mt * 16 + i)) & 1u) ? p.x : 0.f; p.y = ((vb >> (mt * 16 + i + 1)) & 1u) ? p.y : 0.f; }
;       Sx[mt][i] = p.x; Sx[mt][i + 1] = p.y;
;       sum2 += p;
;     }
;   l = l * alpha + (sum2.x + sum2.y);
	v_mfma_f32_32x32x16_bf16 v[82:97], v[112:115], v[98:101], v[82:97]
	ds_read2_b64 v[112:115], v183 offset0:168 offset1:170
	v_add_f32_e64 v190, v116, v190
	v_add_f32_e64 v191, v117, v191
	v_cndmask_b32_e64 v104, v104, 0, s[2:3]
	v_add_f32_e64 v190, v120, v190
	v_add_f32_e64 v191, v121, v191
	v_cndmask_b32_e64 v105, v105, 0, s[4:5]
	v_add_f32_e64 v190, v124, v190
	v_add_f32_e64 v191, v125, v191
	v_exp_f32_e32 v106, v106
	v_add_f32_e64 v190, v104, v190
	v_add_f32_e64 v191, v105, v191
	s_waitcnt lgkmcnt(0)
	v_mfma_f32_32x32x16_bf16 v[66:81], v[112:115], v[98:101], v[66:81]
	v_cvt_pk_bf16_f32 v98, v104, v105
	ds_read2_b64 v[102:105], v182 offset0:140 offset1:142
	v_exp_f32_e32 v107, v107
	v_exp_f32_e32 v108, v108
	v_exp_f32_e32 v109, v109
	v_exp_f32_e32 v111, v111
	v_cndmask_b32_e64 v106, v106, 0, s[6:7]
	v_cndmask_b32_e64 v107, v107, 0, s[8:9]
	v_cndmask_b32_e64 v108, v108, 0, s[10:11]
	v_cndmask_b32_e64 v109, v109, 0, s[12:13]
	v_cndmask_b32_e64 v111, v111, 0, s[16:17]
	v_cvt_pk_bf16_f32 v99, v106, v107
	v_cvt_pk_bf16_f32 v100, v108, v109
	v_cvt_pk_bf16_f32 v101, v110, v111
	v_add_f32_e64 v190, v106, v190
	v_add_f32_e64 v191, v107, v191
	s_mov_b64 s[0:1], 0x2000
	s_waitcnt lgkmcnt(0)
	v_mfma_f32_32x32x16_bf16 v[82:97], v[102:105], v[98:101], v[82:97]
	ds_read2_b64 v[102:105], v183 offset0:172 offset1:174
	v_add_f32_e64 v190, v108, v190
	v_add_f32_e64 v191, v109, v191
	v_lshl_add_u64 v[176:177], v[176:177], 0, s[0:1]
	v_add_f32_e64 v190, v110, v190
	v_add_f32_e64 v191, v111, v191
	s_andn2_b64 vcc, exec, s[66:67]
	v_add_f32_e32 v190, v190, v191
	v_fmac_f32_e32 v190, v188, v32
	s_waitcnt lgkmcnt(0)
	v_mfma_f32_32x32x16_bf16 v[66:81], v[102:105], v[98:101], v[66:81]
	s_cbranch_vccz .LBB0_1056
	v_mov_b32_e32 v189, v187
	v_mov_b32_e32 v188, v190
	s_branch .LBB0_1083
.Lwin_fast:
	s_nop 7
	s_add_i32 s64, s64, 1
	v_mov_b32_e32 v190, v114
	s_add_i32 s80, s80, 64
	s_nop 0
	v_mov_b32_e32 v191, v115
	v_max3_f32 v114, v190, s92, v191
	v_mov_b32_e32 v192, v116
	v_mov_b32_e32 v193, v117
	v_max3_f32 v114, v114, v192, v193
	v_mov_b32_e32 v194, v118
	v_mov_b32_e32 v195, v119
	v_max3_f32 v114, v114, v194, v195
	v_mov_b32_e32 v196, v120
	v_mov_b32_e32 v197, v121
	v_max3_f32 v114, v114, v196, v197
	v_mov_b32_e32 v198, v122
	v_mov_b32_e32 v199, v123
	v_max3_f32 v114, v114, v198, v199
	v_mov_b32_e32 v200, v124
	v_mov_b32_e32 v201, v125
	v_max3_f32 v114, v114, v200, v201
	v_mov_b32_e32 v202, v126
	v_mov_b32_e32 v203, v127
	v_max3_f32 v114, v114, v202, v203
	v_mov_b32_e32 v204, v128
	v_mov_b32_e32 v205, v129
	v_max3_f32 v116, v114, v204, v205
	s_nop 1
	v_mov_b32_e32 v114, v98
	s_nop 1
	v_mov_b32_e32 v115, v99
	v_max3_f32 v98, v116, v114, v115
	v_mov_b32_e32 v116, v100
	v_mov_b32_e32 v117, v101
	v_max3_f32 v98, v98, v116, v117
	v_mov_b32_e32 v120, v102
	v_mov_b32_e32 v121, v103
	v_max3_f32 v98, v98, v120, v121
	v_mov_b32_e32 v124, v104
	v_mov_b32_e32 v125, v105
	v_max3_f32 v98, v98, v124, v125
	v_mov_b32_e32 v104, v106
	v_mov_b32_e32 v105, v107
	v_max3_f32 v98, v98, v104, v105
	v_mov_b32_e32 v106, v108
	v_mov_b32_e32 v107, v109
	v_max3_f32 v98, v98, v106, v107
	v_mov_b32_e32 v108, v110
	v_mov_b32_e32 v109, v111
	v_max3_f32 v98, v98, v108, v109
	v_mov_b32_e32 v111, v113
	v_mov_b32_e32 v110, v112
	v_max3_f32 v32, v98, v110, v111
	ds_bpermute_b32 v98, v169, v32
	s_waitcnt lgkmcnt(0)
; #define MFMA(a, b, c) __builtin_amdgcn_mfma_f32_32x32x16_bf16((a), (b), (c), 0, 0, 0)
; template <int NDT> DI void pv_tile(const bf16_t* sV, const f32x16 (&P)[2], f32x16 (&O)[NDT], int r, int h) {
; #pragma unroll
;   for (int mt = 0; mt < 2; ++mt)
; #pragma unroll
;     for (int sp = 0; sp < 2; ++sp) {
;       u32x4 pk;
;       pk.x = pack2(P[mt][8 * sp + 0], P[mt][8 * sp + 1]); pk.y = pack2(P[mt][8 * sp + 2], P[mt][8 * sp + 3]);
;       pk.z = pack2(P[mt][8 * sp + 4], P[mt][8 * sp + 5]); pk.w = pack2(P[mt][8 * sp + 6], P[mt][8 * sp + 7]);
;       const bf16x8 pb = __builtin_bit_cast(bf16x8, pk);
; #pragma unroll
;       for (int dt = 0; dt < NDT; ++dt) {
;         const bf16_t* vp = sV + (dt * 32 + r) * 68 + mt * 32 + sp * 16 + 4 * h;
;         const bf16x4 lo = *(const bf16x4*)vp, hi = *(const bf16x4*)(vp + 8);
;         const bf16x8 va = __builtin_shufflevector(lo, hi, 0, 1, 2, 3, 4, 5, 6, 7);
;         O[dt] = MFMA(va, pb, O[dt]);
;       }
;       if (NDT > 2) __builtin_amdgcn_sched_barrier(0);
;     }
; }
; template <bool MASKED>
; DI float online_softmax_t(f32x16 (&Sx)[2], unsigned vb, float& m, float& l) {
;     ...
;   const float alpha = __builtin_amdgcn_exp2f((m - mn) * L2E);
;   const float mb = mn * L2E;
;   f32x2 sum2 = {0.f, 0.f};
;   const f32x2 l2e2 = {L2E, L2E}, mb2 = {mb, mb};
; #pragma unroll
;   for (int mt = 0; mt < 2; ++mt)
; #pragma unroll
;     for (int i = 0; i < 16; i += 2) {
;       const f32x2 t = (f32x2){Sx[mt][i], Sx[mt][i + 1]} * l2e2 - mb2;
;       f32x2 p = {__builtin_amdgcn_exp2f(t.x), __builtin_amdgcn_exp2f(t.y)};
;       if (MASKED) { p.x = ((vb >> (mt * 16 + i)) & 1u) ? p.x : 0.f; p.y = ((vb >> (mt * 16 + i + 1)) & 1u) ? p.y : 0.f; }
;       Sx[mt][i] = p.x; Sx[mt][i + 1] = p.y;
;       sum2 += p;
;     }
;   l = l * alpha + (sum2.x + sum2.y);
;   m = mn;
;   return alpha;
; }
; DI float online_softmax(f32x16 (&Sx)[2], unsigned vb, bool masked, float& m, float& l) {
;   float alpha;
;   if (masked) alpha = online_softmax_t<true>(Sx, vb, m, l);
;   else { __builtin_amdgcn_sched_barrier(0); alpha = online_softmax_t<false>(Sx, vb, m, l); __builtin_amdgcn_sched_barrier(0); }
;   return alpha;
; }
; template <int NDT> DI void scale_o(f32x16 (&O)[NDT], float a) {
; #pragma unroll
;   for (int dt = 0; dt < NDT; ++dt)
; #pragma unroll
;     for (int i = 0; i < 16; ++i) O[dt][i] *= a;
; }
	v_max3_f32 v187, v189, v32, v98
	v_mul_f32_e32 v32, 0x3fb8aa3b, v187
	v_fma_f32 v100, v192, s96, -v32
	v_fma_f32 v101, v193, s96, -v32
	v_fma_f32 v98, v190, s96, -v32
	v_fma_f32 v99, v191, s96, -v32
	v_exp_f32_e32 v100, v100
	v_exp_f32_e32 v101, v101
	v_exp_f32_e32 v98, v98
	v_exp_f32_e32 v99, v99
	v_mov_b32_e32 v122, v100
	v_mov_b32_e32 v123, v101
	v_fma_f32 v100, v194, s96, -v32
	v_fma_f32 v101, v195, s96, -v32
	v_mov_b32_e32 v118, v98
	v_exp_f32_e32 v100, v100
	v_exp_f32_e32 v101, v101
	v_mov_b32_e32 v119, v99
	v_add_f32_e64 v98, v118, 0
	v_add_f32_e64 v99, v119, 0
	v_mov_b32_e32 v126, v100
	v_mov_b32_e32 v127, v101
	v_fma_f32 v100, v196, s96, -v32
	v_fma_f32 v101, v197, s96, -v32
	v_add_f32_e64 v98, v122, v98
	v_add_f32_e64 v99, v123, v99
	v_exp_f32_e32 v100, v100
	v_exp_f32_e32 v101, v101
	v_add_f32_e64 v98, v126, v98
	v_add_f32_e64 v99, v127, v99
	v_fma_f32 v110, v110, s96, -v32
	v_fma_f32 v111, v111, s96, -v32
	v_mov_b32_e32 v128, v100
	v_mov_b32_e32 v129, v101
	v_add_f32_e64 v100, v128, v98
	v_add_f32_e64 v101, v129, v99
	v_fma_f32 v98, v198, s96, -v32
	v_fma_f32 v99, v199, s96, -v32
	v_fma_f32 v114, v114, s96, -v32
	v_fma_f32 v115, v115, s96, -v32
	v_exp_f32_e32 v98, v98
	v_exp_f32_e32 v99, v99
	v_fma_f32 v116, v116, s96, -v32
	v_fma_f32 v117, v117, s96, -v32
	v_fma_f32 v120, v120, s96, -v32
	v_fma_f32 v121, v121, s96, -v32
	v_add_f32_e64 v102, v98, v100
	v_add_f32_e64 v103, v99, v101
	v_fma_f32 v100, v200, s96, -v32
	v_fma_f32 v101, v201, s96, -v32
	v_fma_f32 v124, v124, s96, -v32
	v_fma_f32 v125, v125, s96, -v32
	v_exp_f32_e32 v100, v100
	v_exp_f32_e32 v101, v101
	v_fma_f32 v104, v104, s96, -v32
	v_fma_f32 v105, v105, s96, -v32
	v_fma_f32 v106, v106, s96, -v32
	v_fma_f32 v107, v107, s96, -v32
	v_add_f32_e64 v112, v100, v102
	v_add_f32_e64 v113, v101, v103
	v_fma_f32 v102, v202, s96, -v32
	v_fma_f32 v103, v203, s96, -v32
	v_fma_f32 v108, v108, s96, -v32
	v_fma_f32 v109, v109, s96, -v32
	v_exp_f32_e32 v102, v102
	v_exp_f32_e32 v103, v103
	v_cvt_pk_bf16_f32 v194, v126, v127
	v_cvt_pk_bf16_f32 v195, v128, v129
	v_add_f32_e64 v190, v102, v112
	v_add_f32_e64 v191, v103, v113
	v_fma_f32 v112, v204, s96, -v32
	v_fma_f32 v113, v205, s96, -v32
	v_exp_f32_e32 v32, v110
	ds_read2_b64 v[126:129], v182 offset0:128 offset1:130
	ds_read2_b64 v[196:199], v182 offset0:132 offset1:134
	v_cvt_pk_bf16_f32 v192, v118, v119
	v_cvt_pk_bf16_f32 v193, v122, v123
	v_mov_b32_e32 v110, v32
	v_sub_f32_e32 v32, v189, v187
	v_mul_f32_e32 v32, 0x3fb8aa3b, v32
	v_exp_f32_e32 v32, v32
	v_exp_f32_e32 v112, v112
	v_exp_f32_e32 v113, v113
	v_exp_f32_e32 v114, v114
	v_mul_f32_e64 v82, v82, v32
	v_mul_f32_e64 v83, v83, v32
	v_mul_f32_e64 v84, v84, v32
	v_mul_f32_e64 v85, v85, v32
	v_mul_f32_e64 v86, v86, v32
	v_mul_f32_e64 v87, v87, v32
	v_mul_f32_e64 v88, v88, v32
	v_mul_f32_e64 v89, v89, v32
	v_mul_f32_e64 v90, v90, v32
	v_mul_f32_e64 v91, v91, v32
	v_mul_f32_e64 v92, v92, v32
	v_mul_f32_e64 v93, v93, v32
	v_mul_f32_e64 v94, v94, v32
	v_mul_f32_e64 v95, v95, v32
	v_mul_f32_e64 v96, v96, v32
	v_mul_f32_e64 v97, v97, v32
	v_mul_f32_e64 v66, v66, v32
	v_mul_f32_e64 v67, v67, v32
	v_mul_f32_e64 v68, v68, v32
	v_mul_f32_e64 v69, v69, v32
	s_waitcnt lgkmcnt(1)
	v_mfma_f32_32x32x16_bf16 v[82:97], v[126:129], v[192:195], v[82:97]
	ds_read2_b64 v[126:129], v183 offset0:160 offset1:162
	v_mul_f32_e64 v70, v70, v32
	v_mul_f32_e64 v71, v71, v32
	v_mul_f32_e64 v72, v72, v32
	v_mul_f32_e64 v73, v73, v32
	v_mul_f32_e64 v74, v74, v32
	v_mul_f32_e64 v75, v75, v32
	v_mul_f32_e64 v76, v76, v32
	v_mul_f32_e64 v77, v77, v32
	v_mul_f32_e64 v78, v78, v32
	v_mul_f32_e64 v79, v79, v32
	v_mul_f32_e64 v80, v80, v32
	v_mul_f32_e64 v81, v81, v32
	v_exp_f32_e32 v115, v115
	s_waitcnt lgkmcnt(0)
	v_mfma_f32_32x32x16_bf16 v[66:81], v[126:129], v[192:195], v[66:81]
	ds_read2_b64 v[126:129], v183 offset0:164 offset1:166
	v_add_f32_e64 v190, v112, v190
	v_add_f32_e64 v191, v113, v191
	v_cvt_pk_bf16_f32 v98, v98, v99
	v_cvt_pk_bf16_f32 v99, v100, v101
	v_cvt_pk_bf16_f32 v100, v102, v103
	v_cvt_pk_bf16_f32 v101, v112, v113
	v_add_f32_e64 v190, v114, v190
	v_add_f32_e64 v191, v115, v191
	v_exp_f32_e32 v116, v116
	v_mfma_f32_32x32x16_bf16 v[82:97], v[196:199], v[98:101], v[82:97]
	v_exp_f32_e32 v117, v117
	v_exp_f32_e32 v120, v120
	v_exp_f32_e32 v121, v121
	v_exp_f32_e32 v124, v124
	v_exp_f32_e32 v125, v125
	s_waitcnt lgkmcnt(0)
	v_mfma_f32_32x32x16_bf16 v[66:81], v[126:129], v[98:101], v[66:81]
	v_cvt_pk_bf16_f32 v98, v114, v115
	ds_read2_b64 v[112:115], v182 offset0:136 offset1:138
	v_cvt_pk_bf16_f32 v99, v116, v117
	v_cvt_pk_bf16_f32 v100, v120, v121
	v_cvt_pk_bf16_f32 v101, v124, v125
	v_exp_f32_e32 v104, v104
	v_exp_f32_e32 v105, v105
	s_waitcnt lgkmcnt(0)
	v_mfma_f32_32x32x16_bf16 v[82:97], v[112:115], v[98:101], v[82:97]
	ds_read2_b64 v[112:115], v183 offset0:168 offset1:170
	v_add_f32_e64 v190, v116, v190
	v_add_f32_e64 v191, v117, v191
	v_add_f32_e64 v190, v120, v190
	v_add_f32_e64 v191, v121, v191
	v_add_f32_e64 v190, v124, v190
	v_add_f32_e64 v191, v125, v191
	v_exp_f32_e32 v106, v106
	v_add_f32_e64 v190, v104, v190
	v_add_f32_e64 v191, v105, v191
	s_waitcnt lgkmcnt(0)
	v_mfma_f32_32x32x16_bf16 v[66:81], v[112:115], v[98:101], v[66:81]
	v_cvt_pk_bf16_f32 v98, v104, v105
	ds_read2_b64 v[102:105], v182 offset0:140 offset1:142
	v_exp_f32_e32 v107, v107
	v_exp_f32_e32 v108, v108
	v_exp_f32_e32 v109, v109
	v_exp_f32_e32 v111, v111
	v_cvt_pk_bf16_f32 v99, v106, v107
	v_cvt_pk_bf16_f32 v100, v108, v109
	v_cvt_pk_bf16_f32 v101, v110, v111
	v_add_f32_e64 v190, v106, v190
	v_add_f32_e64 v191, v107, v191
	s_mov_b64 s[0:1], 0x2000
	s_waitcnt lgkmcnt(0)
	v_mfma_f32_32x32x16_bf16 v[82:97], v[102:105], v[98:101], v[82:97]
	ds_read2_b64 v[102:105], v183 offset0:172 offset1:174
	v_add_f32_e64 v190, v108, v190
	v_add_f32_e64 v191, v109, v191
	v_lshl_add_u64 v[176:177], v[176:177], 0, s[0:1]
	v_add_f32_e64 v190, v110, v190
	v_add_f32_e64 v191, v111, v191
	s_andn2_b64 vcc, exec, s[66:67]
	v_add_f32_e32 v190, v190, v191
	v_fmac_f32_e32 v190, v188, v32
	s_waitcnt lgkmcnt(0)
	v_mfma_f32_32x32x16_bf16 v[66:81], v[102:105], v[98:101], v[66:81]
	s_cbranch_vccz .LBB0_1056
	v_mov_b32_e32 v189, v187
	v_mov_b32_e32 v188, v190
	s_branch .LBB0_1083
